# MFMA issue order within each 8-group changed to a snake so consecutive MFMAs share one operand (on top of zero-init)
# speedup vs baseline: 1.0129x; 1.0046x over previous
.LBB0_74:
	s_ashr_i32 s27, s26, 31
	s_lshl_b64 s[28:29], s[26:27], 19
	s_add_u32 s28, s3, s28
	s_addc_u32 s29, s35, s29
	s_and_b64 s[30:31], s[4:5], exec
	s_cselect_b32 s27, s29, s49
	s_cselect_b32 s68, s28, s48
	s_ashr_i32 s23, s22, 31
	s_lshl_b64 s[30:31], s[22:23], 19
	s_add_u32 s30, s50, s30
	s_addc_u32 s31, s51, s31
	s_and_b64 s[70:71], s[4:5], exec
	s_cselect_b32 s69, s31, s47
	s_cselect_b32 s70, s30, s46
	s_lshl_b32 s23, s44, 8
	v_add_u32_e32 v0, s23, v148
	s_add_u32 s71, s46, 0x100
	v_ashrrev_i32_e32 v1, 31, v0
	s_addc_u32 s74, s47, 0
	v_lshl_add_u64 v[144:145], v[0:1], 4, s[12:13]
	s_add_u32 s44, s48, 0x40080
	s_addc_u32 s45, s49, 0
	s_mov_b32 s75, -2
	s_mov_b64 s[46:47], 0
	v_add_u32_e32 v153, s64, v147
	ds_read_b128 v[160:163], v153
	ds_read_b128 v[164:167], v153 offset:1024
	ds_read_b128 v[168:171], v153 offset:2048
	ds_read_b128 v[172:175], v153 offset:3072
	v_add_u32_e32 v153, s65, v147
	ds_read_b128 v[176:179], v153
	ds_read_b128 v[180:183], v153 offset:1024
	ds_read_b128 v[186:189], v153 offset:2048
	ds_read_b128 v[190:193], v153 offset:3072
	s_add_u32 s48, s44, 0xfffc0080
	s_addc_u32 s49, s45, -1
	s_and_b64 s[46:47], s[46:47], exec
	s_cselect_b32 s49, s27, s49
	s_cselect_b32 s48, s68, s48
	s_cselect_b32 s47, s69, s74
	s_cselect_b32 s46, s70, s71
	v_lshl_add_u64 v[154:155], s[44:45], 0, v[138:139]
	s_add_i32 m0, s55, 0xc000
	ds_read_b128 v[194:197], v150
	ds_read_b128 v[198:201], v150 offset:1024
	ds_read_b128 v[202:205], v150 offset:2048
	ds_read_b128 v[206:209], v150 offset:3072
	ds_read_b128 v[210:213], v150 offset:4096
	ds_read_b128 v[214:217], v150 offset:5120
	ds_read_b128 v[218:221], v150 offset:6144
	ds_read_b128 v[222:225], v150 offset:7168
	global_load_lds_dwordx4 v[154:155], off
	v_lshl_add_u64 v[154:155], s[44:45], 0, v[136:137]
	s_add_i32 m0, s55, 0xe000
	s_nop 0
	global_load_lds_dwordx4 v[154:155], off
	s_waitcnt vmcnt(8)
	s_waitcnt lgkmcnt(0)
	s_barrier
	s_setprio 1
	s_waitcnt lgkmcnt(0)
	v_mfma_f32_16x16x32_bf16 v[124:127], v[160:163], v[194:197], 0
	v_mfma_f32_16x16x32_bf16 v[116:119], v[168:171], v[194:197], 0
	v_mfma_f32_16x16x32_bf16 v[108:111], v[160:163], v[202:205], 0
	v_mfma_f32_16x16x32_bf16 v[100:103], v[168:171], v[202:205], 0
	v_mfma_f32_16x16x32_bf16 v[92:95], v[160:163], v[210:213], 0
	v_mfma_f32_16x16x32_bf16 v[84:87], v[168:171], v[210:213], 0
	v_mfma_f32_16x16x32_bf16 v[76:79], v[160:163], v[218:221], 0
	v_mfma_f32_16x16x32_bf16 v[68:71], v[168:171], v[218:221], 0
	v_mfma_f32_16x16x32_bf16 v[124:127], v[164:167], v[198:201], v[124:127]
	v_mfma_f32_16x16x32_bf16 v[116:119], v[172:175], v[198:201], v[116:119]
	v_mfma_f32_16x16x32_bf16 v[108:111], v[164:167], v[206:209], v[108:111]
	v_mfma_f32_16x16x32_bf16 v[100:103], v[172:175], v[206:209], v[100:103]
	v_mfma_f32_16x16x32_bf16 v[92:95], v[164:167], v[214:217], v[92:95]
	v_mfma_f32_16x16x32_bf16 v[84:87], v[172:175], v[214:217], v[84:87]
	v_mfma_f32_16x16x32_bf16 v[76:79], v[164:167], v[222:225], v[76:79]
	v_mfma_f32_16x16x32_bf16 v[68:71], v[172:175], v[222:225], v[68:71]
	s_setprio 0
	s_setprio 1
	v_mfma_f32_16x16x32_bf16 v[120:123], v[176:179], v[194:197], 0
	v_mfma_f32_16x16x32_bf16 v[112:115], v[186:189], v[194:197], 0
	v_mfma_f32_16x16x32_bf16 v[104:107], v[176:179], v[202:205], 0
	v_mfma_f32_16x16x32_bf16 v[96:99], v[186:189], v[202:205], 0
	v_mfma_f32_16x16x32_bf16 v[88:91], v[176:179], v[210:213], 0
	v_mfma_f32_16x16x32_bf16 v[80:83], v[186:189], v[210:213], 0
	v_mfma_f32_16x16x32_bf16 v[72:75], v[176:179], v[218:221], 0
	v_mfma_f32_16x16x32_bf16 v[64:67], v[186:189], v[218:221], 0
	v_mfma_f32_16x16x32_bf16 v[120:123], v[180:183], v[198:201], v[120:123]
	v_mfma_f32_16x16x32_bf16 v[112:115], v[190:193], v[198:201], v[112:115]
	v_mfma_f32_16x16x32_bf16 v[104:107], v[180:183], v[206:209], v[104:107]
	v_mfma_f32_16x16x32_bf16 v[96:99], v[190:193], v[206:209], v[96:99]
	v_mfma_f32_16x16x32_bf16 v[88:91], v[180:183], v[214:217], v[88:91]
	v_mfma_f32_16x16x32_bf16 v[80:83], v[190:193], v[214:217], v[80:83]
	v_mfma_f32_16x16x32_bf16 v[72:75], v[180:183], v[222:225], v[72:75]
	v_mfma_f32_16x16x32_bf16 v[64:67], v[190:193], v[222:225], v[64:67]
	s_setprio 0
	s_barrier
	s_add_i32 s76, s64, s52
	v_lshl_add_u64 v[154:155], s[46:47], 0, v[132:133]
	s_mov_b32 m0, s76
	ds_read_b128 v[194:197], v150 offset:16384
	ds_read_b128 v[198:201], v150 offset:17408
	ds_read_b128 v[202:205], v150 offset:18432
	ds_read_b128 v[206:209], v150 offset:19456
	ds_read_b128 v[210:213], v150 offset:20480
	ds_read_b128 v[214:217], v150 offset:21504
	ds_read_b128 v[218:221], v150 offset:22528
	ds_read_b128 v[222:225], v150 offset:23552
	global_load_lds_dwordx4 v[154:155], off
	s_add_i32 m0, s76, 0x2000
	s_add_u32 s76, s46, 0x40000
	v_lshl_add_u64 v[226:227], s[46:47], 0, v[128:129]
	s_addc_u32 s77, s47, 0
	s_add_i32 s78, s65, s52
	global_load_lds_dwordx4 v[226:227], off
	v_lshl_add_u64 v[228:229], s[76:77], 0, v[132:133]
	s_mov_b32 m0, s78
	v_lshl_add_u64 v[230:231], s[48:49], 0, v[130:131]
	global_load_lds_dwordx4 v[228:229], off
	v_lshl_add_u64 v[228:229], s[76:77], 0, v[128:129]
	s_add_i32 m0, s78, 0x2000
	s_nop 0
	global_load_lds_dwordx4 v[228:229], off
	v_lshl_add_u64 v[228:229], s[48:49], 0, v[134:135]
	s_mov_b32 m0, s55
	s_nop 0
	global_load_lds_dwordx4 v[228:229], off
	s_mov_b32 m0, s56
	s_nop 0
	global_load_lds_dwordx4 v[230:231], off
	s_waitcnt vmcnt(8)
	s_waitcnt lgkmcnt(0)
	s_barrier
	s_setprio 1
	s_waitcnt lgkmcnt(0)
	v_mfma_f32_16x16x32_bf16 v[60:63], v[160:163], v[194:197], 0
	v_mfma_f32_16x16x32_bf16 v[52:55], v[168:171], v[194:197], 0
	v_mfma_f32_16x16x32_bf16 v[44:47], v[160:163], v[202:205], 0
	v_mfma_f32_16x16x32_bf16 v[36:39], v[168:171], v[202:205], 0
	v_mfma_f32_16x16x32_bf16 v[28:31], v[160:163], v[210:213], 0
	v_mfma_f32_16x16x32_bf16 v[20:23], v[168:171], v[210:213], 0
	v_mfma_f32_16x16x32_bf16 v[12:15], v[160:163], v[218:221], 0
	v_mfma_f32_16x16x32_bf16 v[4:7], v[168:171], v[218:221], 0
	v_mfma_f32_16x16x32_bf16 v[60:63], v[164:167], v[198:201], v[60:63]
	v_mfma_f32_16x16x32_bf16 v[52:55], v[172:175], v[198:201], v[52:55]
	v_mfma_f32_16x16x32_bf16 v[44:47], v[164:167], v[206:209], v[44:47]
	v_mfma_f32_16x16x32_bf16 v[36:39], v[172:175], v[206:209], v[36:39]
	v_mfma_f32_16x16x32_bf16 v[28:31], v[164:167], v[214:217], v[28:31]
	v_mfma_f32_16x16x32_bf16 v[20:23], v[172:175], v[214:217], v[20:23]
	v_mfma_f32_16x16x32_bf16 v[12:15], v[164:167], v[222:225], v[12:15]
	v_mfma_f32_16x16x32_bf16 v[4:7], v[172:175], v[222:225], v[4:7]
	s_setprio 0
	s_setprio 1
	v_mfma_f32_16x16x32_bf16 v[56:59], v[176:179], v[194:197], 0
	v_mfma_f32_16x16x32_bf16 v[48:51], v[186:189], v[194:197], 0
	v_mfma_f32_16x16x32_bf16 v[40:43], v[176:179], v[202:205], 0
	v_mfma_f32_16x16x32_bf16 v[32:35], v[186:189], v[202:205], 0
	v_mfma_f32_16x16x32_bf16 v[24:27], v[176:179], v[210:213], 0
	v_mfma_f32_16x16x32_bf16 v[16:19], v[186:189], v[210:213], 0
	v_mfma_f32_16x16x32_bf16 v[8:11], v[176:179], v[218:221], 0
	v_mfma_f32_16x16x32_bf16 v[0:3], v[186:189], v[218:221], 0
	v_mfma_f32_16x16x32_bf16 v[56:59], v[180:183], v[198:201], v[56:59]
	v_mfma_f32_16x16x32_bf16 v[48:51], v[190:193], v[198:201], v[48:51]
	v_mfma_f32_16x16x32_bf16 v[40:43], v[180:183], v[206:209], v[40:43]
	v_mfma_f32_16x16x32_bf16 v[32:35], v[190:193], v[206:209], v[32:35]
	v_mfma_f32_16x16x32_bf16 v[24:27], v[180:183], v[214:217], v[24:27]
	v_mfma_f32_16x16x32_bf16 v[16:19], v[190:193], v[214:217], v[16:19]
	v_mfma_f32_16x16x32_bf16 v[8:11], v[180:183], v[222:225], v[8:11]
	v_mfma_f32_16x16x32_bf16 v[0:3], v[190:193], v[222:225], v[0:3]
	s_setprio 0
	s_barrier
	s_add_i32 s76, 0, 0x18000
	v_add_u32_e32 v153, s76, v147
	s_add_i32 s77, 0, 0x1c000
	ds_read_b128 v[160:163], v153
	ds_read_b128 v[164:167], v153 offset:1024
	ds_read_b128 v[168:171], v153 offset:2048
	ds_read_b128 v[172:175], v153 offset:3072
	v_add_u32_e32 v153, s77, v147
	ds_read_b128 v[176:179], v153
	ds_read_b128 v[180:183], v153 offset:1024
	ds_read_b128 v[186:189], v153 offset:2048
	ds_read_b128 v[190:193], v153 offset:3072
	s_add_u32 s48, s48, 0x40000
	s_addc_u32 s49, s49, 0
	s_mov_b32 m0, s57
	v_lshl_add_u64 v[232:233], s[48:49], 0, v[134:135]
	ds_read_b128 v[194:197], v150 offset:32768
	ds_read_b128 v[198:201], v150 offset:33792
	ds_read_b128 v[202:205], v150 offset:34816
	ds_read_b128 v[206:209], v150 offset:35840
	ds_read_b128 v[210:213], v150 offset:36864
	ds_read_b128 v[214:217], v150 offset:37888
	ds_read_b128 v[218:221], v150 offset:38912
	ds_read_b128 v[222:225], v150 offset:39936
	global_load_lds_dwordx4 v[232:233], off
	v_lshl_add_u64 v[232:233], s[48:49], 0, v[130:131]
	s_mov_b32 m0, s58
	s_nop 0
	global_load_lds_dwordx4 v[232:233], off
	s_waitcnt vmcnt(8)
	s_waitcnt lgkmcnt(0)
	s_barrier
	s_setprio 1
	s_waitcnt lgkmcnt(0)
	v_mfma_f32_16x16x32_bf16 v[124:127], v[160:163], v[194:197], v[124:127]
	v_mfma_f32_16x16x32_bf16 v[116:119], v[168:171], v[194:197], v[116:119]
	v_mfma_f32_16x16x32_bf16 v[100:103], v[168:171], v[202:205], v[100:103]
	v_mfma_f32_16x16x32_bf16 v[108:111], v[160:163], v[202:205], v[108:111]
	v_mfma_f32_16x16x32_bf16 v[92:95], v[160:163], v[210:213], v[92:95]
	v_mfma_f32_16x16x32_bf16 v[84:87], v[168:171], v[210:213], v[84:87]
	v_mfma_f32_16x16x32_bf16 v[68:71], v[168:171], v[218:221], v[68:71]
	v_mfma_f32_16x16x32_bf16 v[76:79], v[160:163], v[218:221], v[76:79]
	v_mfma_f32_16x16x32_bf16 v[124:127], v[164:167], v[198:201], v[124:127]
	v_mfma_f32_16x16x32_bf16 v[116:119], v[172:175], v[198:201], v[116:119]
	v_mfma_f32_16x16x32_bf16 v[100:103], v[172:175], v[206:209], v[100:103]
	v_mfma_f32_16x16x32_bf16 v[108:111], v[164:167], v[206:209], v[108:111]
	v_mfma_f32_16x16x32_bf16 v[92:95], v[164:167], v[214:217], v[92:95]
	v_mfma_f32_16x16x32_bf16 v[84:87], v[172:175], v[214:217], v[84:87]
	v_mfma_f32_16x16x32_bf16 v[68:71], v[172:175], v[222:225], v[68:71]
	v_mfma_f32_16x16x32_bf16 v[76:79], v[164:167], v[222:225], v[76:79]
	s_setprio 0
	s_setprio 1
	v_mfma_f32_16x16x32_bf16 v[120:123], v[176:179], v[194:197], v[120:123]
	v_mfma_f32_16x16x32_bf16 v[112:115], v[186:189], v[194:197], v[112:115]
	v_mfma_f32_16x16x32_bf16 v[96:99], v[186:189], v[202:205], v[96:99]
	v_mfma_f32_16x16x32_bf16 v[104:107], v[176:179], v[202:205], v[104:107]
	v_mfma_f32_16x16x32_bf16 v[88:91], v[176:179], v[210:213], v[88:91]
	v_mfma_f32_16x16x32_bf16 v[80:83], v[186:189], v[210:213], v[80:83]
	v_mfma_f32_16x16x32_bf16 v[64:67], v[186:189], v[218:221], v[64:67]
	v_mfma_f32_16x16x32_bf16 v[72:75], v[176:179], v[218:221], v[72:75]
	v_mfma_f32_16x16x32_bf16 v[120:123], v[180:183], v[198:201], v[120:123]
	v_mfma_f32_16x16x32_bf16 v[112:115], v[190:193], v[198:201], v[112:115]
	v_mfma_f32_16x16x32_bf16 v[96:99], v[190:193], v[206:209], v[96:99]
	v_mfma_f32_16x16x32_bf16 v[104:107], v[180:183], v[206:209], v[104:107]
	v_mfma_f32_16x16x32_bf16 v[88:91], v[180:183], v[214:217], v[88:91]
	v_mfma_f32_16x16x32_bf16 v[80:83], v[190:193], v[214:217], v[80:83]
	v_mfma_f32_16x16x32_bf16 v[64:67], v[190:193], v[222:225], v[64:67]
	v_mfma_f32_16x16x32_bf16 v[72:75], v[180:183], v[222:225], v[72:75]
	s_setprio 0
	s_barrier
	s_add_i32 s48, s76, s52
	v_lshl_add_u64 v[154:155], v[154:155], 0, s[14:15]
	s_mov_b32 m0, s48
	ds_read_b128 v[194:197], v150 offset:49152
	ds_read_b128 v[198:201], v150 offset:50176
	ds_read_b128 v[202:205], v150 offset:51200
	ds_read_b128 v[206:209], v150 offset:52224
	ds_read_b128 v[210:213], v150 offset:53248
	ds_read_b128 v[214:217], v150 offset:54272
	ds_read_b128 v[218:221], v150 offset:55296
	ds_read_b128 v[222:225], v150 offset:56320
	global_load_lds_dwordx4 v[154:155], off
	s_add_i32 m0, s48, 0x2000
	s_add_u32 s46, s46, 0x40080
	v_lshl_add_u64 v[154:155], v[226:227], 0, s[14:15]
	s_addc_u32 s47, s47, 0
	s_add_i32 s48, s77, s52
	global_load_lds_dwordx4 v[154:155], off
	v_lshl_add_u64 v[154:155], s[46:47], 0, v[132:133]
	s_mov_b32 m0, s48
	s_nop 0
	global_load_lds_dwordx4 v[154:155], off
	v_lshl_add_u64 v[154:155], s[46:47], 0, v[128:129]
	s_add_i32 m0, s48, 0x2000
	s_nop 0
	global_load_lds_dwordx4 v[154:155], off
	v_lshl_add_u64 v[154:155], v[228:229], 0, s[14:15]
	s_mov_b32 m0, s60
	s_nop 0
	global_load_lds_dwordx4 v[154:155], off
	v_lshl_add_u64 v[154:155], v[230:231], 0, s[14:15]
	s_mov_b32 m0, s61
	s_nop 0
	global_load_lds_dwordx4 v[154:155], off
	s_waitcnt vmcnt(8)
	s_waitcnt lgkmcnt(0)
	s_barrier
	s_setprio 1
	s_waitcnt lgkmcnt(0)
	v_mfma_f32_16x16x32_bf16 v[60:63], v[160:163], v[194:197], v[60:63]
	v_mfma_f32_16x16x32_bf16 v[52:55], v[168:171], v[194:197], v[52:55]
	v_mfma_f32_16x16x32_bf16 v[36:39], v[168:171], v[202:205], v[36:39]
	v_mfma_f32_16x16x32_bf16 v[44:47], v[160:163], v[202:205], v[44:47]
	v_mfma_f32_16x16x32_bf16 v[28:31], v[160:163], v[210:213], v[28:31]
	v_mfma_f32_16x16x32_bf16 v[20:23], v[168:171], v[210:213], v[20:23]
	v_mfma_f32_16x16x32_bf16 v[4:7], v[168:171], v[218:221], v[4:7]
	v_mfma_f32_16x16x32_bf16 v[12:15], v[160:163], v[218:221], v[12:15]
	v_mfma_f32_16x16x32_bf16 v[60:63], v[164:167], v[198:201], v[60:63]
	v_mfma_f32_16x16x32_bf16 v[52:55], v[172:175], v[198:201], v[52:55]
	v_mfma_f32_16x16x32_bf16 v[36:39], v[172:175], v[206:209], v[36:39]
	v_mfma_f32_16x16x32_bf16 v[44:47], v[164:167], v[206:209], v[44:47]
	v_mfma_f32_16x16x32_bf16 v[28:31], v[164:167], v[214:217], v[28:31]
	v_mfma_f32_16x16x32_bf16 v[20:23], v[172:175], v[214:217], v[20:23]
	v_mfma_f32_16x16x32_bf16 v[4:7], v[172:175], v[222:225], v[4:7]
	v_mfma_f32_16x16x32_bf16 v[12:15], v[164:167], v[222:225], v[12:15]
	s_setprio 0
	s_setprio 1
	v_mfma_f32_16x16x32_bf16 v[56:59], v[176:179], v[194:197], v[56:59]
	v_mfma_f32_16x16x32_bf16 v[48:51], v[186:189], v[194:197], v[48:51]
	v_mfma_f32_16x16x32_bf16 v[32:35], v[186:189], v[202:205], v[32:35]
	v_mfma_f32_16x16x32_bf16 v[40:43], v[176:179], v[202:205], v[40:43]
	v_mfma_f32_16x16x32_bf16 v[24:27], v[176:179], v[210:213], v[24:27]
	v_mfma_f32_16x16x32_bf16 v[16:19], v[186:189], v[210:213], v[16:19]
	v_mfma_f32_16x16x32_bf16 v[0:3], v[186:189], v[218:221], v[0:3]
	v_mfma_f32_16x16x32_bf16 v[8:11], v[176:179], v[218:221], v[8:11]
	v_mfma_f32_16x16x32_bf16 v[56:59], v[180:183], v[198:201], v[56:59]
	v_mfma_f32_16x16x32_bf16 v[48:51], v[190:193], v[198:201], v[48:51]
	v_mfma_f32_16x16x32_bf16 v[32:35], v[190:193], v[206:209], v[32:35]
	v_mfma_f32_16x16x32_bf16 v[40:43], v[180:183], v[206:209], v[40:43]
	v_mfma_f32_16x16x32_bf16 v[24:27], v[180:183], v[214:217], v[24:27]
	v_mfma_f32_16x16x32_bf16 v[16:19], v[190:193], v[214:217], v[16:19]
	v_mfma_f32_16x16x32_bf16 v[0:3], v[190:193], v[222:225], v[0:3]
	v_mfma_f32_16x16x32_bf16 v[8:11], v[180:183], v[222:225], v[8:11]
	s_setprio 0
	s_barrier
	s_add_i32 s75, s75, 2
	s_add_u32 s71, s71, 0x100
	s_addc_u32 s74, s74, 0
	s_add_u32 s44, s44, 0x100
	s_addc_u32 s45, s45, 0
	s_branch .LBB0_76
.LBB0_75:
	v_add_u32_e32 v153, s64, v147
	ds_read_b128 v[160:163], v153
	ds_read_b128 v[164:167], v153 offset:1024
	ds_read_b128 v[168:171], v153 offset:2048
	ds_read_b128 v[172:175], v153 offset:3072
	v_add_u32_e32 v153, s65, v147
	ds_read_b128 v[176:179], v153
	ds_read_b128 v[180:183], v153 offset:1024
	ds_read_b128 v[186:189], v153 offset:2048
	ds_read_b128 v[190:193], v153 offset:3072
	s_add_u32 s48, s44, 0xfffc0080
	s_addc_u32 s49, s45, -1
	s_and_b64 s[46:47], s[46:47], exec
	s_cselect_b32 s49, s27, s49
	s_cselect_b32 s48, s68, s48
	s_cselect_b32 s47, s69, s74
	s_cselect_b32 s46, s70, s71
	v_lshl_add_u64 v[154:155], s[44:45], 0, v[138:139]
	s_add_i32 m0, s55, 0xc000
	ds_read_b128 v[194:197], v150
	ds_read_b128 v[198:201], v150 offset:1024
	ds_read_b128 v[202:205], v150 offset:2048
	ds_read_b128 v[206:209], v150 offset:3072
	ds_read_b128 v[210:213], v150 offset:4096
	ds_read_b128 v[214:217], v150 offset:5120
	ds_read_b128 v[218:221], v150 offset:6144
	ds_read_b128 v[222:225], v150 offset:7168
	global_load_lds_dwordx4 v[154:155], off
	v_lshl_add_u64 v[154:155], s[44:45], 0, v[136:137]
	s_add_i32 m0, s55, 0xe000
	s_nop 0
	global_load_lds_dwordx4 v[154:155], off
	s_waitcnt vmcnt(8)
	s_waitcnt lgkmcnt(0)
	s_barrier
	s_setprio 1
	s_waitcnt lgkmcnt(0)
	v_mfma_f32_16x16x32_bf16 v[124:127], v[160:163], v[194:197], v[124:127]
	v_mfma_f32_16x16x32_bf16 v[116:119], v[168:171], v[194:197], v[116:119]
	v_mfma_f32_16x16x32_bf16 v[100:103], v[168:171], v[202:205], v[100:103]
	v_mfma_f32_16x16x32_bf16 v[108:111], v[160:163], v[202:205], v[108:111]
	v_mfma_f32_16x16x32_bf16 v[92:95], v[160:163], v[210:213], v[92:95]
	v_mfma_f32_16x16x32_bf16 v[84:87], v[168:171], v[210:213], v[84:87]
	v_mfma_f32_16x16x32_bf16 v[68:71], v[168:171], v[218:221], v[68:71]
	v_mfma_f32_16x16x32_bf16 v[76:79], v[160:163], v[218:221], v[76:79]
	v_mfma_f32_16x16x32_bf16 v[124:127], v[164:167], v[198:201], v[124:127]
	v_mfma_f32_16x16x32_bf16 v[116:119], v[172:175], v[198:201], v[116:119]
	v_mfma_f32_16x16x32_bf16 v[100:103], v[172:175], v[206:209], v[100:103]
	v_mfma_f32_16x16x32_bf16 v[108:111], v[164:167], v[206:209], v[108:111]
	v_mfma_f32_16x16x32_bf16 v[92:95], v[164:167], v[214:217], v[92:95]
	v_mfma_f32_16x16x32_bf16 v[84:87], v[172:175], v[214:217], v[84:87]
	v_mfma_f32_16x16x32_bf16 v[68:71], v[172:175], v[222:225], v[68:71]
	v_mfma_f32_16x16x32_bf16 v[76:79], v[164:167], v[222:225], v[76:79]
	s_setprio 0
	s_setprio 1
	v_mfma_f32_16x16x32_bf16 v[120:123], v[176:179], v[194:197], v[120:123]
	v_mfma_f32_16x16x32_bf16 v[112:115], v[186:189], v[194:197], v[112:115]
	v_mfma_f32_16x16x32_bf16 v[96:99], v[186:189], v[202:205], v[96:99]
	v_mfma_f32_16x16x32_bf16 v[104:107], v[176:179], v[202:205], v[104:107]
	v_mfma_f32_16x16x32_bf16 v[88:91], v[176:179], v[210:213], v[88:91]
	v_mfma_f32_16x16x32_bf16 v[80:83], v[186:189], v[210:213], v[80:83]
	v_mfma_f32_16x16x32_bf16 v[64:67], v[186:189], v[218:221], v[64:67]
	v_mfma_f32_16x16x32_bf16 v[72:75], v[176:179], v[218:221], v[72:75]
	v_mfma_f32_16x16x32_bf16 v[120:123], v[180:183], v[198:201], v[120:123]
	v_mfma_f32_16x16x32_bf16 v[112:115], v[190:193], v[198:201], v[112:115]
	v_mfma_f32_16x16x32_bf16 v[96:99], v[190:193], v[206:209], v[96:99]
	v_mfma_f32_16x16x32_bf16 v[104:107], v[180:183], v[206:209], v[104:107]
	v_mfma_f32_16x16x32_bf16 v[88:91], v[180:183], v[214:217], v[88:91]
	v_mfma_f32_16x16x32_bf16 v[80:83], v[190:193], v[214:217], v[80:83]
	v_mfma_f32_16x16x32_bf16 v[64:67], v[190:193], v[222:225], v[64:67]
	v_mfma_f32_16x16x32_bf16 v[72:75], v[180:183], v[222:225], v[72:75]
	s_setprio 0
	s_barrier
	s_add_i32 s76, s64, s52
	v_lshl_add_u64 v[154:155], s[46:47], 0, v[132:133]
	s_mov_b32 m0, s76
	ds_read_b128 v[194:197], v150 offset:16384
	ds_read_b128 v[198:201], v150 offset:17408
	ds_read_b128 v[202:205], v150 offset:18432
	ds_read_b128 v[206:209], v150 offset:19456
	ds_read_b128 v[210:213], v150 offset:20480
	ds_read_b128 v[214:217], v150 offset:21504
	ds_read_b128 v[218:221], v150 offset:22528
	ds_read_b128 v[222:225], v150 offset:23552
	global_load_lds_dwordx4 v[154:155], off
	s_add_i32 m0, s76, 0x2000
	s_add_u32 s76, s46, 0x40000
	v_lshl_add_u64 v[226:227], s[46:47], 0, v[128:129]
	s_addc_u32 s77, s47, 0
	s_add_i32 s78, s65, s52
	global_load_lds_dwordx4 v[226:227], off
	v_lshl_add_u64 v[228:229], s[76:77], 0, v[132:133]
	s_mov_b32 m0, s78
	v_lshl_add_u64 v[230:231], s[48:49], 0, v[130:131]
	global_load_lds_dwordx4 v[228:229], off
	v_lshl_add_u64 v[228:229], s[76:77], 0, v[128:129]
	s_add_i32 m0, s78, 0x2000
	s_nop 0
	global_load_lds_dwordx4 v[228:229], off
	v_lshl_add_u64 v[228:229], s[48:49], 0, v[134:135]
	s_mov_b32 m0, s55
	s_nop 0
	global_load_lds_dwordx4 v[228:229], off
	s_mov_b32 m0, s56
	s_nop 0
	global_load_lds_dwordx4 v[230:231], off
	s_waitcnt vmcnt(8)
	s_waitcnt lgkmcnt(0)
	s_barrier
	s_setprio 1
	s_waitcnt lgkmcnt(0)
	v_mfma_f32_16x16x32_bf16 v[60:63], v[160:163], v[194:197], v[60:63]
	v_mfma_f32_16x16x32_bf16 v[52:55], v[168:171], v[194:197], v[52:55]
	v_mfma_f32_16x16x32_bf16 v[36:39], v[168:171], v[202:205], v[36:39]
	v_mfma_f32_16x16x32_bf16 v[44:47], v[160:163], v[202:205], v[44:47]
	v_mfma_f32_16x16x32_bf16 v[28:31], v[160:163], v[210:213], v[28:31]
	v_mfma_f32_16x16x32_bf16 v[20:23], v[168:171], v[210:213], v[20:23]
	v_mfma_f32_16x16x32_bf16 v[4:7], v[168:171], v[218:221], v[4:7]
	v_mfma_f32_16x16x32_bf16 v[12:15], v[160:163], v[218:221], v[12:15]
	v_mfma_f32_16x16x32_bf16 v[60:63], v[164:167], v[198:201], v[60:63]
	v_mfma_f32_16x16x32_bf16 v[52:55], v[172:175], v[198:201], v[52:55]
	v_mfma_f32_16x16x32_bf16 v[36:39], v[172:175], v[206:209], v[36:39]
	v_mfma_f32_16x16x32_bf16 v[44:47], v[164:167], v[206:209], v[44:47]
	v_mfma_f32_16x16x32_bf16 v[28:31], v[164:167], v[214:217], v[28:31]
	v_mfma_f32_16x16x32_bf16 v[20:23], v[172:175], v[214:217], v[20:23]
	v_mfma_f32_16x16x32_bf16 v[4:7], v[172:175], v[222:225], v[4:7]
	v_mfma_f32_16x16x32_bf16 v[12:15], v[164:167], v[222:225], v[12:15]
	s_setprio 0
	s_setprio 1
	v_mfma_f32_16x16x32_bf16 v[56:59], v[176:179], v[194:197], v[56:59]
	v_mfma_f32_16x16x32_bf16 v[48:51], v[186:189], v[194:197], v[48:51]
	v_mfma_f32_16x16x32_bf16 v[32:35], v[186:189], v[202:205], v[32:35]
	v_mfma_f32_16x16x32_bf16 v[40:43], v[176:179], v[202:205], v[40:43]
	v_mfma_f32_16x16x32_bf16 v[24:27], v[176:179], v[210:213], v[24:27]
	v_mfma_f32_16x16x32_bf16 v[16:19], v[186:189], v[210:213], v[16:19]
	v_mfma_f32_16x16x32_bf16 v[0:3], v[186:189], v[218:221], v[0:3]
	v_mfma_f32_16x16x32_bf16 v[8:11], v[176:179], v[218:221], v[8:11]
	v_mfma_f32_16x16x32_bf16 v[56:59], v[180:183], v[198:201], v[56:59]
	v_mfma_f32_16x16x32_bf16 v[48:51], v[190:193], v[198:201], v[48:51]
	v_mfma_f32_16x16x32_bf16 v[32:35], v[190:193], v[206:209], v[32:35]
	v_mfma_f32_16x16x32_bf16 v[40:43], v[180:183], v[206:209], v[40:43]
	v_mfma_f32_16x16x32_bf16 v[24:27], v[180:183], v[214:217], v[24:27]
	v_mfma_f32_16x16x32_bf16 v[16:19], v[190:193], v[214:217], v[16:19]
	v_mfma_f32_16x16x32_bf16 v[0:3], v[190:193], v[222:225], v[0:3]
	v_mfma_f32_16x16x32_bf16 v[8:11], v[180:183], v[222:225], v[8:11]
	s_setprio 0
	s_barrier
	s_add_i32 s76, 0, 0x18000
	v_add_u32_e32 v153, s76, v147
	s_add_i32 s77, 0, 0x1c000
	ds_read_b128 v[160:163], v153
	ds_read_b128 v[164:167], v153 offset:1024
	ds_read_b128 v[168:171], v153 offset:2048
	ds_read_b128 v[172:175], v153 offset:3072
	v_add_u32_e32 v153, s77, v147
	ds_read_b128 v[176:179], v153
	ds_read_b128 v[180:183], v153 offset:1024
	ds_read_b128 v[186:189], v153 offset:2048
	ds_read_b128 v[190:193], v153 offset:3072
	s_add_u32 s48, s48, 0x40000
	s_addc_u32 s49, s49, 0
	s_mov_b32 m0, s57
	v_lshl_add_u64 v[232:233], s[48:49], 0, v[134:135]
	ds_read_b128 v[194:197], v150 offset:32768
	ds_read_b128 v[198:201], v150 offset:33792
	ds_read_b128 v[202:205], v150 offset:34816
	ds_read_b128 v[206:209], v150 offset:35840
	ds_read_b128 v[210:213], v150 offset:36864
	ds_read_b128 v[214:217], v150 offset:37888
	ds_read_b128 v[218:221], v150 offset:38912
	ds_read_b128 v[222:225], v150 offset:39936
	global_load_lds_dwordx4 v[232:233], off
	v_lshl_add_u64 v[232:233], s[48:49], 0, v[130:131]
	s_mov_b32 m0, s58
	s_nop 0
	global_load_lds_dwordx4 v[232:233], off
	s_waitcnt vmcnt(8)
	s_waitcnt lgkmcnt(0)
	s_barrier
	s_setprio 1
	s_waitcnt lgkmcnt(0)
	v_mfma_f32_16x16x32_bf16 v[124:127], v[160:163], v[194:197], v[124:127]
	v_mfma_f32_16x16x32_bf16 v[116:119], v[168:171], v[194:197], v[116:119]
	v_mfma_f32_16x16x32_bf16 v[100:103], v[168:171], v[202:205], v[100:103]
	v_mfma_f32_16x16x32_bf16 v[108:111], v[160:163], v[202:205], v[108:111]
	v_mfma_f32_16x16x32_bf16 v[92:95], v[160:163], v[210:213], v[92:95]
	v_mfma_f32_16x16x32_bf16 v[84:87], v[168:171], v[210:213], v[84:87]
	v_mfma_f32_16x16x32_bf16 v[68:71], v[168:171], v[218:221], v[68:71]
	v_mfma_f32_16x16x32_bf16 v[76:79], v[160:163], v[218:221], v[76:79]
	v_mfma_f32_16x16x32_bf16 v[124:127], v[164:167], v[198:201], v[124:127]
	v_mfma_f32_16x16x32_bf16 v[116:119], v[172:175], v[198:201], v[116:119]
	v_mfma_f32_16x16x32_bf16 v[100:103], v[172:175], v[206:209], v[100:103]
	v_mfma_f32_16x16x32_bf16 v[108:111], v[164:167], v[206:209], v[108:111]
	v_mfma_f32_16x16x32_bf16 v[92:95], v[164:167], v[214:217], v[92:95]
	v_mfma_f32_16x16x32_bf16 v[84:87], v[172:175], v[214:217], v[84:87]
	v_mfma_f32_16x16x32_bf16 v[68:71], v[172:175], v[222:225], v[68:71]
	v_mfma_f32_16x16x32_bf16 v[76:79], v[164:167], v[222:225], v[76:79]
	s_setprio 0
	s_setprio 1
	v_mfma_f32_16x16x32_bf16 v[120:123], v[176:179], v[194:197], v[120:123]
	v_mfma_f32_16x16x32_bf16 v[112:115], v[186:189], v[194:197], v[112:115]
	v_mfma_f32_16x16x32_bf16 v[96:99], v[186:189], v[202:205], v[96:99]
	v_mfma_f32_16x16x32_bf16 v[104:107], v[176:179], v[202:205], v[104:107]
	v_mfma_f32_16x16x32_bf16 v[88:91], v[176:179], v[210:213], v[88:91]
	v_mfma_f32_16x16x32_bf16 v[80:83], v[186:189], v[210:213], v[80:83]
	v_mfma_f32_16x16x32_bf16 v[64:67], v[186:189], v[218:221], v[64:67]
	v_mfma_f32_16x16x32_bf16 v[72:75], v[176:179], v[218:221], v[72:75]
	v_mfma_f32_16x16x32_bf16 v[120:123], v[180:183], v[198:201], v[120:123]
	v_mfma_f32_16x16x32_bf16 v[112:115], v[190:193], v[198:201], v[112:115]
	v_mfma_f32_16x16x32_bf16 v[96:99], v[190:193], v[206:209], v[96:99]
	v_mfma_f32_16x16x32_bf16 v[104:107], v[180:183], v[206:209], v[104:107]
	v_mfma_f32_16x16x32_bf16 v[88:91], v[180:183], v[214:217], v[88:91]
	v_mfma_f32_16x16x32_bf16 v[80:83], v[190:193], v[214:217], v[80:83]
	v_mfma_f32_16x16x32_bf16 v[64:67], v[190:193], v[222:225], v[64:67]
	v_mfma_f32_16x16x32_bf16 v[72:75], v[180:183], v[222:225], v[72:75]
	s_setprio 0
	s_barrier
	s_add_i32 s48, s76, s52
	v_lshl_add_u64 v[154:155], v[154:155], 0, s[14:15]
	s_mov_b32 m0, s48
	ds_read_b128 v[194:197], v150 offset:49152
	ds_read_b128 v[198:201], v150 offset:50176
	ds_read_b128 v[202:205], v150 offset:51200
	ds_read_b128 v[206:209], v150 offset:52224
	ds_read_b128 v[210:213], v150 offset:53248
	ds_read_b128 v[214:217], v150 offset:54272
	ds_read_b128 v[218:221], v150 offset:55296
	ds_read_b128 v[222:225], v150 offset:56320
	global_load_lds_dwordx4 v[154:155], off
	s_add_i32 m0, s48, 0x2000
	s_add_u32 s46, s46, 0x40080
	v_lshl_add_u64 v[154:155], v[226:227], 0, s[14:15]
	s_addc_u32 s47, s47, 0
	s_add_i32 s48, s77, s52
	global_load_lds_dwordx4 v[154:155], off
	v_lshl_add_u64 v[154:155], s[46:47], 0, v[132:133]
	s_mov_b32 m0, s48
	s_nop 0
	global_load_lds_dwordx4 v[154:155], off
	v_lshl_add_u64 v[154:155], s[46:47], 0, v[128:129]
	s_add_i32 m0, s48, 0x2000
	s_nop 0
	global_load_lds_dwordx4 v[154:155], off
	v_lshl_add_u64 v[154:155], v[228:229], 0, s[14:15]
	s_mov_b32 m0, s60
	s_nop 0
	global_load_lds_dwordx4 v[154:155], off
	v_lshl_add_u64 v[154:155], v[230:231], 0, s[14:15]
	s_mov_b32 m0, s61
	s_nop 0
	global_load_lds_dwordx4 v[154:155], off
	s_waitcnt vmcnt(8)
	s_waitcnt lgkmcnt(0)
	s_barrier
	s_setprio 1
	s_waitcnt lgkmcnt(0)
	v_mfma_f32_16x16x32_bf16 v[60:63], v[160:163], v[194:197], v[60:63]
	v_mfma_f32_16x16x32_bf16 v[52:55], v[168:171], v[194:197], v[52:55]
	v_mfma_f32_16x16x32_bf16 v[36:39], v[168:171], v[202:205], v[36:39]
	v_mfma_f32_16x16x32_bf16 v[44:47], v[160:163], v[202:205], v[44:47]
	v_mfma_f32_16x16x32_bf16 v[28:31], v[160:163], v[210:213], v[28:31]
	v_mfma_f32_16x16x32_bf16 v[20:23], v[168:171], v[210:213], v[20:23]
	v_mfma_f32_16x16x32_bf16 v[4:7], v[168:171], v[218:221], v[4:7]
	v_mfma_f32_16x16x32_bf16 v[12:15], v[160:163], v[218:221], v[12:15]
	v_mfma_f32_16x16x32_bf16 v[60:63], v[164:167], v[198:201], v[60:63]
	v_mfma_f32_16x16x32_bf16 v[52:55], v[172:175], v[198:201], v[52:55]
	v_mfma_f32_16x16x32_bf16 v[36:39], v[172:175], v[206:209], v[36:39]
	v_mfma_f32_16x16x32_bf16 v[44:47], v[164:167], v[206:209], v[44:47]
	v_mfma_f32_16x16x32_bf16 v[28:31], v[164:167], v[214:217], v[28:31]
	v_mfma_f32_16x16x32_bf16 v[20:23], v[172:175], v[214:217], v[20:23]
	v_mfma_f32_16x16x32_bf16 v[4:7], v[172:175], v[222:225], v[4:7]
	v_mfma_f32_16x16x32_bf16 v[12:15], v[164:167], v[222:225], v[12:15]
	s_setprio 0
	s_setprio 1
	v_mfma_f32_16x16x32_bf16 v[56:59], v[176:179], v[194:197], v[56:59]
	v_mfma_f32_16x16x32_bf16 v[48:51], v[186:189], v[194:197], v[48:51]
	v_mfma_f32_16x16x32_bf16 v[32:35], v[186:189], v[202:205], v[32:35]
	v_mfma_f32_16x16x32_bf16 v[40:43], v[176:179], v[202:205], v[40:43]
	v_mfma_f32_16x16x32_bf16 v[24:27], v[176:179], v[210:213], v[24:27]
	v_mfma_f32_16x16x32_bf16 v[16:19], v[186:189], v[210:213], v[16:19]
	v_mfma_f32_16x16x32_bf16 v[0:3], v[186:189], v[218:221], v[0:3]
	v_mfma_f32_16x16x32_bf16 v[8:11], v[176:179], v[218:221], v[8:11]
	v_mfma_f32_16x16x32_bf16 v[56:59], v[180:183], v[198:201], v[56:59]
	v_mfma_f32_16x16x32_bf16 v[48:51], v[190:193], v[198:201], v[48:51]
	v_mfma_f32_16x16x32_bf16 v[32:35], v[190:193], v[206:209], v[32:35]
	v_mfma_f32_16x16x32_bf16 v[40:43], v[180:183], v[206:209], v[40:43]
	v_mfma_f32_16x16x32_bf16 v[24:27], v[180:183], v[214:217], v[24:27]
	v_mfma_f32_16x16x32_bf16 v[16:19], v[190:193], v[214:217], v[16:19]
	v_mfma_f32_16x16x32_bf16 v[0:3], v[190:193], v[222:225], v[0:3]
	v_mfma_f32_16x16x32_bf16 v[8:11], v[180:183], v[222:225], v[8:11]
	s_setprio 0
	s_barrier
	s_add_i32 s75, s75, 2
	s_add_u32 s71, s71, 0x100
	s_addc_u32 s74, s74, 0
	s_add_u32 s44, s44, 0x100
	s_addc_u32 s45, s45, 0
	s_cmp_gt_u32 s75, 13
	s_cbranch_scc1 .LBB0_78

.LBB0_158:
	s_add_u32 s81, s56, 0x100
	s_addc_u32 s82, s57, 0
	s_mov_b32 s83, -2
	s_waitcnt lgkmcnt(0)
	ds_read_b128 v[128:131], v189
	ds_read_b128 v[132:135], v189 offset:1024
	ds_read_b128 v[136:139], v189 offset:2048
	ds_read_b128 v[140:143], v189 offset:3072
	ds_read_b128 v[144:147], v190
	ds_read_b128 v[148:151], v190 offset:1024
	ds_read_b128 v[172:175], v190 offset:2048
	ds_read_b128 v[176:179], v190 offset:3072
	s_add_u32 s56, s54, 0x100
	s_addc_u32 s57, s55, 0
	s_cmp_eq_u32 s83, 40
	s_cselect_b32 s61, s15, s57
	s_cselect_b32 s60, s14, s56
	s_cselect_b32 s59, s53, s82
	s_cselect_b32 s58, s52, s81
	v_lshl_add_u64 v[222:223], s[54:55], 0, v[166:167]
	s_add_i32 m0, s66, 0xc000
	ds_read_b128 v[180:183], v191
	ds_read_b128 v[194:197], v191 offset:1024
	ds_read_b128 v[198:201], v191 offset:2048
	ds_read_b128 v[202:205], v191 offset:3072
	ds_read_b128 v[206:209], v191 offset:4096
	ds_read_b128 v[210:213], v191 offset:5120
	ds_read_b128 v[214:217], v191 offset:6144
	ds_read_b128 v[218:221], v191 offset:7168
	global_load_lds_dwordx4 v[222:223], off
	v_lshl_add_u64 v[222:223], s[54:55], 0, v[164:165]
	s_add_i32 m0, s66, 0xe000
	s_nop 0
	global_load_lds_dwordx4 v[222:223], off
	s_waitcnt vmcnt(8)
	s_waitcnt lgkmcnt(0)
	s_barrier
	s_setprio 1
	s_waitcnt lgkmcnt(0)
	v_mfma_f32_16x16x32_bf16 v[124:127], v[128:131], v[180:183], 0
	v_mfma_f32_16x16x32_bf16 v[120:123], v[136:139], v[180:183], 0
	v_mfma_f32_16x16x32_bf16 v[108:111], v[128:131], v[198:201], 0
	v_mfma_f32_16x16x32_bf16 v[104:107], v[136:139], v[198:201], 0
	v_mfma_f32_16x16x32_bf16 v[92:95], v[128:131], v[206:209], 0
	v_mfma_f32_16x16x32_bf16 v[88:91], v[136:139], v[206:209], 0
	v_mfma_f32_16x16x32_bf16 v[76:79], v[128:131], v[214:217], 0
	v_mfma_f32_16x16x32_bf16 v[72:75], v[136:139], v[214:217], 0
	v_mfma_f32_16x16x32_bf16 v[124:127], v[132:135], v[194:197], v[124:127]
	v_mfma_f32_16x16x32_bf16 v[120:123], v[140:143], v[194:197], v[120:123]
	v_mfma_f32_16x16x32_bf16 v[108:111], v[132:135], v[202:205], v[108:111]
	v_mfma_f32_16x16x32_bf16 v[104:107], v[140:143], v[202:205], v[104:107]
	v_mfma_f32_16x16x32_bf16 v[92:95], v[132:135], v[210:213], v[92:95]
	v_mfma_f32_16x16x32_bf16 v[88:91], v[140:143], v[210:213], v[88:91]
	v_mfma_f32_16x16x32_bf16 v[76:79], v[132:135], v[218:221], v[76:79]
	v_mfma_f32_16x16x32_bf16 v[72:75], v[140:143], v[218:221], v[72:75]
	s_setprio 0
	s_setprio 1
	v_mfma_f32_16x16x32_bf16 v[116:119], v[144:147], v[180:183], 0
	v_mfma_f32_16x16x32_bf16 v[112:115], v[172:175], v[180:183], 0
	v_mfma_f32_16x16x32_bf16 v[100:103], v[144:147], v[198:201], 0
	v_mfma_f32_16x16x32_bf16 v[96:99], v[172:175], v[198:201], 0
	v_mfma_f32_16x16x32_bf16 v[84:87], v[144:147], v[206:209], 0
	v_mfma_f32_16x16x32_bf16 v[80:83], v[172:175], v[206:209], 0
	v_mfma_f32_16x16x32_bf16 v[68:71], v[144:147], v[214:217], 0
	v_mfma_f32_16x16x32_bf16 v[64:67], v[172:175], v[214:217], 0
	v_mfma_f32_16x16x32_bf16 v[116:119], v[148:151], v[194:197], v[116:119]
	v_mfma_f32_16x16x32_bf16 v[112:115], v[176:179], v[194:197], v[112:115]
	v_mfma_f32_16x16x32_bf16 v[100:103], v[148:151], v[202:205], v[100:103]
	v_mfma_f32_16x16x32_bf16 v[96:99], v[176:179], v[202:205], v[96:99]
	v_mfma_f32_16x16x32_bf16 v[84:87], v[148:151], v[210:213], v[84:87]
	v_mfma_f32_16x16x32_bf16 v[80:83], v[176:179], v[210:213], v[80:83]
	v_mfma_f32_16x16x32_bf16 v[68:71], v[148:151], v[218:221], v[68:71]
	v_mfma_f32_16x16x32_bf16 v[64:67], v[176:179], v[218:221], v[64:67]
	s_setprio 0
	s_barrier
	s_add_i32 s54, s77, s65
	v_lshl_add_u64 v[222:223], s[58:59], 0, v[154:155]
	s_mov_b32 m0, s54
	ds_read_b128 v[180:183], v191 offset:16384
	ds_read_b128 v[194:197], v191 offset:17408
	ds_read_b128 v[198:201], v191 offset:18432
	ds_read_b128 v[202:205], v191 offset:19456
	ds_read_b128 v[206:209], v191 offset:20480
	ds_read_b128 v[210:213], v191 offset:21504
	ds_read_b128 v[214:217], v191 offset:22528
	ds_read_b128 v[218:221], v191 offset:23552
	global_load_lds_dwordx4 v[222:223], off
	s_add_i32 m0, s54, 0x2000
	s_add_u32 s54, s58, 0xb0000
	v_lshl_add_u64 v[224:225], s[58:59], 0, v[162:163]
	s_addc_u32 s55, s59, 0
	s_add_i32 s84, s78, s65
	global_load_lds_dwordx4 v[224:225], off
	v_lshl_add_u64 v[226:227], s[54:55], 0, v[154:155]
	s_mov_b32 m0, s84
	v_lshl_add_u64 v[228:229], s[60:61], 0, v[160:161]
	global_load_lds_dwordx4 v[226:227], off
	v_lshl_add_u64 v[226:227], s[54:55], 0, v[162:163]
	s_add_i32 m0, s84, 0x2000
	s_nop 0
	global_load_lds_dwordx4 v[226:227], off
	v_lshl_add_u64 v[226:227], s[60:61], 0, v[152:153]
	s_mov_b32 m0, s66
	s_nop 0
	global_load_lds_dwordx4 v[226:227], off
	s_mov_b32 m0, s67
	s_nop 0
	global_load_lds_dwordx4 v[228:229], off
	s_waitcnt vmcnt(8)
	s_waitcnt lgkmcnt(0)
	s_barrier
	s_setprio 1
	s_waitcnt lgkmcnt(0)
	v_mfma_f32_16x16x32_bf16 v[60:63], v[128:131], v[180:183], 0
	v_mfma_f32_16x16x32_bf16 v[56:59], v[136:139], v[180:183], 0
	v_mfma_f32_16x16x32_bf16 v[44:47], v[128:131], v[198:201], 0
	v_mfma_f32_16x16x32_bf16 v[40:43], v[136:139], v[198:201], 0
	v_mfma_f32_16x16x32_bf16 v[28:31], v[128:131], v[206:209], 0
	v_mfma_f32_16x16x32_bf16 v[24:27], v[136:139], v[206:209], 0
	v_mfma_f32_16x16x32_bf16 v[12:15], v[128:131], v[214:217], 0
	v_mfma_f32_16x16x32_bf16 v[8:11], v[136:139], v[214:217], 0
	v_mfma_f32_16x16x32_bf16 v[60:63], v[132:135], v[194:197], v[60:63]
	v_mfma_f32_16x16x32_bf16 v[56:59], v[140:143], v[194:197], v[56:59]
	v_mfma_f32_16x16x32_bf16 v[44:47], v[132:135], v[202:205], v[44:47]
	v_mfma_f32_16x16x32_bf16 v[40:43], v[140:143], v[202:205], v[40:43]
	v_mfma_f32_16x16x32_bf16 v[28:31], v[132:135], v[210:213], v[28:31]
	v_mfma_f32_16x16x32_bf16 v[24:27], v[140:143], v[210:213], v[24:27]
	v_mfma_f32_16x16x32_bf16 v[12:15], v[132:135], v[218:221], v[12:15]
	v_mfma_f32_16x16x32_bf16 v[8:11], v[140:143], v[218:221], v[8:11]
	s_setprio 0
	s_setprio 1
	v_mfma_f32_16x16x32_bf16 v[52:55], v[144:147], v[180:183], 0
	v_mfma_f32_16x16x32_bf16 v[48:51], v[172:175], v[180:183], 0
	v_mfma_f32_16x16x32_bf16 v[36:39], v[144:147], v[198:201], 0
	v_mfma_f32_16x16x32_bf16 v[32:35], v[172:175], v[198:201], 0
	v_mfma_f32_16x16x32_bf16 v[20:23], v[144:147], v[206:209], 0
	v_mfma_f32_16x16x32_bf16 v[16:19], v[172:175], v[206:209], 0
	v_mfma_f32_16x16x32_bf16 v[4:7], v[144:147], v[214:217], 0
	v_mfma_f32_16x16x32_bf16 v[0:3], v[172:175], v[214:217], 0
	v_mfma_f32_16x16x32_bf16 v[52:55], v[148:151], v[194:197], v[52:55]
	v_mfma_f32_16x16x32_bf16 v[48:51], v[176:179], v[194:197], v[48:51]
	v_mfma_f32_16x16x32_bf16 v[36:39], v[148:151], v[202:205], v[36:39]
	v_mfma_f32_16x16x32_bf16 v[32:35], v[176:179], v[202:205], v[32:35]
	v_mfma_f32_16x16x32_bf16 v[20:23], v[148:151], v[210:213], v[20:23]
	v_mfma_f32_16x16x32_bf16 v[16:19], v[176:179], v[210:213], v[16:19]
	v_mfma_f32_16x16x32_bf16 v[4:7], v[148:151], v[218:221], v[4:7]
	v_mfma_f32_16x16x32_bf16 v[0:3], v[176:179], v[218:221], v[0:3]
	s_setprio 0
	s_barrier
	s_add_i32 s84, 0, 0x18000
	s_add_i32 s85, 0, 0x1c000
	v_add_u32_e32 v140, s84, v186
	v_add_u32_e32 v176, s85, v186
	ds_read_b128 v[128:131], v140
	ds_read_b128 v[132:135], v140 offset:1024
	ds_read_b128 v[136:139], v140 offset:2048
	ds_read_b128 v[140:143], v140 offset:3072
	ds_read_b128 v[144:147], v176
	ds_read_b128 v[148:151], v176 offset:1024
	ds_read_b128 v[172:175], v176 offset:2048
	ds_read_b128 v[176:179], v176 offset:3072
	s_add_u32 s54, s60, 0xb0000
	s_addc_u32 s55, s61, 0
	s_mov_b32 m0, s68
	v_lshl_add_u64 v[230:231], s[54:55], 0, v[152:153]
	ds_read_b128 v[180:183], v191 offset:32768
	ds_read_b128 v[194:197], v191 offset:33792
	ds_read_b128 v[198:201], v191 offset:34816
	ds_read_b128 v[202:205], v191 offset:35840
	ds_read_b128 v[206:209], v191 offset:36864
	ds_read_b128 v[210:213], v191 offset:37888
	ds_read_b128 v[214:217], v191 offset:38912
	ds_read_b128 v[218:221], v191 offset:39936
	global_load_lds_dwordx4 v[230:231], off
	v_lshl_add_u64 v[230:231], s[54:55], 0, v[160:161]
	s_mov_b32 m0, s69
	s_nop 0
	global_load_lds_dwordx4 v[230:231], off
	s_waitcnt vmcnt(8)
	s_waitcnt lgkmcnt(0)
	s_barrier
	s_setprio 1
	s_waitcnt lgkmcnt(0)
	v_mfma_f32_16x16x32_bf16 v[124:127], v[128:131], v[180:183], v[124:127]
	v_mfma_f32_16x16x32_bf16 v[120:123], v[136:139], v[180:183], v[120:123]
	v_mfma_f32_16x16x32_bf16 v[104:107], v[136:139], v[198:201], v[104:107]
	v_mfma_f32_16x16x32_bf16 v[108:111], v[128:131], v[198:201], v[108:111]
	v_mfma_f32_16x16x32_bf16 v[92:95], v[128:131], v[206:209], v[92:95]
	v_mfma_f32_16x16x32_bf16 v[88:91], v[136:139], v[206:209], v[88:91]
	v_mfma_f32_16x16x32_bf16 v[72:75], v[136:139], v[214:217], v[72:75]
	v_mfma_f32_16x16x32_bf16 v[76:79], v[128:131], v[214:217], v[76:79]
	v_mfma_f32_16x16x32_bf16 v[124:127], v[132:135], v[194:197], v[124:127]
	v_mfma_f32_16x16x32_bf16 v[120:123], v[140:143], v[194:197], v[120:123]
	v_mfma_f32_16x16x32_bf16 v[104:107], v[140:143], v[202:205], v[104:107]
	v_mfma_f32_16x16x32_bf16 v[108:111], v[132:135], v[202:205], v[108:111]
	v_mfma_f32_16x16x32_bf16 v[92:95], v[132:135], v[210:213], v[92:95]
	v_mfma_f32_16x16x32_bf16 v[88:91], v[140:143], v[210:213], v[88:91]
	v_mfma_f32_16x16x32_bf16 v[72:75], v[140:143], v[218:221], v[72:75]
	v_mfma_f32_16x16x32_bf16 v[76:79], v[132:135], v[218:221], v[76:79]
	s_setprio 0
	s_setprio 1
	v_mfma_f32_16x16x32_bf16 v[116:119], v[144:147], v[180:183], v[116:119]
	v_mfma_f32_16x16x32_bf16 v[112:115], v[172:175], v[180:183], v[112:115]
	v_mfma_f32_16x16x32_bf16 v[96:99], v[172:175], v[198:201], v[96:99]
	v_mfma_f32_16x16x32_bf16 v[100:103], v[144:147], v[198:201], v[100:103]
	v_mfma_f32_16x16x32_bf16 v[84:87], v[144:147], v[206:209], v[84:87]
	v_mfma_f32_16x16x32_bf16 v[80:83], v[172:175], v[206:209], v[80:83]
	v_mfma_f32_16x16x32_bf16 v[64:67], v[172:175], v[214:217], v[64:67]
	v_mfma_f32_16x16x32_bf16 v[68:71], v[144:147], v[214:217], v[68:71]
	v_mfma_f32_16x16x32_bf16 v[116:119], v[148:151], v[194:197], v[116:119]
	v_mfma_f32_16x16x32_bf16 v[112:115], v[176:179], v[194:197], v[112:115]
	v_mfma_f32_16x16x32_bf16 v[96:99], v[176:179], v[202:205], v[96:99]
	v_mfma_f32_16x16x32_bf16 v[100:103], v[148:151], v[202:205], v[100:103]
	v_mfma_f32_16x16x32_bf16 v[84:87], v[148:151], v[210:213], v[84:87]
	v_mfma_f32_16x16x32_bf16 v[80:83], v[176:179], v[210:213], v[80:83]
	v_mfma_f32_16x16x32_bf16 v[64:67], v[176:179], v[218:221], v[64:67]
	v_mfma_f32_16x16x32_bf16 v[68:71], v[148:151], v[218:221], v[68:71]
	s_setprio 0
	s_barrier
	s_add_i32 s54, s84, s65
	v_lshl_add_u64 v[222:223], v[222:223], 0, s[28:29]
	s_mov_b32 m0, s54
	ds_read_b128 v[180:183], v191 offset:49152
	ds_read_b128 v[194:197], v191 offset:50176
	ds_read_b128 v[198:201], v191 offset:51200
	ds_read_b128 v[202:205], v191 offset:52224
	ds_read_b128 v[206:209], v191 offset:53248
	ds_read_b128 v[210:213], v191 offset:54272
	ds_read_b128 v[214:217], v191 offset:55296
	ds_read_b128 v[218:221], v191 offset:56320
	global_load_lds_dwordx4 v[222:223], off
	s_add_i32 m0, s54, 0x2000
	s_add_u32 s54, s58, 0xb0080
	v_lshl_add_u64 v[222:223], v[224:225], 0, s[28:29]
	s_addc_u32 s55, s59, 0
	s_add_i32 s58, s85, s65
	global_load_lds_dwordx4 v[222:223], off
	v_lshl_add_u64 v[222:223], s[54:55], 0, v[154:155]
	s_mov_b32 m0, s58
	s_nop 0
	global_load_lds_dwordx4 v[222:223], off
	v_lshl_add_u64 v[222:223], s[54:55], 0, v[162:163]
	s_add_i32 m0, s58, 0x2000
	s_nop 0
	global_load_lds_dwordx4 v[222:223], off
	v_lshl_add_u64 v[222:223], v[226:227], 0, s[28:29]
	s_mov_b32 m0, s3
	s_nop 0
	global_load_lds_dwordx4 v[222:223], off
	v_lshl_add_u64 v[222:223], v[228:229], 0, s[28:29]
	s_mov_b32 m0, s71
	s_nop 0
	global_load_lds_dwordx4 v[222:223], off
	s_waitcnt vmcnt(8)
	s_waitcnt lgkmcnt(0)
	s_barrier
	s_setprio 1
	s_waitcnt lgkmcnt(0)
	v_mfma_f32_16x16x32_bf16 v[60:63], v[128:131], v[180:183], v[60:63]
	v_mfma_f32_16x16x32_bf16 v[56:59], v[136:139], v[180:183], v[56:59]
	v_mfma_f32_16x16x32_bf16 v[40:43], v[136:139], v[198:201], v[40:43]
	v_mfma_f32_16x16x32_bf16 v[44:47], v[128:131], v[198:201], v[44:47]
	v_mfma_f32_16x16x32_bf16 v[28:31], v[128:131], v[206:209], v[28:31]
	v_mfma_f32_16x16x32_bf16 v[24:27], v[136:139], v[206:209], v[24:27]
	v_mfma_f32_16x16x32_bf16 v[8:11], v[136:139], v[214:217], v[8:11]
	v_mfma_f32_16x16x32_bf16 v[12:15], v[128:131], v[214:217], v[12:15]
	v_mfma_f32_16x16x32_bf16 v[60:63], v[132:135], v[194:197], v[60:63]
	v_mfma_f32_16x16x32_bf16 v[56:59], v[140:143], v[194:197], v[56:59]
	v_mfma_f32_16x16x32_bf16 v[40:43], v[140:143], v[202:205], v[40:43]
	v_mfma_f32_16x16x32_bf16 v[44:47], v[132:135], v[202:205], v[44:47]
	v_mfma_f32_16x16x32_bf16 v[28:31], v[132:135], v[210:213], v[28:31]
	v_mfma_f32_16x16x32_bf16 v[24:27], v[140:143], v[210:213], v[24:27]
	v_mfma_f32_16x16x32_bf16 v[8:11], v[140:143], v[218:221], v[8:11]
	v_mfma_f32_16x16x32_bf16 v[12:15], v[132:135], v[218:221], v[12:15]
	s_setprio 0
	s_setprio 1
	v_mfma_f32_16x16x32_bf16 v[52:55], v[144:147], v[180:183], v[52:55]
	v_mfma_f32_16x16x32_bf16 v[48:51], v[172:175], v[180:183], v[48:51]
	v_mfma_f32_16x16x32_bf16 v[32:35], v[172:175], v[198:201], v[32:35]
	v_mfma_f32_16x16x32_bf16 v[36:39], v[144:147], v[198:201], v[36:39]
	v_mfma_f32_16x16x32_bf16 v[20:23], v[144:147], v[206:209], v[20:23]
	v_mfma_f32_16x16x32_bf16 v[16:19], v[172:175], v[206:209], v[16:19]
	v_mfma_f32_16x16x32_bf16 v[0:3], v[172:175], v[214:217], v[0:3]
	v_mfma_f32_16x16x32_bf16 v[4:7], v[144:147], v[214:217], v[4:7]
	v_mfma_f32_16x16x32_bf16 v[52:55], v[148:151], v[194:197], v[52:55]
	v_mfma_f32_16x16x32_bf16 v[48:51], v[176:179], v[194:197], v[48:51]
	v_mfma_f32_16x16x32_bf16 v[32:35], v[176:179], v[202:205], v[32:35]
	v_mfma_f32_16x16x32_bf16 v[36:39], v[148:151], v[202:205], v[36:39]
	v_mfma_f32_16x16x32_bf16 v[20:23], v[148:151], v[210:213], v[20:23]
	v_mfma_f32_16x16x32_bf16 v[16:19], v[176:179], v[210:213], v[16:19]
	v_mfma_f32_16x16x32_bf16 v[0:3], v[176:179], v[218:221], v[0:3]
	v_mfma_f32_16x16x32_bf16 v[4:7], v[148:151], v[218:221], v[4:7]
	s_setprio 0
	s_barrier
	s_add_i32 s83, s83, 2
	s_add_u32 s81, s81, 0x100
	s_addc_u32 s82, s82, 0
	s_cmp_gt_u32 s83, 41
	s_mov_b64 s[54:55], s[56:57]
.LBB0_159:
	ds_read_b128 v[128:131], v189
	ds_read_b128 v[132:135], v189 offset:1024
	ds_read_b128 v[136:139], v189 offset:2048
	ds_read_b128 v[140:143], v189 offset:3072
	ds_read_b128 v[144:147], v190
	ds_read_b128 v[148:151], v190 offset:1024
	ds_read_b128 v[172:175], v190 offset:2048
	ds_read_b128 v[176:179], v190 offset:3072
	s_add_u32 s56, s54, 0x100
	s_addc_u32 s57, s55, 0
	s_cmp_eq_u32 s83, 40
	s_cselect_b32 s61, s15, s57
	s_cselect_b32 s60, s14, s56
	s_cselect_b32 s59, s53, s82
	s_cselect_b32 s58, s52, s81
	v_lshl_add_u64 v[222:223], s[54:55], 0, v[166:167]
	s_add_i32 m0, s66, 0xc000
	ds_read_b128 v[180:183], v191
	ds_read_b128 v[194:197], v191 offset:1024
	ds_read_b128 v[198:201], v191 offset:2048
	ds_read_b128 v[202:205], v191 offset:3072
	ds_read_b128 v[206:209], v191 offset:4096
	ds_read_b128 v[210:213], v191 offset:5120
	ds_read_b128 v[214:217], v191 offset:6144
	ds_read_b128 v[218:221], v191 offset:7168
	global_load_lds_dwordx4 v[222:223], off
	v_lshl_add_u64 v[222:223], s[54:55], 0, v[164:165]
	s_add_i32 m0, s66, 0xe000
	s_nop 0
	global_load_lds_dwordx4 v[222:223], off
	s_waitcnt vmcnt(8)
	s_waitcnt lgkmcnt(0)
	s_barrier
	s_setprio 1
	s_waitcnt lgkmcnt(0)
	v_mfma_f32_16x16x32_bf16 v[124:127], v[128:131], v[180:183], v[124:127]
	v_mfma_f32_16x16x32_bf16 v[120:123], v[136:139], v[180:183], v[120:123]
	v_mfma_f32_16x16x32_bf16 v[104:107], v[136:139], v[198:201], v[104:107]
	v_mfma_f32_16x16x32_bf16 v[108:111], v[128:131], v[198:201], v[108:111]
	v_mfma_f32_16x16x32_bf16 v[92:95], v[128:131], v[206:209], v[92:95]
	v_mfma_f32_16x16x32_bf16 v[88:91], v[136:139], v[206:209], v[88:91]
	v_mfma_f32_16x16x32_bf16 v[72:75], v[136:139], v[214:217], v[72:75]
	v_mfma_f32_16x16x32_bf16 v[76:79], v[128:131], v[214:217], v[76:79]
	v_mfma_f32_16x16x32_bf16 v[124:127], v[132:135], v[194:197], v[124:127]
	v_mfma_f32_16x16x32_bf16 v[120:123], v[140:143], v[194:197], v[120:123]
	v_mfma_f32_16x16x32_bf16 v[104:107], v[140:143], v[202:205], v[104:107]
	v_mfma_f32_16x16x32_bf16 v[108:111], v[132:135], v[202:205], v[108:111]
	v_mfma_f32_16x16x32_bf16 v[92:95], v[132:135], v[210:213], v[92:95]
	v_mfma_f32_16x16x32_bf16 v[88:91], v[140:143], v[210:213], v[88:91]
	v_mfma_f32_16x16x32_bf16 v[72:75], v[140:143], v[218:221], v[72:75]
	v_mfma_f32_16x16x32_bf16 v[76:79], v[132:135], v[218:221], v[76:79]
	s_setprio 0
	s_setprio 1
	v_mfma_f32_16x16x32_bf16 v[116:119], v[144:147], v[180:183], v[116:119]
	v_mfma_f32_16x16x32_bf16 v[112:115], v[172:175], v[180:183], v[112:115]
	v_mfma_f32_16x16x32_bf16 v[96:99], v[172:175], v[198:201], v[96:99]
	v_mfma_f32_16x16x32_bf16 v[100:103], v[144:147], v[198:201], v[100:103]
	v_mfma_f32_16x16x32_bf16 v[84:87], v[144:147], v[206:209], v[84:87]
	v_mfma_f32_16x16x32_bf16 v[80:83], v[172:175], v[206:209], v[80:83]
	v_mfma_f32_16x16x32_bf16 v[64:67], v[172:175], v[214:217], v[64:67]
	v_mfma_f32_16x16x32_bf16 v[68:71], v[144:147], v[214:217], v[68:71]
	v_mfma_f32_16x16x32_bf16 v[116:119], v[148:151], v[194:197], v[116:119]
	v_mfma_f32_16x16x32_bf16 v[112:115], v[176:179], v[194:197], v[112:115]
	v_mfma_f32_16x16x32_bf16 v[96:99], v[176:179], v[202:205], v[96:99]
	v_mfma_f32_16x16x32_bf16 v[100:103], v[148:151], v[202:205], v[100:103]
	v_mfma_f32_16x16x32_bf16 v[84:87], v[148:151], v[210:213], v[84:87]
	v_mfma_f32_16x16x32_bf16 v[80:83], v[176:179], v[210:213], v[80:83]
	v_mfma_f32_16x16x32_bf16 v[64:67], v[176:179], v[218:221], v[64:67]
	v_mfma_f32_16x16x32_bf16 v[68:71], v[148:151], v[218:221], v[68:71]
	s_setprio 0
	s_barrier
	s_add_i32 s54, s77, s65
	v_lshl_add_u64 v[222:223], s[58:59], 0, v[154:155]
	s_mov_b32 m0, s54
	ds_read_b128 v[180:183], v191 offset:16384
	ds_read_b128 v[194:197], v191 offset:17408
	ds_read_b128 v[198:201], v191 offset:18432
	ds_read_b128 v[202:205], v191 offset:19456
	ds_read_b128 v[206:209], v191 offset:20480
	ds_read_b128 v[210:213], v191 offset:21504
	ds_read_b128 v[214:217], v191 offset:22528
	ds_read_b128 v[218:221], v191 offset:23552
	global_load_lds_dwordx4 v[222:223], off
	s_add_i32 m0, s54, 0x2000
	s_add_u32 s54, s58, 0xb0000
	v_lshl_add_u64 v[224:225], s[58:59], 0, v[162:163]
	s_addc_u32 s55, s59, 0
	s_add_i32 s84, s78, s65
	global_load_lds_dwordx4 v[224:225], off
	v_lshl_add_u64 v[226:227], s[54:55], 0, v[154:155]
	s_mov_b32 m0, s84
	v_lshl_add_u64 v[228:229], s[60:61], 0, v[160:161]
	global_load_lds_dwordx4 v[226:227], off
	v_lshl_add_u64 v[226:227], s[54:55], 0, v[162:163]
	s_add_i32 m0, s84, 0x2000
	s_nop 0
	global_load_lds_dwordx4 v[226:227], off
	v_lshl_add_u64 v[226:227], s[60:61], 0, v[152:153]
	s_mov_b32 m0, s66
	s_nop 0
	global_load_lds_dwordx4 v[226:227], off
	s_mov_b32 m0, s67
	s_nop 0
	global_load_lds_dwordx4 v[228:229], off
	s_waitcnt vmcnt(8)
	s_waitcnt lgkmcnt(0)
	s_barrier
	s_setprio 1
	s_waitcnt lgkmcnt(0)
	v_mfma_f32_16x16x32_bf16 v[60:63], v[128:131], v[180:183], v[60:63]
	v_mfma_f32_16x16x32_bf16 v[56:59], v[136:139], v[180:183], v[56:59]
	v_mfma_f32_16x16x32_bf16 v[40:43], v[136:139], v[198:201], v[40:43]
	v_mfma_f32_16x16x32_bf16 v[44:47], v[128:131], v[198:201], v[44:47]
	v_mfma_f32_16x16x32_bf16 v[28:31], v[128:131], v[206:209], v[28:31]
	v_mfma_f32_16x16x32_bf16 v[24:27], v[136:139], v[206:209], v[24:27]
	v_mfma_f32_16x16x32_bf16 v[8:11], v[136:139], v[214:217], v[8:11]
	v_mfma_f32_16x16x32_bf16 v[12:15], v[128:131], v[214:217], v[12:15]
	v_mfma_f32_16x16x32_bf16 v[60:63], v[132:135], v[194:197], v[60:63]
	v_mfma_f32_16x16x32_bf16 v[56:59], v[140:143], v[194:197], v[56:59]
	v_mfma_f32_16x16x32_bf16 v[40:43], v[140:143], v[202:205], v[40:43]
	v_mfma_f32_16x16x32_bf16 v[44:47], v[132:135], v[202:205], v[44:47]
	v_mfma_f32_16x16x32_bf16 v[28:31], v[132:135], v[210:213], v[28:31]
	v_mfma_f32_16x16x32_bf16 v[24:27], v[140:143], v[210:213], v[24:27]
	v_mfma_f32_16x16x32_bf16 v[8:11], v[140:143], v[218:221], v[8:11]
	v_mfma_f32_16x16x32_bf16 v[12:15], v[132:135], v[218:221], v[12:15]
	s_setprio 0
	s_setprio 1
	v_mfma_f32_16x16x32_bf16 v[52:55], v[144:147], v[180:183], v[52:55]
	v_mfma_f32_16x16x32_bf16 v[48:51], v[172:175], v[180:183], v[48:51]
	v_mfma_f32_16x16x32_bf16 v[32:35], v[172:175], v[198:201], v[32:35]
	v_mfma_f32_16x16x32_bf16 v[36:39], v[144:147], v[198:201], v[36:39]
	v_mfma_f32_16x16x32_bf16 v[20:23], v[144:147], v[206:209], v[20:23]
	v_mfma_f32_16x16x32_bf16 v[16:19], v[172:175], v[206:209], v[16:19]
	v_mfma_f32_16x16x32_bf16 v[0:3], v[172:175], v[214:217], v[0:3]
	v_mfma_f32_16x16x32_bf16 v[4:7], v[144:147], v[214:217], v[4:7]
	v_mfma_f32_16x16x32_bf16 v[52:55], v[148:151], v[194:197], v[52:55]
	v_mfma_f32_16x16x32_bf16 v[48:51], v[176:179], v[194:197], v[48:51]
	v_mfma_f32_16x16x32_bf16 v[32:35], v[176:179], v[202:205], v[32:35]
	v_mfma_f32_16x16x32_bf16 v[36:39], v[148:151], v[202:205], v[36:39]
	v_mfma_f32_16x16x32_bf16 v[20:23], v[148:151], v[210:213], v[20:23]
	v_mfma_f32_16x16x32_bf16 v[16:19], v[176:179], v[210:213], v[16:19]
	v_mfma_f32_16x16x32_bf16 v[0:3], v[176:179], v[218:221], v[0:3]
	v_mfma_f32_16x16x32_bf16 v[4:7], v[148:151], v[218:221], v[4:7]
	s_setprio 0
	s_barrier
	s_add_i32 s84, 0, 0x18000
	s_add_i32 s85, 0, 0x1c000
	v_add_u32_e32 v140, s84, v186
	v_add_u32_e32 v176, s85, v186
	ds_read_b128 v[128:131], v140
	ds_read_b128 v[132:135], v140 offset:1024
	ds_read_b128 v[136:139], v140 offset:2048
	ds_read_b128 v[140:143], v140 offset:3072
	ds_read_b128 v[144:147], v176
	ds_read_b128 v[148:151], v176 offset:1024
	ds_read_b128 v[172:175], v176 offset:2048
	ds_read_b128 v[176:179], v176 offset:3072
	s_add_u32 s54, s60, 0xb0000
	s_addc_u32 s55, s61, 0
	s_mov_b32 m0, s68
	v_lshl_add_u64 v[230:231], s[54:55], 0, v[152:153]
	ds_read_b128 v[180:183], v191 offset:32768
	ds_read_b128 v[194:197], v191 offset:33792
	ds_read_b128 v[198:201], v191 offset:34816
	ds_read_b128 v[202:205], v191 offset:35840
	ds_read_b128 v[206:209], v191 offset:36864
	ds_read_b128 v[210:213], v191 offset:37888
	ds_read_b128 v[214:217], v191 offset:38912
	ds_read_b128 v[218:221], v191 offset:39936
	global_load_lds_dwordx4 v[230:231], off
	v_lshl_add_u64 v[230:231], s[54:55], 0, v[160:161]
	s_mov_b32 m0, s69
	s_nop 0
	global_load_lds_dwordx4 v[230:231], off
	s_waitcnt vmcnt(8)
	s_waitcnt lgkmcnt(0)
	s_barrier
	s_setprio 1
	s_waitcnt lgkmcnt(0)
	v_mfma_f32_16x16x32_bf16 v[124:127], v[128:131], v[180:183], v[124:127]
	v_mfma_f32_16x16x32_bf16 v[120:123], v[136:139], v[180:183], v[120:123]
	v_mfma_f32_16x16x32_bf16 v[104:107], v[136:139], v[198:201], v[104:107]
	v_mfma_f32_16x16x32_bf16 v[108:111], v[128:131], v[198:201], v[108:111]
	v_mfma_f32_16x16x32_bf16 v[92:95], v[128:131], v[206:209], v[92:95]
	v_mfma_f32_16x16x32_bf16 v[88:91], v[136:139], v[206:209], v[88:91]
	v_mfma_f32_16x16x32_bf16 v[72:75], v[136:139], v[214:217], v[72:75]
	v_mfma_f32_16x16x32_bf16 v[76:79], v[128:131], v[214:217], v[76:79]
	v_mfma_f32_16x16x32_bf16 v[124:127], v[132:135], v[194:197], v[124:127]
	v_mfma_f32_16x16x32_bf16 v[120:123], v[140:143], v[194:197], v[120:123]
	v_mfma_f32_16x16x32_bf16 v[104:107], v[140:143], v[202:205], v[104:107]
	v_mfma_f32_16x16x32_bf16 v[108:111], v[132:135], v[202:205], v[108:111]
	v_mfma_f32_16x16x32_bf16 v[92:95], v[132:135], v[210:213], v[92:95]
	v_mfma_f32_16x16x32_bf16 v[88:91], v[140:143], v[210:213], v[88:91]
	v_mfma_f32_16x16x32_bf16 v[72:75], v[140:143], v[218:221], v[72:75]
	v_mfma_f32_16x16x32_bf16 v[76:79], v[132:135], v[218:221], v[76:79]
	s_setprio 0
	s_setprio 1
	v_mfma_f32_16x16x32_bf16 v[116:119], v[144:147], v[180:183], v[116:119]
	v_mfma_f32_16x16x32_bf16 v[112:115], v[172:175], v[180:183], v[112:115]
	v_mfma_f32_16x16x32_bf16 v[96:99], v[172:175], v[198:201], v[96:99]
	v_mfma_f32_16x16x32_bf16 v[100:103], v[144:147], v[198:201], v[100:103]
	v_mfma_f32_16x16x32_bf16 v[84:87], v[144:147], v[206:209], v[84:87]
	v_mfma_f32_16x16x32_bf16 v[80:83], v[172:175], v[206:209], v[80:83]
	v_mfma_f32_16x16x32_bf16 v[64:67], v[172:175], v[214:217], v[64:67]
	v_mfma_f32_16x16x32_bf16 v[68:71], v[144:147], v[214:217], v[68:71]
	v_mfma_f32_16x16x32_bf16 v[116:119], v[148:151], v[194:197], v[116:119]
	v_mfma_f32_16x16x32_bf16 v[112:115], v[176:179], v[194:197], v[112:115]
	v_mfma_f32_16x16x32_bf16 v[96:99], v[176:179], v[202:205], v[96:99]
	v_mfma_f32_16x16x32_bf16 v[100:103], v[148:151], v[202:205], v[100:103]
	v_mfma_f32_16x16x32_bf16 v[84:87], v[148:151], v[210:213], v[84:87]
	v_mfma_f32_16x16x32_bf16 v[80:83], v[176:179], v[210:213], v[80:83]
	v_mfma_f32_16x16x32_bf16 v[64:67], v[176:179], v[218:221], v[64:67]
	v_mfma_f32_16x16x32_bf16 v[68:71], v[148:151], v[218:221], v[68:71]
	s_setprio 0
	s_barrier
	s_add_i32 s54, s84, s65
	v_lshl_add_u64 v[222:223], v[222:223], 0, s[28:29]
	s_mov_b32 m0, s54
	ds_read_b128 v[180:183], v191 offset:49152
	ds_read_b128 v[194:197], v191 offset:50176
	ds_read_b128 v[198:201], v191 offset:51200
	ds_read_b128 v[202:205], v191 offset:52224
	ds_read_b128 v[206:209], v191 offset:53248
	ds_read_b128 v[210:213], v191 offset:54272
	ds_read_b128 v[214:217], v191 offset:55296
	ds_read_b128 v[218:221], v191 offset:56320
	global_load_lds_dwordx4 v[222:223], off
	s_add_i32 m0, s54, 0x2000
	s_add_u32 s54, s58, 0xb0080
	v_lshl_add_u64 v[222:223], v[224:225], 0, s[28:29]
	s_addc_u32 s55, s59, 0
	s_add_i32 s58, s85, s65
	global_load_lds_dwordx4 v[222:223], off
	v_lshl_add_u64 v[222:223], s[54:55], 0, v[154:155]
	s_mov_b32 m0, s58
	s_nop 0
	global_load_lds_dwordx4 v[222:223], off
	v_lshl_add_u64 v[222:223], s[54:55], 0, v[162:163]
	s_add_i32 m0, s58, 0x2000
	s_nop 0
	global_load_lds_dwordx4 v[222:223], off
	v_lshl_add_u64 v[222:223], v[226:227], 0, s[28:29]
	s_mov_b32 m0, s3
	s_nop 0
	global_load_lds_dwordx4 v[222:223], off
	v_lshl_add_u64 v[222:223], v[228:229], 0, s[28:29]
	s_mov_b32 m0, s71
	s_nop 0
	global_load_lds_dwordx4 v[222:223], off
	s_waitcnt vmcnt(8)
	s_waitcnt lgkmcnt(0)
	s_barrier
	s_setprio 1
	s_waitcnt lgkmcnt(0)
	v_mfma_f32_16x16x32_bf16 v[60:63], v[128:131], v[180:183], v[60:63]
	v_mfma_f32_16x16x32_bf16 v[56:59], v[136:139], v[180:183], v[56:59]
	v_mfma_f32_16x16x32_bf16 v[40:43], v[136:139], v[198:201], v[40:43]
	v_mfma_f32_16x16x32_bf16 v[44:47], v[128:131], v[198:201], v[44:47]
	v_mfma_f32_16x16x32_bf16 v[28:31], v[128:131], v[206:209], v[28:31]
	v_mfma_f32_16x16x32_bf16 v[24:27], v[136:139], v[206:209], v[24:27]
	v_mfma_f32_16x16x32_bf16 v[8:11], v[136:139], v[214:217], v[8:11]
	v_mfma_f32_16x16x32_bf16 v[12:15], v[128:131], v[214:217], v[12:15]
	v_mfma_f32_16x16x32_bf16 v[60:63], v[132:135], v[194:197], v[60:63]
	v_mfma_f32_16x16x32_bf16 v[56:59], v[140:143], v[194:197], v[56:59]
	v_mfma_f32_16x16x32_bf16 v[40:43], v[140:143], v[202:205], v[40:43]
	v_mfma_f32_16x16x32_bf16 v[44:47], v[132:135], v[202:205], v[44:47]
	v_mfma_f32_16x16x32_bf16 v[28:31], v[132:135], v[210:213], v[28:31]
	v_mfma_f32_16x16x32_bf16 v[24:27], v[140:143], v[210:213], v[24:27]
	v_mfma_f32_16x16x32_bf16 v[8:11], v[140:143], v[218:221], v[8:11]
	v_mfma_f32_16x16x32_bf16 v[12:15], v[132:135], v[218:221], v[12:15]
	s_setprio 0
	s_setprio 1
	v_mfma_f32_16x16x32_bf16 v[52:55], v[144:147], v[180:183], v[52:55]
	v_mfma_f32_16x16x32_bf16 v[48:51], v[172:175], v[180:183], v[48:51]
	v_mfma_f32_16x16x32_bf16 v[32:35], v[172:175], v[198:201], v[32:35]
	v_mfma_f32_16x16x32_bf16 v[36:39], v[144:147], v[198:201], v[36:39]
	v_mfma_f32_16x16x32_bf16 v[20:23], v[144:147], v[206:209], v[20:23]
	v_mfma_f32_16x16x32_bf16 v[16:19], v[172:175], v[206:209], v[16:19]
	v_mfma_f32_16x16x32_bf16 v[0:3], v[172:175], v[214:217], v[0:3]
	v_mfma_f32_16x16x32_bf16 v[4:7], v[144:147], v[214:217], v[4:7]
	v_mfma_f32_16x16x32_bf16 v[52:55], v[148:151], v[194:197], v[52:55]
	v_mfma_f32_16x16x32_bf16 v[48:51], v[176:179], v[194:197], v[48:51]
	v_mfma_f32_16x16x32_bf16 v[32:35], v[176:179], v[202:205], v[32:35]
	v_mfma_f32_16x16x32_bf16 v[36:39], v[148:151], v[202:205], v[36:39]
	v_mfma_f32_16x16x32_bf16 v[20:23], v[148:151], v[210:213], v[20:23]
	v_mfma_f32_16x16x32_bf16 v[16:19], v[176:179], v[210:213], v[16:19]
	v_mfma_f32_16x16x32_bf16 v[0:3], v[176:179], v[218:221], v[0:3]
	v_mfma_f32_16x16x32_bf16 v[4:7], v[148:151], v[218:221], v[4:7]
	s_setprio 0
	s_barrier
	s_add_i32 s83, s83, 2
	s_add_u32 s81, s81, 0x100
	s_addc_u32 s82, s82, 0
	s_cmp_gt_u32 s83, 41
	s_mov_b64 s[54:55], s[56:57]
	s_cbranch_scc0 .LBB0_159
	s_and_b64 vcc, exec, s[30:31]
	s_cbranch_vccz .LBB0_162
	s_barrier

.LBB0_254:
	s_ashr_i32 s61, s60, 31
	s_lshl_b64 s[62:63], s[60:61], 19
	s_add_u32 s62, s35, s62
	s_addc_u32 s63, s47, s63
	s_and_b64 s[64:65], s[12:13], exec
	s_cselect_b32 s3, s63, s69
	s_cselect_b32 s61, s62, s68
	s_ashr_i32 s59, s58, 31
	s_lshl_b64 s[64:65], s[58:59], 19
	s_add_u32 s64, s49, s64
	s_addc_u32 s65, s70, s65
	s_and_b64 s[92:93], s[12:13], exec
	s_cselect_b32 s91, s65, s67
	s_cselect_b32 s92, s64, s66
	s_lshl_b32 s59, s14, 8
	v_add_u32_e32 v0, s59, v182
	s_add_u32 s93, s66, 0x100
	s_waitcnt lgkmcnt(0)
	v_ashrrev_i32_e32 v1, 31, v0
	s_addc_u32 s94, s67, 0
	v_lshl_add_u64 v[72:73], v[0:1], 4, s[26:27]
	s_add_u32 s14, s68, 0x40080
	s_addc_u32 s15, s69, 0
	s_mov_b32 s95, -2
	s_mov_b64 s[66:67], 0
	v_add_u32_e32 v74, s83, v181
	ds_read_b128 v[88:91], v74
	ds_read_b128 v[108:111], v74 offset:1024
	ds_read_b128 v[128:131], v74 offset:2048
	ds_read_b128 v[144:147], v74 offset:3072
	v_add_u32_e32 v74, s84, v181
	ds_read_b128 v[148:151], v74
	ds_read_b128 v[152:155], v74 offset:1024
	ds_read_b128 v[176:179], v74 offset:2048
	ds_read_b128 v[190:193], v74 offset:3072
	s_add_u32 s68, s14, 0xfffc0080
	s_addc_u32 s69, s15, -1
	s_and_b64 s[66:67], s[66:67], exec
	s_cselect_b32 s69, s3, s69
	s_cselect_b32 s68, s61, s68
	s_cselect_b32 s67, s91, s94
	s_cselect_b32 s66, s92, s93
	v_lshl_add_u64 v[74:75], s[14:15], 0, v[170:171]
	s_add_i32 m0, s74, 0xc000
	ds_read_b128 v[194:197], v187
	ds_read_b128 v[198:201], v187 offset:1024
	ds_read_b128 v[202:205], v187 offset:2048
	ds_read_b128 v[206:209], v187 offset:3072
	ds_read_b128 v[210:213], v187 offset:4096
	ds_read_b128 v[214:217], v187 offset:5120
	ds_read_b128 v[218:221], v187 offset:6144
	ds_read_b128 v[222:225], v187 offset:7168
	global_load_lds_dwordx4 v[74:75], off
	v_lshl_add_u64 v[74:75], s[14:15], 0, v[168:169]
	s_add_i32 m0, s74, 0xe000
	s_nop 0
	global_load_lds_dwordx4 v[74:75], off
	s_waitcnt vmcnt(8)
	s_waitcnt lgkmcnt(0)
	s_barrier
	s_setprio 1
	s_waitcnt lgkmcnt(0)
	v_mfma_f32_16x16x32_bf16 v[140:143], v[88:91], v[194:197], 0
	v_mfma_f32_16x16x32_bf16 v[136:139], v[128:131], v[194:197], 0
	v_mfma_f32_16x16x32_bf16 v[120:123], v[88:91], v[202:205], 0
	v_mfma_f32_16x16x32_bf16 v[116:119], v[128:131], v[202:205], 0
	v_mfma_f32_16x16x32_bf16 v[100:103], v[88:91], v[210:213], 0
	v_mfma_f32_16x16x32_bf16 v[96:99], v[128:131], v[210:213], 0
	v_mfma_f32_16x16x32_bf16 v[80:83], v[88:91], v[218:221], 0
	v_mfma_f32_16x16x32_bf16 v[74:77], v[128:131], v[218:221], 0
	v_mfma_f32_16x16x32_bf16 v[140:143], v[108:111], v[198:201], v[140:143]
	v_mfma_f32_16x16x32_bf16 v[136:139], v[144:147], v[198:201], v[136:139]
	v_mfma_f32_16x16x32_bf16 v[120:123], v[108:111], v[206:209], v[120:123]
	v_mfma_f32_16x16x32_bf16 v[116:119], v[144:147], v[206:209], v[116:119]
	v_mfma_f32_16x16x32_bf16 v[100:103], v[108:111], v[214:217], v[100:103]
	v_mfma_f32_16x16x32_bf16 v[96:99], v[144:147], v[214:217], v[96:99]
	v_mfma_f32_16x16x32_bf16 v[80:83], v[108:111], v[222:225], v[80:83]
	v_mfma_f32_16x16x32_bf16 v[74:77], v[144:147], v[222:225], v[74:77]
	s_setprio 0
	s_setprio 1
	v_mfma_f32_16x16x32_bf16 v[132:135], v[148:151], v[194:197], 0
	v_mfma_f32_16x16x32_bf16 v[124:127], v[176:179], v[194:197], 0
	v_mfma_f32_16x16x32_bf16 v[112:115], v[148:151], v[202:205], 0
	v_mfma_f32_16x16x32_bf16 v[104:107], v[176:179], v[202:205], 0
	v_mfma_f32_16x16x32_bf16 v[92:95], v[148:151], v[210:213], 0
	v_mfma_f32_16x16x32_bf16 v[84:87], v[176:179], v[210:213], 0
	v_mfma_f32_16x16x32_bf16 v[68:71], v[148:151], v[218:221], 0
	v_mfma_f32_16x16x32_bf16 v[64:67], v[176:179], v[218:221], 0
	v_mfma_f32_16x16x32_bf16 v[132:135], v[152:155], v[198:201], v[132:135]
	v_mfma_f32_16x16x32_bf16 v[124:127], v[190:193], v[198:201], v[124:127]
	v_mfma_f32_16x16x32_bf16 v[112:115], v[152:155], v[206:209], v[112:115]
	v_mfma_f32_16x16x32_bf16 v[104:107], v[190:193], v[206:209], v[104:107]
	v_mfma_f32_16x16x32_bf16 v[92:95], v[152:155], v[214:217], v[92:95]
	v_mfma_f32_16x16x32_bf16 v[84:87], v[190:193], v[214:217], v[84:87]
	v_mfma_f32_16x16x32_bf16 v[68:71], v[152:155], v[222:225], v[68:71]
	v_mfma_f32_16x16x32_bf16 v[64:67], v[190:193], v[222:225], v[64:67]
	s_setprio 0
	s_barrier
	s_add_i32 s96, s83, s71
	v_lshl_add_u64 v[226:227], s[66:67], 0, v[162:163]
	s_mov_b32 m0, s96
	ds_read_b128 v[194:197], v187 offset:16384
	ds_read_b128 v[198:201], v187 offset:17408
	ds_read_b128 v[202:205], v187 offset:18432
	ds_read_b128 v[206:209], v187 offset:19456
	ds_read_b128 v[210:213], v187 offset:20480
	ds_read_b128 v[214:217], v187 offset:21504
	ds_read_b128 v[218:221], v187 offset:22528
	ds_read_b128 v[222:225], v187 offset:23552
	global_load_lds_dwordx4 v[226:227], off
	s_add_i32 m0, s96, 0x2000
	s_add_u32 s96, s66, 0x40000
	v_lshl_add_u64 v[228:229], s[66:67], 0, v[166:167]
	s_addc_u32 s97, s67, 0
	s_add_i32 vcc_lo, s84, s71
	global_load_lds_dwordx4 v[228:229], off
	v_lshl_add_u64 v[78:79], s[96:97], 0, v[162:163]
	s_mov_b32 m0, vcc_lo
	v_lshl_add_u64 v[230:231], s[68:69], 0, v[160:161]
	global_load_lds_dwordx4 v[78:79], off
	v_lshl_add_u64 v[78:79], s[96:97], 0, v[166:167]
	s_add_i32 m0, vcc_lo, 0x2000
	v_lshl_add_u64 v[232:233], s[68:69], 0, v[164:165]
	global_load_lds_dwordx4 v[78:79], off
	s_mov_b32 m0, s74
	s_nop 0
	global_load_lds_dwordx4 v[230:231], off
	s_mov_b32 m0, s75
	s_nop 0
	global_load_lds_dwordx4 v[232:233], off
	s_waitcnt vmcnt(8)
	s_waitcnt lgkmcnt(0)
	s_barrier
	s_setprio 1
	s_waitcnt lgkmcnt(0)
	v_mfma_f32_16x16x32_bf16 v[60:63], v[88:91], v[194:197], 0
	v_mfma_f32_16x16x32_bf16 v[56:59], v[128:131], v[194:197], 0
	v_mfma_f32_16x16x32_bf16 v[44:47], v[88:91], v[202:205], 0
	v_mfma_f32_16x16x32_bf16 v[40:43], v[128:131], v[202:205], 0
	v_mfma_f32_16x16x32_bf16 v[28:31], v[88:91], v[210:213], 0
	v_mfma_f32_16x16x32_bf16 v[24:27], v[128:131], v[210:213], 0
	v_mfma_f32_16x16x32_bf16 v[12:15], v[88:91], v[218:221], 0
	v_mfma_f32_16x16x32_bf16 v[8:11], v[128:131], v[218:221], 0
	v_mfma_f32_16x16x32_bf16 v[60:63], v[108:111], v[198:201], v[60:63]
	v_mfma_f32_16x16x32_bf16 v[56:59], v[144:147], v[198:201], v[56:59]
	v_mfma_f32_16x16x32_bf16 v[44:47], v[108:111], v[206:209], v[44:47]
	v_mfma_f32_16x16x32_bf16 v[40:43], v[144:147], v[206:209], v[40:43]
	v_mfma_f32_16x16x32_bf16 v[28:31], v[108:111], v[214:217], v[28:31]
	v_mfma_f32_16x16x32_bf16 v[24:27], v[144:147], v[214:217], v[24:27]
	v_mfma_f32_16x16x32_bf16 v[12:15], v[108:111], v[222:225], v[12:15]
	v_mfma_f32_16x16x32_bf16 v[8:11], v[144:147], v[222:225], v[8:11]
	s_setprio 0
	s_setprio 1
	v_mfma_f32_16x16x32_bf16 v[52:55], v[148:151], v[194:197], 0
	v_mfma_f32_16x16x32_bf16 v[48:51], v[176:179], v[194:197], 0
	v_mfma_f32_16x16x32_bf16 v[36:39], v[148:151], v[202:205], 0
	v_mfma_f32_16x16x32_bf16 v[32:35], v[176:179], v[202:205], 0
	v_mfma_f32_16x16x32_bf16 v[20:23], v[148:151], v[210:213], 0
	v_mfma_f32_16x16x32_bf16 v[16:19], v[176:179], v[210:213], 0
	v_mfma_f32_16x16x32_bf16 v[4:7], v[148:151], v[218:221], 0
	v_mfma_f32_16x16x32_bf16 v[0:3], v[176:179], v[218:221], 0
	v_mfma_f32_16x16x32_bf16 v[52:55], v[152:155], v[198:201], v[52:55]
	v_mfma_f32_16x16x32_bf16 v[48:51], v[190:193], v[198:201], v[48:51]
	v_mfma_f32_16x16x32_bf16 v[36:39], v[152:155], v[206:209], v[36:39]
	v_mfma_f32_16x16x32_bf16 v[32:35], v[190:193], v[206:209], v[32:35]
	v_mfma_f32_16x16x32_bf16 v[20:23], v[152:155], v[214:217], v[20:23]
	v_mfma_f32_16x16x32_bf16 v[16:19], v[190:193], v[214:217], v[16:19]
	v_mfma_f32_16x16x32_bf16 v[4:7], v[152:155], v[222:225], v[4:7]
	v_mfma_f32_16x16x32_bf16 v[0:3], v[190:193], v[222:225], v[0:3]
	s_setprio 0
	s_barrier
	s_add_i32 s96, 0, 0x18000
	v_add_u32_e32 v78, s96, v181
	s_add_i32 s97, 0, 0x1c000
	ds_read_b128 v[88:91], v78
	ds_read_b128 v[108:111], v78 offset:1024
	ds_read_b128 v[128:131], v78 offset:2048
	ds_read_b128 v[144:147], v78 offset:3072
	v_add_u32_e32 v78, s97, v181
	ds_read_b128 v[148:151], v78
	ds_read_b128 v[152:155], v78 offset:1024
	ds_read_b128 v[176:179], v78 offset:2048
	ds_read_b128 v[190:193], v78 offset:3072
	s_add_u32 s68, s68, 0x40000
	s_addc_u32 s69, s69, 0
	s_mov_b32 m0, s76
	v_lshl_add_u64 v[78:79], s[68:69], 0, v[160:161]
	ds_read_b128 v[194:197], v187 offset:32768
	ds_read_b128 v[198:201], v187 offset:33792
	ds_read_b128 v[202:205], v187 offset:34816
	ds_read_b128 v[206:209], v187 offset:35840
	ds_read_b128 v[210:213], v187 offset:36864
	ds_read_b128 v[214:217], v187 offset:37888
	ds_read_b128 v[218:221], v187 offset:38912
	ds_read_b128 v[222:225], v187 offset:39936
	global_load_lds_dwordx4 v[78:79], off
	v_lshl_add_u64 v[78:79], s[68:69], 0, v[164:165]
	s_mov_b32 m0, s77
	s_nop 0
	global_load_lds_dwordx4 v[78:79], off
	s_waitcnt vmcnt(8)
	s_waitcnt lgkmcnt(0)
	s_barrier
	s_setprio 1
	s_waitcnt lgkmcnt(0)
	v_mfma_f32_16x16x32_bf16 v[140:143], v[88:91], v[194:197], v[140:143]
	v_mfma_f32_16x16x32_bf16 v[136:139], v[128:131], v[194:197], v[136:139]
	v_mfma_f32_16x16x32_bf16 v[120:123], v[88:91], v[202:205], v[120:123]
	v_mfma_f32_16x16x32_bf16 v[116:119], v[128:131], v[202:205], v[116:119]
	v_mfma_f32_16x16x32_bf16 v[100:103], v[88:91], v[210:213], v[100:103]
	v_mfma_f32_16x16x32_bf16 v[96:99], v[128:131], v[210:213], v[96:99]
	v_mfma_f32_16x16x32_bf16 v[78:81], v[88:91], v[218:221], v[80:83]
	v_mfma_f32_16x16x32_bf16 v[74:77], v[128:131], v[218:221], v[74:77]
	v_mfma_f32_16x16x32_bf16 v[140:143], v[108:111], v[198:201], v[140:143]
	v_mfma_f32_16x16x32_bf16 v[136:139], v[144:147], v[198:201], v[136:139]
	v_mfma_f32_16x16x32_bf16 v[120:123], v[108:111], v[206:209], v[120:123]
	v_mfma_f32_16x16x32_bf16 v[116:119], v[144:147], v[206:209], v[116:119]
	v_mfma_f32_16x16x32_bf16 v[100:103], v[108:111], v[214:217], v[100:103]
	v_mfma_f32_16x16x32_bf16 v[96:99], v[144:147], v[214:217], v[96:99]
	v_mfma_f32_16x16x32_bf16 v[80:83], v[108:111], v[222:225], v[78:81]
	v_mfma_f32_16x16x32_bf16 v[76:79], v[144:147], v[222:225], v[74:77]
	s_setprio 0
	s_setprio 1
	v_mfma_f32_16x16x32_bf16 v[132:135], v[148:151], v[194:197], v[132:135]
	v_mfma_f32_16x16x32_bf16 v[124:127], v[176:179], v[194:197], v[124:127]
	v_mfma_f32_16x16x32_bf16 v[104:107], v[176:179], v[202:205], v[104:107]
	v_mfma_f32_16x16x32_bf16 v[112:115], v[148:151], v[202:205], v[112:115]
	v_mfma_f32_16x16x32_bf16 v[92:95], v[148:151], v[210:213], v[92:95]
	v_mfma_f32_16x16x32_bf16 v[84:87], v[176:179], v[210:213], v[84:87]
	v_mfma_f32_16x16x32_bf16 v[64:67], v[176:179], v[218:221], v[64:67]
	v_mfma_f32_16x16x32_bf16 v[68:71], v[148:151], v[218:221], v[68:71]
	v_mfma_f32_16x16x32_bf16 v[132:135], v[152:155], v[198:201], v[132:135]
	v_mfma_f32_16x16x32_bf16 v[124:127], v[190:193], v[198:201], v[124:127]
	v_mfma_f32_16x16x32_bf16 v[104:107], v[190:193], v[206:209], v[104:107]
	v_mfma_f32_16x16x32_bf16 v[112:115], v[152:155], v[206:209], v[112:115]
	v_mfma_f32_16x16x32_bf16 v[92:95], v[152:155], v[214:217], v[92:95]
	v_mfma_f32_16x16x32_bf16 v[84:87], v[190:193], v[214:217], v[84:87]
	v_mfma_f32_16x16x32_bf16 v[64:67], v[190:193], v[222:225], v[64:67]
	v_mfma_f32_16x16x32_bf16 v[68:71], v[152:155], v[222:225], v[68:71]
	s_setprio 0
	s_barrier
	s_add_i32 s68, s96, s71
	v_lshl_add_u64 v[74:75], v[226:227], 0, s[28:29]
	s_mov_b32 m0, s68
	ds_read_b128 v[194:197], v187 offset:49152
	ds_read_b128 v[198:201], v187 offset:50176
	ds_read_b128 v[202:205], v187 offset:51200
	ds_read_b128 v[206:209], v187 offset:52224
	ds_read_b128 v[210:213], v187 offset:53248
	ds_read_b128 v[214:217], v187 offset:54272
	ds_read_b128 v[218:221], v187 offset:55296
	ds_read_b128 v[222:225], v187 offset:56320
	global_load_lds_dwordx4 v[74:75], off
	s_add_i32 m0, s68, 0x2000
	s_add_u32 s66, s66, 0x40080
	v_lshl_add_u64 v[74:75], v[228:229], 0, s[28:29]
	s_addc_u32 s67, s67, 0
	s_add_i32 s68, s97, s71
	global_load_lds_dwordx4 v[74:75], off
	v_lshl_add_u64 v[74:75], s[66:67], 0, v[162:163]
	s_mov_b32 m0, s68
	s_nop 0
	global_load_lds_dwordx4 v[74:75], off
	v_lshl_add_u64 v[74:75], s[66:67], 0, v[166:167]
	s_add_i32 m0, s68, 0x2000
	s_nop 0
	global_load_lds_dwordx4 v[74:75], off
	v_lshl_add_u64 v[74:75], v[230:231], 0, s[28:29]
	s_mov_b32 m0, s78
	s_nop 0
	global_load_lds_dwordx4 v[74:75], off
	v_lshl_add_u64 v[74:75], v[232:233], 0, s[28:29]
	s_mov_b32 m0, s79
	s_nop 0
	global_load_lds_dwordx4 v[74:75], off
	s_waitcnt vmcnt(8)
	s_waitcnt lgkmcnt(0)
	s_barrier
	s_setprio 1
	s_waitcnt lgkmcnt(0)
	v_mfma_f32_16x16x32_bf16 v[60:63], v[88:91], v[194:197], v[60:63]
	v_mfma_f32_16x16x32_bf16 v[56:59], v[128:131], v[194:197], v[56:59]
	v_mfma_f32_16x16x32_bf16 v[40:43], v[128:131], v[202:205], v[40:43]
	v_mfma_f32_16x16x32_bf16 v[44:47], v[88:91], v[202:205], v[44:47]
	v_mfma_f32_16x16x32_bf16 v[28:31], v[88:91], v[210:213], v[28:31]
	v_mfma_f32_16x16x32_bf16 v[24:27], v[128:131], v[210:213], v[24:27]
	v_mfma_f32_16x16x32_bf16 v[8:11], v[128:131], v[218:221], v[8:11]
	v_mfma_f32_16x16x32_bf16 v[12:15], v[88:91], v[218:221], v[12:15]
	v_mfma_f32_16x16x32_bf16 v[60:63], v[108:111], v[198:201], v[60:63]
	v_mfma_f32_16x16x32_bf16 v[56:59], v[144:147], v[198:201], v[56:59]
	v_mfma_f32_16x16x32_bf16 v[40:43], v[144:147], v[206:209], v[40:43]
	v_mfma_f32_16x16x32_bf16 v[44:47], v[108:111], v[206:209], v[44:47]
	v_mfma_f32_16x16x32_bf16 v[28:31], v[108:111], v[214:217], v[28:31]
	v_mfma_f32_16x16x32_bf16 v[24:27], v[144:147], v[214:217], v[24:27]
	v_mfma_f32_16x16x32_bf16 v[8:11], v[144:147], v[222:225], v[8:11]
	v_mfma_f32_16x16x32_bf16 v[12:15], v[108:111], v[222:225], v[12:15]
	s_setprio 0
	s_setprio 1
	v_mfma_f32_16x16x32_bf16 v[52:55], v[148:151], v[194:197], v[52:55]
	v_mfma_f32_16x16x32_bf16 v[48:51], v[176:179], v[194:197], v[48:51]
	v_mfma_f32_16x16x32_bf16 v[32:35], v[176:179], v[202:205], v[32:35]
	v_mfma_f32_16x16x32_bf16 v[36:39], v[148:151], v[202:205], v[36:39]
	v_mfma_f32_16x16x32_bf16 v[20:23], v[148:151], v[210:213], v[20:23]
	v_mfma_f32_16x16x32_bf16 v[16:19], v[176:179], v[210:213], v[16:19]
	v_mfma_f32_16x16x32_bf16 v[0:3], v[176:179], v[218:221], v[0:3]
	v_mfma_f32_16x16x32_bf16 v[4:7], v[148:151], v[218:221], v[4:7]
	v_mfma_f32_16x16x32_bf16 v[52:55], v[152:155], v[198:201], v[52:55]
	v_mfma_f32_16x16x32_bf16 v[48:51], v[190:193], v[198:201], v[48:51]
	v_mfma_f32_16x16x32_bf16 v[32:35], v[190:193], v[206:209], v[32:35]
	v_mfma_f32_16x16x32_bf16 v[36:39], v[152:155], v[206:209], v[36:39]
	v_mfma_f32_16x16x32_bf16 v[20:23], v[152:155], v[214:217], v[20:23]
	v_mfma_f32_16x16x32_bf16 v[16:19], v[190:193], v[214:217], v[16:19]
	v_mfma_f32_16x16x32_bf16 v[0:3], v[190:193], v[222:225], v[0:3]
	v_mfma_f32_16x16x32_bf16 v[4:7], v[152:155], v[222:225], v[4:7]
	s_setprio 0
	s_barrier
	s_add_i32 s95, s95, 2
	s_add_u32 s93, s93, 0x100
	s_addc_u32 s94, s94, 0
	s_add_u32 s14, s14, 0x100
	s_addc_u32 s15, s15, 0
	s_branch .LBB0_256
.LBB0_255:
	v_add_u32_e32 v74, s83, v181
	ds_read_b128 v[88:91], v74
	ds_read_b128 v[108:111], v74 offset:1024
	ds_read_b128 v[128:131], v74 offset:2048
	ds_read_b128 v[144:147], v74 offset:3072
	v_add_u32_e32 v74, s84, v181
	ds_read_b128 v[148:151], v74
	ds_read_b128 v[152:155], v74 offset:1024
	ds_read_b128 v[176:179], v74 offset:2048
	ds_read_b128 v[190:193], v74 offset:3072
	s_add_u32 s68, s14, 0xfffc0080
	s_addc_u32 s69, s15, -1
	s_and_b64 s[66:67], s[66:67], exec
	s_cselect_b32 s69, s3, s69
	s_cselect_b32 s68, s61, s68
	s_cselect_b32 s67, s91, s94
	s_cselect_b32 s66, s92, s93
	v_lshl_add_u64 v[74:75], s[14:15], 0, v[170:171]
	s_add_i32 m0, s74, 0xc000
	ds_read_b128 v[194:197], v187
	ds_read_b128 v[198:201], v187 offset:1024
	ds_read_b128 v[202:205], v187 offset:2048
	ds_read_b128 v[206:209], v187 offset:3072
	ds_read_b128 v[210:213], v187 offset:4096
	ds_read_b128 v[214:217], v187 offset:5120
	ds_read_b128 v[218:221], v187 offset:6144
	ds_read_b128 v[222:225], v187 offset:7168
	global_load_lds_dwordx4 v[74:75], off
	v_lshl_add_u64 v[74:75], s[14:15], 0, v[168:169]
	s_add_i32 m0, s74, 0xe000
	s_nop 0
	global_load_lds_dwordx4 v[74:75], off
	s_waitcnt vmcnt(8)
	s_waitcnt lgkmcnt(0)
	s_barrier
	s_setprio 1
	s_waitcnt lgkmcnt(0)
	v_mfma_f32_16x16x32_bf16 v[140:143], v[88:91], v[194:197], v[140:143]
	v_mfma_f32_16x16x32_bf16 v[136:139], v[128:131], v[194:197], v[136:139]
	v_mfma_f32_16x16x32_bf16 v[120:123], v[88:91], v[202:205], v[120:123]
	v_mfma_f32_16x16x32_bf16 v[116:119], v[128:131], v[202:205], v[116:119]
	v_mfma_f32_16x16x32_bf16 v[100:103], v[88:91], v[210:213], v[100:103]
	v_mfma_f32_16x16x32_bf16 v[96:99], v[128:131], v[210:213], v[96:99]
	v_mfma_f32_16x16x32_bf16 v[80:83], v[88:91], v[218:221], v[80:83]
	v_mfma_f32_16x16x32_bf16 v[74:77], v[128:131], v[218:221], v[76:79]
	v_mfma_f32_16x16x32_bf16 v[140:143], v[108:111], v[198:201], v[140:143]
	v_mfma_f32_16x16x32_bf16 v[136:139], v[144:147], v[198:201], v[136:139]
	v_mfma_f32_16x16x32_bf16 v[120:123], v[108:111], v[206:209], v[120:123]
	v_mfma_f32_16x16x32_bf16 v[116:119], v[144:147], v[206:209], v[116:119]
	v_mfma_f32_16x16x32_bf16 v[100:103], v[108:111], v[214:217], v[100:103]
	v_mfma_f32_16x16x32_bf16 v[96:99], v[144:147], v[214:217], v[96:99]
	v_mfma_f32_16x16x32_bf16 v[80:83], v[108:111], v[222:225], v[80:83]
	v_mfma_f32_16x16x32_bf16 v[74:77], v[144:147], v[222:225], v[74:77]
	s_setprio 0
	s_setprio 1
	v_mfma_f32_16x16x32_bf16 v[132:135], v[148:151], v[194:197], v[132:135]
	v_mfma_f32_16x16x32_bf16 v[124:127], v[176:179], v[194:197], v[124:127]
	v_mfma_f32_16x16x32_bf16 v[104:107], v[176:179], v[202:205], v[104:107]
	v_mfma_f32_16x16x32_bf16 v[112:115], v[148:151], v[202:205], v[112:115]
	v_mfma_f32_16x16x32_bf16 v[92:95], v[148:151], v[210:213], v[92:95]
	v_mfma_f32_16x16x32_bf16 v[84:87], v[176:179], v[210:213], v[84:87]
	v_mfma_f32_16x16x32_bf16 v[64:67], v[176:179], v[218:221], v[64:67]
	v_mfma_f32_16x16x32_bf16 v[68:71], v[148:151], v[218:221], v[68:71]
	v_mfma_f32_16x16x32_bf16 v[132:135], v[152:155], v[198:201], v[132:135]
	v_mfma_f32_16x16x32_bf16 v[124:127], v[190:193], v[198:201], v[124:127]
	v_mfma_f32_16x16x32_bf16 v[104:107], v[190:193], v[206:209], v[104:107]
	v_mfma_f32_16x16x32_bf16 v[112:115], v[152:155], v[206:209], v[112:115]
	v_mfma_f32_16x16x32_bf16 v[92:95], v[152:155], v[214:217], v[92:95]
	v_mfma_f32_16x16x32_bf16 v[84:87], v[190:193], v[214:217], v[84:87]
	v_mfma_f32_16x16x32_bf16 v[64:67], v[190:193], v[222:225], v[64:67]
	v_mfma_f32_16x16x32_bf16 v[68:71], v[152:155], v[222:225], v[68:71]
	s_setprio 0
	s_barrier
	s_add_i32 s96, s83, s71
	v_lshl_add_u64 v[226:227], s[66:67], 0, v[162:163]
	s_mov_b32 m0, s96
	ds_read_b128 v[194:197], v187 offset:16384
	ds_read_b128 v[198:201], v187 offset:17408
	ds_read_b128 v[202:205], v187 offset:18432
	ds_read_b128 v[206:209], v187 offset:19456
	ds_read_b128 v[210:213], v187 offset:20480
	ds_read_b128 v[214:217], v187 offset:21504
	ds_read_b128 v[218:221], v187 offset:22528
	ds_read_b128 v[222:225], v187 offset:23552
	global_load_lds_dwordx4 v[226:227], off
	s_add_i32 m0, s96, 0x2000
	s_add_u32 s96, s66, 0x40000
	v_lshl_add_u64 v[228:229], s[66:67], 0, v[166:167]
	s_addc_u32 s97, s67, 0
	s_add_i32 vcc_lo, s84, s71
	global_load_lds_dwordx4 v[228:229], off
	v_lshl_add_u64 v[78:79], s[96:97], 0, v[162:163]
	s_mov_b32 m0, vcc_lo
	v_lshl_add_u64 v[230:231], s[68:69], 0, v[160:161]
	global_load_lds_dwordx4 v[78:79], off
	v_lshl_add_u64 v[78:79], s[96:97], 0, v[166:167]
	s_add_i32 m0, vcc_lo, 0x2000
	v_lshl_add_u64 v[232:233], s[68:69], 0, v[164:165]
	global_load_lds_dwordx4 v[78:79], off
	s_mov_b32 m0, s74
	s_nop 0
	global_load_lds_dwordx4 v[230:231], off
	s_mov_b32 m0, s75
	s_nop 0
	global_load_lds_dwordx4 v[232:233], off
	s_waitcnt vmcnt(8)
	s_waitcnt lgkmcnt(0)
	s_barrier
	s_setprio 1
	s_waitcnt lgkmcnt(0)
	v_mfma_f32_16x16x32_bf16 v[60:63], v[88:91], v[194:197], v[60:63]
	v_mfma_f32_16x16x32_bf16 v[56:59], v[128:131], v[194:197], v[56:59]
	v_mfma_f32_16x16x32_bf16 v[40:43], v[128:131], v[202:205], v[40:43]
	v_mfma_f32_16x16x32_bf16 v[44:47], v[88:91], v[202:205], v[44:47]
	v_mfma_f32_16x16x32_bf16 v[28:31], v[88:91], v[210:213], v[28:31]
	v_mfma_f32_16x16x32_bf16 v[24:27], v[128:131], v[210:213], v[24:27]
	v_mfma_f32_16x16x32_bf16 v[8:11], v[128:131], v[218:221], v[8:11]
	v_mfma_f32_16x16x32_bf16 v[12:15], v[88:91], v[218:221], v[12:15]
	v_mfma_f32_16x16x32_bf16 v[60:63], v[108:111], v[198:201], v[60:63]
	v_mfma_f32_16x16x32_bf16 v[56:59], v[144:147], v[198:201], v[56:59]
	v_mfma_f32_16x16x32_bf16 v[40:43], v[144:147], v[206:209], v[40:43]
	v_mfma_f32_16x16x32_bf16 v[44:47], v[108:111], v[206:209], v[44:47]
	v_mfma_f32_16x16x32_bf16 v[28:31], v[108:111], v[214:217], v[28:31]
	v_mfma_f32_16x16x32_bf16 v[24:27], v[144:147], v[214:217], v[24:27]
	v_mfma_f32_16x16x32_bf16 v[8:11], v[144:147], v[222:225], v[8:11]
	v_mfma_f32_16x16x32_bf16 v[12:15], v[108:111], v[222:225], v[12:15]
	s_setprio 0
	s_setprio 1
	v_mfma_f32_16x16x32_bf16 v[52:55], v[148:151], v[194:197], v[52:55]
	v_mfma_f32_16x16x32_bf16 v[48:51], v[176:179], v[194:197], v[48:51]
	v_mfma_f32_16x16x32_bf16 v[32:35], v[176:179], v[202:205], v[32:35]
	v_mfma_f32_16x16x32_bf16 v[36:39], v[148:151], v[202:205], v[36:39]
	v_mfma_f32_16x16x32_bf16 v[20:23], v[148:151], v[210:213], v[20:23]
	v_mfma_f32_16x16x32_bf16 v[16:19], v[176:179], v[210:213], v[16:19]
	v_mfma_f32_16x16x32_bf16 v[0:3], v[176:179], v[218:221], v[0:3]
	v_mfma_f32_16x16x32_bf16 v[4:7], v[148:151], v[218:221], v[4:7]
	v_mfma_f32_16x16x32_bf16 v[52:55], v[152:155], v[198:201], v[52:55]
	v_mfma_f32_16x16x32_bf16 v[48:51], v[190:193], v[198:201], v[48:51]
	v_mfma_f32_16x16x32_bf16 v[32:35], v[190:193], v[206:209], v[32:35]
	v_mfma_f32_16x16x32_bf16 v[36:39], v[152:155], v[206:209], v[36:39]
	v_mfma_f32_16x16x32_bf16 v[20:23], v[152:155], v[214:217], v[20:23]
	v_mfma_f32_16x16x32_bf16 v[16:19], v[190:193], v[214:217], v[16:19]
	v_mfma_f32_16x16x32_bf16 v[0:3], v[190:193], v[222:225], v[0:3]
	v_mfma_f32_16x16x32_bf16 v[4:7], v[152:155], v[222:225], v[4:7]
	s_setprio 0
	s_barrier
	s_add_i32 s96, 0, 0x18000
	v_add_u32_e32 v78, s96, v181
	s_add_i32 s97, 0, 0x1c000
	ds_read_b128 v[88:91], v78
	ds_read_b128 v[108:111], v78 offset:1024
	ds_read_b128 v[128:131], v78 offset:2048
	ds_read_b128 v[144:147], v78 offset:3072
	v_add_u32_e32 v78, s97, v181
	ds_read_b128 v[148:151], v78
	ds_read_b128 v[152:155], v78 offset:1024
	ds_read_b128 v[176:179], v78 offset:2048
	ds_read_b128 v[190:193], v78 offset:3072
	s_add_u32 s68, s68, 0x40000
	s_addc_u32 s69, s69, 0
	s_mov_b32 m0, s76
	v_lshl_add_u64 v[78:79], s[68:69], 0, v[160:161]
	ds_read_b128 v[194:197], v187 offset:32768
	ds_read_b128 v[198:201], v187 offset:33792
	ds_read_b128 v[202:205], v187 offset:34816
	ds_read_b128 v[206:209], v187 offset:35840
	ds_read_b128 v[210:213], v187 offset:36864
	ds_read_b128 v[214:217], v187 offset:37888
	ds_read_b128 v[218:221], v187 offset:38912
	ds_read_b128 v[222:225], v187 offset:39936
	global_load_lds_dwordx4 v[78:79], off
	v_lshl_add_u64 v[78:79], s[68:69], 0, v[164:165]
	s_mov_b32 m0, s77
	s_nop 0
	global_load_lds_dwordx4 v[78:79], off
	s_waitcnt vmcnt(8)
	s_waitcnt lgkmcnt(0)
	s_barrier
	s_setprio 1
	s_waitcnt lgkmcnt(0)
	v_mfma_f32_16x16x32_bf16 v[140:143], v[88:91], v[194:197], v[140:143]
	v_mfma_f32_16x16x32_bf16 v[136:139], v[128:131], v[194:197], v[136:139]
	v_mfma_f32_16x16x32_bf16 v[120:123], v[88:91], v[202:205], v[120:123]
	v_mfma_f32_16x16x32_bf16 v[116:119], v[128:131], v[202:205], v[116:119]
	v_mfma_f32_16x16x32_bf16 v[100:103], v[88:91], v[210:213], v[100:103]
	v_mfma_f32_16x16x32_bf16 v[96:99], v[128:131], v[210:213], v[96:99]
	v_mfma_f32_16x16x32_bf16 v[78:81], v[88:91], v[218:221], v[80:83]
	v_mfma_f32_16x16x32_bf16 v[74:77], v[128:131], v[218:221], v[74:77]
	v_mfma_f32_16x16x32_bf16 v[140:143], v[108:111], v[198:201], v[140:143]
	v_mfma_f32_16x16x32_bf16 v[136:139], v[144:147], v[198:201], v[136:139]
	v_mfma_f32_16x16x32_bf16 v[120:123], v[108:111], v[206:209], v[120:123]
	v_mfma_f32_16x16x32_bf16 v[116:119], v[144:147], v[206:209], v[116:119]
	v_mfma_f32_16x16x32_bf16 v[100:103], v[108:111], v[214:217], v[100:103]
	v_mfma_f32_16x16x32_bf16 v[96:99], v[144:147], v[214:217], v[96:99]
	v_mfma_f32_16x16x32_bf16 v[80:83], v[108:111], v[222:225], v[78:81]
	v_mfma_f32_16x16x32_bf16 v[76:79], v[144:147], v[222:225], v[74:77]
	s_setprio 0
	s_setprio 1
	v_mfma_f32_16x16x32_bf16 v[132:135], v[148:151], v[194:197], v[132:135]
	v_mfma_f32_16x16x32_bf16 v[124:127], v[176:179], v[194:197], v[124:127]
	v_mfma_f32_16x16x32_bf16 v[104:107], v[176:179], v[202:205], v[104:107]
	v_mfma_f32_16x16x32_bf16 v[112:115], v[148:151], v[202:205], v[112:115]
	v_mfma_f32_16x16x32_bf16 v[92:95], v[148:151], v[210:213], v[92:95]
	v_mfma_f32_16x16x32_bf16 v[84:87], v[176:179], v[210:213], v[84:87]
	v_mfma_f32_16x16x32_bf16 v[64:67], v[176:179], v[218:221], v[64:67]
	v_mfma_f32_16x16x32_bf16 v[68:71], v[148:151], v[218:221], v[68:71]
	v_mfma_f32_16x16x32_bf16 v[132:135], v[152:155], v[198:201], v[132:135]
	v_mfma_f32_16x16x32_bf16 v[124:127], v[190:193], v[198:201], v[124:127]
	v_mfma_f32_16x16x32_bf16 v[104:107], v[190:193], v[206:209], v[104:107]
	v_mfma_f32_16x16x32_bf16 v[112:115], v[152:155], v[206:209], v[112:115]
	v_mfma_f32_16x16x32_bf16 v[92:95], v[152:155], v[214:217], v[92:95]
	v_mfma_f32_16x16x32_bf16 v[84:87], v[190:193], v[214:217], v[84:87]
	v_mfma_f32_16x16x32_bf16 v[64:67], v[190:193], v[222:225], v[64:67]
	v_mfma_f32_16x16x32_bf16 v[68:71], v[152:155], v[222:225], v[68:71]
	s_setprio 0
	s_barrier
	s_add_i32 s68, s96, s71
	v_lshl_add_u64 v[74:75], v[226:227], 0, s[28:29]
	s_mov_b32 m0, s68
	ds_read_b128 v[194:197], v187 offset:49152
	ds_read_b128 v[198:201], v187 offset:50176
	ds_read_b128 v[202:205], v187 offset:51200
	ds_read_b128 v[206:209], v187 offset:52224
	ds_read_b128 v[210:213], v187 offset:53248
	ds_read_b128 v[214:217], v187 offset:54272
	ds_read_b128 v[218:221], v187 offset:55296
	ds_read_b128 v[222:225], v187 offset:56320
	global_load_lds_dwordx4 v[74:75], off
	s_add_i32 m0, s68, 0x2000
	s_add_u32 s66, s66, 0x40080
	v_lshl_add_u64 v[74:75], v[228:229], 0, s[28:29]
	s_addc_u32 s67, s67, 0
	s_add_i32 s68, s97, s71
	global_load_lds_dwordx4 v[74:75], off
	v_lshl_add_u64 v[74:75], s[66:67], 0, v[162:163]
	s_mov_b32 m0, s68
	s_nop 0
	global_load_lds_dwordx4 v[74:75], off
	v_lshl_add_u64 v[74:75], s[66:67], 0, v[166:167]
	s_add_i32 m0, s68, 0x2000
	s_nop 0
	global_load_lds_dwordx4 v[74:75], off
	v_lshl_add_u64 v[74:75], v[230:231], 0, s[28:29]
	s_mov_b32 m0, s78
	s_nop 0
	global_load_lds_dwordx4 v[74:75], off
	v_lshl_add_u64 v[74:75], v[232:233], 0, s[28:29]
	s_mov_b32 m0, s79
	s_nop 0
	global_load_lds_dwordx4 v[74:75], off
	s_waitcnt vmcnt(8)
	s_waitcnt lgkmcnt(0)
	s_barrier
	s_setprio 1
	s_waitcnt lgkmcnt(0)
	v_mfma_f32_16x16x32_bf16 v[60:63], v[88:91], v[194:197], v[60:63]
	v_mfma_f32_16x16x32_bf16 v[56:59], v[128:131], v[194:197], v[56:59]
	v_mfma_f32_16x16x32_bf16 v[40:43], v[128:131], v[202:205], v[40:43]
	v_mfma_f32_16x16x32_bf16 v[44:47], v[88:91], v[202:205], v[44:47]
	v_mfma_f32_16x16x32_bf16 v[28:31], v[88:91], v[210:213], v[28:31]
	v_mfma_f32_16x16x32_bf16 v[24:27], v[128:131], v[210:213], v[24:27]
	v_mfma_f32_16x16x32_bf16 v[8:11], v[128:131], v[218:221], v[8:11]
	v_mfma_f32_16x16x32_bf16 v[12:15], v[88:91], v[218:221], v[12:15]
	v_mfma_f32_16x16x32_bf16 v[60:63], v[108:111], v[198:201], v[60:63]
	v_mfma_f32_16x16x32_bf16 v[56:59], v[144:147], v[198:201], v[56:59]
	v_mfma_f32_16x16x32_bf16 v[40:43], v[144:147], v[206:209], v[40:43]
	v_mfma_f32_16x16x32_bf16 v[44:47], v[108:111], v[206:209], v[44:47]
	v_mfma_f32_16x16x32_bf16 v[28:31], v[108:111], v[214:217], v[28:31]
	v_mfma_f32_16x16x32_bf16 v[24:27], v[144:147], v[214:217], v[24:27]
	v_mfma_f32_16x16x32_bf16 v[8:11], v[144:147], v[222:225], v[8:11]
	v_mfma_f32_16x16x32_bf16 v[12:15], v[108:111], v[222:225], v[12:15]
	s_setprio 0
	s_setprio 1
	v_mfma_f32_16x16x32_bf16 v[52:55], v[148:151], v[194:197], v[52:55]
	v_mfma_f32_16x16x32_bf16 v[48:51], v[176:179], v[194:197], v[48:51]
	v_mfma_f32_16x16x32_bf16 v[32:35], v[176:179], v[202:205], v[32:35]
	v_mfma_f32_16x16x32_bf16 v[36:39], v[148:151], v[202:205], v[36:39]
	v_mfma_f32_16x16x32_bf16 v[20:23], v[148:151], v[210:213], v[20:23]
	v_mfma_f32_16x16x32_bf16 v[16:19], v[176:179], v[210:213], v[16:19]
	v_mfma_f32_16x16x32_bf16 v[0:3], v[176:179], v[218:221], v[0:3]
	v_mfma_f32_16x16x32_bf16 v[4:7], v[148:151], v[218:221], v[4:7]
	v_mfma_f32_16x16x32_bf16 v[52:55], v[152:155], v[198:201], v[52:55]
	v_mfma_f32_16x16x32_bf16 v[48:51], v[190:193], v[198:201], v[48:51]
	v_mfma_f32_16x16x32_bf16 v[32:35], v[190:193], v[206:209], v[32:35]
	v_mfma_f32_16x16x32_bf16 v[36:39], v[152:155], v[206:209], v[36:39]
	v_mfma_f32_16x16x32_bf16 v[20:23], v[152:155], v[214:217], v[20:23]
	v_mfma_f32_16x16x32_bf16 v[16:19], v[190:193], v[214:217], v[16:19]
	v_mfma_f32_16x16x32_bf16 v[0:3], v[190:193], v[222:225], v[0:3]
	v_mfma_f32_16x16x32_bf16 v[4:7], v[152:155], v[222:225], v[4:7]
	s_setprio 0
	s_barrier
	s_add_i32 s95, s95, 2
	s_add_u32 s93, s93, 0x100
	s_addc_u32 s94, s94, 0
	s_add_u32 s14, s14, 0x100
	s_addc_u32 s15, s15, 0
	s_cmp_gt_u32 s95, 13
	s_cbranch_scc1 .LBB0_258

.LBB0_439:
	s_ashr_i32 s53, s52, 31
	s_lshl_b64 s[54:55], s[52:53], 20
	s_add_u32 s54, s35, s54
	s_addc_u32 s55, s66, s55
	s_and_b64 s[56:57], s[12:13], exec
	s_cselect_b32 s15, s55, s63
	s_cselect_b32 s53, s54, s62
	s_ashr_i32 s51, s50, 31
	s_lshl_b64 s[56:57], s[50:51], 20
	s_add_u32 s56, s67, s56
	s_addc_u32 s57, s68, s57
	s_and_b64 s[64:65], s[12:13], exec
	s_cselect_b32 s51, s57, s61
	s_cselect_b32 s59, s56, s60
	s_add_u32 s81, s60, 0x100
	s_addc_u32 s82, s61, 0
	s_add_u32 s60, s62, 0x80080
	s_addc_u32 s61, s63, 0
	s_mov_b32 s83, -2
	s_waitcnt lgkmcnt(0)
	ds_read_b128 v[128:131], v189
	ds_read_b128 v[132:135], v189 offset:1024
	ds_read_b128 v[136:139], v189 offset:2048
	ds_read_b128 v[140:143], v189 offset:3072
	ds_read_b128 v[144:147], v190
	ds_read_b128 v[148:151], v190 offset:1024
	ds_read_b128 v[172:175], v190 offset:2048
	ds_read_b128 v[176:179], v190 offset:3072
	s_add_u32 s62, s60, 0xfff80080
	s_addc_u32 s63, s61, -1
	s_cmp_eq_u32 s83, 28
	s_cselect_b32 s65, s15, s63
	s_cselect_b32 s64, s53, s62
	s_cselect_b32 s63, s51, s82
	s_cselect_b32 s62, s59, s81
	v_lshl_add_u64 v[222:223], s[60:61], 0, v[166:167]
	s_add_i32 m0, s70, 0xc000
	ds_read_b128 v[180:183], v191
	ds_read_b128 v[194:197], v191 offset:1024
	ds_read_b128 v[198:201], v191 offset:2048
	ds_read_b128 v[202:205], v191 offset:3072
	ds_read_b128 v[206:209], v191 offset:4096
	ds_read_b128 v[210:213], v191 offset:5120
	ds_read_b128 v[214:217], v191 offset:6144
	ds_read_b128 v[218:221], v191 offset:7168
	global_load_lds_dwordx4 v[222:223], off
	v_lshl_add_u64 v[222:223], s[60:61], 0, v[164:165]
	s_add_i32 m0, s70, 0xe000
	s_nop 0
	global_load_lds_dwordx4 v[222:223], off
	s_waitcnt vmcnt(8)
	s_waitcnt lgkmcnt(0)
	s_barrier
	s_setprio 1
	s_waitcnt lgkmcnt(0)
	v_mfma_f32_16x16x32_bf16 v[124:127], v[128:131], v[180:183], 0
	v_mfma_f32_16x16x32_bf16 v[120:123], v[136:139], v[180:183], 0
	v_mfma_f32_16x16x32_bf16 v[108:111], v[128:131], v[198:201], 0
	v_mfma_f32_16x16x32_bf16 v[104:107], v[136:139], v[198:201], 0
	v_mfma_f32_16x16x32_bf16 v[92:95], v[128:131], v[206:209], 0
	v_mfma_f32_16x16x32_bf16 v[88:91], v[136:139], v[206:209], 0
	v_mfma_f32_16x16x32_bf16 v[76:79], v[128:131], v[214:217], 0
	v_mfma_f32_16x16x32_bf16 v[72:75], v[136:139], v[214:217], 0
	v_mfma_f32_16x16x32_bf16 v[124:127], v[132:135], v[194:197], v[124:127]
	v_mfma_f32_16x16x32_bf16 v[120:123], v[140:143], v[194:197], v[120:123]
	v_mfma_f32_16x16x32_bf16 v[108:111], v[132:135], v[202:205], v[108:111]
	v_mfma_f32_16x16x32_bf16 v[104:107], v[140:143], v[202:205], v[104:107]
	v_mfma_f32_16x16x32_bf16 v[92:95], v[132:135], v[210:213], v[92:95]
	v_mfma_f32_16x16x32_bf16 v[88:91], v[140:143], v[210:213], v[88:91]
	v_mfma_f32_16x16x32_bf16 v[76:79], v[132:135], v[218:221], v[76:79]
	v_mfma_f32_16x16x32_bf16 v[72:75], v[140:143], v[218:221], v[72:75]
	s_setprio 0
	s_setprio 1
	v_mfma_f32_16x16x32_bf16 v[116:119], v[144:147], v[180:183], 0
	v_mfma_f32_16x16x32_bf16 v[112:115], v[172:175], v[180:183], 0
	v_mfma_f32_16x16x32_bf16 v[100:103], v[144:147], v[198:201], 0
	v_mfma_f32_16x16x32_bf16 v[96:99], v[172:175], v[198:201], 0
	v_mfma_f32_16x16x32_bf16 v[84:87], v[144:147], v[206:209], 0
	v_mfma_f32_16x16x32_bf16 v[80:83], v[172:175], v[206:209], 0
	v_mfma_f32_16x16x32_bf16 v[68:71], v[144:147], v[214:217], 0
	v_mfma_f32_16x16x32_bf16 v[64:67], v[172:175], v[214:217], 0
	v_mfma_f32_16x16x32_bf16 v[116:119], v[148:151], v[194:197], v[116:119]
	v_mfma_f32_16x16x32_bf16 v[112:115], v[176:179], v[194:197], v[112:115]
	v_mfma_f32_16x16x32_bf16 v[100:103], v[148:151], v[202:205], v[100:103]
	v_mfma_f32_16x16x32_bf16 v[96:99], v[176:179], v[202:205], v[96:99]
	v_mfma_f32_16x16x32_bf16 v[84:87], v[148:151], v[210:213], v[84:87]
	v_mfma_f32_16x16x32_bf16 v[80:83], v[176:179], v[210:213], v[80:83]
	v_mfma_f32_16x16x32_bf16 v[68:71], v[148:151], v[218:221], v[68:71]
	v_mfma_f32_16x16x32_bf16 v[64:67], v[176:179], v[218:221], v[64:67]
	s_setprio 0
	s_barrier
	s_add_i32 s84, s79, s69
	v_lshl_add_u64 v[222:223], s[62:63], 0, v[154:155]
	s_mov_b32 m0, s84
	ds_read_b128 v[180:183], v191 offset:16384
	ds_read_b128 v[194:197], v191 offset:17408
	ds_read_b128 v[198:201], v191 offset:18432
	ds_read_b128 v[202:205], v191 offset:19456
	ds_read_b128 v[206:209], v191 offset:20480
	ds_read_b128 v[210:213], v191 offset:21504
	ds_read_b128 v[214:217], v191 offset:22528
	ds_read_b128 v[218:221], v191 offset:23552
	global_load_lds_dwordx4 v[222:223], off
	s_add_i32 m0, s84, 0x2000
	s_add_u32 s84, s62, 0x80000
	v_lshl_add_u64 v[224:225], s[62:63], 0, v[162:163]
	s_addc_u32 s85, s63, 0
	s_add_i32 s86, s80, s69
	global_load_lds_dwordx4 v[224:225], off
	v_lshl_add_u64 v[226:227], s[84:85], 0, v[154:155]
	s_mov_b32 m0, s86
	v_lshl_add_u64 v[228:229], s[64:65], 0, v[160:161]
	global_load_lds_dwordx4 v[226:227], off
	v_lshl_add_u64 v[226:227], s[84:85], 0, v[162:163]
	s_add_i32 m0, s86, 0x2000
	s_nop 0
	global_load_lds_dwordx4 v[226:227], off
	v_lshl_add_u64 v[226:227], s[64:65], 0, v[152:153]
	s_mov_b32 m0, s70
	s_nop 0
	global_load_lds_dwordx4 v[226:227], off
	s_mov_b32 m0, s71
	s_nop 0
	global_load_lds_dwordx4 v[228:229], off
	s_waitcnt vmcnt(8)
	s_waitcnt lgkmcnt(0)
	s_barrier
	s_setprio 1
	s_waitcnt lgkmcnt(0)
	v_mfma_f32_16x16x32_bf16 v[60:63], v[128:131], v[180:183], 0
	v_mfma_f32_16x16x32_bf16 v[56:59], v[136:139], v[180:183], 0
	v_mfma_f32_16x16x32_bf16 v[44:47], v[128:131], v[198:201], 0
	v_mfma_f32_16x16x32_bf16 v[40:43], v[136:139], v[198:201], 0
	v_mfma_f32_16x16x32_bf16 v[28:31], v[128:131], v[206:209], 0
	v_mfma_f32_16x16x32_bf16 v[24:27], v[136:139], v[206:209], 0
	v_mfma_f32_16x16x32_bf16 v[12:15], v[128:131], v[214:217], 0
	v_mfma_f32_16x16x32_bf16 v[8:11], v[136:139], v[214:217], 0
	v_mfma_f32_16x16x32_bf16 v[60:63], v[132:135], v[194:197], v[60:63]
	v_mfma_f32_16x16x32_bf16 v[56:59], v[140:143], v[194:197], v[56:59]
	v_mfma_f32_16x16x32_bf16 v[44:47], v[132:135], v[202:205], v[44:47]
	v_mfma_f32_16x16x32_bf16 v[40:43], v[140:143], v[202:205], v[40:43]
	v_mfma_f32_16x16x32_bf16 v[28:31], v[132:135], v[210:213], v[28:31]
	v_mfma_f32_16x16x32_bf16 v[24:27], v[140:143], v[210:213], v[24:27]
	v_mfma_f32_16x16x32_bf16 v[12:15], v[132:135], v[218:221], v[12:15]
	v_mfma_f32_16x16x32_bf16 v[8:11], v[140:143], v[218:221], v[8:11]
	s_setprio 0
	s_setprio 1
	v_mfma_f32_16x16x32_bf16 v[52:55], v[144:147], v[180:183], 0
	v_mfma_f32_16x16x32_bf16 v[48:51], v[172:175], v[180:183], 0
	v_mfma_f32_16x16x32_bf16 v[36:39], v[144:147], v[198:201], 0
	v_mfma_f32_16x16x32_bf16 v[32:35], v[172:175], v[198:201], 0
	v_mfma_f32_16x16x32_bf16 v[20:23], v[144:147], v[206:209], 0
	v_mfma_f32_16x16x32_bf16 v[16:19], v[172:175], v[206:209], 0
	v_mfma_f32_16x16x32_bf16 v[4:7], v[144:147], v[214:217], 0
	v_mfma_f32_16x16x32_bf16 v[0:3], v[172:175], v[214:217], 0
	v_mfma_f32_16x16x32_bf16 v[52:55], v[148:151], v[194:197], v[52:55]
	v_mfma_f32_16x16x32_bf16 v[48:51], v[176:179], v[194:197], v[48:51]
	v_mfma_f32_16x16x32_bf16 v[36:39], v[148:151], v[202:205], v[36:39]
	v_mfma_f32_16x16x32_bf16 v[32:35], v[176:179], v[202:205], v[32:35]
	v_mfma_f32_16x16x32_bf16 v[20:23], v[148:151], v[210:213], v[20:23]
	v_mfma_f32_16x16x32_bf16 v[16:19], v[176:179], v[210:213], v[16:19]
	v_mfma_f32_16x16x32_bf16 v[4:7], v[148:151], v[218:221], v[4:7]
	v_mfma_f32_16x16x32_bf16 v[0:3], v[176:179], v[218:221], v[0:3]
	s_setprio 0
	s_barrier
	s_add_i32 s84, 0, 0x18000
	s_add_i32 s85, 0, 0x1c000
	v_add_u32_e32 v140, s84, v186
	v_add_u32_e32 v176, s85, v186
	ds_read_b128 v[128:131], v140
	ds_read_b128 v[132:135], v140 offset:1024
	ds_read_b128 v[136:139], v140 offset:2048
	ds_read_b128 v[140:143], v140 offset:3072
	ds_read_b128 v[144:147], v176
	ds_read_b128 v[148:151], v176 offset:1024
	ds_read_b128 v[172:175], v176 offset:2048
	ds_read_b128 v[176:179], v176 offset:3072
	s_add_u32 s64, s64, 0x80000
	s_addc_u32 s65, s65, 0
	s_mov_b32 m0, s72
	v_lshl_add_u64 v[230:231], s[64:65], 0, v[152:153]
	ds_read_b128 v[180:183], v191 offset:32768
	ds_read_b128 v[194:197], v191 offset:33792
	ds_read_b128 v[198:201], v191 offset:34816
	ds_read_b128 v[202:205], v191 offset:35840
	ds_read_b128 v[206:209], v191 offset:36864
	ds_read_b128 v[210:213], v191 offset:37888
	ds_read_b128 v[214:217], v191 offset:38912
	ds_read_b128 v[218:221], v191 offset:39936
	global_load_lds_dwordx4 v[230:231], off
	v_lshl_add_u64 v[230:231], s[64:65], 0, v[160:161]
	s_mov_b32 m0, s73
	s_nop 0
	global_load_lds_dwordx4 v[230:231], off
	s_waitcnt vmcnt(8)
	s_waitcnt lgkmcnt(0)
	s_barrier
	s_setprio 1
	s_waitcnt lgkmcnt(0)
	v_mfma_f32_16x16x32_bf16 v[124:127], v[128:131], v[180:183], v[124:127]
	v_mfma_f32_16x16x32_bf16 v[120:123], v[136:139], v[180:183], v[120:123]
	v_mfma_f32_16x16x32_bf16 v[104:107], v[136:139], v[198:201], v[104:107]
	v_mfma_f32_16x16x32_bf16 v[108:111], v[128:131], v[198:201], v[108:111]
	v_mfma_f32_16x16x32_bf16 v[92:95], v[128:131], v[206:209], v[92:95]
	v_mfma_f32_16x16x32_bf16 v[88:91], v[136:139], v[206:209], v[88:91]
	v_mfma_f32_16x16x32_bf16 v[72:75], v[136:139], v[214:217], v[72:75]
	v_mfma_f32_16x16x32_bf16 v[76:79], v[128:131], v[214:217], v[76:79]
	v_mfma_f32_16x16x32_bf16 v[124:127], v[132:135], v[194:197], v[124:127]
	v_mfma_f32_16x16x32_bf16 v[120:123], v[140:143], v[194:197], v[120:123]
	v_mfma_f32_16x16x32_bf16 v[104:107], v[140:143], v[202:205], v[104:107]
	v_mfma_f32_16x16x32_bf16 v[108:111], v[132:135], v[202:205], v[108:111]
	v_mfma_f32_16x16x32_bf16 v[92:95], v[132:135], v[210:213], v[92:95]
	v_mfma_f32_16x16x32_bf16 v[88:91], v[140:143], v[210:213], v[88:91]
	v_mfma_f32_16x16x32_bf16 v[72:75], v[140:143], v[218:221], v[72:75]
	v_mfma_f32_16x16x32_bf16 v[76:79], v[132:135], v[218:221], v[76:79]
	s_setprio 0
	s_setprio 1
	v_mfma_f32_16x16x32_bf16 v[116:119], v[144:147], v[180:183], v[116:119]
	v_mfma_f32_16x16x32_bf16 v[112:115], v[172:175], v[180:183], v[112:115]
	v_mfma_f32_16x16x32_bf16 v[96:99], v[172:175], v[198:201], v[96:99]
	v_mfma_f32_16x16x32_bf16 v[100:103], v[144:147], v[198:201], v[100:103]
	v_mfma_f32_16x16x32_bf16 v[84:87], v[144:147], v[206:209], v[84:87]
	v_mfma_f32_16x16x32_bf16 v[80:83], v[172:175], v[206:209], v[80:83]
	v_mfma_f32_16x16x32_bf16 v[64:67], v[172:175], v[214:217], v[64:67]
	v_mfma_f32_16x16x32_bf16 v[68:71], v[144:147], v[214:217], v[68:71]
	v_mfma_f32_16x16x32_bf16 v[116:119], v[148:151], v[194:197], v[116:119]
	v_mfma_f32_16x16x32_bf16 v[112:115], v[176:179], v[194:197], v[112:115]
	v_mfma_f32_16x16x32_bf16 v[96:99], v[176:179], v[202:205], v[96:99]
	v_mfma_f32_16x16x32_bf16 v[100:103], v[148:151], v[202:205], v[100:103]
	v_mfma_f32_16x16x32_bf16 v[84:87], v[148:151], v[210:213], v[84:87]
	v_mfma_f32_16x16x32_bf16 v[80:83], v[176:179], v[210:213], v[80:83]
	v_mfma_f32_16x16x32_bf16 v[64:67], v[176:179], v[218:221], v[64:67]
	v_mfma_f32_16x16x32_bf16 v[68:71], v[148:151], v[218:221], v[68:71]
	s_setprio 0
	s_barrier
	s_add_i32 s64, s84, s69
	v_lshl_add_u64 v[222:223], v[222:223], 0, s[26:27]
	s_mov_b32 m0, s64
	ds_read_b128 v[180:183], v191 offset:49152
	ds_read_b128 v[194:197], v191 offset:50176
	ds_read_b128 v[198:201], v191 offset:51200
	ds_read_b128 v[202:205], v191 offset:52224
	ds_read_b128 v[206:209], v191 offset:53248
	ds_read_b128 v[210:213], v191 offset:54272
	ds_read_b128 v[214:217], v191 offset:55296
	ds_read_b128 v[218:221], v191 offset:56320
	global_load_lds_dwordx4 v[222:223], off
	s_add_i32 m0, s64, 0x2000
	s_add_u32 s62, s62, 0x80080
	v_lshl_add_u64 v[222:223], v[224:225], 0, s[26:27]
	s_addc_u32 s63, s63, 0
	s_add_i32 s64, s85, s69
	global_load_lds_dwordx4 v[222:223], off
	v_lshl_add_u64 v[222:223], s[62:63], 0, v[154:155]
	s_mov_b32 m0, s64
	s_nop 0
	global_load_lds_dwordx4 v[222:223], off
	v_lshl_add_u64 v[222:223], s[62:63], 0, v[162:163]
	s_add_i32 m0, s64, 0x2000
	s_nop 0
	global_load_lds_dwordx4 v[222:223], off
	v_lshl_add_u64 v[222:223], v[226:227], 0, s[26:27]
	s_mov_b32 m0, s3
	s_nop 0
	global_load_lds_dwordx4 v[222:223], off
	v_lshl_add_u64 v[222:223], v[228:229], 0, s[26:27]
	s_mov_b32 m0, s75
	s_nop 0
	global_load_lds_dwordx4 v[222:223], off
	s_waitcnt vmcnt(8)
	s_waitcnt lgkmcnt(0)
	s_barrier
	s_setprio 1
	s_waitcnt lgkmcnt(0)
	v_mfma_f32_16x16x32_bf16 v[60:63], v[128:131], v[180:183], v[60:63]
	v_mfma_f32_16x16x32_bf16 v[56:59], v[136:139], v[180:183], v[56:59]
	v_mfma_f32_16x16x32_bf16 v[40:43], v[136:139], v[198:201], v[40:43]
	v_mfma_f32_16x16x32_bf16 v[44:47], v[128:131], v[198:201], v[44:47]
	v_mfma_f32_16x16x32_bf16 v[28:31], v[128:131], v[206:209], v[28:31]
	v_mfma_f32_16x16x32_bf16 v[24:27], v[136:139], v[206:209], v[24:27]
	v_mfma_f32_16x16x32_bf16 v[8:11], v[136:139], v[214:217], v[8:11]
	v_mfma_f32_16x16x32_bf16 v[12:15], v[128:131], v[214:217], v[12:15]
	v_mfma_f32_16x16x32_bf16 v[60:63], v[132:135], v[194:197], v[60:63]
	v_mfma_f32_16x16x32_bf16 v[56:59], v[140:143], v[194:197], v[56:59]
	v_mfma_f32_16x16x32_bf16 v[40:43], v[140:143], v[202:205], v[40:43]
	v_mfma_f32_16x16x32_bf16 v[44:47], v[132:135], v[202:205], v[44:47]
	v_mfma_f32_16x16x32_bf16 v[28:31], v[132:135], v[210:213], v[28:31]
	v_mfma_f32_16x16x32_bf16 v[24:27], v[140:143], v[210:213], v[24:27]
	v_mfma_f32_16x16x32_bf16 v[8:11], v[140:143], v[218:221], v[8:11]
	v_mfma_f32_16x16x32_bf16 v[12:15], v[132:135], v[218:221], v[12:15]
	s_setprio 0
	s_setprio 1
	v_mfma_f32_16x16x32_bf16 v[52:55], v[144:147], v[180:183], v[52:55]
	v_mfma_f32_16x16x32_bf16 v[48:51], v[172:175], v[180:183], v[48:51]
	v_mfma_f32_16x16x32_bf16 v[32:35], v[172:175], v[198:201], v[32:35]
	v_mfma_f32_16x16x32_bf16 v[36:39], v[144:147], v[198:201], v[36:39]
	v_mfma_f32_16x16x32_bf16 v[20:23], v[144:147], v[206:209], v[20:23]
	v_mfma_f32_16x16x32_bf16 v[16:19], v[172:175], v[206:209], v[16:19]
	v_mfma_f32_16x16x32_bf16 v[0:3], v[172:175], v[214:217], v[0:3]
	v_mfma_f32_16x16x32_bf16 v[4:7], v[144:147], v[214:217], v[4:7]
	v_mfma_f32_16x16x32_bf16 v[52:55], v[148:151], v[194:197], v[52:55]
	v_mfma_f32_16x16x32_bf16 v[48:51], v[176:179], v[194:197], v[48:51]
	v_mfma_f32_16x16x32_bf16 v[32:35], v[176:179], v[202:205], v[32:35]
	v_mfma_f32_16x16x32_bf16 v[36:39], v[148:151], v[202:205], v[36:39]
	v_mfma_f32_16x16x32_bf16 v[20:23], v[148:151], v[210:213], v[20:23]
	v_mfma_f32_16x16x32_bf16 v[16:19], v[176:179], v[210:213], v[16:19]
	v_mfma_f32_16x16x32_bf16 v[0:3], v[176:179], v[218:221], v[0:3]
	v_mfma_f32_16x16x32_bf16 v[4:7], v[148:151], v[218:221], v[4:7]
	s_setprio 0
	s_barrier
	s_add_i32 s83, s83, 2
	s_add_u32 s81, s81, 0x100
	s_addc_u32 s82, s82, 0
	s_add_u32 s60, s60, 0x100
	s_addc_u32 s61, s61, 0
	s_cmp_gt_u32 s83, 29
.LBB0_440:
	ds_read_b128 v[128:131], v189
	ds_read_b128 v[132:135], v189 offset:1024
	ds_read_b128 v[136:139], v189 offset:2048
	ds_read_b128 v[140:143], v189 offset:3072
	ds_read_b128 v[144:147], v190
	ds_read_b128 v[148:151], v190 offset:1024
	ds_read_b128 v[172:175], v190 offset:2048
	ds_read_b128 v[176:179], v190 offset:3072
	s_add_u32 s62, s60, 0xfff80080
	s_addc_u32 s63, s61, -1
	s_cmp_eq_u32 s83, 28
	s_cselect_b32 s65, s15, s63
	s_cselect_b32 s64, s53, s62
	s_cselect_b32 s63, s51, s82
	s_cselect_b32 s62, s59, s81
	v_lshl_add_u64 v[222:223], s[60:61], 0, v[166:167]
	s_add_i32 m0, s70, 0xc000
	ds_read_b128 v[180:183], v191
	ds_read_b128 v[194:197], v191 offset:1024
	ds_read_b128 v[198:201], v191 offset:2048
	ds_read_b128 v[202:205], v191 offset:3072
	ds_read_b128 v[206:209], v191 offset:4096
	ds_read_b128 v[210:213], v191 offset:5120
	ds_read_b128 v[214:217], v191 offset:6144
	ds_read_b128 v[218:221], v191 offset:7168
	global_load_lds_dwordx4 v[222:223], off
	v_lshl_add_u64 v[222:223], s[60:61], 0, v[164:165]
	s_add_i32 m0, s70, 0xe000
	s_nop 0
	global_load_lds_dwordx4 v[222:223], off
	s_waitcnt vmcnt(8)
	s_waitcnt lgkmcnt(0)
	s_barrier
	s_setprio 1
	s_waitcnt lgkmcnt(0)
	v_mfma_f32_16x16x32_bf16 v[124:127], v[128:131], v[180:183], v[124:127]
	v_mfma_f32_16x16x32_bf16 v[120:123], v[136:139], v[180:183], v[120:123]
	v_mfma_f32_16x16x32_bf16 v[104:107], v[136:139], v[198:201], v[104:107]
	v_mfma_f32_16x16x32_bf16 v[108:111], v[128:131], v[198:201], v[108:111]
	v_mfma_f32_16x16x32_bf16 v[92:95], v[128:131], v[206:209], v[92:95]
	v_mfma_f32_16x16x32_bf16 v[88:91], v[136:139], v[206:209], v[88:91]
	v_mfma_f32_16x16x32_bf16 v[72:75], v[136:139], v[214:217], v[72:75]
	v_mfma_f32_16x16x32_bf16 v[76:79], v[128:131], v[214:217], v[76:79]
	v_mfma_f32_16x16x32_bf16 v[124:127], v[132:135], v[194:197], v[124:127]
	v_mfma_f32_16x16x32_bf16 v[120:123], v[140:143], v[194:197], v[120:123]
	v_mfma_f32_16x16x32_bf16 v[104:107], v[140:143], v[202:205], v[104:107]
	v_mfma_f32_16x16x32_bf16 v[108:111], v[132:135], v[202:205], v[108:111]
	v_mfma_f32_16x16x32_bf16 v[92:95], v[132:135], v[210:213], v[92:95]
	v_mfma_f32_16x16x32_bf16 v[88:91], v[140:143], v[210:213], v[88:91]
	v_mfma_f32_16x16x32_bf16 v[72:75], v[140:143], v[218:221], v[72:75]
	v_mfma_f32_16x16x32_bf16 v[76:79], v[132:135], v[218:221], v[76:79]
	s_setprio 0
	s_setprio 1
	v_mfma_f32_16x16x32_bf16 v[116:119], v[144:147], v[180:183], v[116:119]
	v_mfma_f32_16x16x32_bf16 v[112:115], v[172:175], v[180:183], v[112:115]
	v_mfma_f32_16x16x32_bf16 v[96:99], v[172:175], v[198:201], v[96:99]
	v_mfma_f32_16x16x32_bf16 v[100:103], v[144:147], v[198:201], v[100:103]
	v_mfma_f32_16x16x32_bf16 v[84:87], v[144:147], v[206:209], v[84:87]
	v_mfma_f32_16x16x32_bf16 v[80:83], v[172:175], v[206:209], v[80:83]
	v_mfma_f32_16x16x32_bf16 v[64:67], v[172:175], v[214:217], v[64:67]
	v_mfma_f32_16x16x32_bf16 v[68:71], v[144:147], v[214:217], v[68:71]
	v_mfma_f32_16x16x32_bf16 v[116:119], v[148:151], v[194:197], v[116:119]
	v_mfma_f32_16x16x32_bf16 v[112:115], v[176:179], v[194:197], v[112:115]
	v_mfma_f32_16x16x32_bf16 v[96:99], v[176:179], v[202:205], v[96:99]
	v_mfma_f32_16x16x32_bf16 v[100:103], v[148:151], v[202:205], v[100:103]
	v_mfma_f32_16x16x32_bf16 v[84:87], v[148:151], v[210:213], v[84:87]
	v_mfma_f32_16x16x32_bf16 v[80:83], v[176:179], v[210:213], v[80:83]
	v_mfma_f32_16x16x32_bf16 v[64:67], v[176:179], v[218:221], v[64:67]
	v_mfma_f32_16x16x32_bf16 v[68:71], v[148:151], v[218:221], v[68:71]
	s_setprio 0
	s_barrier
	s_add_i32 s84, s79, s69
	v_lshl_add_u64 v[222:223], s[62:63], 0, v[154:155]
	s_mov_b32 m0, s84
	ds_read_b128 v[180:183], v191 offset:16384
	ds_read_b128 v[194:197], v191 offset:17408
	ds_read_b128 v[198:201], v191 offset:18432
	ds_read_b128 v[202:205], v191 offset:19456
	ds_read_b128 v[206:209], v191 offset:20480
	ds_read_b128 v[210:213], v191 offset:21504
	ds_read_b128 v[214:217], v191 offset:22528
	ds_read_b128 v[218:221], v191 offset:23552
	global_load_lds_dwordx4 v[222:223], off
	s_add_i32 m0, s84, 0x2000
	s_add_u32 s84, s62, 0x80000
	v_lshl_add_u64 v[224:225], s[62:63], 0, v[162:163]
	s_addc_u32 s85, s63, 0
	s_add_i32 s86, s80, s69
	global_load_lds_dwordx4 v[224:225], off
	v_lshl_add_u64 v[226:227], s[84:85], 0, v[154:155]
	s_mov_b32 m0, s86
	v_lshl_add_u64 v[228:229], s[64:65], 0, v[160:161]
	global_load_lds_dwordx4 v[226:227], off
	v_lshl_add_u64 v[226:227], s[84:85], 0, v[162:163]
	s_add_i32 m0, s86, 0x2000
	s_nop 0
	global_load_lds_dwordx4 v[226:227], off
	v_lshl_add_u64 v[226:227], s[64:65], 0, v[152:153]
	s_mov_b32 m0, s70
	s_nop 0
	global_load_lds_dwordx4 v[226:227], off
	s_mov_b32 m0, s71
	s_nop 0
	global_load_lds_dwordx4 v[228:229], off
	s_waitcnt vmcnt(8)
	s_waitcnt lgkmcnt(0)
	s_barrier
	s_setprio 1
	s_waitcnt lgkmcnt(0)
	v_mfma_f32_16x16x32_bf16 v[60:63], v[128:131], v[180:183], v[60:63]
	v_mfma_f32_16x16x32_bf16 v[56:59], v[136:139], v[180:183], v[56:59]
	v_mfma_f32_16x16x32_bf16 v[40:43], v[136:139], v[198:201], v[40:43]
	v_mfma_f32_16x16x32_bf16 v[44:47], v[128:131], v[198:201], v[44:47]
	v_mfma_f32_16x16x32_bf16 v[28:31], v[128:131], v[206:209], v[28:31]
	v_mfma_f32_16x16x32_bf16 v[24:27], v[136:139], v[206:209], v[24:27]
	v_mfma_f32_16x16x32_bf16 v[8:11], v[136:139], v[214:217], v[8:11]
	v_mfma_f32_16x16x32_bf16 v[12:15], v[128:131], v[214:217], v[12:15]
	v_mfma_f32_16x16x32_bf16 v[60:63], v[132:135], v[194:197], v[60:63]
	v_mfma_f32_16x16x32_bf16 v[56:59], v[140:143], v[194:197], v[56:59]
	v_mfma_f32_16x16x32_bf16 v[40:43], v[140:143], v[202:205], v[40:43]
	v_mfma_f32_16x16x32_bf16 v[44:47], v[132:135], v[202:205], v[44:47]
	v_mfma_f32_16x16x32_bf16 v[28:31], v[132:135], v[210:213], v[28:31]
	v_mfma_f32_16x16x32_bf16 v[24:27], v[140:143], v[210:213], v[24:27]
	v_mfma_f32_16x16x32_bf16 v[8:11], v[140:143], v[218:221], v[8:11]
	v_mfma_f32_16x16x32_bf16 v[12:15], v[132:135], v[218:221], v[12:15]
	s_setprio 0
	s_setprio 1
	v_mfma_f32_16x16x32_bf16 v[52:55], v[144:147], v[180:183], v[52:55]
	v_mfma_f32_16x16x32_bf16 v[48:51], v[172:175], v[180:183], v[48:51]
	v_mfma_f32_16x16x32_bf16 v[32:35], v[172:175], v[198:201], v[32:35]
	v_mfma_f32_16x16x32_bf16 v[36:39], v[144:147], v[198:201], v[36:39]
	v_mfma_f32_16x16x32_bf16 v[20:23], v[144:147], v[206:209], v[20:23]
	v_mfma_f32_16x16x32_bf16 v[16:19], v[172:175], v[206:209], v[16:19]
	v_mfma_f32_16x16x32_bf16 v[0:3], v[172:175], v[214:217], v[0:3]
	v_mfma_f32_16x16x32_bf16 v[4:7], v[144:147], v[214:217], v[4:7]
	v_mfma_f32_16x16x32_bf16 v[52:55], v[148:151], v[194:197], v[52:55]
	v_mfma_f32_16x16x32_bf16 v[48:51], v[176:179], v[194:197], v[48:51]
	v_mfma_f32_16x16x32_bf16 v[32:35], v[176:179], v[202:205], v[32:35]
	v_mfma_f32_16x16x32_bf16 v[36:39], v[148:151], v[202:205], v[36:39]
	v_mfma_f32_16x16x32_bf16 v[20:23], v[148:151], v[210:213], v[20:23]
	v_mfma_f32_16x16x32_bf16 v[16:19], v[176:179], v[210:213], v[16:19]
	v_mfma_f32_16x16x32_bf16 v[0:3], v[176:179], v[218:221], v[0:3]
	v_mfma_f32_16x16x32_bf16 v[4:7], v[148:151], v[218:221], v[4:7]
	s_setprio 0
	s_barrier
	s_add_i32 s84, 0, 0x18000
	s_add_i32 s85, 0, 0x1c000
	v_add_u32_e32 v140, s84, v186
	v_add_u32_e32 v176, s85, v186
	ds_read_b128 v[128:131], v140
	ds_read_b128 v[132:135], v140 offset:1024
	ds_read_b128 v[136:139], v140 offset:2048
	ds_read_b128 v[140:143], v140 offset:3072
	ds_read_b128 v[144:147], v176
	ds_read_b128 v[148:151], v176 offset:1024
	ds_read_b128 v[172:175], v176 offset:2048
	ds_read_b128 v[176:179], v176 offset:3072
	s_add_u32 s64, s64, 0x80000
	s_addc_u32 s65, s65, 0
	s_mov_b32 m0, s72
	v_lshl_add_u64 v[230:231], s[64:65], 0, v[152:153]
	ds_read_b128 v[180:183], v191 offset:32768
	ds_read_b128 v[194:197], v191 offset:33792
	ds_read_b128 v[198:201], v191 offset:34816
	ds_read_b128 v[202:205], v191 offset:35840
	ds_read_b128 v[206:209], v191 offset:36864
	ds_read_b128 v[210:213], v191 offset:37888
	ds_read_b128 v[214:217], v191 offset:38912
	ds_read_b128 v[218:221], v191 offset:39936
	global_load_lds_dwordx4 v[230:231], off
	v_lshl_add_u64 v[230:231], s[64:65], 0, v[160:161]
	s_mov_b32 m0, s73
	s_nop 0
	global_load_lds_dwordx4 v[230:231], off
	s_waitcnt vmcnt(8)
	s_waitcnt lgkmcnt(0)
	s_barrier
	s_setprio 1
	s_waitcnt lgkmcnt(0)
	v_mfma_f32_16x16x32_bf16 v[124:127], v[128:131], v[180:183], v[124:127]
	v_mfma_f32_16x16x32_bf16 v[120:123], v[136:139], v[180:183], v[120:123]
	v_mfma_f32_16x16x32_bf16 v[104:107], v[136:139], v[198:201], v[104:107]
	v_mfma_f32_16x16x32_bf16 v[108:111], v[128:131], v[198:201], v[108:111]
	v_mfma_f32_16x16x32_bf16 v[92:95], v[128:131], v[206:209], v[92:95]
	v_mfma_f32_16x16x32_bf16 v[88:91], v[136:139], v[206:209], v[88:91]
	v_mfma_f32_16x16x32_bf16 v[72:75], v[136:139], v[214:217], v[72:75]
	v_mfma_f32_16x16x32_bf16 v[76:79], v[128:131], v[214:217], v[76:79]
	v_mfma_f32_16x16x32_bf16 v[124:127], v[132:135], v[194:197], v[124:127]
	v_mfma_f32_16x16x32_bf16 v[120:123], v[140:143], v[194:197], v[120:123]
	v_mfma_f32_16x16x32_bf16 v[104:107], v[140:143], v[202:205], v[104:107]
	v_mfma_f32_16x16x32_bf16 v[108:111], v[132:135], v[202:205], v[108:111]
	v_mfma_f32_16x16x32_bf16 v[92:95], v[132:135], v[210:213], v[92:95]
	v_mfma_f32_16x16x32_bf16 v[88:91], v[140:143], v[210:213], v[88:91]
	v_mfma_f32_16x16x32_bf16 v[72:75], v[140:143], v[218:221], v[72:75]
	v_mfma_f32_16x16x32_bf16 v[76:79], v[132:135], v[218:221], v[76:79]
	s_setprio 0
	s_setprio 1
	v_mfma_f32_16x16x32_bf16 v[116:119], v[144:147], v[180:183], v[116:119]
	v_mfma_f32_16x16x32_bf16 v[112:115], v[172:175], v[180:183], v[112:115]
	v_mfma_f32_16x16x32_bf16 v[96:99], v[172:175], v[198:201], v[96:99]
	v_mfma_f32_16x16x32_bf16 v[100:103], v[144:147], v[198:201], v[100:103]
	v_mfma_f32_16x16x32_bf16 v[84:87], v[144:147], v[206:209], v[84:87]
	v_mfma_f32_16x16x32_bf16 v[80:83], v[172:175], v[206:209], v[80:83]
	v_mfma_f32_16x16x32_bf16 v[64:67], v[172:175], v[214:217], v[64:67]
	v_mfma_f32_16x16x32_bf16 v[68:71], v[144:147], v[214:217], v[68:71]
	v_mfma_f32_16x16x32_bf16 v[116:119], v[148:151], v[194:197], v[116:119]
	v_mfma_f32_16x16x32_bf16 v[112:115], v[176:179], v[194:197], v[112:115]
	v_mfma_f32_16x16x32_bf16 v[96:99], v[176:179], v[202:205], v[96:99]
	v_mfma_f32_16x16x32_bf16 v[100:103], v[148:151], v[202:205], v[100:103]
	v_mfma_f32_16x16x32_bf16 v[84:87], v[148:151], v[210:213], v[84:87]
	v_mfma_f32_16x16x32_bf16 v[80:83], v[176:179], v[210:213], v[80:83]
	v_mfma_f32_16x16x32_bf16 v[64:67], v[176:179], v[218:221], v[64:67]
	v_mfma_f32_16x16x32_bf16 v[68:71], v[148:151], v[218:221], v[68:71]
	s_setprio 0
	s_barrier
	s_add_i32 s64, s84, s69
	v_lshl_add_u64 v[222:223], v[222:223], 0, s[26:27]
	s_mov_b32 m0, s64
	ds_read_b128 v[180:183], v191 offset:49152
	ds_read_b128 v[194:197], v191 offset:50176
	ds_read_b128 v[198:201], v191 offset:51200
	ds_read_b128 v[202:205], v191 offset:52224
	ds_read_b128 v[206:209], v191 offset:53248
	ds_read_b128 v[210:213], v191 offset:54272
	ds_read_b128 v[214:217], v191 offset:55296
	ds_read_b128 v[218:221], v191 offset:56320
	global_load_lds_dwordx4 v[222:223], off
	s_add_i32 m0, s64, 0x2000
	s_add_u32 s62, s62, 0x80080
	v_lshl_add_u64 v[222:223], v[224:225], 0, s[26:27]
	s_addc_u32 s63, s63, 0
	s_add_i32 s64, s85, s69
	global_load_lds_dwordx4 v[222:223], off
	v_lshl_add_u64 v[222:223], s[62:63], 0, v[154:155]
	s_mov_b32 m0, s64
	s_nop 0
	global_load_lds_dwordx4 v[222:223], off
	v_lshl_add_u64 v[222:223], s[62:63], 0, v[162:163]
	s_add_i32 m0, s64, 0x2000
	s_nop 0
	global_load_lds_dwordx4 v[222:223], off
	v_lshl_add_u64 v[222:223], v[226:227], 0, s[26:27]
	s_mov_b32 m0, s3
	s_nop 0
	global_load_lds_dwordx4 v[222:223], off
	v_lshl_add_u64 v[222:223], v[228:229], 0, s[26:27]
	s_mov_b32 m0, s75
	s_nop 0
	global_load_lds_dwordx4 v[222:223], off
	s_waitcnt vmcnt(8)
	s_waitcnt lgkmcnt(0)
	s_barrier
	s_setprio 1
	s_waitcnt lgkmcnt(0)
	v_mfma_f32_16x16x32_bf16 v[60:63], v[128:131], v[180:183], v[60:63]
	v_mfma_f32_16x16x32_bf16 v[56:59], v[136:139], v[180:183], v[56:59]
	v_mfma_f32_16x16x32_bf16 v[40:43], v[136:139], v[198:201], v[40:43]
	v_mfma_f32_16x16x32_bf16 v[44:47], v[128:131], v[198:201], v[44:47]
	v_mfma_f32_16x16x32_bf16 v[28:31], v[128:131], v[206:209], v[28:31]
	v_mfma_f32_16x16x32_bf16 v[24:27], v[136:139], v[206:209], v[24:27]
	v_mfma_f32_16x16x32_bf16 v[8:11], v[136:139], v[214:217], v[8:11]
	v_mfma_f32_16x16x32_bf16 v[12:15], v[128:131], v[214:217], v[12:15]
	v_mfma_f32_16x16x32_bf16 v[60:63], v[132:135], v[194:197], v[60:63]
	v_mfma_f32_16x16x32_bf16 v[56:59], v[140:143], v[194:197], v[56:59]
	v_mfma_f32_16x16x32_bf16 v[40:43], v[140:143], v[202:205], v[40:43]
	v_mfma_f32_16x16x32_bf16 v[44:47], v[132:135], v[202:205], v[44:47]
	v_mfma_f32_16x16x32_bf16 v[28:31], v[132:135], v[210:213], v[28:31]
	v_mfma_f32_16x16x32_bf16 v[24:27], v[140:143], v[210:213], v[24:27]
	v_mfma_f32_16x16x32_bf16 v[8:11], v[140:143], v[218:221], v[8:11]
	v_mfma_f32_16x16x32_bf16 v[12:15], v[132:135], v[218:221], v[12:15]
	s_setprio 0
	s_setprio 1
	v_mfma_f32_16x16x32_bf16 v[52:55], v[144:147], v[180:183], v[52:55]
	v_mfma_f32_16x16x32_bf16 v[48:51], v[172:175], v[180:183], v[48:51]
	v_mfma_f32_16x16x32_bf16 v[32:35], v[172:175], v[198:201], v[32:35]
	v_mfma_f32_16x16x32_bf16 v[36:39], v[144:147], v[198:201], v[36:39]
	v_mfma_f32_16x16x32_bf16 v[20:23], v[144:147], v[206:209], v[20:23]
	v_mfma_f32_16x16x32_bf16 v[16:19], v[172:175], v[206:209], v[16:19]
	v_mfma_f32_16x16x32_bf16 v[0:3], v[172:175], v[214:217], v[0:3]
	v_mfma_f32_16x16x32_bf16 v[4:7], v[144:147], v[214:217], v[4:7]
	v_mfma_f32_16x16x32_bf16 v[52:55], v[148:151], v[194:197], v[52:55]
	v_mfma_f32_16x16x32_bf16 v[48:51], v[176:179], v[194:197], v[48:51]
	v_mfma_f32_16x16x32_bf16 v[32:35], v[176:179], v[202:205], v[32:35]
	v_mfma_f32_16x16x32_bf16 v[36:39], v[148:151], v[202:205], v[36:39]
	v_mfma_f32_16x16x32_bf16 v[20:23], v[148:151], v[210:213], v[20:23]
	v_mfma_f32_16x16x32_bf16 v[16:19], v[176:179], v[210:213], v[16:19]
	v_mfma_f32_16x16x32_bf16 v[0:3], v[176:179], v[218:221], v[0:3]
	v_mfma_f32_16x16x32_bf16 v[4:7], v[148:151], v[218:221], v[4:7]
	s_setprio 0
	s_barrier
	s_add_i32 s83, s83, 2
	s_add_u32 s81, s81, 0x100
	s_addc_u32 s82, s82, 0
	s_add_u32 s60, s60, 0x100
	s_addc_u32 s61, s61, 0
	s_cmp_gt_u32 s83, 29
	s_cbranch_scc0 .LBB0_440
	s_and_b64 vcc, exec, s[28:29]
	s_cbranch_vccz .LBB0_443
	s_barrier

.LBB0_525:
	s_ashr_i32 s29, s28, 31
	s_lshl_b64 s[30:31], s[28:29], 19
	s_add_u32 s30, s3, s30
	s_addc_u32 s31, s35, s31
	s_and_b64 s[44:45], s[10:11], exec
	s_cselect_b32 s29, s31, s51
	s_cselect_b32 s70, s30, s50
	s_ashr_i32 s27, s26, 31
	s_lshl_b64 s[44:45], s[26:27], 19
	s_add_u32 s44, s52, s44
	s_addc_u32 s45, s53, s45
	s_and_b64 s[72:73], s[10:11], exec
	s_cselect_b32 s71, s45, s49
	s_cselect_b32 s72, s44, s48
	s_lshl_b32 s27, s46, 8
	v_add_u32_e32 v0, s27, v148
	s_add_u32 s73, s48, 0x100
	v_ashrrev_i32_e32 v1, 31, v0
	s_addc_u32 s74, s49, 0
	v_lshl_add_u64 v[144:145], v[0:1], 4, s[16:17]
	s_add_u32 s46, s50, 0x40080
	s_addc_u32 s47, s51, 0
	s_mov_b32 s75, -2
	s_mov_b64 s[48:49], 0
	v_add_u32_e32 v153, s66, v147
	ds_read_b128 v[160:163], v153
	ds_read_b128 v[164:167], v153 offset:1024
	ds_read_b128 v[168:171], v153 offset:2048
	ds_read_b128 v[172:175], v153 offset:3072
	v_add_u32_e32 v153, s67, v147
	ds_read_b128 v[176:179], v153
	ds_read_b128 v[180:183], v153 offset:1024
	ds_read_b128 v[186:189], v153 offset:2048
	ds_read_b128 v[190:193], v153 offset:3072
	s_add_u32 s50, s46, 0xfffc0080
	s_addc_u32 s51, s47, -1
	s_and_b64 s[48:49], s[48:49], exec
	s_cselect_b32 s51, s29, s51
	s_cselect_b32 s50, s70, s50
	s_cselect_b32 s49, s71, s74
	s_cselect_b32 s48, s72, s73
	v_lshl_add_u64 v[154:155], s[46:47], 0, v[138:139]
	s_add_i32 m0, s57, 0xc000
	ds_read_b128 v[194:197], v150
	ds_read_b128 v[198:201], v150 offset:1024
	ds_read_b128 v[202:205], v150 offset:2048
	ds_read_b128 v[206:209], v150 offset:3072
	ds_read_b128 v[210:213], v150 offset:4096
	ds_read_b128 v[214:217], v150 offset:5120
	ds_read_b128 v[218:221], v150 offset:6144
	ds_read_b128 v[222:225], v150 offset:7168
	global_load_lds_dwordx4 v[154:155], off
	v_lshl_add_u64 v[154:155], s[46:47], 0, v[136:137]
	s_add_i32 m0, s57, 0xe000
	s_nop 0
	global_load_lds_dwordx4 v[154:155], off
	s_waitcnt vmcnt(8)
	s_waitcnt lgkmcnt(0)
	s_barrier
	s_setprio 1
	s_waitcnt lgkmcnt(0)
	v_mfma_f32_16x16x32_bf16 v[124:127], v[160:163], v[194:197], 0
	v_mfma_f32_16x16x32_bf16 v[116:119], v[168:171], v[194:197], 0
	v_mfma_f32_16x16x32_bf16 v[108:111], v[160:163], v[202:205], 0
	v_mfma_f32_16x16x32_bf16 v[100:103], v[168:171], v[202:205], 0
	v_mfma_f32_16x16x32_bf16 v[92:95], v[160:163], v[210:213], 0
	v_mfma_f32_16x16x32_bf16 v[84:87], v[168:171], v[210:213], 0
	v_mfma_f32_16x16x32_bf16 v[76:79], v[160:163], v[218:221], 0
	v_mfma_f32_16x16x32_bf16 v[68:71], v[168:171], v[218:221], 0
	v_mfma_f32_16x16x32_bf16 v[124:127], v[164:167], v[198:201], v[124:127]
	v_mfma_f32_16x16x32_bf16 v[116:119], v[172:175], v[198:201], v[116:119]
	v_mfma_f32_16x16x32_bf16 v[108:111], v[164:167], v[206:209], v[108:111]
	v_mfma_f32_16x16x32_bf16 v[100:103], v[172:175], v[206:209], v[100:103]
	v_mfma_f32_16x16x32_bf16 v[92:95], v[164:167], v[214:217], v[92:95]
	v_mfma_f32_16x16x32_bf16 v[84:87], v[172:175], v[214:217], v[84:87]
	v_mfma_f32_16x16x32_bf16 v[76:79], v[164:167], v[222:225], v[76:79]
	v_mfma_f32_16x16x32_bf16 v[68:71], v[172:175], v[222:225], v[68:71]
	s_setprio 0
	s_setprio 1
	v_mfma_f32_16x16x32_bf16 v[120:123], v[176:179], v[194:197], 0
	v_mfma_f32_16x16x32_bf16 v[112:115], v[186:189], v[194:197], 0
	v_mfma_f32_16x16x32_bf16 v[104:107], v[176:179], v[202:205], 0
	v_mfma_f32_16x16x32_bf16 v[96:99], v[186:189], v[202:205], 0
	v_mfma_f32_16x16x32_bf16 v[88:91], v[176:179], v[210:213], 0
	v_mfma_f32_16x16x32_bf16 v[80:83], v[186:189], v[210:213], 0
	v_mfma_f32_16x16x32_bf16 v[72:75], v[176:179], v[218:221], 0
	v_mfma_f32_16x16x32_bf16 v[64:67], v[186:189], v[218:221], 0
	v_mfma_f32_16x16x32_bf16 v[120:123], v[180:183], v[198:201], v[120:123]
	v_mfma_f32_16x16x32_bf16 v[112:115], v[190:193], v[198:201], v[112:115]
	v_mfma_f32_16x16x32_bf16 v[104:107], v[180:183], v[206:209], v[104:107]
	v_mfma_f32_16x16x32_bf16 v[96:99], v[190:193], v[206:209], v[96:99]
	v_mfma_f32_16x16x32_bf16 v[88:91], v[180:183], v[214:217], v[88:91]
	v_mfma_f32_16x16x32_bf16 v[80:83], v[190:193], v[214:217], v[80:83]
	v_mfma_f32_16x16x32_bf16 v[72:75], v[180:183], v[222:225], v[72:75]
	v_mfma_f32_16x16x32_bf16 v[64:67], v[190:193], v[222:225], v[64:67]
	s_setprio 0
	s_barrier
	s_add_i32 s76, s66, s54
	v_lshl_add_u64 v[154:155], s[48:49], 0, v[132:133]
	s_mov_b32 m0, s76
	ds_read_b128 v[194:197], v150 offset:16384
	ds_read_b128 v[198:201], v150 offset:17408
	ds_read_b128 v[202:205], v150 offset:18432
	ds_read_b128 v[206:209], v150 offset:19456
	ds_read_b128 v[210:213], v150 offset:20480
	ds_read_b128 v[214:217], v150 offset:21504
	ds_read_b128 v[218:221], v150 offset:22528
	ds_read_b128 v[222:225], v150 offset:23552
	global_load_lds_dwordx4 v[154:155], off
	s_add_i32 m0, s76, 0x2000
	s_add_u32 s76, s48, 0x40000
	v_lshl_add_u64 v[226:227], s[48:49], 0, v[128:129]
	s_addc_u32 s77, s49, 0
	s_add_i32 s78, s67, s54
	global_load_lds_dwordx4 v[226:227], off
	v_lshl_add_u64 v[228:229], s[76:77], 0, v[132:133]
	s_mov_b32 m0, s78
	v_lshl_add_u64 v[230:231], s[50:51], 0, v[130:131]
	global_load_lds_dwordx4 v[228:229], off
	v_lshl_add_u64 v[228:229], s[76:77], 0, v[128:129]
	s_add_i32 m0, s78, 0x2000
	s_nop 0
	global_load_lds_dwordx4 v[228:229], off
	v_lshl_add_u64 v[228:229], s[50:51], 0, v[134:135]
	s_mov_b32 m0, s57
	s_nop 0
	global_load_lds_dwordx4 v[228:229], off
	s_mov_b32 m0, s58
	s_nop 0
	global_load_lds_dwordx4 v[230:231], off
	s_waitcnt vmcnt(8)
	s_waitcnt lgkmcnt(0)
	s_barrier
	s_setprio 1
	s_waitcnt lgkmcnt(0)
	v_mfma_f32_16x16x32_bf16 v[60:63], v[160:163], v[194:197], 0
	v_mfma_f32_16x16x32_bf16 v[52:55], v[168:171], v[194:197], 0
	v_mfma_f32_16x16x32_bf16 v[44:47], v[160:163], v[202:205], 0
	v_mfma_f32_16x16x32_bf16 v[36:39], v[168:171], v[202:205], 0
	v_mfma_f32_16x16x32_bf16 v[28:31], v[160:163], v[210:213], 0
	v_mfma_f32_16x16x32_bf16 v[20:23], v[168:171], v[210:213], 0
	v_mfma_f32_16x16x32_bf16 v[12:15], v[160:163], v[218:221], 0
	v_mfma_f32_16x16x32_bf16 v[4:7], v[168:171], v[218:221], 0
	v_mfma_f32_16x16x32_bf16 v[60:63], v[164:167], v[198:201], v[60:63]
	v_mfma_f32_16x16x32_bf16 v[52:55], v[172:175], v[198:201], v[52:55]
	v_mfma_f32_16x16x32_bf16 v[44:47], v[164:167], v[206:209], v[44:47]
	v_mfma_f32_16x16x32_bf16 v[36:39], v[172:175], v[206:209], v[36:39]
	v_mfma_f32_16x16x32_bf16 v[28:31], v[164:167], v[214:217], v[28:31]
	v_mfma_f32_16x16x32_bf16 v[20:23], v[172:175], v[214:217], v[20:23]
	v_mfma_f32_16x16x32_bf16 v[12:15], v[164:167], v[222:225], v[12:15]
	v_mfma_f32_16x16x32_bf16 v[4:7], v[172:175], v[222:225], v[4:7]
	s_setprio 0
	s_setprio 1
	v_mfma_f32_16x16x32_bf16 v[56:59], v[176:179], v[194:197], 0
	v_mfma_f32_16x16x32_bf16 v[48:51], v[186:189], v[194:197], 0
	v_mfma_f32_16x16x32_bf16 v[40:43], v[176:179], v[202:205], 0
	v_mfma_f32_16x16x32_bf16 v[32:35], v[186:189], v[202:205], 0
	v_mfma_f32_16x16x32_bf16 v[24:27], v[176:179], v[210:213], 0
	v_mfma_f32_16x16x32_bf16 v[16:19], v[186:189], v[210:213], 0
	v_mfma_f32_16x16x32_bf16 v[8:11], v[176:179], v[218:221], 0
	v_mfma_f32_16x16x32_bf16 v[0:3], v[186:189], v[218:221], 0
	v_mfma_f32_16x16x32_bf16 v[56:59], v[180:183], v[198:201], v[56:59]
	v_mfma_f32_16x16x32_bf16 v[48:51], v[190:193], v[198:201], v[48:51]
	v_mfma_f32_16x16x32_bf16 v[40:43], v[180:183], v[206:209], v[40:43]
	v_mfma_f32_16x16x32_bf16 v[32:35], v[190:193], v[206:209], v[32:35]
	v_mfma_f32_16x16x32_bf16 v[24:27], v[180:183], v[214:217], v[24:27]
	v_mfma_f32_16x16x32_bf16 v[16:19], v[190:193], v[214:217], v[16:19]
	v_mfma_f32_16x16x32_bf16 v[8:11], v[180:183], v[222:225], v[8:11]
	v_mfma_f32_16x16x32_bf16 v[0:3], v[190:193], v[222:225], v[0:3]
	s_setprio 0
	s_barrier
	s_add_i32 s76, 0, 0x18000
	v_add_u32_e32 v153, s76, v147
	s_add_i32 s77, 0, 0x1c000
	ds_read_b128 v[160:163], v153
	ds_read_b128 v[164:167], v153 offset:1024
	ds_read_b128 v[168:171], v153 offset:2048
	ds_read_b128 v[172:175], v153 offset:3072
	v_add_u32_e32 v153, s77, v147
	ds_read_b128 v[176:179], v153
	ds_read_b128 v[180:183], v153 offset:1024
	ds_read_b128 v[186:189], v153 offset:2048
	ds_read_b128 v[190:193], v153 offset:3072
	s_add_u32 s50, s50, 0x40000
	s_addc_u32 s51, s51, 0
	s_mov_b32 m0, s59
	v_lshl_add_u64 v[232:233], s[50:51], 0, v[134:135]
	ds_read_b128 v[194:197], v150 offset:32768
	ds_read_b128 v[198:201], v150 offset:33792
	ds_read_b128 v[202:205], v150 offset:34816
	ds_read_b128 v[206:209], v150 offset:35840
	ds_read_b128 v[210:213], v150 offset:36864
	ds_read_b128 v[214:217], v150 offset:37888
	ds_read_b128 v[218:221], v150 offset:38912
	ds_read_b128 v[222:225], v150 offset:39936
	global_load_lds_dwordx4 v[232:233], off
	v_lshl_add_u64 v[232:233], s[50:51], 0, v[130:131]
	s_mov_b32 m0, s60
	s_nop 0
	global_load_lds_dwordx4 v[232:233], off
	s_waitcnt vmcnt(8)
	s_waitcnt lgkmcnt(0)
	s_barrier
	s_setprio 1
	s_waitcnt lgkmcnt(0)
	v_mfma_f32_16x16x32_bf16 v[124:127], v[160:163], v[194:197], v[124:127]
	v_mfma_f32_16x16x32_bf16 v[116:119], v[168:171], v[194:197], v[116:119]
	v_mfma_f32_16x16x32_bf16 v[100:103], v[168:171], v[202:205], v[100:103]
	v_mfma_f32_16x16x32_bf16 v[108:111], v[160:163], v[202:205], v[108:111]
	v_mfma_f32_16x16x32_bf16 v[92:95], v[160:163], v[210:213], v[92:95]
	v_mfma_f32_16x16x32_bf16 v[84:87], v[168:171], v[210:213], v[84:87]
	v_mfma_f32_16x16x32_bf16 v[68:71], v[168:171], v[218:221], v[68:71]
	v_mfma_f32_16x16x32_bf16 v[76:79], v[160:163], v[218:221], v[76:79]
	v_mfma_f32_16x16x32_bf16 v[124:127], v[164:167], v[198:201], v[124:127]
	v_mfma_f32_16x16x32_bf16 v[116:119], v[172:175], v[198:201], v[116:119]
	v_mfma_f32_16x16x32_bf16 v[100:103], v[172:175], v[206:209], v[100:103]
	v_mfma_f32_16x16x32_bf16 v[108:111], v[164:167], v[206:209], v[108:111]
	v_mfma_f32_16x16x32_bf16 v[92:95], v[164:167], v[214:217], v[92:95]
	v_mfma_f32_16x16x32_bf16 v[84:87], v[172:175], v[214:217], v[84:87]
	v_mfma_f32_16x16x32_bf16 v[68:71], v[172:175], v[222:225], v[68:71]
	v_mfma_f32_16x16x32_bf16 v[76:79], v[164:167], v[222:225], v[76:79]
	s_setprio 0
	s_setprio 1
	v_mfma_f32_16x16x32_bf16 v[120:123], v[176:179], v[194:197], v[120:123]
	v_mfma_f32_16x16x32_bf16 v[112:115], v[186:189], v[194:197], v[112:115]
	v_mfma_f32_16x16x32_bf16 v[96:99], v[186:189], v[202:205], v[96:99]
	v_mfma_f32_16x16x32_bf16 v[104:107], v[176:179], v[202:205], v[104:107]
	v_mfma_f32_16x16x32_bf16 v[88:91], v[176:179], v[210:213], v[88:91]
	v_mfma_f32_16x16x32_bf16 v[80:83], v[186:189], v[210:213], v[80:83]
	v_mfma_f32_16x16x32_bf16 v[64:67], v[186:189], v[218:221], v[64:67]
	v_mfma_f32_16x16x32_bf16 v[72:75], v[176:179], v[218:221], v[72:75]
	v_mfma_f32_16x16x32_bf16 v[120:123], v[180:183], v[198:201], v[120:123]
	v_mfma_f32_16x16x32_bf16 v[112:115], v[190:193], v[198:201], v[112:115]
	v_mfma_f32_16x16x32_bf16 v[96:99], v[190:193], v[206:209], v[96:99]
	v_mfma_f32_16x16x32_bf16 v[104:107], v[180:183], v[206:209], v[104:107]
	v_mfma_f32_16x16x32_bf16 v[88:91], v[180:183], v[214:217], v[88:91]
	v_mfma_f32_16x16x32_bf16 v[80:83], v[190:193], v[214:217], v[80:83]
	v_mfma_f32_16x16x32_bf16 v[64:67], v[190:193], v[222:225], v[64:67]
	v_mfma_f32_16x16x32_bf16 v[72:75], v[180:183], v[222:225], v[72:75]
	s_setprio 0
	s_barrier
	s_add_i32 s50, s76, s54
	v_lshl_add_u64 v[154:155], v[154:155], 0, s[20:21]
	s_mov_b32 m0, s50
	ds_read_b128 v[194:197], v150 offset:49152
	ds_read_b128 v[198:201], v150 offset:50176
	ds_read_b128 v[202:205], v150 offset:51200
	ds_read_b128 v[206:209], v150 offset:52224
	ds_read_b128 v[210:213], v150 offset:53248
	ds_read_b128 v[214:217], v150 offset:54272
	ds_read_b128 v[218:221], v150 offset:55296
	ds_read_b128 v[222:225], v150 offset:56320
	global_load_lds_dwordx4 v[154:155], off
	s_add_i32 m0, s50, 0x2000
	s_add_u32 s48, s48, 0x40080
	v_lshl_add_u64 v[154:155], v[226:227], 0, s[20:21]
	s_addc_u32 s49, s49, 0
	s_add_i32 s50, s77, s54
	global_load_lds_dwordx4 v[154:155], off
	v_lshl_add_u64 v[154:155], s[48:49], 0, v[132:133]
	s_mov_b32 m0, s50
	s_nop 0
	global_load_lds_dwordx4 v[154:155], off
	v_lshl_add_u64 v[154:155], s[48:49], 0, v[128:129]
	s_add_i32 m0, s50, 0x2000
	s_nop 0
	global_load_lds_dwordx4 v[154:155], off
	v_lshl_add_u64 v[154:155], v[228:229], 0, s[20:21]
	s_mov_b32 m0, s62
	s_nop 0
	global_load_lds_dwordx4 v[154:155], off
	v_lshl_add_u64 v[154:155], v[230:231], 0, s[20:21]
	s_mov_b32 m0, s63
	s_nop 0
	global_load_lds_dwordx4 v[154:155], off
	s_waitcnt vmcnt(8)
	s_waitcnt lgkmcnt(0)
	s_barrier
	s_setprio 1
	s_waitcnt lgkmcnt(0)
	v_mfma_f32_16x16x32_bf16 v[60:63], v[160:163], v[194:197], v[60:63]
	v_mfma_f32_16x16x32_bf16 v[52:55], v[168:171], v[194:197], v[52:55]
	v_mfma_f32_16x16x32_bf16 v[36:39], v[168:171], v[202:205], v[36:39]
	v_mfma_f32_16x16x32_bf16 v[44:47], v[160:163], v[202:205], v[44:47]
	v_mfma_f32_16x16x32_bf16 v[28:31], v[160:163], v[210:213], v[28:31]
	v_mfma_f32_16x16x32_bf16 v[20:23], v[168:171], v[210:213], v[20:23]
	v_mfma_f32_16x16x32_bf16 v[4:7], v[168:171], v[218:221], v[4:7]
	v_mfma_f32_16x16x32_bf16 v[12:15], v[160:163], v[218:221], v[12:15]
	v_mfma_f32_16x16x32_bf16 v[60:63], v[164:167], v[198:201], v[60:63]
	v_mfma_f32_16x16x32_bf16 v[52:55], v[172:175], v[198:201], v[52:55]
	v_mfma_f32_16x16x32_bf16 v[36:39], v[172:175], v[206:209], v[36:39]
	v_mfma_f32_16x16x32_bf16 v[44:47], v[164:167], v[206:209], v[44:47]
	v_mfma_f32_16x16x32_bf16 v[28:31], v[164:167], v[214:217], v[28:31]
	v_mfma_f32_16x16x32_bf16 v[20:23], v[172:175], v[214:217], v[20:23]
	v_mfma_f32_16x16x32_bf16 v[4:7], v[172:175], v[222:225], v[4:7]
	v_mfma_f32_16x16x32_bf16 v[12:15], v[164:167], v[222:225], v[12:15]
	s_setprio 0
	s_setprio 1
	v_mfma_f32_16x16x32_bf16 v[56:59], v[176:179], v[194:197], v[56:59]
	v_mfma_f32_16x16x32_bf16 v[48:51], v[186:189], v[194:197], v[48:51]
	v_mfma_f32_16x16x32_bf16 v[32:35], v[186:189], v[202:205], v[32:35]
	v_mfma_f32_16x16x32_bf16 v[40:43], v[176:179], v[202:205], v[40:43]
	v_mfma_f32_16x16x32_bf16 v[24:27], v[176:179], v[210:213], v[24:27]
	v_mfma_f32_16x16x32_bf16 v[16:19], v[186:189], v[210:213], v[16:19]
	v_mfma_f32_16x16x32_bf16 v[0:3], v[186:189], v[218:221], v[0:3]
	v_mfma_f32_16x16x32_bf16 v[8:11], v[176:179], v[218:221], v[8:11]
	v_mfma_f32_16x16x32_bf16 v[56:59], v[180:183], v[198:201], v[56:59]
	v_mfma_f32_16x16x32_bf16 v[48:51], v[190:193], v[198:201], v[48:51]
	v_mfma_f32_16x16x32_bf16 v[32:35], v[190:193], v[206:209], v[32:35]
	v_mfma_f32_16x16x32_bf16 v[40:43], v[180:183], v[206:209], v[40:43]
	v_mfma_f32_16x16x32_bf16 v[24:27], v[180:183], v[214:217], v[24:27]
	v_mfma_f32_16x16x32_bf16 v[16:19], v[190:193], v[214:217], v[16:19]
	v_mfma_f32_16x16x32_bf16 v[0:3], v[190:193], v[222:225], v[0:3]
	v_mfma_f32_16x16x32_bf16 v[8:11], v[180:183], v[222:225], v[8:11]
	s_setprio 0
	s_barrier
	s_add_i32 s75, s75, 2
	s_add_u32 s73, s73, 0x100
	s_addc_u32 s74, s74, 0
	s_add_u32 s46, s46, 0x100
	s_addc_u32 s47, s47, 0
	s_branch .LBB0_527
.LBB0_526:
	v_add_u32_e32 v153, s66, v147
	ds_read_b128 v[160:163], v153
	ds_read_b128 v[164:167], v153 offset:1024
	ds_read_b128 v[168:171], v153 offset:2048
	ds_read_b128 v[172:175], v153 offset:3072
	v_add_u32_e32 v153, s67, v147
	ds_read_b128 v[176:179], v153
	ds_read_b128 v[180:183], v153 offset:1024
	ds_read_b128 v[186:189], v153 offset:2048
	ds_read_b128 v[190:193], v153 offset:3072
	s_add_u32 s50, s46, 0xfffc0080
	s_addc_u32 s51, s47, -1
	s_and_b64 s[48:49], s[48:49], exec
	s_cselect_b32 s51, s29, s51
	s_cselect_b32 s50, s70, s50
	s_cselect_b32 s49, s71, s74
	s_cselect_b32 s48, s72, s73
	v_lshl_add_u64 v[154:155], s[46:47], 0, v[138:139]
	s_add_i32 m0, s57, 0xc000
	ds_read_b128 v[194:197], v150
	ds_read_b128 v[198:201], v150 offset:1024
	ds_read_b128 v[202:205], v150 offset:2048
	ds_read_b128 v[206:209], v150 offset:3072
	ds_read_b128 v[210:213], v150 offset:4096
	ds_read_b128 v[214:217], v150 offset:5120
	ds_read_b128 v[218:221], v150 offset:6144
	ds_read_b128 v[222:225], v150 offset:7168
	global_load_lds_dwordx4 v[154:155], off
	v_lshl_add_u64 v[154:155], s[46:47], 0, v[136:137]
	s_add_i32 m0, s57, 0xe000
	s_nop 0
	global_load_lds_dwordx4 v[154:155], off
	s_waitcnt vmcnt(8)
	s_waitcnt lgkmcnt(0)
	s_barrier
	s_setprio 1
	s_waitcnt lgkmcnt(0)
	v_mfma_f32_16x16x32_bf16 v[124:127], v[160:163], v[194:197], v[124:127]
	v_mfma_f32_16x16x32_bf16 v[116:119], v[168:171], v[194:197], v[116:119]
	v_mfma_f32_16x16x32_bf16 v[100:103], v[168:171], v[202:205], v[100:103]
	v_mfma_f32_16x16x32_bf16 v[108:111], v[160:163], v[202:205], v[108:111]
	v_mfma_f32_16x16x32_bf16 v[92:95], v[160:163], v[210:213], v[92:95]
	v_mfma_f32_16x16x32_bf16 v[84:87], v[168:171], v[210:213], v[84:87]
	v_mfma_f32_16x16x32_bf16 v[68:71], v[168:171], v[218:221], v[68:71]
	v_mfma_f32_16x16x32_bf16 v[76:79], v[160:163], v[218:221], v[76:79]
	v_mfma_f32_16x16x32_bf16 v[124:127], v[164:167], v[198:201], v[124:127]
	v_mfma_f32_16x16x32_bf16 v[116:119], v[172:175], v[198:201], v[116:119]
	v_mfma_f32_16x16x32_bf16 v[100:103], v[172:175], v[206:209], v[100:103]
	v_mfma_f32_16x16x32_bf16 v[108:111], v[164:167], v[206:209], v[108:111]
	v_mfma_f32_16x16x32_bf16 v[92:95], v[164:167], v[214:217], v[92:95]
	v_mfma_f32_16x16x32_bf16 v[84:87], v[172:175], v[214:217], v[84:87]
	v_mfma_f32_16x16x32_bf16 v[68:71], v[172:175], v[222:225], v[68:71]
	v_mfma_f32_16x16x32_bf16 v[76:79], v[164:167], v[222:225], v[76:79]
	s_setprio 0
	s_setprio 1
	v_mfma_f32_16x16x32_bf16 v[120:123], v[176:179], v[194:197], v[120:123]
	v_mfma_f32_16x16x32_bf16 v[112:115], v[186:189], v[194:197], v[112:115]
	v_mfma_f32_16x16x32_bf16 v[96:99], v[186:189], v[202:205], v[96:99]
	v_mfma_f32_16x16x32_bf16 v[104:107], v[176:179], v[202:205], v[104:107]
	v_mfma_f32_16x16x32_bf16 v[88:91], v[176:179], v[210:213], v[88:91]
	v_mfma_f32_16x16x32_bf16 v[80:83], v[186:189], v[210:213], v[80:83]
	v_mfma_f32_16x16x32_bf16 v[64:67], v[186:189], v[218:221], v[64:67]
	v_mfma_f32_16x16x32_bf16 v[72:75], v[176:179], v[218:221], v[72:75]
	v_mfma_f32_16x16x32_bf16 v[120:123], v[180:183], v[198:201], v[120:123]
	v_mfma_f32_16x16x32_bf16 v[112:115], v[190:193], v[198:201], v[112:115]
	v_mfma_f32_16x16x32_bf16 v[96:99], v[190:193], v[206:209], v[96:99]
	v_mfma_f32_16x16x32_bf16 v[104:107], v[180:183], v[206:209], v[104:107]
	v_mfma_f32_16x16x32_bf16 v[88:91], v[180:183], v[214:217], v[88:91]
	v_mfma_f32_16x16x32_bf16 v[80:83], v[190:193], v[214:217], v[80:83]
	v_mfma_f32_16x16x32_bf16 v[64:67], v[190:193], v[222:225], v[64:67]
	v_mfma_f32_16x16x32_bf16 v[72:75], v[180:183], v[222:225], v[72:75]
	s_setprio 0
	s_barrier
	s_add_i32 s76, s66, s54
	v_lshl_add_u64 v[154:155], s[48:49], 0, v[132:133]
	s_mov_b32 m0, s76
	ds_read_b128 v[194:197], v150 offset:16384
	ds_read_b128 v[198:201], v150 offset:17408
	ds_read_b128 v[202:205], v150 offset:18432
	ds_read_b128 v[206:209], v150 offset:19456
	ds_read_b128 v[210:213], v150 offset:20480
	ds_read_b128 v[214:217], v150 offset:21504
	ds_read_b128 v[218:221], v150 offset:22528
	ds_read_b128 v[222:225], v150 offset:23552
	global_load_lds_dwordx4 v[154:155], off
	s_add_i32 m0, s76, 0x2000
	s_add_u32 s76, s48, 0x40000
	v_lshl_add_u64 v[226:227], s[48:49], 0, v[128:129]
	s_addc_u32 s77, s49, 0
	s_add_i32 s78, s67, s54
	global_load_lds_dwordx4 v[226:227], off
	v_lshl_add_u64 v[228:229], s[76:77], 0, v[132:133]
	s_mov_b32 m0, s78
	v_lshl_add_u64 v[230:231], s[50:51], 0, v[130:131]
	global_load_lds_dwordx4 v[228:229], off
	v_lshl_add_u64 v[228:229], s[76:77], 0, v[128:129]
	s_add_i32 m0, s78, 0x2000
	s_nop 0
	global_load_lds_dwordx4 v[228:229], off
	v_lshl_add_u64 v[228:229], s[50:51], 0, v[134:135]
	s_mov_b32 m0, s57
	s_nop 0
	global_load_lds_dwordx4 v[228:229], off
	s_mov_b32 m0, s58
	s_nop 0
	global_load_lds_dwordx4 v[230:231], off
	s_waitcnt vmcnt(8)
	s_waitcnt lgkmcnt(0)
	s_barrier
	s_setprio 1
	s_waitcnt lgkmcnt(0)
	v_mfma_f32_16x16x32_bf16 v[60:63], v[160:163], v[194:197], v[60:63]
	v_mfma_f32_16x16x32_bf16 v[52:55], v[168:171], v[194:197], v[52:55]
	v_mfma_f32_16x16x32_bf16 v[36:39], v[168:171], v[202:205], v[36:39]
	v_mfma_f32_16x16x32_bf16 v[44:47], v[160:163], v[202:205], v[44:47]
	v_mfma_f32_16x16x32_bf16 v[28:31], v[160:163], v[210:213], v[28:31]
	v_mfma_f32_16x16x32_bf16 v[20:23], v[168:171], v[210:213], v[20:23]
	v_mfma_f32_16x16x32_bf16 v[4:7], v[168:171], v[218:221], v[4:7]
	v_mfma_f32_16x16x32_bf16 v[12:15], v[160:163], v[218:221], v[12:15]
	v_mfma_f32_16x16x32_bf16 v[60:63], v[164:167], v[198:201], v[60:63]
	v_mfma_f32_16x16x32_bf16 v[52:55], v[172:175], v[198:201], v[52:55]
	v_mfma_f32_16x16x32_bf16 v[36:39], v[172:175], v[206:209], v[36:39]
	v_mfma_f32_16x16x32_bf16 v[44:47], v[164:167], v[206:209], v[44:47]
	v_mfma_f32_16x16x32_bf16 v[28:31], v[164:167], v[214:217], v[28:31]
	v_mfma_f32_16x16x32_bf16 v[20:23], v[172:175], v[214:217], v[20:23]
	v_mfma_f32_16x16x32_bf16 v[4:7], v[172:175], v[222:225], v[4:7]
	v_mfma_f32_16x16x32_bf16 v[12:15], v[164:167], v[222:225], v[12:15]
	s_setprio 0
	s_setprio 1
	v_mfma_f32_16x16x32_bf16 v[56:59], v[176:179], v[194:197], v[56:59]
	v_mfma_f32_16x16x32_bf16 v[48:51], v[186:189], v[194:197], v[48:51]
	v_mfma_f32_16x16x32_bf16 v[32:35], v[186:189], v[202:205], v[32:35]
	v_mfma_f32_16x16x32_bf16 v[40:43], v[176:179], v[202:205], v[40:43]
	v_mfma_f32_16x16x32_bf16 v[24:27], v[176:179], v[210:213], v[24:27]
	v_mfma_f32_16x16x32_bf16 v[16:19], v[186:189], v[210:213], v[16:19]
	v_mfma_f32_16x16x32_bf16 v[0:3], v[186:189], v[218:221], v[0:3]
	v_mfma_f32_16x16x32_bf16 v[8:11], v[176:179], v[218:221], v[8:11]
	v_mfma_f32_16x16x32_bf16 v[56:59], v[180:183], v[198:201], v[56:59]
	v_mfma_f32_16x16x32_bf16 v[48:51], v[190:193], v[198:201], v[48:51]
	v_mfma_f32_16x16x32_bf16 v[32:35], v[190:193], v[206:209], v[32:35]
	v_mfma_f32_16x16x32_bf16 v[40:43], v[180:183], v[206:209], v[40:43]
	v_mfma_f32_16x16x32_bf16 v[24:27], v[180:183], v[214:217], v[24:27]
	v_mfma_f32_16x16x32_bf16 v[16:19], v[190:193], v[214:217], v[16:19]
	v_mfma_f32_16x16x32_bf16 v[0:3], v[190:193], v[222:225], v[0:3]
	v_mfma_f32_16x16x32_bf16 v[8:11], v[180:183], v[222:225], v[8:11]
	s_setprio 0
	s_barrier
	s_add_i32 s76, 0, 0x18000
	v_add_u32_e32 v153, s76, v147
	s_add_i32 s77, 0, 0x1c000
	ds_read_b128 v[160:163], v153
	ds_read_b128 v[164:167], v153 offset:1024
	ds_read_b128 v[168:171], v153 offset:2048
	ds_read_b128 v[172:175], v153 offset:3072
	v_add_u32_e32 v153, s77, v147
	ds_read_b128 v[176:179], v153
	ds_read_b128 v[180:183], v153 offset:1024
	ds_read_b128 v[186:189], v153 offset:2048
	ds_read_b128 v[190:193], v153 offset:3072
	s_add_u32 s50, s50, 0x40000
	s_addc_u32 s51, s51, 0
	s_mov_b32 m0, s59
	v_lshl_add_u64 v[232:233], s[50:51], 0, v[134:135]
	ds_read_b128 v[194:197], v150 offset:32768
	ds_read_b128 v[198:201], v150 offset:33792
	ds_read_b128 v[202:205], v150 offset:34816
	ds_read_b128 v[206:209], v150 offset:35840
	ds_read_b128 v[210:213], v150 offset:36864
	ds_read_b128 v[214:217], v150 offset:37888
	ds_read_b128 v[218:221], v150 offset:38912
	ds_read_b128 v[222:225], v150 offset:39936
	global_load_lds_dwordx4 v[232:233], off
	v_lshl_add_u64 v[232:233], s[50:51], 0, v[130:131]
	s_mov_b32 m0, s60
	s_nop 0
	global_load_lds_dwordx4 v[232:233], off
	s_waitcnt vmcnt(8)
	s_waitcnt lgkmcnt(0)
	s_barrier
	s_setprio 1
	s_waitcnt lgkmcnt(0)
	v_mfma_f32_16x16x32_bf16 v[124:127], v[160:163], v[194:197], v[124:127]
	v_mfma_f32_16x16x32_bf16 v[116:119], v[168:171], v[194:197], v[116:119]
	v_mfma_f32_16x16x32_bf16 v[100:103], v[168:171], v[202:205], v[100:103]
	v_mfma_f32_16x16x32_bf16 v[108:111], v[160:163], v[202:205], v[108:111]
	v_mfma_f32_16x16x32_bf16 v[92:95], v[160:163], v[210:213], v[92:95]
	v_mfma_f32_16x16x32_bf16 v[84:87], v[168:171], v[210:213], v[84:87]
	v_mfma_f32_16x16x32_bf16 v[68:71], v[168:171], v[218:221], v[68:71]
	v_mfma_f32_16x16x32_bf16 v[76:79], v[160:163], v[218:221], v[76:79]
	v_mfma_f32_16x16x32_bf16 v[124:127], v[164:167], v[198:201], v[124:127]
	v_mfma_f32_16x16x32_bf16 v[116:119], v[172:175], v[198:201], v[116:119]
	v_mfma_f32_16x16x32_bf16 v[100:103], v[172:175], v[206:209], v[100:103]
	v_mfma_f32_16x16x32_bf16 v[108:111], v[164:167], v[206:209], v[108:111]
	v_mfma_f32_16x16x32_bf16 v[92:95], v[164:167], v[214:217], v[92:95]
	v_mfma_f32_16x16x32_bf16 v[84:87], v[172:175], v[214:217], v[84:87]
	v_mfma_f32_16x16x32_bf16 v[68:71], v[172:175], v[222:225], v[68:71]
	v_mfma_f32_16x16x32_bf16 v[76:79], v[164:167], v[222:225], v[76:79]
	s_setprio 0
	s_setprio 1
	v_mfma_f32_16x16x32_bf16 v[120:123], v[176:179], v[194:197], v[120:123]
	v_mfma_f32_16x16x32_bf16 v[112:115], v[186:189], v[194:197], v[112:115]
	v_mfma_f32_16x16x32_bf16 v[96:99], v[186:189], v[202:205], v[96:99]
	v_mfma_f32_16x16x32_bf16 v[104:107], v[176:179], v[202:205], v[104:107]
	v_mfma_f32_16x16x32_bf16 v[88:91], v[176:179], v[210:213], v[88:91]
	v_mfma_f32_16x16x32_bf16 v[80:83], v[186:189], v[210:213], v[80:83]
	v_mfma_f32_16x16x32_bf16 v[64:67], v[186:189], v[218:221], v[64:67]
	v_mfma_f32_16x16x32_bf16 v[72:75], v[176:179], v[218:221], v[72:75]
	v_mfma_f32_16x16x32_bf16 v[120:123], v[180:183], v[198:201], v[120:123]
	v_mfma_f32_16x16x32_bf16 v[112:115], v[190:193], v[198:201], v[112:115]
	v_mfma_f32_16x16x32_bf16 v[96:99], v[190:193], v[206:209], v[96:99]
	v_mfma_f32_16x16x32_bf16 v[104:107], v[180:183], v[206:209], v[104:107]
	v_mfma_f32_16x16x32_bf16 v[88:91], v[180:183], v[214:217], v[88:91]
	v_mfma_f32_16x16x32_bf16 v[80:83], v[190:193], v[214:217], v[80:83]
	v_mfma_f32_16x16x32_bf16 v[64:67], v[190:193], v[222:225], v[64:67]
	v_mfma_f32_16x16x32_bf16 v[72:75], v[180:183], v[222:225], v[72:75]
	s_setprio 0
	s_barrier
	s_add_i32 s50, s76, s54
	v_lshl_add_u64 v[154:155], v[154:155], 0, s[20:21]
	s_mov_b32 m0, s50
	ds_read_b128 v[194:197], v150 offset:49152
	ds_read_b128 v[198:201], v150 offset:50176
	ds_read_b128 v[202:205], v150 offset:51200
	ds_read_b128 v[206:209], v150 offset:52224
	ds_read_b128 v[210:213], v150 offset:53248
	ds_read_b128 v[214:217], v150 offset:54272
	ds_read_b128 v[218:221], v150 offset:55296
	ds_read_b128 v[222:225], v150 offset:56320
	global_load_lds_dwordx4 v[154:155], off
	s_add_i32 m0, s50, 0x2000
	s_add_u32 s48, s48, 0x40080
	v_lshl_add_u64 v[154:155], v[226:227], 0, s[20:21]
	s_addc_u32 s49, s49, 0
	s_add_i32 s50, s77, s54
	global_load_lds_dwordx4 v[154:155], off
	v_lshl_add_u64 v[154:155], s[48:49], 0, v[132:133]
	s_mov_b32 m0, s50
	s_nop 0
	global_load_lds_dwordx4 v[154:155], off
	v_lshl_add_u64 v[154:155], s[48:49], 0, v[128:129]
	s_add_i32 m0, s50, 0x2000
	s_nop 0
	global_load_lds_dwordx4 v[154:155], off
	v_lshl_add_u64 v[154:155], v[228:229], 0, s[20:21]
	s_mov_b32 m0, s62
	s_nop 0
	global_load_lds_dwordx4 v[154:155], off
	v_lshl_add_u64 v[154:155], v[230:231], 0, s[20:21]
	s_mov_b32 m0, s63
	s_nop 0
	global_load_lds_dwordx4 v[154:155], off
	s_waitcnt vmcnt(8)
	s_waitcnt lgkmcnt(0)
	s_barrier
	s_setprio 1
	s_waitcnt lgkmcnt(0)
	v_mfma_f32_16x16x32_bf16 v[60:63], v[160:163], v[194:197], v[60:63]
	v_mfma_f32_16x16x32_bf16 v[52:55], v[168:171], v[194:197], v[52:55]
	v_mfma_f32_16x16x32_bf16 v[36:39], v[168:171], v[202:205], v[36:39]
	v_mfma_f32_16x16x32_bf16 v[44:47], v[160:163], v[202:205], v[44:47]
	v_mfma_f32_16x16x32_bf16 v[28:31], v[160:163], v[210:213], v[28:31]
	v_mfma_f32_16x16x32_bf16 v[20:23], v[168:171], v[210:213], v[20:23]
	v_mfma_f32_16x16x32_bf16 v[4:7], v[168:171], v[218:221], v[4:7]
	v_mfma_f32_16x16x32_bf16 v[12:15], v[160:163], v[218:221], v[12:15]
	v_mfma_f32_16x16x32_bf16 v[60:63], v[164:167], v[198:201], v[60:63]
	v_mfma_f32_16x16x32_bf16 v[52:55], v[172:175], v[198:201], v[52:55]
	v_mfma_f32_16x16x32_bf16 v[36:39], v[172:175], v[206:209], v[36:39]
	v_mfma_f32_16x16x32_bf16 v[44:47], v[164:167], v[206:209], v[44:47]
	v_mfma_f32_16x16x32_bf16 v[28:31], v[164:167], v[214:217], v[28:31]
	v_mfma_f32_16x16x32_bf16 v[20:23], v[172:175], v[214:217], v[20:23]
	v_mfma_f32_16x16x32_bf16 v[4:7], v[172:175], v[222:225], v[4:7]
	v_mfma_f32_16x16x32_bf16 v[12:15], v[164:167], v[222:225], v[12:15]
	s_setprio 0
	s_setprio 1
	v_mfma_f32_16x16x32_bf16 v[56:59], v[176:179], v[194:197], v[56:59]
	v_mfma_f32_16x16x32_bf16 v[48:51], v[186:189], v[194:197], v[48:51]
	v_mfma_f32_16x16x32_bf16 v[32:35], v[186:189], v[202:205], v[32:35]
	v_mfma_f32_16x16x32_bf16 v[40:43], v[176:179], v[202:205], v[40:43]
	v_mfma_f32_16x16x32_bf16 v[24:27], v[176:179], v[210:213], v[24:27]
	v_mfma_f32_16x16x32_bf16 v[16:19], v[186:189], v[210:213], v[16:19]
	v_mfma_f32_16x16x32_bf16 v[0:3], v[186:189], v[218:221], v[0:3]
	v_mfma_f32_16x16x32_bf16 v[8:11], v[176:179], v[218:221], v[8:11]
	v_mfma_f32_16x16x32_bf16 v[56:59], v[180:183], v[198:201], v[56:59]
	v_mfma_f32_16x16x32_bf16 v[48:51], v[190:193], v[198:201], v[48:51]
	v_mfma_f32_16x16x32_bf16 v[32:35], v[190:193], v[206:209], v[32:35]
	v_mfma_f32_16x16x32_bf16 v[40:43], v[180:183], v[206:209], v[40:43]
	v_mfma_f32_16x16x32_bf16 v[24:27], v[180:183], v[214:217], v[24:27]
	v_mfma_f32_16x16x32_bf16 v[16:19], v[190:193], v[214:217], v[16:19]
	v_mfma_f32_16x16x32_bf16 v[0:3], v[190:193], v[222:225], v[0:3]
	v_mfma_f32_16x16x32_bf16 v[8:11], v[180:183], v[222:225], v[8:11]
	s_setprio 0
	s_barrier
	s_add_i32 s75, s75, 2
	s_add_u32 s73, s73, 0x100
	s_addc_u32 s74, s74, 0
	s_add_u32 s46, s46, 0x100
	s_addc_u32 s47, s47, 0
	s_cmp_gt_u32 s75, 13
	s_cbranch_scc1 .LBB0_529

.LBB0_609:
	s_add_u32 s79, s56, 0x100
	s_addc_u32 s80, s57, 0
	s_mov_b32 s81, -2
	s_waitcnt lgkmcnt(0)
	ds_read_b128 v[128:131], v189
	ds_read_b128 v[132:135], v189 offset:1024
	ds_read_b128 v[136:139], v189 offset:2048
	ds_read_b128 v[140:143], v189 offset:3072
	ds_read_b128 v[144:147], v190
	ds_read_b128 v[148:151], v190 offset:1024
	ds_read_b128 v[172:175], v190 offset:2048
	ds_read_b128 v[176:179], v190 offset:3072
	s_add_u32 s56, s54, 0x100
	s_addc_u32 s57, s55, 0
	s_cmp_eq_u32 s81, 40
	s_cselect_b32 s61, s17, s57
	s_cselect_b32 s60, s16, s56
	s_cselect_b32 s59, s53, s80
	s_cselect_b32 s58, s52, s79
	v_lshl_add_u64 v[222:223], s[54:55], 0, v[166:167]
	s_add_i32 m0, s66, 0xc000
	ds_read_b128 v[180:183], v191
	ds_read_b128 v[194:197], v191 offset:1024
	ds_read_b128 v[198:201], v191 offset:2048
	ds_read_b128 v[202:205], v191 offset:3072
	ds_read_b128 v[206:209], v191 offset:4096
	ds_read_b128 v[210:213], v191 offset:5120
	ds_read_b128 v[214:217], v191 offset:6144
	ds_read_b128 v[218:221], v191 offset:7168
	global_load_lds_dwordx4 v[222:223], off
	v_lshl_add_u64 v[222:223], s[54:55], 0, v[164:165]
	s_add_i32 m0, s66, 0xe000
	s_nop 0
	global_load_lds_dwordx4 v[222:223], off
	s_waitcnt vmcnt(8)
	s_waitcnt lgkmcnt(0)
	s_barrier
	s_setprio 1
	s_waitcnt lgkmcnt(0)
	v_mfma_f32_16x16x32_bf16 v[124:127], v[128:131], v[180:183], 0
	v_mfma_f32_16x16x32_bf16 v[120:123], v[136:139], v[180:183], 0
	v_mfma_f32_16x16x32_bf16 v[108:111], v[128:131], v[198:201], 0
	v_mfma_f32_16x16x32_bf16 v[104:107], v[136:139], v[198:201], 0
	v_mfma_f32_16x16x32_bf16 v[92:95], v[128:131], v[206:209], 0
	v_mfma_f32_16x16x32_bf16 v[88:91], v[136:139], v[206:209], 0
	v_mfma_f32_16x16x32_bf16 v[76:79], v[128:131], v[214:217], 0
	v_mfma_f32_16x16x32_bf16 v[72:75], v[136:139], v[214:217], 0
	v_mfma_f32_16x16x32_bf16 v[124:127], v[132:135], v[194:197], v[124:127]
	v_mfma_f32_16x16x32_bf16 v[120:123], v[140:143], v[194:197], v[120:123]
	v_mfma_f32_16x16x32_bf16 v[108:111], v[132:135], v[202:205], v[108:111]
	v_mfma_f32_16x16x32_bf16 v[104:107], v[140:143], v[202:205], v[104:107]
	v_mfma_f32_16x16x32_bf16 v[92:95], v[132:135], v[210:213], v[92:95]
	v_mfma_f32_16x16x32_bf16 v[88:91], v[140:143], v[210:213], v[88:91]
	v_mfma_f32_16x16x32_bf16 v[76:79], v[132:135], v[218:221], v[76:79]
	v_mfma_f32_16x16x32_bf16 v[72:75], v[140:143], v[218:221], v[72:75]
	s_setprio 0
	s_setprio 1
	v_mfma_f32_16x16x32_bf16 v[116:119], v[144:147], v[180:183], 0
	v_mfma_f32_16x16x32_bf16 v[112:115], v[172:175], v[180:183], 0
	v_mfma_f32_16x16x32_bf16 v[100:103], v[144:147], v[198:201], 0
	v_mfma_f32_16x16x32_bf16 v[96:99], v[172:175], v[198:201], 0
	v_mfma_f32_16x16x32_bf16 v[84:87], v[144:147], v[206:209], 0
	v_mfma_f32_16x16x32_bf16 v[80:83], v[172:175], v[206:209], 0
	v_mfma_f32_16x16x32_bf16 v[68:71], v[144:147], v[214:217], 0
	v_mfma_f32_16x16x32_bf16 v[64:67], v[172:175], v[214:217], 0
	v_mfma_f32_16x16x32_bf16 v[116:119], v[148:151], v[194:197], v[116:119]
	v_mfma_f32_16x16x32_bf16 v[112:115], v[176:179], v[194:197], v[112:115]
	v_mfma_f32_16x16x32_bf16 v[100:103], v[148:151], v[202:205], v[100:103]
	v_mfma_f32_16x16x32_bf16 v[96:99], v[176:179], v[202:205], v[96:99]
	v_mfma_f32_16x16x32_bf16 v[84:87], v[148:151], v[210:213], v[84:87]
	v_mfma_f32_16x16x32_bf16 v[80:83], v[176:179], v[210:213], v[80:83]
	v_mfma_f32_16x16x32_bf16 v[68:71], v[148:151], v[218:221], v[68:71]
	v_mfma_f32_16x16x32_bf16 v[64:67], v[176:179], v[218:221], v[64:67]
	s_setprio 0
	s_barrier
	s_add_i32 s54, s75, s65
	v_lshl_add_u64 v[222:223], s[58:59], 0, v[154:155]
	s_mov_b32 m0, s54
	ds_read_b128 v[180:183], v191 offset:16384
	ds_read_b128 v[194:197], v191 offset:17408
	ds_read_b128 v[198:201], v191 offset:18432
	ds_read_b128 v[202:205], v191 offset:19456
	ds_read_b128 v[206:209], v191 offset:20480
	ds_read_b128 v[210:213], v191 offset:21504
	ds_read_b128 v[214:217], v191 offset:22528
	ds_read_b128 v[218:221], v191 offset:23552
	global_load_lds_dwordx4 v[222:223], off
	s_add_i32 m0, s54, 0x2000
	s_add_u32 s54, s58, 0xb0000
	v_lshl_add_u64 v[224:225], s[58:59], 0, v[162:163]
	s_addc_u32 s55, s59, 0
	s_add_i32 s82, s76, s65
	global_load_lds_dwordx4 v[224:225], off
	v_lshl_add_u64 v[226:227], s[54:55], 0, v[154:155]
	s_mov_b32 m0, s82
	v_lshl_add_u64 v[228:229], s[60:61], 0, v[160:161]
	global_load_lds_dwordx4 v[226:227], off
	v_lshl_add_u64 v[226:227], s[54:55], 0, v[162:163]
	s_add_i32 m0, s82, 0x2000
	s_nop 0
	global_load_lds_dwordx4 v[226:227], off
	v_lshl_add_u64 v[226:227], s[60:61], 0, v[152:153]
	s_mov_b32 m0, s66
	s_nop 0
	global_load_lds_dwordx4 v[226:227], off
	s_mov_b32 m0, s67
	s_nop 0
	global_load_lds_dwordx4 v[228:229], off
	s_waitcnt vmcnt(8)
	s_waitcnt lgkmcnt(0)
	s_barrier
	s_setprio 1
	s_waitcnt lgkmcnt(0)
	v_mfma_f32_16x16x32_bf16 v[60:63], v[128:131], v[180:183], 0
	v_mfma_f32_16x16x32_bf16 v[56:59], v[136:139], v[180:183], 0
	v_mfma_f32_16x16x32_bf16 v[44:47], v[128:131], v[198:201], 0
	v_mfma_f32_16x16x32_bf16 v[40:43], v[136:139], v[198:201], 0
	v_mfma_f32_16x16x32_bf16 v[28:31], v[128:131], v[206:209], 0
	v_mfma_f32_16x16x32_bf16 v[24:27], v[136:139], v[206:209], 0
	v_mfma_f32_16x16x32_bf16 v[12:15], v[128:131], v[214:217], 0
	v_mfma_f32_16x16x32_bf16 v[8:11], v[136:139], v[214:217], 0
	v_mfma_f32_16x16x32_bf16 v[60:63], v[132:135], v[194:197], v[60:63]
	v_mfma_f32_16x16x32_bf16 v[56:59], v[140:143], v[194:197], v[56:59]
	v_mfma_f32_16x16x32_bf16 v[44:47], v[132:135], v[202:205], v[44:47]
	v_mfma_f32_16x16x32_bf16 v[40:43], v[140:143], v[202:205], v[40:43]
	v_mfma_f32_16x16x32_bf16 v[28:31], v[132:135], v[210:213], v[28:31]
	v_mfma_f32_16x16x32_bf16 v[24:27], v[140:143], v[210:213], v[24:27]
	v_mfma_f32_16x16x32_bf16 v[12:15], v[132:135], v[218:221], v[12:15]
	v_mfma_f32_16x16x32_bf16 v[8:11], v[140:143], v[218:221], v[8:11]
	s_setprio 0
	s_setprio 1
	v_mfma_f32_16x16x32_bf16 v[52:55], v[144:147], v[180:183], 0
	v_mfma_f32_16x16x32_bf16 v[48:51], v[172:175], v[180:183], 0
	v_mfma_f32_16x16x32_bf16 v[36:39], v[144:147], v[198:201], 0
	v_mfma_f32_16x16x32_bf16 v[32:35], v[172:175], v[198:201], 0
	v_mfma_f32_16x16x32_bf16 v[20:23], v[144:147], v[206:209], 0
	v_mfma_f32_16x16x32_bf16 v[16:19], v[172:175], v[206:209], 0
	v_mfma_f32_16x16x32_bf16 v[4:7], v[144:147], v[214:217], 0
	v_mfma_f32_16x16x32_bf16 v[0:3], v[172:175], v[214:217], 0
	v_mfma_f32_16x16x32_bf16 v[52:55], v[148:151], v[194:197], v[52:55]
	v_mfma_f32_16x16x32_bf16 v[48:51], v[176:179], v[194:197], v[48:51]
	v_mfma_f32_16x16x32_bf16 v[36:39], v[148:151], v[202:205], v[36:39]
	v_mfma_f32_16x16x32_bf16 v[32:35], v[176:179], v[202:205], v[32:35]
	v_mfma_f32_16x16x32_bf16 v[20:23], v[148:151], v[210:213], v[20:23]
	v_mfma_f32_16x16x32_bf16 v[16:19], v[176:179], v[210:213], v[16:19]
	v_mfma_f32_16x16x32_bf16 v[4:7], v[148:151], v[218:221], v[4:7]
	v_mfma_f32_16x16x32_bf16 v[0:3], v[176:179], v[218:221], v[0:3]
	s_setprio 0
	s_barrier
	s_add_i32 s82, 0, 0x18000
	s_add_i32 s83, 0, 0x1c000
	v_add_u32_e32 v140, s82, v186
	v_add_u32_e32 v176, s83, v186
	ds_read_b128 v[128:131], v140
	ds_read_b128 v[132:135], v140 offset:1024
	ds_read_b128 v[136:139], v140 offset:2048
	ds_read_b128 v[140:143], v140 offset:3072
	ds_read_b128 v[144:147], v176
	ds_read_b128 v[148:151], v176 offset:1024
	ds_read_b128 v[172:175], v176 offset:2048
	ds_read_b128 v[176:179], v176 offset:3072
	s_add_u32 s54, s60, 0xb0000
	s_addc_u32 s55, s61, 0
	s_mov_b32 m0, s68
	v_lshl_add_u64 v[230:231], s[54:55], 0, v[152:153]
	ds_read_b128 v[180:183], v191 offset:32768
	ds_read_b128 v[194:197], v191 offset:33792
	ds_read_b128 v[198:201], v191 offset:34816
	ds_read_b128 v[202:205], v191 offset:35840
	ds_read_b128 v[206:209], v191 offset:36864
	ds_read_b128 v[210:213], v191 offset:37888
	ds_read_b128 v[214:217], v191 offset:38912
	ds_read_b128 v[218:221], v191 offset:39936
	global_load_lds_dwordx4 v[230:231], off
	v_lshl_add_u64 v[230:231], s[54:55], 0, v[160:161]
	s_mov_b32 m0, s69
	s_nop 0
	global_load_lds_dwordx4 v[230:231], off
	s_waitcnt vmcnt(8)
	s_waitcnt lgkmcnt(0)
	s_barrier
	s_setprio 1
	s_waitcnt lgkmcnt(0)
	v_mfma_f32_16x16x32_bf16 v[124:127], v[128:131], v[180:183], v[124:127]
	v_mfma_f32_16x16x32_bf16 v[120:123], v[136:139], v[180:183], v[120:123]
	v_mfma_f32_16x16x32_bf16 v[104:107], v[136:139], v[198:201], v[104:107]
	v_mfma_f32_16x16x32_bf16 v[108:111], v[128:131], v[198:201], v[108:111]
	v_mfma_f32_16x16x32_bf16 v[92:95], v[128:131], v[206:209], v[92:95]
	v_mfma_f32_16x16x32_bf16 v[88:91], v[136:139], v[206:209], v[88:91]
	v_mfma_f32_16x16x32_bf16 v[72:75], v[136:139], v[214:217], v[72:75]
	v_mfma_f32_16x16x32_bf16 v[76:79], v[128:131], v[214:217], v[76:79]
	v_mfma_f32_16x16x32_bf16 v[124:127], v[132:135], v[194:197], v[124:127]
	v_mfma_f32_16x16x32_bf16 v[120:123], v[140:143], v[194:197], v[120:123]
	v_mfma_f32_16x16x32_bf16 v[104:107], v[140:143], v[202:205], v[104:107]
	v_mfma_f32_16x16x32_bf16 v[108:111], v[132:135], v[202:205], v[108:111]
	v_mfma_f32_16x16x32_bf16 v[92:95], v[132:135], v[210:213], v[92:95]
	v_mfma_f32_16x16x32_bf16 v[88:91], v[140:143], v[210:213], v[88:91]
	v_mfma_f32_16x16x32_bf16 v[72:75], v[140:143], v[218:221], v[72:75]
	v_mfma_f32_16x16x32_bf16 v[76:79], v[132:135], v[218:221], v[76:79]
	s_setprio 0
	s_setprio 1
	v_mfma_f32_16x16x32_bf16 v[116:119], v[144:147], v[180:183], v[116:119]
	v_mfma_f32_16x16x32_bf16 v[112:115], v[172:175], v[180:183], v[112:115]
	v_mfma_f32_16x16x32_bf16 v[96:99], v[172:175], v[198:201], v[96:99]
	v_mfma_f32_16x16x32_bf16 v[100:103], v[144:147], v[198:201], v[100:103]
	v_mfma_f32_16x16x32_bf16 v[84:87], v[144:147], v[206:209], v[84:87]
	v_mfma_f32_16x16x32_bf16 v[80:83], v[172:175], v[206:209], v[80:83]
	v_mfma_f32_16x16x32_bf16 v[64:67], v[172:175], v[214:217], v[64:67]
	v_mfma_f32_16x16x32_bf16 v[68:71], v[144:147], v[214:217], v[68:71]
	v_mfma_f32_16x16x32_bf16 v[116:119], v[148:151], v[194:197], v[116:119]
	v_mfma_f32_16x16x32_bf16 v[112:115], v[176:179], v[194:197], v[112:115]
	v_mfma_f32_16x16x32_bf16 v[96:99], v[176:179], v[202:205], v[96:99]
	v_mfma_f32_16x16x32_bf16 v[100:103], v[148:151], v[202:205], v[100:103]
	v_mfma_f32_16x16x32_bf16 v[84:87], v[148:151], v[210:213], v[84:87]
	v_mfma_f32_16x16x32_bf16 v[80:83], v[176:179], v[210:213], v[80:83]
	v_mfma_f32_16x16x32_bf16 v[64:67], v[176:179], v[218:221], v[64:67]
	v_mfma_f32_16x16x32_bf16 v[68:71], v[148:151], v[218:221], v[68:71]
	s_setprio 0
	s_barrier
	s_add_i32 s54, s82, s65
	v_lshl_add_u64 v[222:223], v[222:223], 0, s[28:29]
	s_mov_b32 m0, s54
	ds_read_b128 v[180:183], v191 offset:49152
	ds_read_b128 v[194:197], v191 offset:50176
	ds_read_b128 v[198:201], v191 offset:51200
	ds_read_b128 v[202:205], v191 offset:52224
	ds_read_b128 v[206:209], v191 offset:53248
	ds_read_b128 v[210:213], v191 offset:54272
	ds_read_b128 v[214:217], v191 offset:55296
	ds_read_b128 v[218:221], v191 offset:56320
	global_load_lds_dwordx4 v[222:223], off
	s_add_i32 m0, s54, 0x2000
	s_add_u32 s54, s58, 0xb0080
	v_lshl_add_u64 v[222:223], v[224:225], 0, s[28:29]
	s_addc_u32 s55, s59, 0
	s_add_i32 s58, s83, s65
	global_load_lds_dwordx4 v[222:223], off
	v_lshl_add_u64 v[222:223], s[54:55], 0, v[154:155]
	s_mov_b32 m0, s58
	s_nop 0
	global_load_lds_dwordx4 v[222:223], off
	v_lshl_add_u64 v[222:223], s[54:55], 0, v[162:163]
	s_add_i32 m0, s58, 0x2000
	s_nop 0
	global_load_lds_dwordx4 v[222:223], off
	v_lshl_add_u64 v[222:223], v[226:227], 0, s[28:29]
	s_mov_b32 m0, s3
	s_nop 0
	global_load_lds_dwordx4 v[222:223], off
	v_lshl_add_u64 v[222:223], v[228:229], 0, s[28:29]
	s_mov_b32 m0, s71
	s_nop 0
	global_load_lds_dwordx4 v[222:223], off
	s_waitcnt vmcnt(8)
	s_waitcnt lgkmcnt(0)
	s_barrier
	s_setprio 1
	s_waitcnt lgkmcnt(0)
	v_mfma_f32_16x16x32_bf16 v[60:63], v[128:131], v[180:183], v[60:63]
	v_mfma_f32_16x16x32_bf16 v[56:59], v[136:139], v[180:183], v[56:59]
	v_mfma_f32_16x16x32_bf16 v[40:43], v[136:139], v[198:201], v[40:43]
	v_mfma_f32_16x16x32_bf16 v[44:47], v[128:131], v[198:201], v[44:47]
	v_mfma_f32_16x16x32_bf16 v[28:31], v[128:131], v[206:209], v[28:31]
	v_mfma_f32_16x16x32_bf16 v[24:27], v[136:139], v[206:209], v[24:27]
	v_mfma_f32_16x16x32_bf16 v[8:11], v[136:139], v[214:217], v[8:11]
	v_mfma_f32_16x16x32_bf16 v[12:15], v[128:131], v[214:217], v[12:15]
	v_mfma_f32_16x16x32_bf16 v[60:63], v[132:135], v[194:197], v[60:63]
	v_mfma_f32_16x16x32_bf16 v[56:59], v[140:143], v[194:197], v[56:59]
	v_mfma_f32_16x16x32_bf16 v[40:43], v[140:143], v[202:205], v[40:43]
	v_mfma_f32_16x16x32_bf16 v[44:47], v[132:135], v[202:205], v[44:47]
	v_mfma_f32_16x16x32_bf16 v[28:31], v[132:135], v[210:213], v[28:31]
	v_mfma_f32_16x16x32_bf16 v[24:27], v[140:143], v[210:213], v[24:27]
	v_mfma_f32_16x16x32_bf16 v[8:11], v[140:143], v[218:221], v[8:11]
	v_mfma_f32_16x16x32_bf16 v[12:15], v[132:135], v[218:221], v[12:15]
	s_setprio 0
	s_setprio 1
	v_mfma_f32_16x16x32_bf16 v[52:55], v[144:147], v[180:183], v[52:55]
	v_mfma_f32_16x16x32_bf16 v[48:51], v[172:175], v[180:183], v[48:51]
	v_mfma_f32_16x16x32_bf16 v[32:35], v[172:175], v[198:201], v[32:35]
	v_mfma_f32_16x16x32_bf16 v[36:39], v[144:147], v[198:201], v[36:39]
	v_mfma_f32_16x16x32_bf16 v[20:23], v[144:147], v[206:209], v[20:23]
	v_mfma_f32_16x16x32_bf16 v[16:19], v[172:175], v[206:209], v[16:19]
	v_mfma_f32_16x16x32_bf16 v[0:3], v[172:175], v[214:217], v[0:3]
	v_mfma_f32_16x16x32_bf16 v[4:7], v[144:147], v[214:217], v[4:7]
	v_mfma_f32_16x16x32_bf16 v[52:55], v[148:151], v[194:197], v[52:55]
	v_mfma_f32_16x16x32_bf16 v[48:51], v[176:179], v[194:197], v[48:51]
	v_mfma_f32_16x16x32_bf16 v[32:35], v[176:179], v[202:205], v[32:35]
	v_mfma_f32_16x16x32_bf16 v[36:39], v[148:151], v[202:205], v[36:39]
	v_mfma_f32_16x16x32_bf16 v[20:23], v[148:151], v[210:213], v[20:23]
	v_mfma_f32_16x16x32_bf16 v[16:19], v[176:179], v[210:213], v[16:19]
	v_mfma_f32_16x16x32_bf16 v[0:3], v[176:179], v[218:221], v[0:3]
	v_mfma_f32_16x16x32_bf16 v[4:7], v[148:151], v[218:221], v[4:7]
	s_setprio 0
	s_barrier
	s_add_i32 s81, s81, 2
	s_add_u32 s79, s79, 0x100
	s_addc_u32 s80, s80, 0
	s_cmp_gt_u32 s81, 41
	s_mov_b64 s[54:55], s[56:57]
.LBB0_610:
	ds_read_b128 v[128:131], v189
	ds_read_b128 v[132:135], v189 offset:1024
	ds_read_b128 v[136:139], v189 offset:2048
	ds_read_b128 v[140:143], v189 offset:3072
	ds_read_b128 v[144:147], v190
	ds_read_b128 v[148:151], v190 offset:1024
	ds_read_b128 v[172:175], v190 offset:2048
	ds_read_b128 v[176:179], v190 offset:3072
	s_add_u32 s56, s54, 0x100
	s_addc_u32 s57, s55, 0
	s_cmp_eq_u32 s81, 40
	s_cselect_b32 s61, s17, s57
	s_cselect_b32 s60, s16, s56
	s_cselect_b32 s59, s53, s80
	s_cselect_b32 s58, s52, s79
	v_lshl_add_u64 v[222:223], s[54:55], 0, v[166:167]
	s_add_i32 m0, s66, 0xc000
	ds_read_b128 v[180:183], v191
	ds_read_b128 v[194:197], v191 offset:1024
	ds_read_b128 v[198:201], v191 offset:2048
	ds_read_b128 v[202:205], v191 offset:3072
	ds_read_b128 v[206:209], v191 offset:4096
	ds_read_b128 v[210:213], v191 offset:5120
	ds_read_b128 v[214:217], v191 offset:6144
	ds_read_b128 v[218:221], v191 offset:7168
	global_load_lds_dwordx4 v[222:223], off
	v_lshl_add_u64 v[222:223], s[54:55], 0, v[164:165]
	s_add_i32 m0, s66, 0xe000
	s_nop 0
	global_load_lds_dwordx4 v[222:223], off
	s_waitcnt vmcnt(8)
	s_waitcnt lgkmcnt(0)
	s_barrier
	s_setprio 1
	s_waitcnt lgkmcnt(0)
	v_mfma_f32_16x16x32_bf16 v[124:127], v[128:131], v[180:183], v[124:127]
	v_mfma_f32_16x16x32_bf16 v[120:123], v[136:139], v[180:183], v[120:123]
	v_mfma_f32_16x16x32_bf16 v[104:107], v[136:139], v[198:201], v[104:107]
	v_mfma_f32_16x16x32_bf16 v[108:111], v[128:131], v[198:201], v[108:111]
	v_mfma_f32_16x16x32_bf16 v[92:95], v[128:131], v[206:209], v[92:95]
	v_mfma_f32_16x16x32_bf16 v[88:91], v[136:139], v[206:209], v[88:91]
	v_mfma_f32_16x16x32_bf16 v[72:75], v[136:139], v[214:217], v[72:75]
	v_mfma_f32_16x16x32_bf16 v[76:79], v[128:131], v[214:217], v[76:79]
	v_mfma_f32_16x16x32_bf16 v[124:127], v[132:135], v[194:197], v[124:127]
	v_mfma_f32_16x16x32_bf16 v[120:123], v[140:143], v[194:197], v[120:123]
	v_mfma_f32_16x16x32_bf16 v[104:107], v[140:143], v[202:205], v[104:107]
	v_mfma_f32_16x16x32_bf16 v[108:111], v[132:135], v[202:205], v[108:111]
	v_mfma_f32_16x16x32_bf16 v[92:95], v[132:135], v[210:213], v[92:95]
	v_mfma_f32_16x16x32_bf16 v[88:91], v[140:143], v[210:213], v[88:91]
	v_mfma_f32_16x16x32_bf16 v[72:75], v[140:143], v[218:221], v[72:75]
	v_mfma_f32_16x16x32_bf16 v[76:79], v[132:135], v[218:221], v[76:79]
	s_setprio 0
	s_setprio 1
	v_mfma_f32_16x16x32_bf16 v[116:119], v[144:147], v[180:183], v[116:119]
	v_mfma_f32_16x16x32_bf16 v[112:115], v[172:175], v[180:183], v[112:115]
	v_mfma_f32_16x16x32_bf16 v[96:99], v[172:175], v[198:201], v[96:99]
	v_mfma_f32_16x16x32_bf16 v[100:103], v[144:147], v[198:201], v[100:103]
	v_mfma_f32_16x16x32_bf16 v[84:87], v[144:147], v[206:209], v[84:87]
	v_mfma_f32_16x16x32_bf16 v[80:83], v[172:175], v[206:209], v[80:83]
	v_mfma_f32_16x16x32_bf16 v[64:67], v[172:175], v[214:217], v[64:67]
	v_mfma_f32_16x16x32_bf16 v[68:71], v[144:147], v[214:217], v[68:71]
	v_mfma_f32_16x16x32_bf16 v[116:119], v[148:151], v[194:197], v[116:119]
	v_mfma_f32_16x16x32_bf16 v[112:115], v[176:179], v[194:197], v[112:115]
	v_mfma_f32_16x16x32_bf16 v[96:99], v[176:179], v[202:205], v[96:99]
	v_mfma_f32_16x16x32_bf16 v[100:103], v[148:151], v[202:205], v[100:103]
	v_mfma_f32_16x16x32_bf16 v[84:87], v[148:151], v[210:213], v[84:87]
	v_mfma_f32_16x16x32_bf16 v[80:83], v[176:179], v[210:213], v[80:83]
	v_mfma_f32_16x16x32_bf16 v[64:67], v[176:179], v[218:221], v[64:67]
	v_mfma_f32_16x16x32_bf16 v[68:71], v[148:151], v[218:221], v[68:71]
	s_setprio 0
	s_barrier
	s_add_i32 s54, s75, s65
	v_lshl_add_u64 v[222:223], s[58:59], 0, v[154:155]
	s_mov_b32 m0, s54
	ds_read_b128 v[180:183], v191 offset:16384
	ds_read_b128 v[194:197], v191 offset:17408
	ds_read_b128 v[198:201], v191 offset:18432
	ds_read_b128 v[202:205], v191 offset:19456
	ds_read_b128 v[206:209], v191 offset:20480
	ds_read_b128 v[210:213], v191 offset:21504
	ds_read_b128 v[214:217], v191 offset:22528
	ds_read_b128 v[218:221], v191 offset:23552
	global_load_lds_dwordx4 v[222:223], off
	s_add_i32 m0, s54, 0x2000
	s_add_u32 s54, s58, 0xb0000
	v_lshl_add_u64 v[224:225], s[58:59], 0, v[162:163]
	s_addc_u32 s55, s59, 0
	s_add_i32 s82, s76, s65
	global_load_lds_dwordx4 v[224:225], off
	v_lshl_add_u64 v[226:227], s[54:55], 0, v[154:155]
	s_mov_b32 m0, s82
	v_lshl_add_u64 v[228:229], s[60:61], 0, v[160:161]
	global_load_lds_dwordx4 v[226:227], off
	v_lshl_add_u64 v[226:227], s[54:55], 0, v[162:163]
	s_add_i32 m0, s82, 0x2000
	s_nop 0
	global_load_lds_dwordx4 v[226:227], off
	v_lshl_add_u64 v[226:227], s[60:61], 0, v[152:153]
	s_mov_b32 m0, s66
	s_nop 0
	global_load_lds_dwordx4 v[226:227], off
	s_mov_b32 m0, s67
	s_nop 0
	global_load_lds_dwordx4 v[228:229], off
	s_waitcnt vmcnt(8)
	s_waitcnt lgkmcnt(0)
	s_barrier
	s_setprio 1
	s_waitcnt lgkmcnt(0)
	v_mfma_f32_16x16x32_bf16 v[60:63], v[128:131], v[180:183], v[60:63]
	v_mfma_f32_16x16x32_bf16 v[56:59], v[136:139], v[180:183], v[56:59]
	v_mfma_f32_16x16x32_bf16 v[40:43], v[136:139], v[198:201], v[40:43]
	v_mfma_f32_16x16x32_bf16 v[44:47], v[128:131], v[198:201], v[44:47]
	v_mfma_f32_16x16x32_bf16 v[28:31], v[128:131], v[206:209], v[28:31]
	v_mfma_f32_16x16x32_bf16 v[24:27], v[136:139], v[206:209], v[24:27]
	v_mfma_f32_16x16x32_bf16 v[8:11], v[136:139], v[214:217], v[8:11]
	v_mfma_f32_16x16x32_bf16 v[12:15], v[128:131], v[214:217], v[12:15]
	v_mfma_f32_16x16x32_bf16 v[60:63], v[132:135], v[194:197], v[60:63]
	v_mfma_f32_16x16x32_bf16 v[56:59], v[140:143], v[194:197], v[56:59]
	v_mfma_f32_16x16x32_bf16 v[40:43], v[140:143], v[202:205], v[40:43]
	v_mfma_f32_16x16x32_bf16 v[44:47], v[132:135], v[202:205], v[44:47]
	v_mfma_f32_16x16x32_bf16 v[28:31], v[132:135], v[210:213], v[28:31]
	v_mfma_f32_16x16x32_bf16 v[24:27], v[140:143], v[210:213], v[24:27]
	v_mfma_f32_16x16x32_bf16 v[8:11], v[140:143], v[218:221], v[8:11]
	v_mfma_f32_16x16x32_bf16 v[12:15], v[132:135], v[218:221], v[12:15]
	s_setprio 0
	s_setprio 1
	v_mfma_f32_16x16x32_bf16 v[52:55], v[144:147], v[180:183], v[52:55]
	v_mfma_f32_16x16x32_bf16 v[48:51], v[172:175], v[180:183], v[48:51]
	v_mfma_f32_16x16x32_bf16 v[32:35], v[172:175], v[198:201], v[32:35]
	v_mfma_f32_16x16x32_bf16 v[36:39], v[144:147], v[198:201], v[36:39]
	v_mfma_f32_16x16x32_bf16 v[20:23], v[144:147], v[206:209], v[20:23]
	v_mfma_f32_16x16x32_bf16 v[16:19], v[172:175], v[206:209], v[16:19]
	v_mfma_f32_16x16x32_bf16 v[0:3], v[172:175], v[214:217], v[0:3]
	v_mfma_f32_16x16x32_bf16 v[4:7], v[144:147], v[214:217], v[4:7]
	v_mfma_f32_16x16x32_bf16 v[52:55], v[148:151], v[194:197], v[52:55]
	v_mfma_f32_16x16x32_bf16 v[48:51], v[176:179], v[194:197], v[48:51]
	v_mfma_f32_16x16x32_bf16 v[32:35], v[176:179], v[202:205], v[32:35]
	v_mfma_f32_16x16x32_bf16 v[36:39], v[148:151], v[202:205], v[36:39]
	v_mfma_f32_16x16x32_bf16 v[20:23], v[148:151], v[210:213], v[20:23]
	v_mfma_f32_16x16x32_bf16 v[16:19], v[176:179], v[210:213], v[16:19]
	v_mfma_f32_16x16x32_bf16 v[0:3], v[176:179], v[218:221], v[0:3]
	v_mfma_f32_16x16x32_bf16 v[4:7], v[148:151], v[218:221], v[4:7]
	s_setprio 0
	s_barrier
	s_add_i32 s82, 0, 0x18000
	s_add_i32 s83, 0, 0x1c000
	v_add_u32_e32 v140, s82, v186
	v_add_u32_e32 v176, s83, v186
	ds_read_b128 v[128:131], v140
	ds_read_b128 v[132:135], v140 offset:1024
	ds_read_b128 v[136:139], v140 offset:2048
	ds_read_b128 v[140:143], v140 offset:3072
	ds_read_b128 v[144:147], v176
	ds_read_b128 v[148:151], v176 offset:1024
	ds_read_b128 v[172:175], v176 offset:2048
	ds_read_b128 v[176:179], v176 offset:3072
	s_add_u32 s54, s60, 0xb0000
	s_addc_u32 s55, s61, 0
	s_mov_b32 m0, s68
	v_lshl_add_u64 v[230:231], s[54:55], 0, v[152:153]
	ds_read_b128 v[180:183], v191 offset:32768
	ds_read_b128 v[194:197], v191 offset:33792
	ds_read_b128 v[198:201], v191 offset:34816
	ds_read_b128 v[202:205], v191 offset:35840
	ds_read_b128 v[206:209], v191 offset:36864
	ds_read_b128 v[210:213], v191 offset:37888
	ds_read_b128 v[214:217], v191 offset:38912
	ds_read_b128 v[218:221], v191 offset:39936
	global_load_lds_dwordx4 v[230:231], off
	v_lshl_add_u64 v[230:231], s[54:55], 0, v[160:161]
	s_mov_b32 m0, s69
	s_nop 0
	global_load_lds_dwordx4 v[230:231], off
	s_waitcnt vmcnt(8)
	s_waitcnt lgkmcnt(0)
	s_barrier
	s_setprio 1
	s_waitcnt lgkmcnt(0)
	v_mfma_f32_16x16x32_bf16 v[124:127], v[128:131], v[180:183], v[124:127]
	v_mfma_f32_16x16x32_bf16 v[120:123], v[136:139], v[180:183], v[120:123]
	v_mfma_f32_16x16x32_bf16 v[104:107], v[136:139], v[198:201], v[104:107]
	v_mfma_f32_16x16x32_bf16 v[108:111], v[128:131], v[198:201], v[108:111]
	v_mfma_f32_16x16x32_bf16 v[92:95], v[128:131], v[206:209], v[92:95]
	v_mfma_f32_16x16x32_bf16 v[88:91], v[136:139], v[206:209], v[88:91]
	v_mfma_f32_16x16x32_bf16 v[72:75], v[136:139], v[214:217], v[72:75]
	v_mfma_f32_16x16x32_bf16 v[76:79], v[128:131], v[214:217], v[76:79]
	v_mfma_f32_16x16x32_bf16 v[124:127], v[132:135], v[194:197], v[124:127]
	v_mfma_f32_16x16x32_bf16 v[120:123], v[140:143], v[194:197], v[120:123]
	v_mfma_f32_16x16x32_bf16 v[104:107], v[140:143], v[202:205], v[104:107]
	v_mfma_f32_16x16x32_bf16 v[108:111], v[132:135], v[202:205], v[108:111]
	v_mfma_f32_16x16x32_bf16 v[92:95], v[132:135], v[210:213], v[92:95]
	v_mfma_f32_16x16x32_bf16 v[88:91], v[140:143], v[210:213], v[88:91]
	v_mfma_f32_16x16x32_bf16 v[72:75], v[140:143], v[218:221], v[72:75]
	v_mfma_f32_16x16x32_bf16 v[76:79], v[132:135], v[218:221], v[76:79]
	s_setprio 0
	s_setprio 1
	v_mfma_f32_16x16x32_bf16 v[116:119], v[144:147], v[180:183], v[116:119]
	v_mfma_f32_16x16x32_bf16 v[112:115], v[172:175], v[180:183], v[112:115]
	v_mfma_f32_16x16x32_bf16 v[96:99], v[172:175], v[198:201], v[96:99]
	v_mfma_f32_16x16x32_bf16 v[100:103], v[144:147], v[198:201], v[100:103]
	v_mfma_f32_16x16x32_bf16 v[84:87], v[144:147], v[206:209], v[84:87]
	v_mfma_f32_16x16x32_bf16 v[80:83], v[172:175], v[206:209], v[80:83]
	v_mfma_f32_16x16x32_bf16 v[64:67], v[172:175], v[214:217], v[64:67]
	v_mfma_f32_16x16x32_bf16 v[68:71], v[144:147], v[214:217], v[68:71]
	v_mfma_f32_16x16x32_bf16 v[116:119], v[148:151], v[194:197], v[116:119]
	v_mfma_f32_16x16x32_bf16 v[112:115], v[176:179], v[194:197], v[112:115]
	v_mfma_f32_16x16x32_bf16 v[96:99], v[176:179], v[202:205], v[96:99]
	v_mfma_f32_16x16x32_bf16 v[100:103], v[148:151], v[202:205], v[100:103]
	v_mfma_f32_16x16x32_bf16 v[84:87], v[148:151], v[210:213], v[84:87]
	v_mfma_f32_16x16x32_bf16 v[80:83], v[176:179], v[210:213], v[80:83]
	v_mfma_f32_16x16x32_bf16 v[64:67], v[176:179], v[218:221], v[64:67]
	v_mfma_f32_16x16x32_bf16 v[68:71], v[148:151], v[218:221], v[68:71]
	s_setprio 0
	s_barrier
	s_add_i32 s54, s82, s65
	v_lshl_add_u64 v[222:223], v[222:223], 0, s[28:29]
	s_mov_b32 m0, s54
	ds_read_b128 v[180:183], v191 offset:49152
	ds_read_b128 v[194:197], v191 offset:50176
	ds_read_b128 v[198:201], v191 offset:51200
	ds_read_b128 v[202:205], v191 offset:52224
	ds_read_b128 v[206:209], v191 offset:53248
	ds_read_b128 v[210:213], v191 offset:54272
	ds_read_b128 v[214:217], v191 offset:55296
	ds_read_b128 v[218:221], v191 offset:56320
	global_load_lds_dwordx4 v[222:223], off
	s_add_i32 m0, s54, 0x2000
	s_add_u32 s54, s58, 0xb0080
	v_lshl_add_u64 v[222:223], v[224:225], 0, s[28:29]
	s_addc_u32 s55, s59, 0
	s_add_i32 s58, s83, s65
	global_load_lds_dwordx4 v[222:223], off
	v_lshl_add_u64 v[222:223], s[54:55], 0, v[154:155]
	s_mov_b32 m0, s58
	s_nop 0
	global_load_lds_dwordx4 v[222:223], off
	v_lshl_add_u64 v[222:223], s[54:55], 0, v[162:163]
	s_add_i32 m0, s58, 0x2000
	s_nop 0
	global_load_lds_dwordx4 v[222:223], off
	v_lshl_add_u64 v[222:223], v[226:227], 0, s[28:29]
	s_mov_b32 m0, s3
	s_nop 0
	global_load_lds_dwordx4 v[222:223], off
	v_lshl_add_u64 v[222:223], v[228:229], 0, s[28:29]
	s_mov_b32 m0, s71
	s_nop 0
	global_load_lds_dwordx4 v[222:223], off
	s_waitcnt vmcnt(8)
	s_waitcnt lgkmcnt(0)
	s_barrier
	s_setprio 1
	s_waitcnt lgkmcnt(0)
	v_mfma_f32_16x16x32_bf16 v[60:63], v[128:131], v[180:183], v[60:63]
	v_mfma_f32_16x16x32_bf16 v[56:59], v[136:139], v[180:183], v[56:59]
	v_mfma_f32_16x16x32_bf16 v[40:43], v[136:139], v[198:201], v[40:43]
	v_mfma_f32_16x16x32_bf16 v[44:47], v[128:131], v[198:201], v[44:47]
	v_mfma_f32_16x16x32_bf16 v[28:31], v[128:131], v[206:209], v[28:31]
	v_mfma_f32_16x16x32_bf16 v[24:27], v[136:139], v[206:209], v[24:27]
	v_mfma_f32_16x16x32_bf16 v[8:11], v[136:139], v[214:217], v[8:11]
	v_mfma_f32_16x16x32_bf16 v[12:15], v[128:131], v[214:217], v[12:15]
	v_mfma_f32_16x16x32_bf16 v[60:63], v[132:135], v[194:197], v[60:63]
	v_mfma_f32_16x16x32_bf16 v[56:59], v[140:143], v[194:197], v[56:59]
	v_mfma_f32_16x16x32_bf16 v[40:43], v[140:143], v[202:205], v[40:43]
	v_mfma_f32_16x16x32_bf16 v[44:47], v[132:135], v[202:205], v[44:47]
	v_mfma_f32_16x16x32_bf16 v[28:31], v[132:135], v[210:213], v[28:31]
	v_mfma_f32_16x16x32_bf16 v[24:27], v[140:143], v[210:213], v[24:27]
	v_mfma_f32_16x16x32_bf16 v[8:11], v[140:143], v[218:221], v[8:11]
	v_mfma_f32_16x16x32_bf16 v[12:15], v[132:135], v[218:221], v[12:15]
	s_setprio 0
	s_setprio 1
	v_mfma_f32_16x16x32_bf16 v[52:55], v[144:147], v[180:183], v[52:55]
	v_mfma_f32_16x16x32_bf16 v[48:51], v[172:175], v[180:183], v[48:51]
	v_mfma_f32_16x16x32_bf16 v[32:35], v[172:175], v[198:201], v[32:35]
	v_mfma_f32_16x16x32_bf16 v[36:39], v[144:147], v[198:201], v[36:39]
	v_mfma_f32_16x16x32_bf16 v[20:23], v[144:147], v[206:209], v[20:23]
	v_mfma_f32_16x16x32_bf16 v[16:19], v[172:175], v[206:209], v[16:19]
	v_mfma_f32_16x16x32_bf16 v[0:3], v[172:175], v[214:217], v[0:3]
	v_mfma_f32_16x16x32_bf16 v[4:7], v[144:147], v[214:217], v[4:7]
	v_mfma_f32_16x16x32_bf16 v[52:55], v[148:151], v[194:197], v[52:55]
	v_mfma_f32_16x16x32_bf16 v[48:51], v[176:179], v[194:197], v[48:51]
	v_mfma_f32_16x16x32_bf16 v[32:35], v[176:179], v[202:205], v[32:35]
	v_mfma_f32_16x16x32_bf16 v[36:39], v[148:151], v[202:205], v[36:39]
	v_mfma_f32_16x16x32_bf16 v[20:23], v[148:151], v[210:213], v[20:23]
	v_mfma_f32_16x16x32_bf16 v[16:19], v[176:179], v[210:213], v[16:19]
	v_mfma_f32_16x16x32_bf16 v[0:3], v[176:179], v[218:221], v[0:3]
	v_mfma_f32_16x16x32_bf16 v[4:7], v[148:151], v[218:221], v[4:7]
	s_setprio 0
	s_barrier
	s_add_i32 s81, s81, 2
	s_add_u32 s79, s79, 0x100
	s_addc_u32 s80, s80, 0
	s_cmp_gt_u32 s81, 41
	s_mov_b64 s[54:55], s[56:57]
	s_cbranch_scc0 .LBB0_610
	s_and_b64 vcc, exec, s[30:31]
	s_cbranch_vccz .LBB0_613
	s_barrier

.LBB0_873:
	s_ashr_i32 s49, s48, 31
	s_lshl_b64 s[50:51], s[48:49], 19
	s_add_u32 s50, s35, s50
	s_addc_u32 s51, s60, s51
	s_and_b64 s[52:53], s[10:11], exec
	s_cselect_b32 s49, s51, s59
	s_cselect_b32 s80, s50, s58
	s_ashr_i32 s47, s46, 31
	s_lshl_b64 s[52:53], s[46:47], 19
	s_add_u32 s52, s61, s52
	s_addc_u32 s53, s62, s53
	s_and_b64 s[82:83], s[10:11], exec
	s_cselect_b32 s81, s53, s57
	s_cselect_b32 s82, s52, s56
	s_lshl_b32 s47, s54, 8
	v_add_u32_e32 v0, s47, v151
	s_add_u32 s83, s56, 0x100
	v_ashrrev_i32_e32 v1, 31, v0
	s_addc_u32 s84, s57, 0
	v_lshl_add_u64 v[144:145], v[0:1], 4, s[20:21]
	s_add_u32 s54, s58, 0x40080
	s_addc_u32 s55, s59, 0
	s_mov_b32 s85, -2
	s_mov_b64 s[56:57], 0
	v_add_u32_e32 v146, s73, v149
	ds_read_b128 v[162:165], v146
	ds_read_b128 v[166:169], v146 offset:1024
	ds_read_b128 v[170:173], v146 offset:2048
	ds_read_b128 v[174:177], v146 offset:3072
	v_add_u32_e32 v146, s74, v149
	ds_read_b128 v[178:181], v146
	ds_read_b128 v[186:189], v146 offset:1024
	ds_read_b128 v[190:193], v146 offset:2048
	ds_read_b128 v[194:197], v146 offset:3072
	s_add_u32 s58, s54, 0xfffc0080
	s_addc_u32 s59, s55, -1
	s_and_b64 s[56:57], s[56:57], exec
	s_cselect_b32 s59, s49, s59
	s_cselect_b32 s58, s80, s58
	s_cselect_b32 s57, s81, s84
	s_cselect_b32 s56, s82, s83
	v_lshl_add_u64 v[182:183], s[54:55], 0, v[138:139]
	s_add_i32 m0, s64, 0xc000
	ds_read_b128 v[198:201], v154
	ds_read_b128 v[202:205], v154 offset:1024
	ds_read_b128 v[206:209], v154 offset:2048
	ds_read_b128 v[210:213], v154 offset:3072
	ds_read_b128 v[214:217], v154 offset:4096
	ds_read_b128 v[218:221], v154 offset:5120
	ds_read_b128 v[222:225], v154 offset:6144
	ds_read_b128 v[226:229], v154 offset:7168
	global_load_lds_dwordx4 v[182:183], off
	v_lshl_add_u64 v[182:183], s[54:55], 0, v[136:137]
	s_add_i32 m0, s64, 0xe000
	s_nop 0
	global_load_lds_dwordx4 v[182:183], off
	s_waitcnt vmcnt(8)
	s_waitcnt lgkmcnt(0)
	s_barrier
	s_setprio 1
	s_waitcnt lgkmcnt(0)
	v_mfma_f32_16x16x32_bf16 v[124:127], v[162:165], v[198:201], 0
	v_mfma_f32_16x16x32_bf16 v[120:123], v[170:173], v[198:201], 0
	v_mfma_f32_16x16x32_bf16 v[112:115], v[162:165], v[206:209], 0
	v_mfma_f32_16x16x32_bf16 v[104:107], v[170:173], v[206:209], 0
	v_mfma_f32_16x16x32_bf16 v[96:99], v[162:165], v[214:217], 0
	v_mfma_f32_16x16x32_bf16 v[88:91], v[170:173], v[214:217], 0
	v_mfma_f32_16x16x32_bf16 v[80:83], v[162:165], v[222:225], 0
	v_mfma_f32_16x16x32_bf16 v[72:75], v[170:173], v[222:225], 0
	v_mfma_f32_16x16x32_bf16 v[124:127], v[166:169], v[202:205], v[124:127]
	v_mfma_f32_16x16x32_bf16 v[120:123], v[174:177], v[202:205], v[120:123]
	v_mfma_f32_16x16x32_bf16 v[112:115], v[166:169], v[210:213], v[112:115]
	v_mfma_f32_16x16x32_bf16 v[104:107], v[174:177], v[210:213], v[104:107]
	v_mfma_f32_16x16x32_bf16 v[96:99], v[166:169], v[218:221], v[96:99]
	v_mfma_f32_16x16x32_bf16 v[88:91], v[174:177], v[218:221], v[88:91]
	v_mfma_f32_16x16x32_bf16 v[80:83], v[166:169], v[226:229], v[80:83]
	v_mfma_f32_16x16x32_bf16 v[72:75], v[174:177], v[226:229], v[72:75]
	s_setprio 0
	s_setprio 1
	v_mfma_f32_16x16x32_bf16 v[116:119], v[178:181], v[198:201], 0
	v_mfma_f32_16x16x32_bf16 v[108:111], v[190:193], v[198:201], 0
	v_mfma_f32_16x16x32_bf16 v[100:103], v[178:181], v[206:209], 0
	v_mfma_f32_16x16x32_bf16 v[92:95], v[190:193], v[206:209], 0
	v_mfma_f32_16x16x32_bf16 v[84:87], v[178:181], v[214:217], 0
	v_mfma_f32_16x16x32_bf16 v[76:79], v[190:193], v[214:217], 0
	v_mfma_f32_16x16x32_bf16 v[68:71], v[178:181], v[222:225], 0
	v_mfma_f32_16x16x32_bf16 v[64:67], v[190:193], v[222:225], 0
	v_mfma_f32_16x16x32_bf16 v[116:119], v[186:189], v[202:205], v[116:119]
	v_mfma_f32_16x16x32_bf16 v[108:111], v[194:197], v[202:205], v[108:111]
	v_mfma_f32_16x16x32_bf16 v[100:103], v[186:189], v[210:213], v[100:103]
	v_mfma_f32_16x16x32_bf16 v[92:95], v[194:197], v[210:213], v[92:95]
	v_mfma_f32_16x16x32_bf16 v[84:87], v[186:189], v[218:221], v[84:87]
	v_mfma_f32_16x16x32_bf16 v[76:79], v[194:197], v[218:221], v[76:79]
	v_mfma_f32_16x16x32_bf16 v[68:71], v[186:189], v[226:229], v[68:71]
	v_mfma_f32_16x16x32_bf16 v[64:67], v[194:197], v[226:229], v[64:67]
	s_setprio 0
	s_barrier
	s_add_i32 s86, s73, s63
	v_lshl_add_u64 v[182:183], s[56:57], 0, v[130:131]
	s_mov_b32 m0, s86
	ds_read_b128 v[198:201], v154 offset:16384
	ds_read_b128 v[202:205], v154 offset:17408
	ds_read_b128 v[206:209], v154 offset:18432
	ds_read_b128 v[210:213], v154 offset:19456
	ds_read_b128 v[214:217], v154 offset:20480
	ds_read_b128 v[218:221], v154 offset:21504
	ds_read_b128 v[222:225], v154 offset:22528
	ds_read_b128 v[226:229], v154 offset:23552
	global_load_lds_dwordx4 v[182:183], off
	s_add_i32 m0, s86, 0x2000
	s_add_u32 s86, s56, 0x40000
	v_lshl_add_u64 v[230:231], s[56:57], 0, v[134:135]
	s_addc_u32 s87, s57, 0
	s_add_i32 s88, s74, s63
	global_load_lds_dwordx4 v[230:231], off
	v_lshl_add_u64 v[232:233], s[86:87], 0, v[130:131]
	s_mov_b32 m0, s88
	v_lshl_add_u64 v[234:235], s[58:59], 0, v[132:133]
	global_load_lds_dwordx4 v[232:233], off
	v_lshl_add_u64 v[232:233], s[86:87], 0, v[134:135]
	s_add_i32 m0, s88, 0x2000
	s_nop 0
	global_load_lds_dwordx4 v[232:233], off
	v_lshl_add_u64 v[232:233], s[58:59], 0, v[128:129]
	s_mov_b32 m0, s64
	s_nop 0
	global_load_lds_dwordx4 v[232:233], off
	s_mov_b32 m0, s65
	s_nop 0
	global_load_lds_dwordx4 v[234:235], off
	s_waitcnt vmcnt(8)
	s_waitcnt lgkmcnt(0)
	s_barrier
	s_setprio 1
	s_waitcnt lgkmcnt(0)
	v_mfma_f32_16x16x32_bf16 v[60:63], v[162:165], v[198:201], 0
	v_mfma_f32_16x16x32_bf16 v[56:59], v[170:173], v[198:201], 0
	v_mfma_f32_16x16x32_bf16 v[48:51], v[162:165], v[206:209], 0
	v_mfma_f32_16x16x32_bf16 v[40:43], v[170:173], v[206:209], 0
	v_mfma_f32_16x16x32_bf16 v[32:35], v[162:165], v[214:217], 0
	v_mfma_f32_16x16x32_bf16 v[24:27], v[170:173], v[214:217], 0
	v_mfma_f32_16x16x32_bf16 v[16:19], v[162:165], v[222:225], 0
	v_mfma_f32_16x16x32_bf16 v[8:11], v[170:173], v[222:225], 0
	v_mfma_f32_16x16x32_bf16 v[60:63], v[166:169], v[202:205], v[60:63]
	v_mfma_f32_16x16x32_bf16 v[56:59], v[174:177], v[202:205], v[56:59]
	v_mfma_f32_16x16x32_bf16 v[48:51], v[166:169], v[210:213], v[48:51]
	v_mfma_f32_16x16x32_bf16 v[40:43], v[174:177], v[210:213], v[40:43]
	v_mfma_f32_16x16x32_bf16 v[32:35], v[166:169], v[218:221], v[32:35]
	v_mfma_f32_16x16x32_bf16 v[24:27], v[174:177], v[218:221], v[24:27]
	v_mfma_f32_16x16x32_bf16 v[16:19], v[166:169], v[226:229], v[16:19]
	v_mfma_f32_16x16x32_bf16 v[8:11], v[174:177], v[226:229], v[8:11]
	s_setprio 0
	s_setprio 1
	v_mfma_f32_16x16x32_bf16 v[52:55], v[178:181], v[198:201], 0
	v_mfma_f32_16x16x32_bf16 v[44:47], v[190:193], v[198:201], 0
	v_mfma_f32_16x16x32_bf16 v[36:39], v[178:181], v[206:209], 0
	v_mfma_f32_16x16x32_bf16 v[28:31], v[190:193], v[206:209], 0
	v_mfma_f32_16x16x32_bf16 v[20:23], v[178:181], v[214:217], 0
	v_mfma_f32_16x16x32_bf16 v[12:15], v[190:193], v[214:217], 0
	v_mfma_f32_16x16x32_bf16 v[4:7], v[178:181], v[222:225], 0
	v_mfma_f32_16x16x32_bf16 v[0:3], v[190:193], v[222:225], 0
	v_mfma_f32_16x16x32_bf16 v[52:55], v[186:189], v[202:205], v[52:55]
	v_mfma_f32_16x16x32_bf16 v[44:47], v[194:197], v[202:205], v[44:47]
	v_mfma_f32_16x16x32_bf16 v[36:39], v[186:189], v[210:213], v[36:39]
	v_mfma_f32_16x16x32_bf16 v[28:31], v[194:197], v[210:213], v[28:31]
	v_mfma_f32_16x16x32_bf16 v[20:23], v[186:189], v[218:221], v[20:23]
	v_mfma_f32_16x16x32_bf16 v[12:15], v[194:197], v[218:221], v[12:15]
	v_mfma_f32_16x16x32_bf16 v[4:7], v[186:189], v[226:229], v[4:7]
	v_mfma_f32_16x16x32_bf16 v[0:3], v[194:197], v[226:229], v[0:3]
	s_setprio 0
	s_barrier
	s_add_i32 s86, 0, 0x18000
	v_add_u32_e32 v146, s86, v149
	s_add_i32 s87, 0, 0x1c000
	ds_read_b128 v[162:165], v146
	ds_read_b128 v[166:169], v146 offset:1024
	ds_read_b128 v[170:173], v146 offset:2048
	ds_read_b128 v[174:177], v146 offset:3072
	v_add_u32_e32 v146, s87, v149
	ds_read_b128 v[178:181], v146
	ds_read_b128 v[186:189], v146 offset:1024
	ds_read_b128 v[190:193], v146 offset:2048
	ds_read_b128 v[194:197], v146 offset:3072
	s_add_u32 s58, s58, 0x40000
	s_addc_u32 s59, s59, 0
	s_mov_b32 m0, s66
	v_lshl_add_u64 v[236:237], s[58:59], 0, v[128:129]
	ds_read_b128 v[198:201], v154 offset:32768
	ds_read_b128 v[202:205], v154 offset:33792
	ds_read_b128 v[206:209], v154 offset:34816
	ds_read_b128 v[210:213], v154 offset:35840
	ds_read_b128 v[214:217], v154 offset:36864
	ds_read_b128 v[218:221], v154 offset:37888
	ds_read_b128 v[222:225], v154 offset:38912
	ds_read_b128 v[226:229], v154 offset:39936
	global_load_lds_dwordx4 v[236:237], off
	v_lshl_add_u64 v[236:237], s[58:59], 0, v[132:133]
	s_mov_b32 m0, s67
	s_nop 0
	global_load_lds_dwordx4 v[236:237], off
	s_waitcnt vmcnt(8)
	s_waitcnt lgkmcnt(0)
	s_barrier
	s_setprio 1
	s_waitcnt lgkmcnt(0)
	v_mfma_f32_16x16x32_bf16 v[124:127], v[162:165], v[198:201], v[124:127]
	v_mfma_f32_16x16x32_bf16 v[120:123], v[170:173], v[198:201], v[120:123]
	v_mfma_f32_16x16x32_bf16 v[104:107], v[170:173], v[206:209], v[104:107]
	v_mfma_f32_16x16x32_bf16 v[112:115], v[162:165], v[206:209], v[112:115]
	v_mfma_f32_16x16x32_bf16 v[96:99], v[162:165], v[214:217], v[96:99]
	v_mfma_f32_16x16x32_bf16 v[88:91], v[170:173], v[214:217], v[88:91]
	v_mfma_f32_16x16x32_bf16 v[72:75], v[170:173], v[222:225], v[72:75]
	v_mfma_f32_16x16x32_bf16 v[80:83], v[162:165], v[222:225], v[80:83]
	v_mfma_f32_16x16x32_bf16 v[124:127], v[166:169], v[202:205], v[124:127]
	v_mfma_f32_16x16x32_bf16 v[120:123], v[174:177], v[202:205], v[120:123]
	v_mfma_f32_16x16x32_bf16 v[104:107], v[174:177], v[210:213], v[104:107]
	v_mfma_f32_16x16x32_bf16 v[112:115], v[166:169], v[210:213], v[112:115]
	v_mfma_f32_16x16x32_bf16 v[96:99], v[166:169], v[218:221], v[96:99]
	v_mfma_f32_16x16x32_bf16 v[88:91], v[174:177], v[218:221], v[88:91]
	v_mfma_f32_16x16x32_bf16 v[72:75], v[174:177], v[226:229], v[72:75]
	v_mfma_f32_16x16x32_bf16 v[80:83], v[166:169], v[226:229], v[80:83]
	s_setprio 0
	s_setprio 1
	v_mfma_f32_16x16x32_bf16 v[116:119], v[178:181], v[198:201], v[116:119]
	v_mfma_f32_16x16x32_bf16 v[108:111], v[190:193], v[198:201], v[108:111]
	v_mfma_f32_16x16x32_bf16 v[92:95], v[190:193], v[206:209], v[92:95]
	v_mfma_f32_16x16x32_bf16 v[100:103], v[178:181], v[206:209], v[100:103]
	v_mfma_f32_16x16x32_bf16 v[84:87], v[178:181], v[214:217], v[84:87]
	v_mfma_f32_16x16x32_bf16 v[76:79], v[190:193], v[214:217], v[76:79]
	v_mfma_f32_16x16x32_bf16 v[64:67], v[190:193], v[222:225], v[64:67]
	v_mfma_f32_16x16x32_bf16 v[68:71], v[178:181], v[222:225], v[68:71]
	v_mfma_f32_16x16x32_bf16 v[116:119], v[186:189], v[202:205], v[116:119]
	v_mfma_f32_16x16x32_bf16 v[108:111], v[194:197], v[202:205], v[108:111]
	v_mfma_f32_16x16x32_bf16 v[92:95], v[194:197], v[210:213], v[92:95]
	v_mfma_f32_16x16x32_bf16 v[100:103], v[186:189], v[210:213], v[100:103]
	v_mfma_f32_16x16x32_bf16 v[84:87], v[186:189], v[218:221], v[84:87]
	v_mfma_f32_16x16x32_bf16 v[76:79], v[194:197], v[218:221], v[76:79]
	v_mfma_f32_16x16x32_bf16 v[64:67], v[194:197], v[226:229], v[64:67]
	v_mfma_f32_16x16x32_bf16 v[68:71], v[186:189], v[226:229], v[68:71]
	s_setprio 0
	s_barrier
	s_add_i32 s58, s86, s63
	v_lshl_add_u64 v[182:183], v[182:183], 0, s[22:23]
	s_mov_b32 m0, s58
	ds_read_b128 v[198:201], v154 offset:49152
	ds_read_b128 v[202:205], v154 offset:50176
	ds_read_b128 v[206:209], v154 offset:51200
	ds_read_b128 v[210:213], v154 offset:52224
	ds_read_b128 v[214:217], v154 offset:53248
	ds_read_b128 v[218:221], v154 offset:54272
	ds_read_b128 v[222:225], v154 offset:55296
	ds_read_b128 v[226:229], v154 offset:56320
	global_load_lds_dwordx4 v[182:183], off
	s_add_i32 m0, s58, 0x2000
	s_add_u32 s56, s56, 0x40080
	v_lshl_add_u64 v[182:183], v[230:231], 0, s[22:23]
	s_addc_u32 s57, s57, 0
	s_add_i32 s58, s87, s63
	global_load_lds_dwordx4 v[182:183], off
	v_lshl_add_u64 v[182:183], s[56:57], 0, v[130:131]
	s_mov_b32 m0, s58
	s_nop 0
	global_load_lds_dwordx4 v[182:183], off
	v_lshl_add_u64 v[182:183], s[56:57], 0, v[134:135]
	s_add_i32 m0, s58, 0x2000
	s_nop 0
	global_load_lds_dwordx4 v[182:183], off
	v_lshl_add_u64 v[182:183], v[232:233], 0, s[22:23]
	s_mov_b32 m0, s69
	s_nop 0
	global_load_lds_dwordx4 v[182:183], off
	v_lshl_add_u64 v[182:183], v[234:235], 0, s[22:23]
	s_mov_b32 m0, s70
	s_nop 0
	global_load_lds_dwordx4 v[182:183], off
	s_waitcnt vmcnt(8)
	s_waitcnt lgkmcnt(0)
	s_barrier
	s_setprio 1
	s_waitcnt lgkmcnt(0)
	v_mfma_f32_16x16x32_bf16 v[60:63], v[162:165], v[198:201], v[60:63]
	v_mfma_f32_16x16x32_bf16 v[56:59], v[170:173], v[198:201], v[56:59]
	v_mfma_f32_16x16x32_bf16 v[40:43], v[170:173], v[206:209], v[40:43]
	v_mfma_f32_16x16x32_bf16 v[48:51], v[162:165], v[206:209], v[48:51]
	v_mfma_f32_16x16x32_bf16 v[32:35], v[162:165], v[214:217], v[32:35]
	v_mfma_f32_16x16x32_bf16 v[24:27], v[170:173], v[214:217], v[24:27]
	v_mfma_f32_16x16x32_bf16 v[8:11], v[170:173], v[222:225], v[8:11]
	v_mfma_f32_16x16x32_bf16 v[16:19], v[162:165], v[222:225], v[16:19]
	v_mfma_f32_16x16x32_bf16 v[60:63], v[166:169], v[202:205], v[60:63]
	v_mfma_f32_16x16x32_bf16 v[56:59], v[174:177], v[202:205], v[56:59]
	v_mfma_f32_16x16x32_bf16 v[40:43], v[174:177], v[210:213], v[40:43]
	v_mfma_f32_16x16x32_bf16 v[48:51], v[166:169], v[210:213], v[48:51]
	v_mfma_f32_16x16x32_bf16 v[32:35], v[166:169], v[218:221], v[32:35]
	v_mfma_f32_16x16x32_bf16 v[24:27], v[174:177], v[218:221], v[24:27]
	v_mfma_f32_16x16x32_bf16 v[8:11], v[174:177], v[226:229], v[8:11]
	v_mfma_f32_16x16x32_bf16 v[16:19], v[166:169], v[226:229], v[16:19]
	s_setprio 0
	s_setprio 1
	v_mfma_f32_16x16x32_bf16 v[52:55], v[178:181], v[198:201], v[52:55]
	v_mfma_f32_16x16x32_bf16 v[44:47], v[190:193], v[198:201], v[44:47]
	v_mfma_f32_16x16x32_bf16 v[28:31], v[190:193], v[206:209], v[28:31]
	v_mfma_f32_16x16x32_bf16 v[36:39], v[178:181], v[206:209], v[36:39]
	v_mfma_f32_16x16x32_bf16 v[20:23], v[178:181], v[214:217], v[20:23]
	v_mfma_f32_16x16x32_bf16 v[12:15], v[190:193], v[214:217], v[12:15]
	v_mfma_f32_16x16x32_bf16 v[0:3], v[190:193], v[222:225], v[0:3]
	v_mfma_f32_16x16x32_bf16 v[4:7], v[178:181], v[222:225], v[4:7]
	v_mfma_f32_16x16x32_bf16 v[52:55], v[186:189], v[202:205], v[52:55]
	v_mfma_f32_16x16x32_bf16 v[44:47], v[194:197], v[202:205], v[44:47]
	v_mfma_f32_16x16x32_bf16 v[28:31], v[194:197], v[210:213], v[28:31]
	v_mfma_f32_16x16x32_bf16 v[36:39], v[186:189], v[210:213], v[36:39]
	v_mfma_f32_16x16x32_bf16 v[20:23], v[186:189], v[218:221], v[20:23]
	v_mfma_f32_16x16x32_bf16 v[12:15], v[194:197], v[218:221], v[12:15]
	v_mfma_f32_16x16x32_bf16 v[0:3], v[194:197], v[226:229], v[0:3]
	v_mfma_f32_16x16x32_bf16 v[4:7], v[186:189], v[226:229], v[4:7]
	s_setprio 0
	s_barrier
	s_add_i32 s85, s85, 2
	s_add_u32 s83, s83, 0x100
	s_addc_u32 s84, s84, 0
	s_add_u32 s54, s54, 0x100
	s_addc_u32 s55, s55, 0
	s_branch .LBB0_875
.LBB0_874:
	v_add_u32_e32 v146, s73, v149
	ds_read_b128 v[162:165], v146
	ds_read_b128 v[166:169], v146 offset:1024
	ds_read_b128 v[170:173], v146 offset:2048
	ds_read_b128 v[174:177], v146 offset:3072
	v_add_u32_e32 v146, s74, v149
	ds_read_b128 v[178:181], v146
	ds_read_b128 v[186:189], v146 offset:1024
	ds_read_b128 v[190:193], v146 offset:2048
	ds_read_b128 v[194:197], v146 offset:3072
	s_add_u32 s58, s54, 0xfffc0080
	s_addc_u32 s59, s55, -1
	s_and_b64 s[56:57], s[56:57], exec
	s_cselect_b32 s59, s49, s59
	s_cselect_b32 s58, s80, s58
	s_cselect_b32 s57, s81, s84
	s_cselect_b32 s56, s82, s83
	v_lshl_add_u64 v[182:183], s[54:55], 0, v[138:139]
	s_add_i32 m0, s64, 0xc000
	ds_read_b128 v[198:201], v154
	ds_read_b128 v[202:205], v154 offset:1024
	ds_read_b128 v[206:209], v154 offset:2048
	ds_read_b128 v[210:213], v154 offset:3072
	ds_read_b128 v[214:217], v154 offset:4096
	ds_read_b128 v[218:221], v154 offset:5120
	ds_read_b128 v[222:225], v154 offset:6144
	ds_read_b128 v[226:229], v154 offset:7168
	global_load_lds_dwordx4 v[182:183], off
	v_lshl_add_u64 v[182:183], s[54:55], 0, v[136:137]
	s_add_i32 m0, s64, 0xe000
	s_nop 0
	global_load_lds_dwordx4 v[182:183], off
	s_waitcnt vmcnt(8)
	s_waitcnt lgkmcnt(0)
	s_barrier
	s_setprio 1
	s_waitcnt lgkmcnt(0)
	v_mfma_f32_16x16x32_bf16 v[124:127], v[162:165], v[198:201], v[124:127]
	v_mfma_f32_16x16x32_bf16 v[120:123], v[170:173], v[198:201], v[120:123]
	v_mfma_f32_16x16x32_bf16 v[104:107], v[170:173], v[206:209], v[104:107]
	v_mfma_f32_16x16x32_bf16 v[112:115], v[162:165], v[206:209], v[112:115]
	v_mfma_f32_16x16x32_bf16 v[96:99], v[162:165], v[214:217], v[96:99]
	v_mfma_f32_16x16x32_bf16 v[88:91], v[170:173], v[214:217], v[88:91]
	v_mfma_f32_16x16x32_bf16 v[72:75], v[170:173], v[222:225], v[72:75]
	v_mfma_f32_16x16x32_bf16 v[80:83], v[162:165], v[222:225], v[80:83]
	v_mfma_f32_16x16x32_bf16 v[124:127], v[166:169], v[202:205], v[124:127]
	v_mfma_f32_16x16x32_bf16 v[120:123], v[174:177], v[202:205], v[120:123]
	v_mfma_f32_16x16x32_bf16 v[104:107], v[174:177], v[210:213], v[104:107]
	v_mfma_f32_16x16x32_bf16 v[112:115], v[166:169], v[210:213], v[112:115]
	v_mfma_f32_16x16x32_bf16 v[96:99], v[166:169], v[218:221], v[96:99]
	v_mfma_f32_16x16x32_bf16 v[88:91], v[174:177], v[218:221], v[88:91]
	v_mfma_f32_16x16x32_bf16 v[72:75], v[174:177], v[226:229], v[72:75]
	v_mfma_f32_16x16x32_bf16 v[80:83], v[166:169], v[226:229], v[80:83]
	s_setprio 0
	s_setprio 1
	v_mfma_f32_16x16x32_bf16 v[116:119], v[178:181], v[198:201], v[116:119]
	v_mfma_f32_16x16x32_bf16 v[108:111], v[190:193], v[198:201], v[108:111]
	v_mfma_f32_16x16x32_bf16 v[92:95], v[190:193], v[206:209], v[92:95]
	v_mfma_f32_16x16x32_bf16 v[100:103], v[178:181], v[206:209], v[100:103]
	v_mfma_f32_16x16x32_bf16 v[84:87], v[178:181], v[214:217], v[84:87]
	v_mfma_f32_16x16x32_bf16 v[76:79], v[190:193], v[214:217], v[76:79]
	v_mfma_f32_16x16x32_bf16 v[64:67], v[190:193], v[222:225], v[64:67]
	v_mfma_f32_16x16x32_bf16 v[68:71], v[178:181], v[222:225], v[68:71]
	v_mfma_f32_16x16x32_bf16 v[116:119], v[186:189], v[202:205], v[116:119]
	v_mfma_f32_16x16x32_bf16 v[108:111], v[194:197], v[202:205], v[108:111]
	v_mfma_f32_16x16x32_bf16 v[92:95], v[194:197], v[210:213], v[92:95]
	v_mfma_f32_16x16x32_bf16 v[100:103], v[186:189], v[210:213], v[100:103]
	v_mfma_f32_16x16x32_bf16 v[84:87], v[186:189], v[218:221], v[84:87]
	v_mfma_f32_16x16x32_bf16 v[76:79], v[194:197], v[218:221], v[76:79]
	v_mfma_f32_16x16x32_bf16 v[64:67], v[194:197], v[226:229], v[64:67]
	v_mfma_f32_16x16x32_bf16 v[68:71], v[186:189], v[226:229], v[68:71]
	s_setprio 0
	s_barrier
	s_add_i32 s86, s73, s63
	v_lshl_add_u64 v[182:183], s[56:57], 0, v[130:131]
	s_mov_b32 m0, s86
	ds_read_b128 v[198:201], v154 offset:16384
	ds_read_b128 v[202:205], v154 offset:17408
	ds_read_b128 v[206:209], v154 offset:18432
	ds_read_b128 v[210:213], v154 offset:19456
	ds_read_b128 v[214:217], v154 offset:20480
	ds_read_b128 v[218:221], v154 offset:21504
	ds_read_b128 v[222:225], v154 offset:22528
	ds_read_b128 v[226:229], v154 offset:23552
	global_load_lds_dwordx4 v[182:183], off
	s_add_i32 m0, s86, 0x2000
	s_add_u32 s86, s56, 0x40000
	v_lshl_add_u64 v[230:231], s[56:57], 0, v[134:135]
	s_addc_u32 s87, s57, 0
	s_add_i32 s88, s74, s63
	global_load_lds_dwordx4 v[230:231], off
	v_lshl_add_u64 v[232:233], s[86:87], 0, v[130:131]
	s_mov_b32 m0, s88
	v_lshl_add_u64 v[234:235], s[58:59], 0, v[132:133]
	global_load_lds_dwordx4 v[232:233], off
	v_lshl_add_u64 v[232:233], s[86:87], 0, v[134:135]
	s_add_i32 m0, s88, 0x2000
	s_nop 0
	global_load_lds_dwordx4 v[232:233], off
	v_lshl_add_u64 v[232:233], s[58:59], 0, v[128:129]
	s_mov_b32 m0, s64
	s_nop 0
	global_load_lds_dwordx4 v[232:233], off
	s_mov_b32 m0, s65
	s_nop 0
	global_load_lds_dwordx4 v[234:235], off
	s_waitcnt vmcnt(8)
	s_waitcnt lgkmcnt(0)
	s_barrier
	s_setprio 1
	s_waitcnt lgkmcnt(0)
	v_mfma_f32_16x16x32_bf16 v[60:63], v[162:165], v[198:201], v[60:63]
	v_mfma_f32_16x16x32_bf16 v[56:59], v[170:173], v[198:201], v[56:59]
	v_mfma_f32_16x16x32_bf16 v[40:43], v[170:173], v[206:209], v[40:43]
	v_mfma_f32_16x16x32_bf16 v[48:51], v[162:165], v[206:209], v[48:51]
	v_mfma_f32_16x16x32_bf16 v[32:35], v[162:165], v[214:217], v[32:35]
	v_mfma_f32_16x16x32_bf16 v[24:27], v[170:173], v[214:217], v[24:27]
	v_mfma_f32_16x16x32_bf16 v[8:11], v[170:173], v[222:225], v[8:11]
	v_mfma_f32_16x16x32_bf16 v[16:19], v[162:165], v[222:225], v[16:19]
	v_mfma_f32_16x16x32_bf16 v[60:63], v[166:169], v[202:205], v[60:63]
	v_mfma_f32_16x16x32_bf16 v[56:59], v[174:177], v[202:205], v[56:59]
	v_mfma_f32_16x16x32_bf16 v[40:43], v[174:177], v[210:213], v[40:43]
	v_mfma_f32_16x16x32_bf16 v[48:51], v[166:169], v[210:213], v[48:51]
	v_mfma_f32_16x16x32_bf16 v[32:35], v[166:169], v[218:221], v[32:35]
	v_mfma_f32_16x16x32_bf16 v[24:27], v[174:177], v[218:221], v[24:27]
	v_mfma_f32_16x16x32_bf16 v[8:11], v[174:177], v[226:229], v[8:11]
	v_mfma_f32_16x16x32_bf16 v[16:19], v[166:169], v[226:229], v[16:19]
	s_setprio 0
	s_setprio 1
	v_mfma_f32_16x16x32_bf16 v[52:55], v[178:181], v[198:201], v[52:55]
	v_mfma_f32_16x16x32_bf16 v[44:47], v[190:193], v[198:201], v[44:47]
	v_mfma_f32_16x16x32_bf16 v[28:31], v[190:193], v[206:209], v[28:31]
	v_mfma_f32_16x16x32_bf16 v[36:39], v[178:181], v[206:209], v[36:39]
	v_mfma_f32_16x16x32_bf16 v[20:23], v[178:181], v[214:217], v[20:23]
	v_mfma_f32_16x16x32_bf16 v[12:15], v[190:193], v[214:217], v[12:15]
	v_mfma_f32_16x16x32_bf16 v[0:3], v[190:193], v[222:225], v[0:3]
	v_mfma_f32_16x16x32_bf16 v[4:7], v[178:181], v[222:225], v[4:7]
	v_mfma_f32_16x16x32_bf16 v[52:55], v[186:189], v[202:205], v[52:55]
	v_mfma_f32_16x16x32_bf16 v[44:47], v[194:197], v[202:205], v[44:47]
	v_mfma_f32_16x16x32_bf16 v[28:31], v[194:197], v[210:213], v[28:31]
	v_mfma_f32_16x16x32_bf16 v[36:39], v[186:189], v[210:213], v[36:39]
	v_mfma_f32_16x16x32_bf16 v[20:23], v[186:189], v[218:221], v[20:23]
	v_mfma_f32_16x16x32_bf16 v[12:15], v[194:197], v[218:221], v[12:15]
	v_mfma_f32_16x16x32_bf16 v[0:3], v[194:197], v[226:229], v[0:3]
	v_mfma_f32_16x16x32_bf16 v[4:7], v[186:189], v[226:229], v[4:7]
	s_setprio 0
	s_barrier
	s_add_i32 s86, 0, 0x18000
	v_add_u32_e32 v146, s86, v149
	s_add_i32 s87, 0, 0x1c000
	ds_read_b128 v[162:165], v146
	ds_read_b128 v[166:169], v146 offset:1024
	ds_read_b128 v[170:173], v146 offset:2048
	ds_read_b128 v[174:177], v146 offset:3072
	v_add_u32_e32 v146, s87, v149
	ds_read_b128 v[178:181], v146
	ds_read_b128 v[186:189], v146 offset:1024
	ds_read_b128 v[190:193], v146 offset:2048
	ds_read_b128 v[194:197], v146 offset:3072
	s_add_u32 s58, s58, 0x40000
	s_addc_u32 s59, s59, 0
	s_mov_b32 m0, s66
	v_lshl_add_u64 v[236:237], s[58:59], 0, v[128:129]
	ds_read_b128 v[198:201], v154 offset:32768
	ds_read_b128 v[202:205], v154 offset:33792
	ds_read_b128 v[206:209], v154 offset:34816
	ds_read_b128 v[210:213], v154 offset:35840
	ds_read_b128 v[214:217], v154 offset:36864
	ds_read_b128 v[218:221], v154 offset:37888
	ds_read_b128 v[222:225], v154 offset:38912
	ds_read_b128 v[226:229], v154 offset:39936
	global_load_lds_dwordx4 v[236:237], off
	v_lshl_add_u64 v[236:237], s[58:59], 0, v[132:133]
	s_mov_b32 m0, s67
	s_nop 0
	global_load_lds_dwordx4 v[236:237], off
	s_waitcnt vmcnt(8)
	s_waitcnt lgkmcnt(0)
	s_barrier
	s_setprio 1
	s_waitcnt lgkmcnt(0)
	v_mfma_f32_16x16x32_bf16 v[124:127], v[162:165], v[198:201], v[124:127]
	v_mfma_f32_16x16x32_bf16 v[120:123], v[170:173], v[198:201], v[120:123]
	v_mfma_f32_16x16x32_bf16 v[104:107], v[170:173], v[206:209], v[104:107]
	v_mfma_f32_16x16x32_bf16 v[112:115], v[162:165], v[206:209], v[112:115]
	v_mfma_f32_16x16x32_bf16 v[96:99], v[162:165], v[214:217], v[96:99]
	v_mfma_f32_16x16x32_bf16 v[88:91], v[170:173], v[214:217], v[88:91]
	v_mfma_f32_16x16x32_bf16 v[72:75], v[170:173], v[222:225], v[72:75]
	v_mfma_f32_16x16x32_bf16 v[80:83], v[162:165], v[222:225], v[80:83]
	v_mfma_f32_16x16x32_bf16 v[124:127], v[166:169], v[202:205], v[124:127]
	v_mfma_f32_16x16x32_bf16 v[120:123], v[174:177], v[202:205], v[120:123]
	v_mfma_f32_16x16x32_bf16 v[104:107], v[174:177], v[210:213], v[104:107]
	v_mfma_f32_16x16x32_bf16 v[112:115], v[166:169], v[210:213], v[112:115]
	v_mfma_f32_16x16x32_bf16 v[96:99], v[166:169], v[218:221], v[96:99]
	v_mfma_f32_16x16x32_bf16 v[88:91], v[174:177], v[218:221], v[88:91]
	v_mfma_f32_16x16x32_bf16 v[72:75], v[174:177], v[226:229], v[72:75]
	v_mfma_f32_16x16x32_bf16 v[80:83], v[166:169], v[226:229], v[80:83]
	s_setprio 0
	s_setprio 1
	v_mfma_f32_16x16x32_bf16 v[116:119], v[178:181], v[198:201], v[116:119]
	v_mfma_f32_16x16x32_bf16 v[108:111], v[190:193], v[198:201], v[108:111]
	v_mfma_f32_16x16x32_bf16 v[92:95], v[190:193], v[206:209], v[92:95]
	v_mfma_f32_16x16x32_bf16 v[100:103], v[178:181], v[206:209], v[100:103]
	v_mfma_f32_16x16x32_bf16 v[84:87], v[178:181], v[214:217], v[84:87]
	v_mfma_f32_16x16x32_bf16 v[76:79], v[190:193], v[214:217], v[76:79]
	v_mfma_f32_16x16x32_bf16 v[64:67], v[190:193], v[222:225], v[64:67]
	v_mfma_f32_16x16x32_bf16 v[68:71], v[178:181], v[222:225], v[68:71]
	v_mfma_f32_16x16x32_bf16 v[116:119], v[186:189], v[202:205], v[116:119]
	v_mfma_f32_16x16x32_bf16 v[108:111], v[194:197], v[202:205], v[108:111]
	v_mfma_f32_16x16x32_bf16 v[92:95], v[194:197], v[210:213], v[92:95]
	v_mfma_f32_16x16x32_bf16 v[100:103], v[186:189], v[210:213], v[100:103]
	v_mfma_f32_16x16x32_bf16 v[84:87], v[186:189], v[218:221], v[84:87]
	v_mfma_f32_16x16x32_bf16 v[76:79], v[194:197], v[218:221], v[76:79]
	v_mfma_f32_16x16x32_bf16 v[64:67], v[194:197], v[226:229], v[64:67]
	v_mfma_f32_16x16x32_bf16 v[68:71], v[186:189], v[226:229], v[68:71]
	s_setprio 0
	s_barrier
	s_add_i32 s58, s86, s63
	v_lshl_add_u64 v[182:183], v[182:183], 0, s[22:23]
	s_mov_b32 m0, s58
	ds_read_b128 v[198:201], v154 offset:49152
	ds_read_b128 v[202:205], v154 offset:50176
	ds_read_b128 v[206:209], v154 offset:51200
	ds_read_b128 v[210:213], v154 offset:52224
	ds_read_b128 v[214:217], v154 offset:53248
	ds_read_b128 v[218:221], v154 offset:54272
	ds_read_b128 v[222:225], v154 offset:55296
	ds_read_b128 v[226:229], v154 offset:56320
	global_load_lds_dwordx4 v[182:183], off
	s_add_i32 m0, s58, 0x2000
	s_add_u32 s56, s56, 0x40080
	v_lshl_add_u64 v[182:183], v[230:231], 0, s[22:23]
	s_addc_u32 s57, s57, 0
	s_add_i32 s58, s87, s63
	global_load_lds_dwordx4 v[182:183], off
	v_lshl_add_u64 v[182:183], s[56:57], 0, v[130:131]
	s_mov_b32 m0, s58
	s_nop 0
	global_load_lds_dwordx4 v[182:183], off
	v_lshl_add_u64 v[182:183], s[56:57], 0, v[134:135]
	s_add_i32 m0, s58, 0x2000
	s_nop 0
	global_load_lds_dwordx4 v[182:183], off
	v_lshl_add_u64 v[182:183], v[232:233], 0, s[22:23]
	s_mov_b32 m0, s69
	s_nop 0
	global_load_lds_dwordx4 v[182:183], off
	v_lshl_add_u64 v[182:183], v[234:235], 0, s[22:23]
	s_mov_b32 m0, s70
	s_nop 0
	global_load_lds_dwordx4 v[182:183], off
	s_waitcnt vmcnt(8)
	s_waitcnt lgkmcnt(0)
	s_barrier
	s_setprio 1
	s_waitcnt lgkmcnt(0)
	v_mfma_f32_16x16x32_bf16 v[60:63], v[162:165], v[198:201], v[60:63]
	v_mfma_f32_16x16x32_bf16 v[56:59], v[170:173], v[198:201], v[56:59]
	v_mfma_f32_16x16x32_bf16 v[40:43], v[170:173], v[206:209], v[40:43]
	v_mfma_f32_16x16x32_bf16 v[48:51], v[162:165], v[206:209], v[48:51]
	v_mfma_f32_16x16x32_bf16 v[32:35], v[162:165], v[214:217], v[32:35]
	v_mfma_f32_16x16x32_bf16 v[24:27], v[170:173], v[214:217], v[24:27]
	v_mfma_f32_16x16x32_bf16 v[8:11], v[170:173], v[222:225], v[8:11]
	v_mfma_f32_16x16x32_bf16 v[16:19], v[162:165], v[222:225], v[16:19]
	v_mfma_f32_16x16x32_bf16 v[60:63], v[166:169], v[202:205], v[60:63]
	v_mfma_f32_16x16x32_bf16 v[56:59], v[174:177], v[202:205], v[56:59]
	v_mfma_f32_16x16x32_bf16 v[40:43], v[174:177], v[210:213], v[40:43]
	v_mfma_f32_16x16x32_bf16 v[48:51], v[166:169], v[210:213], v[48:51]
	v_mfma_f32_16x16x32_bf16 v[32:35], v[166:169], v[218:221], v[32:35]
	v_mfma_f32_16x16x32_bf16 v[24:27], v[174:177], v[218:221], v[24:27]
	v_mfma_f32_16x16x32_bf16 v[8:11], v[174:177], v[226:229], v[8:11]
	v_mfma_f32_16x16x32_bf16 v[16:19], v[166:169], v[226:229], v[16:19]
	s_setprio 0
	s_setprio 1
	v_mfma_f32_16x16x32_bf16 v[52:55], v[178:181], v[198:201], v[52:55]
	v_mfma_f32_16x16x32_bf16 v[44:47], v[190:193], v[198:201], v[44:47]
	v_mfma_f32_16x16x32_bf16 v[28:31], v[190:193], v[206:209], v[28:31]
	v_mfma_f32_16x16x32_bf16 v[36:39], v[178:181], v[206:209], v[36:39]
	v_mfma_f32_16x16x32_bf16 v[20:23], v[178:181], v[214:217], v[20:23]
	v_mfma_f32_16x16x32_bf16 v[12:15], v[190:193], v[214:217], v[12:15]
	v_mfma_f32_16x16x32_bf16 v[0:3], v[190:193], v[222:225], v[0:3]
	v_mfma_f32_16x16x32_bf16 v[4:7], v[178:181], v[222:225], v[4:7]
	v_mfma_f32_16x16x32_bf16 v[52:55], v[186:189], v[202:205], v[52:55]
	v_mfma_f32_16x16x32_bf16 v[44:47], v[194:197], v[202:205], v[44:47]
	v_mfma_f32_16x16x32_bf16 v[28:31], v[194:197], v[210:213], v[28:31]
	v_mfma_f32_16x16x32_bf16 v[36:39], v[186:189], v[210:213], v[36:39]
	v_mfma_f32_16x16x32_bf16 v[20:23], v[186:189], v[218:221], v[20:23]
	v_mfma_f32_16x16x32_bf16 v[12:15], v[194:197], v[218:221], v[12:15]
	v_mfma_f32_16x16x32_bf16 v[0:3], v[194:197], v[226:229], v[0:3]
	v_mfma_f32_16x16x32_bf16 v[4:7], v[186:189], v[226:229], v[4:7]
	s_setprio 0
	s_barrier
	s_add_i32 s85, s85, 2
	s_add_u32 s83, s83, 0x100
	s_addc_u32 s84, s84, 0
	s_add_u32 s54, s54, 0x100
	s_addc_u32 s55, s55, 0
	s_cmp_gt_u32 s85, 13
	s_cbranch_scc1 .LBB0_877

.LBB0_1010:
	s_ashr_i32 s51, s50, 31
	s_lshl_b64 s[52:53], s[50:51], 19
	s_add_u32 s52, s33, s52
	s_addc_u32 s53, s35, s53
	s_and_b64 s[54:55], s[12:13], exec
	s_cselect_b32 s15, s53, s61
	s_cselect_b32 s51, s52, s60
	s_ashr_i32 s49, s48, 31
	s_lshl_b64 s[54:55], s[48:49], 19
	s_add_u32 s54, s64, s54
	s_addc_u32 s55, s65, s55
	s_and_b64 s[62:63], s[12:13], exec
	s_cselect_b32 s49, s55, s59
	s_cselect_b32 s57, s54, s58
	s_add_u32 s78, s58, 0x100
	s_addc_u32 s79, s59, 0
	s_add_u32 s58, s60, 0x40080
	s_addc_u32 s59, s61, 0
	s_mov_b32 s80, -2
	s_waitcnt lgkmcnt(0)
	ds_read_b128 v[128:131], v188
	ds_read_b128 v[132:135], v188 offset:1024
	ds_read_b128 v[136:139], v188 offset:2048
	ds_read_b128 v[140:143], v188 offset:3072
	ds_read_b128 v[144:147], v189
	ds_read_b128 v[148:151], v189 offset:1024
	ds_read_b128 v[172:175], v189 offset:2048
	ds_read_b128 v[176:179], v189 offset:3072
	s_add_u32 s60, s58, 0xfffc0080
	s_addc_u32 s61, s59, -1
	s_cmp_eq_u32 s80, 12
	s_cselect_b32 s63, s15, s61
	s_cselect_b32 s62, s51, s60
	s_cselect_b32 s61, s49, s79
	s_cselect_b32 s60, s57, s78
	v_lshl_add_u64 v[220:221], s[58:59], 0, v[166:167]
	s_add_i32 m0, s67, 0xc000
	ds_read_b128 v[180:183], v190
	ds_read_b128 v[192:195], v190 offset:1024
	ds_read_b128 v[196:199], v190 offset:2048
	ds_read_b128 v[200:203], v190 offset:3072
	ds_read_b128 v[204:207], v190 offset:4096
	ds_read_b128 v[208:211], v190 offset:5120
	ds_read_b128 v[212:215], v190 offset:6144
	ds_read_b128 v[216:219], v190 offset:7168
	global_load_lds_dwordx4 v[220:221], off
	v_lshl_add_u64 v[220:221], s[58:59], 0, v[164:165]
	s_add_i32 m0, s67, 0xe000
	s_nop 0
	global_load_lds_dwordx4 v[220:221], off
	s_waitcnt vmcnt(8)
	s_waitcnt lgkmcnt(0)
	s_barrier
	s_setprio 1
	s_waitcnt lgkmcnt(0)
	v_mfma_f32_16x16x32_bf16 v[124:127], v[128:131], v[180:183], 0
	v_mfma_f32_16x16x32_bf16 v[120:123], v[136:139], v[180:183], 0
	v_mfma_f32_16x16x32_bf16 v[108:111], v[128:131], v[196:199], 0
	v_mfma_f32_16x16x32_bf16 v[104:107], v[136:139], v[196:199], 0
	v_mfma_f32_16x16x32_bf16 v[92:95], v[128:131], v[204:207], 0
	v_mfma_f32_16x16x32_bf16 v[88:91], v[136:139], v[204:207], 0
	v_mfma_f32_16x16x32_bf16 v[76:79], v[128:131], v[212:215], 0
	v_mfma_f32_16x16x32_bf16 v[72:75], v[136:139], v[212:215], 0
	v_mfma_f32_16x16x32_bf16 v[124:127], v[132:135], v[192:195], v[124:127]
	v_mfma_f32_16x16x32_bf16 v[120:123], v[140:143], v[192:195], v[120:123]
	v_mfma_f32_16x16x32_bf16 v[108:111], v[132:135], v[200:203], v[108:111]
	v_mfma_f32_16x16x32_bf16 v[104:107], v[140:143], v[200:203], v[104:107]
	v_mfma_f32_16x16x32_bf16 v[92:95], v[132:135], v[208:211], v[92:95]
	v_mfma_f32_16x16x32_bf16 v[88:91], v[140:143], v[208:211], v[88:91]
	v_mfma_f32_16x16x32_bf16 v[76:79], v[132:135], v[216:219], v[76:79]
	v_mfma_f32_16x16x32_bf16 v[72:75], v[140:143], v[216:219], v[72:75]
	s_setprio 0
	s_setprio 1
	v_mfma_f32_16x16x32_bf16 v[116:119], v[144:147], v[180:183], 0
	v_mfma_f32_16x16x32_bf16 v[112:115], v[172:175], v[180:183], 0
	v_mfma_f32_16x16x32_bf16 v[100:103], v[144:147], v[196:199], 0
	v_mfma_f32_16x16x32_bf16 v[96:99], v[172:175], v[196:199], 0
	v_mfma_f32_16x16x32_bf16 v[84:87], v[144:147], v[204:207], 0
	v_mfma_f32_16x16x32_bf16 v[80:83], v[172:175], v[204:207], 0
	v_mfma_f32_16x16x32_bf16 v[68:71], v[144:147], v[212:215], 0
	v_mfma_f32_16x16x32_bf16 v[64:67], v[172:175], v[212:215], 0
	v_mfma_f32_16x16x32_bf16 v[116:119], v[148:151], v[192:195], v[116:119]
	v_mfma_f32_16x16x32_bf16 v[112:115], v[176:179], v[192:195], v[112:115]
	v_mfma_f32_16x16x32_bf16 v[100:103], v[148:151], v[200:203], v[100:103]
	v_mfma_f32_16x16x32_bf16 v[96:99], v[176:179], v[200:203], v[96:99]
	v_mfma_f32_16x16x32_bf16 v[84:87], v[148:151], v[208:211], v[84:87]
	v_mfma_f32_16x16x32_bf16 v[80:83], v[176:179], v[208:211], v[80:83]
	v_mfma_f32_16x16x32_bf16 v[68:71], v[148:151], v[216:219], v[68:71]
	v_mfma_f32_16x16x32_bf16 v[64:67], v[176:179], v[216:219], v[64:67]
	s_setprio 0
	s_barrier
	s_add_i32 s81, s76, s66
	v_lshl_add_u64 v[220:221], s[60:61], 0, v[154:155]
	s_mov_b32 m0, s81
	ds_read_b128 v[180:183], v190 offset:16384
	ds_read_b128 v[192:195], v190 offset:17408
	ds_read_b128 v[196:199], v190 offset:18432
	ds_read_b128 v[200:203], v190 offset:19456
	ds_read_b128 v[204:207], v190 offset:20480
	ds_read_b128 v[208:211], v190 offset:21504
	ds_read_b128 v[212:215], v190 offset:22528
	ds_read_b128 v[216:219], v190 offset:23552
	global_load_lds_dwordx4 v[220:221], off
	s_add_i32 m0, s81, 0x2000
	s_add_u32 s82, s60, 0x40000
	v_lshl_add_u64 v[222:223], s[60:61], 0, v[162:163]
	s_addc_u32 s83, s61, 0
	s_add_i32 s81, s77, s66
	global_load_lds_dwordx4 v[222:223], off
	v_lshl_add_u64 v[224:225], s[82:83], 0, v[154:155]
	s_mov_b32 m0, s81
	v_lshl_add_u64 v[226:227], s[62:63], 0, v[160:161]
	global_load_lds_dwordx4 v[224:225], off
	v_lshl_add_u64 v[224:225], s[82:83], 0, v[162:163]
	s_add_i32 m0, s81, 0x2000
	s_nop 0
	global_load_lds_dwordx4 v[224:225], off
	v_lshl_add_u64 v[224:225], s[62:63], 0, v[152:153]
	s_mov_b32 m0, s67
	s_nop 0
	global_load_lds_dwordx4 v[224:225], off
	s_mov_b32 m0, s68
	s_nop 0
	global_load_lds_dwordx4 v[226:227], off
	s_waitcnt vmcnt(8)
	s_waitcnt lgkmcnt(0)
	s_barrier
	s_setprio 1
	s_waitcnt lgkmcnt(0)
	v_mfma_f32_16x16x32_bf16 v[60:63], v[128:131], v[180:183], 0
	v_mfma_f32_16x16x32_bf16 v[56:59], v[136:139], v[180:183], 0
	v_mfma_f32_16x16x32_bf16 v[44:47], v[128:131], v[196:199], 0
	v_mfma_f32_16x16x32_bf16 v[40:43], v[136:139], v[196:199], 0
	v_mfma_f32_16x16x32_bf16 v[28:31], v[128:131], v[204:207], 0
	v_mfma_f32_16x16x32_bf16 v[24:27], v[136:139], v[204:207], 0
	v_mfma_f32_16x16x32_bf16 v[12:15], v[128:131], v[212:215], 0
	v_mfma_f32_16x16x32_bf16 v[8:11], v[136:139], v[212:215], 0
	v_mfma_f32_16x16x32_bf16 v[60:63], v[132:135], v[192:195], v[60:63]
	v_mfma_f32_16x16x32_bf16 v[56:59], v[140:143], v[192:195], v[56:59]
	v_mfma_f32_16x16x32_bf16 v[44:47], v[132:135], v[200:203], v[44:47]
	v_mfma_f32_16x16x32_bf16 v[40:43], v[140:143], v[200:203], v[40:43]
	v_mfma_f32_16x16x32_bf16 v[28:31], v[132:135], v[208:211], v[28:31]
	v_mfma_f32_16x16x32_bf16 v[24:27], v[140:143], v[208:211], v[24:27]
	v_mfma_f32_16x16x32_bf16 v[12:15], v[132:135], v[216:219], v[12:15]
	v_mfma_f32_16x16x32_bf16 v[8:11], v[140:143], v[216:219], v[8:11]
	s_setprio 0
	s_setprio 1
	v_mfma_f32_16x16x32_bf16 v[52:55], v[144:147], v[180:183], 0
	v_mfma_f32_16x16x32_bf16 v[48:51], v[172:175], v[180:183], 0
	v_mfma_f32_16x16x32_bf16 v[36:39], v[144:147], v[196:199], 0
	v_mfma_f32_16x16x32_bf16 v[32:35], v[172:175], v[196:199], 0
	v_mfma_f32_16x16x32_bf16 v[20:23], v[144:147], v[204:207], 0
	v_mfma_f32_16x16x32_bf16 v[16:19], v[172:175], v[204:207], 0
	v_mfma_f32_16x16x32_bf16 v[4:7], v[144:147], v[212:215], 0
	v_mfma_f32_16x16x32_bf16 v[0:3], v[172:175], v[212:215], 0
	v_mfma_f32_16x16x32_bf16 v[52:55], v[148:151], v[192:195], v[52:55]
	v_mfma_f32_16x16x32_bf16 v[48:51], v[176:179], v[192:195], v[48:51]
	v_mfma_f32_16x16x32_bf16 v[36:39], v[148:151], v[200:203], v[36:39]
	v_mfma_f32_16x16x32_bf16 v[32:35], v[176:179], v[200:203], v[32:35]
	v_mfma_f32_16x16x32_bf16 v[20:23], v[148:151], v[208:211], v[20:23]
	v_mfma_f32_16x16x32_bf16 v[16:19], v[176:179], v[208:211], v[16:19]
	v_mfma_f32_16x16x32_bf16 v[4:7], v[148:151], v[216:219], v[4:7]
	v_mfma_f32_16x16x32_bf16 v[0:3], v[176:179], v[216:219], v[0:3]
	s_setprio 0
	s_barrier
	s_add_i32 s81, 0, 0x18000
	s_add_i32 s82, 0, 0x1c000
	v_add_u32_e32 v140, s81, v185
	v_add_u32_e32 v176, s82, v185
	ds_read_b128 v[128:131], v140
	ds_read_b128 v[132:135], v140 offset:1024
	ds_read_b128 v[136:139], v140 offset:2048
	ds_read_b128 v[140:143], v140 offset:3072
	ds_read_b128 v[144:147], v176
	ds_read_b128 v[148:151], v176 offset:1024
	ds_read_b128 v[172:175], v176 offset:2048
	ds_read_b128 v[176:179], v176 offset:3072
	s_add_u32 s62, s62, 0x40000
	s_addc_u32 s63, s63, 0
	s_mov_b32 m0, s69
	v_lshl_add_u64 v[228:229], s[62:63], 0, v[152:153]
	ds_read_b128 v[180:183], v190 offset:32768
	ds_read_b128 v[192:195], v190 offset:33792
	ds_read_b128 v[196:199], v190 offset:34816
	ds_read_b128 v[200:203], v190 offset:35840
	ds_read_b128 v[204:207], v190 offset:36864
	ds_read_b128 v[208:211], v190 offset:37888
	ds_read_b128 v[212:215], v190 offset:38912
	ds_read_b128 v[216:219], v190 offset:39936
	global_load_lds_dwordx4 v[228:229], off
	v_lshl_add_u64 v[228:229], s[62:63], 0, v[160:161]
	s_mov_b32 m0, s70
	s_nop 0
	global_load_lds_dwordx4 v[228:229], off
	s_waitcnt vmcnt(8)
	s_waitcnt lgkmcnt(0)
	s_barrier
	s_setprio 1
	s_waitcnt lgkmcnt(0)
	v_mfma_f32_16x16x32_bf16 v[124:127], v[128:131], v[180:183], v[124:127]
	v_mfma_f32_16x16x32_bf16 v[120:123], v[136:139], v[180:183], v[120:123]
	v_mfma_f32_16x16x32_bf16 v[104:107], v[136:139], v[196:199], v[104:107]
	v_mfma_f32_16x16x32_bf16 v[108:111], v[128:131], v[196:199], v[108:111]
	v_mfma_f32_16x16x32_bf16 v[92:95], v[128:131], v[204:207], v[92:95]
	v_mfma_f32_16x16x32_bf16 v[88:91], v[136:139], v[204:207], v[88:91]
	v_mfma_f32_16x16x32_bf16 v[72:75], v[136:139], v[212:215], v[72:75]
	v_mfma_f32_16x16x32_bf16 v[76:79], v[128:131], v[212:215], v[76:79]
	v_mfma_f32_16x16x32_bf16 v[124:127], v[132:135], v[192:195], v[124:127]
	v_mfma_f32_16x16x32_bf16 v[120:123], v[140:143], v[192:195], v[120:123]
	v_mfma_f32_16x16x32_bf16 v[104:107], v[140:143], v[200:203], v[104:107]
	v_mfma_f32_16x16x32_bf16 v[108:111], v[132:135], v[200:203], v[108:111]
	v_mfma_f32_16x16x32_bf16 v[92:95], v[132:135], v[208:211], v[92:95]
	v_mfma_f32_16x16x32_bf16 v[88:91], v[140:143], v[208:211], v[88:91]
	v_mfma_f32_16x16x32_bf16 v[72:75], v[140:143], v[216:219], v[72:75]
	v_mfma_f32_16x16x32_bf16 v[76:79], v[132:135], v[216:219], v[76:79]
	s_setprio 0
	s_setprio 1
	v_mfma_f32_16x16x32_bf16 v[116:119], v[144:147], v[180:183], v[116:119]
	v_mfma_f32_16x16x32_bf16 v[112:115], v[172:175], v[180:183], v[112:115]
	v_mfma_f32_16x16x32_bf16 v[96:99], v[172:175], v[196:199], v[96:99]
	v_mfma_f32_16x16x32_bf16 v[100:103], v[144:147], v[196:199], v[100:103]
	v_mfma_f32_16x16x32_bf16 v[84:87], v[144:147], v[204:207], v[84:87]
	v_mfma_f32_16x16x32_bf16 v[80:83], v[172:175], v[204:207], v[80:83]
	v_mfma_f32_16x16x32_bf16 v[64:67], v[172:175], v[212:215], v[64:67]
	v_mfma_f32_16x16x32_bf16 v[68:71], v[144:147], v[212:215], v[68:71]
	v_mfma_f32_16x16x32_bf16 v[116:119], v[148:151], v[192:195], v[116:119]
	v_mfma_f32_16x16x32_bf16 v[112:115], v[176:179], v[192:195], v[112:115]
	v_mfma_f32_16x16x32_bf16 v[96:99], v[176:179], v[200:203], v[96:99]
	v_mfma_f32_16x16x32_bf16 v[100:103], v[148:151], v[200:203], v[100:103]
	v_mfma_f32_16x16x32_bf16 v[84:87], v[148:151], v[208:211], v[84:87]
	v_mfma_f32_16x16x32_bf16 v[80:83], v[176:179], v[208:211], v[80:83]
	v_mfma_f32_16x16x32_bf16 v[64:67], v[176:179], v[216:219], v[64:67]
	v_mfma_f32_16x16x32_bf16 v[68:71], v[148:151], v[216:219], v[68:71]
	s_setprio 0
	s_barrier
	s_add_i32 s62, s81, s66
	v_lshl_add_u64 v[220:221], v[220:221], 0, s[26:27]
	s_mov_b32 m0, s62
	ds_read_b128 v[180:183], v190 offset:49152
	ds_read_b128 v[192:195], v190 offset:50176
	ds_read_b128 v[196:199], v190 offset:51200
	ds_read_b128 v[200:203], v190 offset:52224
	ds_read_b128 v[204:207], v190 offset:53248
	ds_read_b128 v[208:211], v190 offset:54272
	ds_read_b128 v[212:215], v190 offset:55296
	ds_read_b128 v[216:219], v190 offset:56320
	global_load_lds_dwordx4 v[220:221], off
	s_add_i32 m0, s62, 0x2000
	s_add_u32 s60, s60, 0x40080
	v_lshl_add_u64 v[220:221], v[222:223], 0, s[26:27]
	s_addc_u32 s61, s61, 0
	s_add_i32 s62, s82, s66
	global_load_lds_dwordx4 v[220:221], off
	v_lshl_add_u64 v[220:221], s[60:61], 0, v[154:155]
	s_mov_b32 m0, s62
	s_nop 0
	global_load_lds_dwordx4 v[220:221], off
	v_lshl_add_u64 v[220:221], s[60:61], 0, v[162:163]
	s_add_i32 m0, s62, 0x2000
	s_nop 0
	global_load_lds_dwordx4 v[220:221], off
	v_lshl_add_u64 v[220:221], v[224:225], 0, s[26:27]
	s_mov_b32 m0, s3
	s_nop 0
	global_load_lds_dwordx4 v[220:221], off
	v_lshl_add_u64 v[220:221], v[226:227], 0, s[26:27]
	s_mov_b32 m0, s72
	s_nop 0
	global_load_lds_dwordx4 v[220:221], off
	s_waitcnt vmcnt(8)
	s_waitcnt lgkmcnt(0)
	s_barrier
	s_setprio 1
	s_waitcnt lgkmcnt(0)
	v_mfma_f32_16x16x32_bf16 v[60:63], v[128:131], v[180:183], v[60:63]
	v_mfma_f32_16x16x32_bf16 v[56:59], v[136:139], v[180:183], v[56:59]
	v_mfma_f32_16x16x32_bf16 v[40:43], v[136:139], v[196:199], v[40:43]
	v_mfma_f32_16x16x32_bf16 v[44:47], v[128:131], v[196:199], v[44:47]
	v_mfma_f32_16x16x32_bf16 v[28:31], v[128:131], v[204:207], v[28:31]
	v_mfma_f32_16x16x32_bf16 v[24:27], v[136:139], v[204:207], v[24:27]
	v_mfma_f32_16x16x32_bf16 v[8:11], v[136:139], v[212:215], v[8:11]
	v_mfma_f32_16x16x32_bf16 v[12:15], v[128:131], v[212:215], v[12:15]
	v_mfma_f32_16x16x32_bf16 v[60:63], v[132:135], v[192:195], v[60:63]
	v_mfma_f32_16x16x32_bf16 v[56:59], v[140:143], v[192:195], v[56:59]
	v_mfma_f32_16x16x32_bf16 v[40:43], v[140:143], v[200:203], v[40:43]
	v_mfma_f32_16x16x32_bf16 v[44:47], v[132:135], v[200:203], v[44:47]
	v_mfma_f32_16x16x32_bf16 v[28:31], v[132:135], v[208:211], v[28:31]
	v_mfma_f32_16x16x32_bf16 v[24:27], v[140:143], v[208:211], v[24:27]
	v_mfma_f32_16x16x32_bf16 v[8:11], v[140:143], v[216:219], v[8:11]
	v_mfma_f32_16x16x32_bf16 v[12:15], v[132:135], v[216:219], v[12:15]
	s_setprio 0
	s_setprio 1
	v_mfma_f32_16x16x32_bf16 v[52:55], v[144:147], v[180:183], v[52:55]
	v_mfma_f32_16x16x32_bf16 v[48:51], v[172:175], v[180:183], v[48:51]
	v_mfma_f32_16x16x32_bf16 v[32:35], v[172:175], v[196:199], v[32:35]
	v_mfma_f32_16x16x32_bf16 v[36:39], v[144:147], v[196:199], v[36:39]
	v_mfma_f32_16x16x32_bf16 v[20:23], v[144:147], v[204:207], v[20:23]
	v_mfma_f32_16x16x32_bf16 v[16:19], v[172:175], v[204:207], v[16:19]
	v_mfma_f32_16x16x32_bf16 v[0:3], v[172:175], v[212:215], v[0:3]
	v_mfma_f32_16x16x32_bf16 v[4:7], v[144:147], v[212:215], v[4:7]
	v_mfma_f32_16x16x32_bf16 v[52:55], v[148:151], v[192:195], v[52:55]
	v_mfma_f32_16x16x32_bf16 v[48:51], v[176:179], v[192:195], v[48:51]
	v_mfma_f32_16x16x32_bf16 v[32:35], v[176:179], v[200:203], v[32:35]
	v_mfma_f32_16x16x32_bf16 v[36:39], v[148:151], v[200:203], v[36:39]
	v_mfma_f32_16x16x32_bf16 v[20:23], v[148:151], v[208:211], v[20:23]
	v_mfma_f32_16x16x32_bf16 v[16:19], v[176:179], v[208:211], v[16:19]
	v_mfma_f32_16x16x32_bf16 v[0:3], v[176:179], v[216:219], v[0:3]
	v_mfma_f32_16x16x32_bf16 v[4:7], v[148:151], v[216:219], v[4:7]
	s_setprio 0
	s_barrier
	s_add_i32 s80, s80, 2
	s_add_u32 s78, s78, 0x100
	s_addc_u32 s79, s79, 0
	s_add_u32 s58, s58, 0x100
	s_addc_u32 s59, s59, 0
	s_cmp_gt_u32 s80, 13
.LBB0_1011:
	ds_read_b128 v[128:131], v188
	ds_read_b128 v[132:135], v188 offset:1024
	ds_read_b128 v[136:139], v188 offset:2048
	ds_read_b128 v[140:143], v188 offset:3072
	ds_read_b128 v[144:147], v189
	ds_read_b128 v[148:151], v189 offset:1024
	ds_read_b128 v[172:175], v189 offset:2048
	ds_read_b128 v[176:179], v189 offset:3072
	s_add_u32 s60, s58, 0xfffc0080
	s_addc_u32 s61, s59, -1
	s_cmp_eq_u32 s80, 12
	s_cselect_b32 s63, s15, s61
	s_cselect_b32 s62, s51, s60
	s_cselect_b32 s61, s49, s79
	s_cselect_b32 s60, s57, s78
	v_lshl_add_u64 v[220:221], s[58:59], 0, v[166:167]
	s_add_i32 m0, s67, 0xc000
	ds_read_b128 v[180:183], v190
	ds_read_b128 v[192:195], v190 offset:1024
	ds_read_b128 v[196:199], v190 offset:2048
	ds_read_b128 v[200:203], v190 offset:3072
	ds_read_b128 v[204:207], v190 offset:4096
	ds_read_b128 v[208:211], v190 offset:5120
	ds_read_b128 v[212:215], v190 offset:6144
	ds_read_b128 v[216:219], v190 offset:7168
	global_load_lds_dwordx4 v[220:221], off
	v_lshl_add_u64 v[220:221], s[58:59], 0, v[164:165]
	s_add_i32 m0, s67, 0xe000
	s_nop 0
	global_load_lds_dwordx4 v[220:221], off
	s_waitcnt vmcnt(8)
	s_waitcnt lgkmcnt(0)
	s_barrier
	s_setprio 1
	s_waitcnt lgkmcnt(0)
	v_mfma_f32_16x16x32_bf16 v[124:127], v[128:131], v[180:183], v[124:127]
	v_mfma_f32_16x16x32_bf16 v[120:123], v[136:139], v[180:183], v[120:123]
	v_mfma_f32_16x16x32_bf16 v[104:107], v[136:139], v[196:199], v[104:107]
	v_mfma_f32_16x16x32_bf16 v[108:111], v[128:131], v[196:199], v[108:111]
	v_mfma_f32_16x16x32_bf16 v[92:95], v[128:131], v[204:207], v[92:95]
	v_mfma_f32_16x16x32_bf16 v[88:91], v[136:139], v[204:207], v[88:91]
	v_mfma_f32_16x16x32_bf16 v[72:75], v[136:139], v[212:215], v[72:75]
	v_mfma_f32_16x16x32_bf16 v[76:79], v[128:131], v[212:215], v[76:79]
	v_mfma_f32_16x16x32_bf16 v[124:127], v[132:135], v[192:195], v[124:127]
	v_mfma_f32_16x16x32_bf16 v[120:123], v[140:143], v[192:195], v[120:123]
	v_mfma_f32_16x16x32_bf16 v[104:107], v[140:143], v[200:203], v[104:107]
	v_mfma_f32_16x16x32_bf16 v[108:111], v[132:135], v[200:203], v[108:111]
	v_mfma_f32_16x16x32_bf16 v[92:95], v[132:135], v[208:211], v[92:95]
	v_mfma_f32_16x16x32_bf16 v[88:91], v[140:143], v[208:211], v[88:91]
	v_mfma_f32_16x16x32_bf16 v[72:75], v[140:143], v[216:219], v[72:75]
	v_mfma_f32_16x16x32_bf16 v[76:79], v[132:135], v[216:219], v[76:79]
	s_setprio 0
	s_setprio 1
	v_mfma_f32_16x16x32_bf16 v[116:119], v[144:147], v[180:183], v[116:119]
	v_mfma_f32_16x16x32_bf16 v[112:115], v[172:175], v[180:183], v[112:115]
	v_mfma_f32_16x16x32_bf16 v[96:99], v[172:175], v[196:199], v[96:99]
	v_mfma_f32_16x16x32_bf16 v[100:103], v[144:147], v[196:199], v[100:103]
	v_mfma_f32_16x16x32_bf16 v[84:87], v[144:147], v[204:207], v[84:87]
	v_mfma_f32_16x16x32_bf16 v[80:83], v[172:175], v[204:207], v[80:83]
	v_mfma_f32_16x16x32_bf16 v[64:67], v[172:175], v[212:215], v[64:67]
	v_mfma_f32_16x16x32_bf16 v[68:71], v[144:147], v[212:215], v[68:71]
	v_mfma_f32_16x16x32_bf16 v[116:119], v[148:151], v[192:195], v[116:119]
	v_mfma_f32_16x16x32_bf16 v[112:115], v[176:179], v[192:195], v[112:115]
	v_mfma_f32_16x16x32_bf16 v[96:99], v[176:179], v[200:203], v[96:99]
	v_mfma_f32_16x16x32_bf16 v[100:103], v[148:151], v[200:203], v[100:103]
	v_mfma_f32_16x16x32_bf16 v[84:87], v[148:151], v[208:211], v[84:87]
	v_mfma_f32_16x16x32_bf16 v[80:83], v[176:179], v[208:211], v[80:83]
	v_mfma_f32_16x16x32_bf16 v[64:67], v[176:179], v[216:219], v[64:67]
	v_mfma_f32_16x16x32_bf16 v[68:71], v[148:151], v[216:219], v[68:71]
	s_setprio 0
	s_barrier
	s_add_i32 s81, s76, s66
	v_lshl_add_u64 v[220:221], s[60:61], 0, v[154:155]
	s_mov_b32 m0, s81
	ds_read_b128 v[180:183], v190 offset:16384
	ds_read_b128 v[192:195], v190 offset:17408
	ds_read_b128 v[196:199], v190 offset:18432
	ds_read_b128 v[200:203], v190 offset:19456
	ds_read_b128 v[204:207], v190 offset:20480
	ds_read_b128 v[208:211], v190 offset:21504
	ds_read_b128 v[212:215], v190 offset:22528
	ds_read_b128 v[216:219], v190 offset:23552
	global_load_lds_dwordx4 v[220:221], off
	s_add_i32 m0, s81, 0x2000
	s_add_u32 s82, s60, 0x40000
	v_lshl_add_u64 v[222:223], s[60:61], 0, v[162:163]
	s_addc_u32 s83, s61, 0
	s_add_i32 s81, s77, s66
	global_load_lds_dwordx4 v[222:223], off
	v_lshl_add_u64 v[224:225], s[82:83], 0, v[154:155]
	s_mov_b32 m0, s81
	v_lshl_add_u64 v[226:227], s[62:63], 0, v[160:161]
	global_load_lds_dwordx4 v[224:225], off
	v_lshl_add_u64 v[224:225], s[82:83], 0, v[162:163]
	s_add_i32 m0, s81, 0x2000
	s_nop 0
	global_load_lds_dwordx4 v[224:225], off
	v_lshl_add_u64 v[224:225], s[62:63], 0, v[152:153]
	s_mov_b32 m0, s67
	s_nop 0
	global_load_lds_dwordx4 v[224:225], off
	s_mov_b32 m0, s68
	s_nop 0
	global_load_lds_dwordx4 v[226:227], off
	s_waitcnt vmcnt(8)
	s_waitcnt lgkmcnt(0)
	s_barrier
	s_setprio 1
	s_waitcnt lgkmcnt(0)
	v_mfma_f32_16x16x32_bf16 v[60:63], v[128:131], v[180:183], v[60:63]
	v_mfma_f32_16x16x32_bf16 v[56:59], v[136:139], v[180:183], v[56:59]
	v_mfma_f32_16x16x32_bf16 v[40:43], v[136:139], v[196:199], v[40:43]
	v_mfma_f32_16x16x32_bf16 v[44:47], v[128:131], v[196:199], v[44:47]
	v_mfma_f32_16x16x32_bf16 v[28:31], v[128:131], v[204:207], v[28:31]
	v_mfma_f32_16x16x32_bf16 v[24:27], v[136:139], v[204:207], v[24:27]
	v_mfma_f32_16x16x32_bf16 v[8:11], v[136:139], v[212:215], v[8:11]
	v_mfma_f32_16x16x32_bf16 v[12:15], v[128:131], v[212:215], v[12:15]
	v_mfma_f32_16x16x32_bf16 v[60:63], v[132:135], v[192:195], v[60:63]
	v_mfma_f32_16x16x32_bf16 v[56:59], v[140:143], v[192:195], v[56:59]
	v_mfma_f32_16x16x32_bf16 v[40:43], v[140:143], v[200:203], v[40:43]
	v_mfma_f32_16x16x32_bf16 v[44:47], v[132:135], v[200:203], v[44:47]
	v_mfma_f32_16x16x32_bf16 v[28:31], v[132:135], v[208:211], v[28:31]
	v_mfma_f32_16x16x32_bf16 v[24:27], v[140:143], v[208:211], v[24:27]
	v_mfma_f32_16x16x32_bf16 v[8:11], v[140:143], v[216:219], v[8:11]
	v_mfma_f32_16x16x32_bf16 v[12:15], v[132:135], v[216:219], v[12:15]
	s_setprio 0
	s_setprio 1
	v_mfma_f32_16x16x32_bf16 v[52:55], v[144:147], v[180:183], v[52:55]
	v_mfma_f32_16x16x32_bf16 v[48:51], v[172:175], v[180:183], v[48:51]
	v_mfma_f32_16x16x32_bf16 v[32:35], v[172:175], v[196:199], v[32:35]
	v_mfma_f32_16x16x32_bf16 v[36:39], v[144:147], v[196:199], v[36:39]
	v_mfma_f32_16x16x32_bf16 v[20:23], v[144:147], v[204:207], v[20:23]
	v_mfma_f32_16x16x32_bf16 v[16:19], v[172:175], v[204:207], v[16:19]
	v_mfma_f32_16x16x32_bf16 v[0:3], v[172:175], v[212:215], v[0:3]
	v_mfma_f32_16x16x32_bf16 v[4:7], v[144:147], v[212:215], v[4:7]
	v_mfma_f32_16x16x32_bf16 v[52:55], v[148:151], v[192:195], v[52:55]
	v_mfma_f32_16x16x32_bf16 v[48:51], v[176:179], v[192:195], v[48:51]
	v_mfma_f32_16x16x32_bf16 v[32:35], v[176:179], v[200:203], v[32:35]
	v_mfma_f32_16x16x32_bf16 v[36:39], v[148:151], v[200:203], v[36:39]
	v_mfma_f32_16x16x32_bf16 v[20:23], v[148:151], v[208:211], v[20:23]
	v_mfma_f32_16x16x32_bf16 v[16:19], v[176:179], v[208:211], v[16:19]
	v_mfma_f32_16x16x32_bf16 v[0:3], v[176:179], v[216:219], v[0:3]
	v_mfma_f32_16x16x32_bf16 v[4:7], v[148:151], v[216:219], v[4:7]
	s_setprio 0
	s_barrier
	s_add_i32 s81, 0, 0x18000
	s_add_i32 s82, 0, 0x1c000
	v_add_u32_e32 v140, s81, v185
	v_add_u32_e32 v176, s82, v185
	ds_read_b128 v[128:131], v140
	ds_read_b128 v[132:135], v140 offset:1024
	ds_read_b128 v[136:139], v140 offset:2048
	ds_read_b128 v[140:143], v140 offset:3072
	ds_read_b128 v[144:147], v176
	ds_read_b128 v[148:151], v176 offset:1024
	ds_read_b128 v[172:175], v176 offset:2048
	ds_read_b128 v[176:179], v176 offset:3072
	s_add_u32 s62, s62, 0x40000
	s_addc_u32 s63, s63, 0
	s_mov_b32 m0, s69
	v_lshl_add_u64 v[228:229], s[62:63], 0, v[152:153]
	ds_read_b128 v[180:183], v190 offset:32768
	ds_read_b128 v[192:195], v190 offset:33792
	ds_read_b128 v[196:199], v190 offset:34816
	ds_read_b128 v[200:203], v190 offset:35840
	ds_read_b128 v[204:207], v190 offset:36864
	ds_read_b128 v[208:211], v190 offset:37888
	ds_read_b128 v[212:215], v190 offset:38912
	ds_read_b128 v[216:219], v190 offset:39936
	global_load_lds_dwordx4 v[228:229], off
	v_lshl_add_u64 v[228:229], s[62:63], 0, v[160:161]
	s_mov_b32 m0, s70
	s_nop 0
	global_load_lds_dwordx4 v[228:229], off
	s_waitcnt vmcnt(8)
	s_waitcnt lgkmcnt(0)
	s_barrier
	s_setprio 1
	s_waitcnt lgkmcnt(0)
	v_mfma_f32_16x16x32_bf16 v[124:127], v[128:131], v[180:183], v[124:127]
	v_mfma_f32_16x16x32_bf16 v[120:123], v[136:139], v[180:183], v[120:123]
	v_mfma_f32_16x16x32_bf16 v[104:107], v[136:139], v[196:199], v[104:107]
	v_mfma_f32_16x16x32_bf16 v[108:111], v[128:131], v[196:199], v[108:111]
	v_mfma_f32_16x16x32_bf16 v[92:95], v[128:131], v[204:207], v[92:95]
	v_mfma_f32_16x16x32_bf16 v[88:91], v[136:139], v[204:207], v[88:91]
	v_mfma_f32_16x16x32_bf16 v[72:75], v[136:139], v[212:215], v[72:75]
	v_mfma_f32_16x16x32_bf16 v[76:79], v[128:131], v[212:215], v[76:79]
	v_mfma_f32_16x16x32_bf16 v[124:127], v[132:135], v[192:195], v[124:127]
	v_mfma_f32_16x16x32_bf16 v[120:123], v[140:143], v[192:195], v[120:123]
	v_mfma_f32_16x16x32_bf16 v[104:107], v[140:143], v[200:203], v[104:107]
	v_mfma_f32_16x16x32_bf16 v[108:111], v[132:135], v[200:203], v[108:111]
	v_mfma_f32_16x16x32_bf16 v[92:95], v[132:135], v[208:211], v[92:95]
	v_mfma_f32_16x16x32_bf16 v[88:91], v[140:143], v[208:211], v[88:91]
	v_mfma_f32_16x16x32_bf16 v[72:75], v[140:143], v[216:219], v[72:75]
	v_mfma_f32_16x16x32_bf16 v[76:79], v[132:135], v[216:219], v[76:79]
	s_setprio 0
	s_setprio 1
	v_mfma_f32_16x16x32_bf16 v[116:119], v[144:147], v[180:183], v[116:119]
	v_mfma_f32_16x16x32_bf16 v[112:115], v[172:175], v[180:183], v[112:115]
	v_mfma_f32_16x16x32_bf16 v[96:99], v[172:175], v[196:199], v[96:99]
	v_mfma_f32_16x16x32_bf16 v[100:103], v[144:147], v[196:199], v[100:103]
	v_mfma_f32_16x16x32_bf16 v[84:87], v[144:147], v[204:207], v[84:87]
	v_mfma_f32_16x16x32_bf16 v[80:83], v[172:175], v[204:207], v[80:83]
	v_mfma_f32_16x16x32_bf16 v[64:67], v[172:175], v[212:215], v[64:67]
	v_mfma_f32_16x16x32_bf16 v[68:71], v[144:147], v[212:215], v[68:71]
	v_mfma_f32_16x16x32_bf16 v[116:119], v[148:151], v[192:195], v[116:119]
	v_mfma_f32_16x16x32_bf16 v[112:115], v[176:179], v[192:195], v[112:115]
	v_mfma_f32_16x16x32_bf16 v[96:99], v[176:179], v[200:203], v[96:99]
	v_mfma_f32_16x16x32_bf16 v[100:103], v[148:151], v[200:203], v[100:103]
	v_mfma_f32_16x16x32_bf16 v[84:87], v[148:151], v[208:211], v[84:87]
	v_mfma_f32_16x16x32_bf16 v[80:83], v[176:179], v[208:211], v[80:83]
	v_mfma_f32_16x16x32_bf16 v[64:67], v[176:179], v[216:219], v[64:67]
	v_mfma_f32_16x16x32_bf16 v[68:71], v[148:151], v[216:219], v[68:71]
	s_setprio 0
	s_barrier
	s_add_i32 s62, s81, s66
	v_lshl_add_u64 v[220:221], v[220:221], 0, s[26:27]
	s_mov_b32 m0, s62
	ds_read_b128 v[180:183], v190 offset:49152
	ds_read_b128 v[192:195], v190 offset:50176
	ds_read_b128 v[196:199], v190 offset:51200
	ds_read_b128 v[200:203], v190 offset:52224
	ds_read_b128 v[204:207], v190 offset:53248
	ds_read_b128 v[208:211], v190 offset:54272
	ds_read_b128 v[212:215], v190 offset:55296
	ds_read_b128 v[216:219], v190 offset:56320
	global_load_lds_dwordx4 v[220:221], off
	s_add_i32 m0, s62, 0x2000
	s_add_u32 s60, s60, 0x40080
	v_lshl_add_u64 v[220:221], v[222:223], 0, s[26:27]
	s_addc_u32 s61, s61, 0
	s_add_i32 s62, s82, s66
	global_load_lds_dwordx4 v[220:221], off
	v_lshl_add_u64 v[220:221], s[60:61], 0, v[154:155]
	s_mov_b32 m0, s62
	s_nop 0
	global_load_lds_dwordx4 v[220:221], off
	v_lshl_add_u64 v[220:221], s[60:61], 0, v[162:163]
	s_add_i32 m0, s62, 0x2000
	s_nop 0
	global_load_lds_dwordx4 v[220:221], off
	v_lshl_add_u64 v[220:221], v[224:225], 0, s[26:27]
	s_mov_b32 m0, s3
	s_nop 0
	global_load_lds_dwordx4 v[220:221], off
	v_lshl_add_u64 v[220:221], v[226:227], 0, s[26:27]
	s_mov_b32 m0, s72
	s_nop 0
	global_load_lds_dwordx4 v[220:221], off
	s_waitcnt vmcnt(8)
	s_waitcnt lgkmcnt(0)
	s_barrier
	s_setprio 1
	s_waitcnt lgkmcnt(0)
	v_mfma_f32_16x16x32_bf16 v[60:63], v[128:131], v[180:183], v[60:63]
	v_mfma_f32_16x16x32_bf16 v[56:59], v[136:139], v[180:183], v[56:59]
	v_mfma_f32_16x16x32_bf16 v[40:43], v[136:139], v[196:199], v[40:43]
	v_mfma_f32_16x16x32_bf16 v[44:47], v[128:131], v[196:199], v[44:47]
	v_mfma_f32_16x16x32_bf16 v[28:31], v[128:131], v[204:207], v[28:31]
	v_mfma_f32_16x16x32_bf16 v[24:27], v[136:139], v[204:207], v[24:27]
	v_mfma_f32_16x16x32_bf16 v[8:11], v[136:139], v[212:215], v[8:11]
	v_mfma_f32_16x16x32_bf16 v[12:15], v[128:131], v[212:215], v[12:15]
	v_mfma_f32_16x16x32_bf16 v[60:63], v[132:135], v[192:195], v[60:63]
	v_mfma_f32_16x16x32_bf16 v[56:59], v[140:143], v[192:195], v[56:59]
	v_mfma_f32_16x16x32_bf16 v[40:43], v[140:143], v[200:203], v[40:43]
	v_mfma_f32_16x16x32_bf16 v[44:47], v[132:135], v[200:203], v[44:47]
	v_mfma_f32_16x16x32_bf16 v[28:31], v[132:135], v[208:211], v[28:31]
	v_mfma_f32_16x16x32_bf16 v[24:27], v[140:143], v[208:211], v[24:27]
	v_mfma_f32_16x16x32_bf16 v[8:11], v[140:143], v[216:219], v[8:11]
	v_mfma_f32_16x16x32_bf16 v[12:15], v[132:135], v[216:219], v[12:15]
	s_setprio 0
	s_setprio 1
	v_mfma_f32_16x16x32_bf16 v[52:55], v[144:147], v[180:183], v[52:55]
	v_mfma_f32_16x16x32_bf16 v[48:51], v[172:175], v[180:183], v[48:51]
	v_mfma_f32_16x16x32_bf16 v[32:35], v[172:175], v[196:199], v[32:35]
	v_mfma_f32_16x16x32_bf16 v[36:39], v[144:147], v[196:199], v[36:39]
	v_mfma_f32_16x16x32_bf16 v[20:23], v[144:147], v[204:207], v[20:23]
	v_mfma_f32_16x16x32_bf16 v[16:19], v[172:175], v[204:207], v[16:19]
	v_mfma_f32_16x16x32_bf16 v[0:3], v[172:175], v[212:215], v[0:3]
	v_mfma_f32_16x16x32_bf16 v[4:7], v[144:147], v[212:215], v[4:7]
	v_mfma_f32_16x16x32_bf16 v[52:55], v[148:151], v[192:195], v[52:55]
	v_mfma_f32_16x16x32_bf16 v[48:51], v[176:179], v[192:195], v[48:51]
	v_mfma_f32_16x16x32_bf16 v[32:35], v[176:179], v[200:203], v[32:35]
	v_mfma_f32_16x16x32_bf16 v[36:39], v[148:151], v[200:203], v[36:39]
	v_mfma_f32_16x16x32_bf16 v[20:23], v[148:151], v[208:211], v[20:23]
	v_mfma_f32_16x16x32_bf16 v[16:19], v[176:179], v[208:211], v[16:19]
	v_mfma_f32_16x16x32_bf16 v[0:3], v[176:179], v[216:219], v[0:3]
	v_mfma_f32_16x16x32_bf16 v[4:7], v[148:151], v[216:219], v[4:7]
	s_setprio 0
	s_barrier
	s_add_i32 s80, s80, 2
	s_add_u32 s78, s78, 0x100
	s_addc_u32 s79, s79, 0
	s_add_u32 s58, s58, 0x100
	s_addc_u32 s59, s59, 0
	s_cmp_gt_u32 s80, 13
	s_cbranch_scc0 .LBB0_1011
	s_and_b64 vcc, exec, s[28:29]
	s_cbranch_vccz .LBB0_1014
	s_barrier

.LBB0_1096:
	s_ashr_i32 s25, s24, 31
	s_lshl_b64 s[26:27], s[24:25], 19
	s_add_u32 s26, s3, s26
	s_addc_u32 s27, s33, s27
	s_and_b64 s[28:29], s[6:7], exec
	s_cselect_b32 s25, s27, s47
	s_cselect_b32 s65, s26, s46
	s_ashr_i32 s23, s22, 31
	s_lshl_b64 s[28:29], s[22:23], 19
	s_add_u32 s28, s35, s28
	s_addc_u32 s29, s48, s29
	s_and_b64 s[66:67], s[6:7], exec
	s_cselect_b32 s66, s29, s45
	s_cselect_b32 s67, s28, s44
	s_lshl_b32 s23, s30, 8
	v_add_u32_e32 v0, s23, v148
	s_add_u32 s68, s44, 0x100
	v_ashrrev_i32_e32 v1, 31, v0
	s_addc_u32 s69, s45, 0
	v_lshl_add_u64 v[144:145], v[0:1], 4, s[12:13]
	s_add_u32 s30, s46, 0x40080
	s_addc_u32 s31, s47, 0
	s_mov_b32 s70, -2
	s_mov_b64 s[44:45], 0
	v_add_u32_e32 v153, s61, v147
	ds_read_b128 v[160:163], v153
	ds_read_b128 v[164:167], v153 offset:1024
	ds_read_b128 v[168:171], v153 offset:2048
	ds_read_b128 v[172:175], v153 offset:3072
	v_add_u32_e32 v153, s62, v147
	ds_read_b128 v[176:179], v153
	ds_read_b128 v[180:183], v153 offset:1024
	ds_read_b128 v[184:187], v153 offset:2048
	ds_read_b128 v[188:191], v153 offset:3072
	s_add_u32 s46, s30, 0xfffc0080
	s_addc_u32 s47, s31, -1
	s_and_b64 s[44:45], s[44:45], exec
	s_cselect_b32 s47, s25, s47
	s_cselect_b32 s46, s65, s46
	s_cselect_b32 s45, s66, s69
	s_cselect_b32 s44, s67, s68
	v_lshl_add_u64 v[154:155], s[30:31], 0, v[138:139]
	s_add_i32 m0, s52, 0xc000
	ds_read_b128 v[192:195], v150
	ds_read_b128 v[196:199], v150 offset:1024
	ds_read_b128 v[200:203], v150 offset:2048
	ds_read_b128 v[204:207], v150 offset:3072
	ds_read_b128 v[208:211], v150 offset:4096
	ds_read_b128 v[212:215], v150 offset:5120
	ds_read_b128 v[216:219], v150 offset:6144
	ds_read_b128 v[220:223], v150 offset:7168
	global_load_lds_dwordx4 v[154:155], off
	v_lshl_add_u64 v[154:155], s[30:31], 0, v[136:137]
	s_add_i32 m0, s52, 0xe000
	s_nop 0
	global_load_lds_dwordx4 v[154:155], off
	s_waitcnt vmcnt(8)
	s_waitcnt lgkmcnt(0)
	s_barrier
	s_setprio 1
	s_waitcnt lgkmcnt(0)
	v_mfma_f32_16x16x32_bf16 v[124:127], v[160:163], v[192:195], 0
	v_mfma_f32_16x16x32_bf16 v[116:119], v[168:171], v[192:195], 0
	v_mfma_f32_16x16x32_bf16 v[108:111], v[160:163], v[200:203], 0
	v_mfma_f32_16x16x32_bf16 v[100:103], v[168:171], v[200:203], 0
	v_mfma_f32_16x16x32_bf16 v[92:95], v[160:163], v[208:211], 0
	v_mfma_f32_16x16x32_bf16 v[84:87], v[168:171], v[208:211], 0
	v_mfma_f32_16x16x32_bf16 v[76:79], v[160:163], v[216:219], 0
	v_mfma_f32_16x16x32_bf16 v[68:71], v[168:171], v[216:219], 0
	v_mfma_f32_16x16x32_bf16 v[124:127], v[164:167], v[196:199], v[124:127]
	v_mfma_f32_16x16x32_bf16 v[116:119], v[172:175], v[196:199], v[116:119]
	v_mfma_f32_16x16x32_bf16 v[108:111], v[164:167], v[204:207], v[108:111]
	v_mfma_f32_16x16x32_bf16 v[100:103], v[172:175], v[204:207], v[100:103]
	v_mfma_f32_16x16x32_bf16 v[92:95], v[164:167], v[212:215], v[92:95]
	v_mfma_f32_16x16x32_bf16 v[84:87], v[172:175], v[212:215], v[84:87]
	v_mfma_f32_16x16x32_bf16 v[76:79], v[164:167], v[220:223], v[76:79]
	v_mfma_f32_16x16x32_bf16 v[68:71], v[172:175], v[220:223], v[68:71]
	s_setprio 0
	s_setprio 1
	v_mfma_f32_16x16x32_bf16 v[120:123], v[176:179], v[192:195], 0
	v_mfma_f32_16x16x32_bf16 v[112:115], v[184:187], v[192:195], 0
	v_mfma_f32_16x16x32_bf16 v[104:107], v[176:179], v[200:203], 0
	v_mfma_f32_16x16x32_bf16 v[96:99], v[184:187], v[200:203], 0
	v_mfma_f32_16x16x32_bf16 v[88:91], v[176:179], v[208:211], 0
	v_mfma_f32_16x16x32_bf16 v[80:83], v[184:187], v[208:211], 0
	v_mfma_f32_16x16x32_bf16 v[72:75], v[176:179], v[216:219], 0
	v_mfma_f32_16x16x32_bf16 v[64:67], v[184:187], v[216:219], 0
	v_mfma_f32_16x16x32_bf16 v[120:123], v[180:183], v[196:199], v[120:123]
	v_mfma_f32_16x16x32_bf16 v[112:115], v[188:191], v[196:199], v[112:115]
	v_mfma_f32_16x16x32_bf16 v[104:107], v[180:183], v[204:207], v[104:107]
	v_mfma_f32_16x16x32_bf16 v[96:99], v[188:191], v[204:207], v[96:99]
	v_mfma_f32_16x16x32_bf16 v[88:91], v[180:183], v[212:215], v[88:91]
	v_mfma_f32_16x16x32_bf16 v[80:83], v[188:191], v[212:215], v[80:83]
	v_mfma_f32_16x16x32_bf16 v[72:75], v[180:183], v[220:223], v[72:75]
	v_mfma_f32_16x16x32_bf16 v[64:67], v[188:191], v[220:223], v[64:67]
	s_setprio 0
	s_barrier
	s_add_i32 s71, s61, s49
	v_lshl_add_u64 v[154:155], s[44:45], 0, v[132:133]
	s_mov_b32 m0, s71
	ds_read_b128 v[192:195], v150 offset:16384
	ds_read_b128 v[196:199], v150 offset:17408
	ds_read_b128 v[200:203], v150 offset:18432
	ds_read_b128 v[204:207], v150 offset:19456
	ds_read_b128 v[208:211], v150 offset:20480
	ds_read_b128 v[212:215], v150 offset:21504
	ds_read_b128 v[216:219], v150 offset:22528
	ds_read_b128 v[220:223], v150 offset:23552
	global_load_lds_dwordx4 v[154:155], off
	s_add_i32 m0, s71, 0x2000
	s_add_u32 s72, s44, 0x40000
	v_lshl_add_u64 v[224:225], s[44:45], 0, v[128:129]
	s_addc_u32 s73, s45, 0
	s_add_i32 s71, s62, s49
	global_load_lds_dwordx4 v[224:225], off
	v_lshl_add_u64 v[226:227], s[72:73], 0, v[132:133]
	s_mov_b32 m0, s71
	v_lshl_add_u64 v[228:229], s[46:47], 0, v[130:131]
	global_load_lds_dwordx4 v[226:227], off
	v_lshl_add_u64 v[226:227], s[72:73], 0, v[128:129]
	s_add_i32 m0, s71, 0x2000
	s_nop 0
	global_load_lds_dwordx4 v[226:227], off
	v_lshl_add_u64 v[226:227], s[46:47], 0, v[134:135]
	s_mov_b32 m0, s52
	s_nop 0
	global_load_lds_dwordx4 v[226:227], off
	s_mov_b32 m0, s53
	s_nop 0
	global_load_lds_dwordx4 v[228:229], off
	s_waitcnt vmcnt(8)
	s_waitcnt lgkmcnt(0)
	s_barrier
	s_setprio 1
	s_waitcnt lgkmcnt(0)
	v_mfma_f32_16x16x32_bf16 v[60:63], v[160:163], v[192:195], 0
	v_mfma_f32_16x16x32_bf16 v[52:55], v[168:171], v[192:195], 0
	v_mfma_f32_16x16x32_bf16 v[44:47], v[160:163], v[200:203], 0
	v_mfma_f32_16x16x32_bf16 v[36:39], v[168:171], v[200:203], 0
	v_mfma_f32_16x16x32_bf16 v[28:31], v[160:163], v[208:211], 0
	v_mfma_f32_16x16x32_bf16 v[20:23], v[168:171], v[208:211], 0
	v_mfma_f32_16x16x32_bf16 v[12:15], v[160:163], v[216:219], 0
	v_mfma_f32_16x16x32_bf16 v[4:7], v[168:171], v[216:219], 0
	v_mfma_f32_16x16x32_bf16 v[60:63], v[164:167], v[196:199], v[60:63]
	v_mfma_f32_16x16x32_bf16 v[52:55], v[172:175], v[196:199], v[52:55]
	v_mfma_f32_16x16x32_bf16 v[44:47], v[164:167], v[204:207], v[44:47]
	v_mfma_f32_16x16x32_bf16 v[36:39], v[172:175], v[204:207], v[36:39]
	v_mfma_f32_16x16x32_bf16 v[28:31], v[164:167], v[212:215], v[28:31]
	v_mfma_f32_16x16x32_bf16 v[20:23], v[172:175], v[212:215], v[20:23]
	v_mfma_f32_16x16x32_bf16 v[12:15], v[164:167], v[220:223], v[12:15]
	v_mfma_f32_16x16x32_bf16 v[4:7], v[172:175], v[220:223], v[4:7]
	s_setprio 0
	s_setprio 1
	v_mfma_f32_16x16x32_bf16 v[56:59], v[176:179], v[192:195], 0
	v_mfma_f32_16x16x32_bf16 v[48:51], v[184:187], v[192:195], 0
	v_mfma_f32_16x16x32_bf16 v[40:43], v[176:179], v[200:203], 0
	v_mfma_f32_16x16x32_bf16 v[32:35], v[184:187], v[200:203], 0
	v_mfma_f32_16x16x32_bf16 v[24:27], v[176:179], v[208:211], 0
	v_mfma_f32_16x16x32_bf16 v[16:19], v[184:187], v[208:211], 0
	v_mfma_f32_16x16x32_bf16 v[8:11], v[176:179], v[216:219], 0
	v_mfma_f32_16x16x32_bf16 v[0:3], v[184:187], v[216:219], 0
	v_mfma_f32_16x16x32_bf16 v[56:59], v[180:183], v[196:199], v[56:59]
	v_mfma_f32_16x16x32_bf16 v[48:51], v[188:191], v[196:199], v[48:51]
	v_mfma_f32_16x16x32_bf16 v[40:43], v[180:183], v[204:207], v[40:43]
	v_mfma_f32_16x16x32_bf16 v[32:35], v[188:191], v[204:207], v[32:35]
	v_mfma_f32_16x16x32_bf16 v[24:27], v[180:183], v[212:215], v[24:27]
	v_mfma_f32_16x16x32_bf16 v[16:19], v[188:191], v[212:215], v[16:19]
	v_mfma_f32_16x16x32_bf16 v[8:11], v[180:183], v[220:223], v[8:11]
	v_mfma_f32_16x16x32_bf16 v[0:3], v[188:191], v[220:223], v[0:3]
	s_setprio 0
	s_barrier
	s_add_i32 s71, 0, 0x18000
	v_add_u32_e32 v153, s71, v147
	s_add_i32 s72, 0, 0x1c000
	ds_read_b128 v[160:163], v153
	ds_read_b128 v[164:167], v153 offset:1024
	ds_read_b128 v[168:171], v153 offset:2048
	ds_read_b128 v[172:175], v153 offset:3072
	v_add_u32_e32 v153, s72, v147
	ds_read_b128 v[176:179], v153
	ds_read_b128 v[180:183], v153 offset:1024
	ds_read_b128 v[184:187], v153 offset:2048
	ds_read_b128 v[188:191], v153 offset:3072
	s_add_u32 s46, s46, 0x40000
	s_addc_u32 s47, s47, 0
	s_mov_b32 m0, s54
	v_lshl_add_u64 v[230:231], s[46:47], 0, v[134:135]
	ds_read_b128 v[192:195], v150 offset:32768
	ds_read_b128 v[196:199], v150 offset:33792
	ds_read_b128 v[200:203], v150 offset:34816
	ds_read_b128 v[204:207], v150 offset:35840
	ds_read_b128 v[208:211], v150 offset:36864
	ds_read_b128 v[212:215], v150 offset:37888
	ds_read_b128 v[216:219], v150 offset:38912
	ds_read_b128 v[220:223], v150 offset:39936
	global_load_lds_dwordx4 v[230:231], off
	v_lshl_add_u64 v[230:231], s[46:47], 0, v[130:131]
	s_mov_b32 m0, s55
	s_nop 0
	global_load_lds_dwordx4 v[230:231], off
	s_waitcnt vmcnt(8)
	s_waitcnt lgkmcnt(0)
	s_barrier
	s_setprio 1
	s_waitcnt lgkmcnt(0)
	v_mfma_f32_16x16x32_bf16 v[124:127], v[160:163], v[192:195], v[124:127]
	v_mfma_f32_16x16x32_bf16 v[116:119], v[168:171], v[192:195], v[116:119]
	v_mfma_f32_16x16x32_bf16 v[100:103], v[168:171], v[200:203], v[100:103]
	v_mfma_f32_16x16x32_bf16 v[108:111], v[160:163], v[200:203], v[108:111]
	v_mfma_f32_16x16x32_bf16 v[92:95], v[160:163], v[208:211], v[92:95]
	v_mfma_f32_16x16x32_bf16 v[84:87], v[168:171], v[208:211], v[84:87]
	v_mfma_f32_16x16x32_bf16 v[68:71], v[168:171], v[216:219], v[68:71]
	v_mfma_f32_16x16x32_bf16 v[76:79], v[160:163], v[216:219], v[76:79]
	v_mfma_f32_16x16x32_bf16 v[124:127], v[164:167], v[196:199], v[124:127]
	v_mfma_f32_16x16x32_bf16 v[116:119], v[172:175], v[196:199], v[116:119]
	v_mfma_f32_16x16x32_bf16 v[100:103], v[172:175], v[204:207], v[100:103]
	v_mfma_f32_16x16x32_bf16 v[108:111], v[164:167], v[204:207], v[108:111]
	v_mfma_f32_16x16x32_bf16 v[92:95], v[164:167], v[212:215], v[92:95]
	v_mfma_f32_16x16x32_bf16 v[84:87], v[172:175], v[212:215], v[84:87]
	v_mfma_f32_16x16x32_bf16 v[68:71], v[172:175], v[220:223], v[68:71]
	v_mfma_f32_16x16x32_bf16 v[76:79], v[164:167], v[220:223], v[76:79]
	s_setprio 0
	s_setprio 1
	v_mfma_f32_16x16x32_bf16 v[120:123], v[176:179], v[192:195], v[120:123]
	v_mfma_f32_16x16x32_bf16 v[112:115], v[184:187], v[192:195], v[112:115]
	v_mfma_f32_16x16x32_bf16 v[96:99], v[184:187], v[200:203], v[96:99]
	v_mfma_f32_16x16x32_bf16 v[104:107], v[176:179], v[200:203], v[104:107]
	v_mfma_f32_16x16x32_bf16 v[88:91], v[176:179], v[208:211], v[88:91]
	v_mfma_f32_16x16x32_bf16 v[80:83], v[184:187], v[208:211], v[80:83]
	v_mfma_f32_16x16x32_bf16 v[64:67], v[184:187], v[216:219], v[64:67]
	v_mfma_f32_16x16x32_bf16 v[72:75], v[176:179], v[216:219], v[72:75]
	v_mfma_f32_16x16x32_bf16 v[120:123], v[180:183], v[196:199], v[120:123]
	v_mfma_f32_16x16x32_bf16 v[112:115], v[188:191], v[196:199], v[112:115]
	v_mfma_f32_16x16x32_bf16 v[96:99], v[188:191], v[204:207], v[96:99]
	v_mfma_f32_16x16x32_bf16 v[104:107], v[180:183], v[204:207], v[104:107]
	v_mfma_f32_16x16x32_bf16 v[88:91], v[180:183], v[212:215], v[88:91]
	v_mfma_f32_16x16x32_bf16 v[80:83], v[188:191], v[212:215], v[80:83]
	v_mfma_f32_16x16x32_bf16 v[64:67], v[188:191], v[220:223], v[64:67]
	v_mfma_f32_16x16x32_bf16 v[72:75], v[180:183], v[220:223], v[72:75]
	s_setprio 0
	s_barrier
	s_add_i32 s46, s71, s49
	v_lshl_add_u64 v[154:155], v[154:155], 0, s[14:15]
	s_mov_b32 m0, s46
	ds_read_b128 v[192:195], v150 offset:49152
	ds_read_b128 v[196:199], v150 offset:50176
	ds_read_b128 v[200:203], v150 offset:51200
	ds_read_b128 v[204:207], v150 offset:52224
	ds_read_b128 v[208:211], v150 offset:53248
	ds_read_b128 v[212:215], v150 offset:54272
	ds_read_b128 v[216:219], v150 offset:55296
	ds_read_b128 v[220:223], v150 offset:56320
	global_load_lds_dwordx4 v[154:155], off
	s_add_i32 m0, s46, 0x2000
	s_add_u32 s44, s44, 0x40080
	v_lshl_add_u64 v[154:155], v[224:225], 0, s[14:15]
	s_addc_u32 s45, s45, 0
	s_add_i32 s46, s72, s49
	global_load_lds_dwordx4 v[154:155], off
	v_lshl_add_u64 v[154:155], s[44:45], 0, v[132:133]
	s_mov_b32 m0, s46
	s_nop 0
	global_load_lds_dwordx4 v[154:155], off
	v_lshl_add_u64 v[154:155], s[44:45], 0, v[128:129]
	s_add_i32 m0, s46, 0x2000
	s_nop 0
	global_load_lds_dwordx4 v[154:155], off
	v_lshl_add_u64 v[154:155], v[226:227], 0, s[14:15]
	s_mov_b32 m0, s57
	s_nop 0
	global_load_lds_dwordx4 v[154:155], off
	v_lshl_add_u64 v[154:155], v[228:229], 0, s[14:15]
	s_mov_b32 m0, s58
	s_nop 0
	global_load_lds_dwordx4 v[154:155], off
	s_waitcnt vmcnt(8)
	s_waitcnt lgkmcnt(0)
	s_barrier
	s_setprio 1
	s_waitcnt lgkmcnt(0)
	v_mfma_f32_16x16x32_bf16 v[60:63], v[160:163], v[192:195], v[60:63]
	v_mfma_f32_16x16x32_bf16 v[52:55], v[168:171], v[192:195], v[52:55]
	v_mfma_f32_16x16x32_bf16 v[36:39], v[168:171], v[200:203], v[36:39]
	v_mfma_f32_16x16x32_bf16 v[44:47], v[160:163], v[200:203], v[44:47]
	v_mfma_f32_16x16x32_bf16 v[28:31], v[160:163], v[208:211], v[28:31]
	v_mfma_f32_16x16x32_bf16 v[20:23], v[168:171], v[208:211], v[20:23]
	v_mfma_f32_16x16x32_bf16 v[4:7], v[168:171], v[216:219], v[4:7]
	v_mfma_f32_16x16x32_bf16 v[12:15], v[160:163], v[216:219], v[12:15]
	v_mfma_f32_16x16x32_bf16 v[60:63], v[164:167], v[196:199], v[60:63]
	v_mfma_f32_16x16x32_bf16 v[52:55], v[172:175], v[196:199], v[52:55]
	v_mfma_f32_16x16x32_bf16 v[36:39], v[172:175], v[204:207], v[36:39]
	v_mfma_f32_16x16x32_bf16 v[44:47], v[164:167], v[204:207], v[44:47]
	v_mfma_f32_16x16x32_bf16 v[28:31], v[164:167], v[212:215], v[28:31]
	v_mfma_f32_16x16x32_bf16 v[20:23], v[172:175], v[212:215], v[20:23]
	v_mfma_f32_16x16x32_bf16 v[4:7], v[172:175], v[220:223], v[4:7]
	v_mfma_f32_16x16x32_bf16 v[12:15], v[164:167], v[220:223], v[12:15]
	s_setprio 0
	s_setprio 1
	v_mfma_f32_16x16x32_bf16 v[56:59], v[176:179], v[192:195], v[56:59]
	v_mfma_f32_16x16x32_bf16 v[48:51], v[184:187], v[192:195], v[48:51]
	v_mfma_f32_16x16x32_bf16 v[32:35], v[184:187], v[200:203], v[32:35]
	v_mfma_f32_16x16x32_bf16 v[40:43], v[176:179], v[200:203], v[40:43]
	v_mfma_f32_16x16x32_bf16 v[24:27], v[176:179], v[208:211], v[24:27]
	v_mfma_f32_16x16x32_bf16 v[16:19], v[184:187], v[208:211], v[16:19]
	v_mfma_f32_16x16x32_bf16 v[0:3], v[184:187], v[216:219], v[0:3]
	v_mfma_f32_16x16x32_bf16 v[8:11], v[176:179], v[216:219], v[8:11]
	v_mfma_f32_16x16x32_bf16 v[56:59], v[180:183], v[196:199], v[56:59]
	v_mfma_f32_16x16x32_bf16 v[48:51], v[188:191], v[196:199], v[48:51]
	v_mfma_f32_16x16x32_bf16 v[32:35], v[188:191], v[204:207], v[32:35]
	v_mfma_f32_16x16x32_bf16 v[40:43], v[180:183], v[204:207], v[40:43]
	v_mfma_f32_16x16x32_bf16 v[24:27], v[180:183], v[212:215], v[24:27]
	v_mfma_f32_16x16x32_bf16 v[16:19], v[188:191], v[212:215], v[16:19]
	v_mfma_f32_16x16x32_bf16 v[0:3], v[188:191], v[220:223], v[0:3]
	v_mfma_f32_16x16x32_bf16 v[8:11], v[180:183], v[220:223], v[8:11]
	s_setprio 0
	s_barrier
	s_add_i32 s70, s70, 2
	s_add_u32 s68, s68, 0x100
	s_addc_u32 s69, s69, 0
	s_add_u32 s30, s30, 0x100
	s_addc_u32 s31, s31, 0
	s_branch .LBB0_1098
.LBB0_1097:
	v_add_u32_e32 v153, s61, v147
	ds_read_b128 v[160:163], v153
	ds_read_b128 v[164:167], v153 offset:1024
	ds_read_b128 v[168:171], v153 offset:2048
	ds_read_b128 v[172:175], v153 offset:3072
	v_add_u32_e32 v153, s62, v147
	ds_read_b128 v[176:179], v153
	ds_read_b128 v[180:183], v153 offset:1024
	ds_read_b128 v[184:187], v153 offset:2048
	ds_read_b128 v[188:191], v153 offset:3072
	s_add_u32 s46, s30, 0xfffc0080
	s_addc_u32 s47, s31, -1
	s_and_b64 s[44:45], s[44:45], exec
	s_cselect_b32 s47, s25, s47
	s_cselect_b32 s46, s65, s46
	s_cselect_b32 s45, s66, s69
	s_cselect_b32 s44, s67, s68
	v_lshl_add_u64 v[154:155], s[30:31], 0, v[138:139]
	s_add_i32 m0, s52, 0xc000
	ds_read_b128 v[192:195], v150
	ds_read_b128 v[196:199], v150 offset:1024
	ds_read_b128 v[200:203], v150 offset:2048
	ds_read_b128 v[204:207], v150 offset:3072
	ds_read_b128 v[208:211], v150 offset:4096
	ds_read_b128 v[212:215], v150 offset:5120
	ds_read_b128 v[216:219], v150 offset:6144
	ds_read_b128 v[220:223], v150 offset:7168
	global_load_lds_dwordx4 v[154:155], off
	v_lshl_add_u64 v[154:155], s[30:31], 0, v[136:137]
	s_add_i32 m0, s52, 0xe000
	s_nop 0
	global_load_lds_dwordx4 v[154:155], off
	s_waitcnt vmcnt(8)
	s_waitcnt lgkmcnt(0)
	s_barrier
	s_setprio 1
	s_waitcnt lgkmcnt(0)
	v_mfma_f32_16x16x32_bf16 v[124:127], v[160:163], v[192:195], v[124:127]
	v_mfma_f32_16x16x32_bf16 v[116:119], v[168:171], v[192:195], v[116:119]
	v_mfma_f32_16x16x32_bf16 v[100:103], v[168:171], v[200:203], v[100:103]
	v_mfma_f32_16x16x32_bf16 v[108:111], v[160:163], v[200:203], v[108:111]
	v_mfma_f32_16x16x32_bf16 v[92:95], v[160:163], v[208:211], v[92:95]
	v_mfma_f32_16x16x32_bf16 v[84:87], v[168:171], v[208:211], v[84:87]
	v_mfma_f32_16x16x32_bf16 v[68:71], v[168:171], v[216:219], v[68:71]
	v_mfma_f32_16x16x32_bf16 v[76:79], v[160:163], v[216:219], v[76:79]
	v_mfma_f32_16x16x32_bf16 v[124:127], v[164:167], v[196:199], v[124:127]
	v_mfma_f32_16x16x32_bf16 v[116:119], v[172:175], v[196:199], v[116:119]
	v_mfma_f32_16x16x32_bf16 v[100:103], v[172:175], v[204:207], v[100:103]
	v_mfma_f32_16x16x32_bf16 v[108:111], v[164:167], v[204:207], v[108:111]
	v_mfma_f32_16x16x32_bf16 v[92:95], v[164:167], v[212:215], v[92:95]
	v_mfma_f32_16x16x32_bf16 v[84:87], v[172:175], v[212:215], v[84:87]
	v_mfma_f32_16x16x32_bf16 v[68:71], v[172:175], v[220:223], v[68:71]
	v_mfma_f32_16x16x32_bf16 v[76:79], v[164:167], v[220:223], v[76:79]
	s_setprio 0
	s_setprio 1
	v_mfma_f32_16x16x32_bf16 v[120:123], v[176:179], v[192:195], v[120:123]
	v_mfma_f32_16x16x32_bf16 v[112:115], v[184:187], v[192:195], v[112:115]
	v_mfma_f32_16x16x32_bf16 v[96:99], v[184:187], v[200:203], v[96:99]
	v_mfma_f32_16x16x32_bf16 v[104:107], v[176:179], v[200:203], v[104:107]
	v_mfma_f32_16x16x32_bf16 v[88:91], v[176:179], v[208:211], v[88:91]
	v_mfma_f32_16x16x32_bf16 v[80:83], v[184:187], v[208:211], v[80:83]
	v_mfma_f32_16x16x32_bf16 v[64:67], v[184:187], v[216:219], v[64:67]
	v_mfma_f32_16x16x32_bf16 v[72:75], v[176:179], v[216:219], v[72:75]
	v_mfma_f32_16x16x32_bf16 v[120:123], v[180:183], v[196:199], v[120:123]
	v_mfma_f32_16x16x32_bf16 v[112:115], v[188:191], v[196:199], v[112:115]
	v_mfma_f32_16x16x32_bf16 v[96:99], v[188:191], v[204:207], v[96:99]
	v_mfma_f32_16x16x32_bf16 v[104:107], v[180:183], v[204:207], v[104:107]
	v_mfma_f32_16x16x32_bf16 v[88:91], v[180:183], v[212:215], v[88:91]
	v_mfma_f32_16x16x32_bf16 v[80:83], v[188:191], v[212:215], v[80:83]
	v_mfma_f32_16x16x32_bf16 v[64:67], v[188:191], v[220:223], v[64:67]
	v_mfma_f32_16x16x32_bf16 v[72:75], v[180:183], v[220:223], v[72:75]
	s_setprio 0
	s_barrier
	s_add_i32 s71, s61, s49
	v_lshl_add_u64 v[154:155], s[44:45], 0, v[132:133]
	s_mov_b32 m0, s71
	ds_read_b128 v[192:195], v150 offset:16384
	ds_read_b128 v[196:199], v150 offset:17408
	ds_read_b128 v[200:203], v150 offset:18432
	ds_read_b128 v[204:207], v150 offset:19456
	ds_read_b128 v[208:211], v150 offset:20480
	ds_read_b128 v[212:215], v150 offset:21504
	ds_read_b128 v[216:219], v150 offset:22528
	ds_read_b128 v[220:223], v150 offset:23552
	global_load_lds_dwordx4 v[154:155], off
	s_add_i32 m0, s71, 0x2000
	s_add_u32 s72, s44, 0x40000
	v_lshl_add_u64 v[224:225], s[44:45], 0, v[128:129]
	s_addc_u32 s73, s45, 0
	s_add_i32 s71, s62, s49
	global_load_lds_dwordx4 v[224:225], off
	v_lshl_add_u64 v[226:227], s[72:73], 0, v[132:133]
	s_mov_b32 m0, s71
	v_lshl_add_u64 v[228:229], s[46:47], 0, v[130:131]
	global_load_lds_dwordx4 v[226:227], off
	v_lshl_add_u64 v[226:227], s[72:73], 0, v[128:129]
	s_add_i32 m0, s71, 0x2000
	s_nop 0
	global_load_lds_dwordx4 v[226:227], off
	v_lshl_add_u64 v[226:227], s[46:47], 0, v[134:135]
	s_mov_b32 m0, s52
	s_nop 0
	global_load_lds_dwordx4 v[226:227], off
	s_mov_b32 m0, s53
	s_nop 0
	global_load_lds_dwordx4 v[228:229], off
	s_waitcnt vmcnt(8)
	s_waitcnt lgkmcnt(0)
	s_barrier
	s_setprio 1
	s_waitcnt lgkmcnt(0)
	v_mfma_f32_16x16x32_bf16 v[60:63], v[160:163], v[192:195], v[60:63]
	v_mfma_f32_16x16x32_bf16 v[52:55], v[168:171], v[192:195], v[52:55]
	v_mfma_f32_16x16x32_bf16 v[36:39], v[168:171], v[200:203], v[36:39]
	v_mfma_f32_16x16x32_bf16 v[44:47], v[160:163], v[200:203], v[44:47]
	v_mfma_f32_16x16x32_bf16 v[28:31], v[160:163], v[208:211], v[28:31]
	v_mfma_f32_16x16x32_bf16 v[20:23], v[168:171], v[208:211], v[20:23]
	v_mfma_f32_16x16x32_bf16 v[4:7], v[168:171], v[216:219], v[4:7]
	v_mfma_f32_16x16x32_bf16 v[12:15], v[160:163], v[216:219], v[12:15]
	v_mfma_f32_16x16x32_bf16 v[60:63], v[164:167], v[196:199], v[60:63]
	v_mfma_f32_16x16x32_bf16 v[52:55], v[172:175], v[196:199], v[52:55]
	v_mfma_f32_16x16x32_bf16 v[36:39], v[172:175], v[204:207], v[36:39]
	v_mfma_f32_16x16x32_bf16 v[44:47], v[164:167], v[204:207], v[44:47]
	v_mfma_f32_16x16x32_bf16 v[28:31], v[164:167], v[212:215], v[28:31]
	v_mfma_f32_16x16x32_bf16 v[20:23], v[172:175], v[212:215], v[20:23]
	v_mfma_f32_16x16x32_bf16 v[4:7], v[172:175], v[220:223], v[4:7]
	v_mfma_f32_16x16x32_bf16 v[12:15], v[164:167], v[220:223], v[12:15]
	s_setprio 0
	s_setprio 1
	v_mfma_f32_16x16x32_bf16 v[56:59], v[176:179], v[192:195], v[56:59]
	v_mfma_f32_16x16x32_bf16 v[48:51], v[184:187], v[192:195], v[48:51]
	v_mfma_f32_16x16x32_bf16 v[32:35], v[184:187], v[200:203], v[32:35]
	v_mfma_f32_16x16x32_bf16 v[40:43], v[176:179], v[200:203], v[40:43]
	v_mfma_f32_16x16x32_bf16 v[24:27], v[176:179], v[208:211], v[24:27]
	v_mfma_f32_16x16x32_bf16 v[16:19], v[184:187], v[208:211], v[16:19]
	v_mfma_f32_16x16x32_bf16 v[0:3], v[184:187], v[216:219], v[0:3]
	v_mfma_f32_16x16x32_bf16 v[8:11], v[176:179], v[216:219], v[8:11]
	v_mfma_f32_16x16x32_bf16 v[56:59], v[180:183], v[196:199], v[56:59]
	v_mfma_f32_16x16x32_bf16 v[48:51], v[188:191], v[196:199], v[48:51]
	v_mfma_f32_16x16x32_bf16 v[32:35], v[188:191], v[204:207], v[32:35]
	v_mfma_f32_16x16x32_bf16 v[40:43], v[180:183], v[204:207], v[40:43]
	v_mfma_f32_16x16x32_bf16 v[24:27], v[180:183], v[212:215], v[24:27]
	v_mfma_f32_16x16x32_bf16 v[16:19], v[188:191], v[212:215], v[16:19]
	v_mfma_f32_16x16x32_bf16 v[0:3], v[188:191], v[220:223], v[0:3]
	v_mfma_f32_16x16x32_bf16 v[8:11], v[180:183], v[220:223], v[8:11]
	s_setprio 0
	s_barrier
	s_add_i32 s71, 0, 0x18000
	v_add_u32_e32 v153, s71, v147
	s_add_i32 s72, 0, 0x1c000
	ds_read_b128 v[160:163], v153
	ds_read_b128 v[164:167], v153 offset:1024
	ds_read_b128 v[168:171], v153 offset:2048
	ds_read_b128 v[172:175], v153 offset:3072
	v_add_u32_e32 v153, s72, v147
	ds_read_b128 v[176:179], v153
	ds_read_b128 v[180:183], v153 offset:1024
	ds_read_b128 v[184:187], v153 offset:2048
	ds_read_b128 v[188:191], v153 offset:3072
	s_add_u32 s46, s46, 0x40000
	s_addc_u32 s47, s47, 0
	s_mov_b32 m0, s54
	v_lshl_add_u64 v[230:231], s[46:47], 0, v[134:135]
	ds_read_b128 v[192:195], v150 offset:32768
	ds_read_b128 v[196:199], v150 offset:33792
	ds_read_b128 v[200:203], v150 offset:34816
	ds_read_b128 v[204:207], v150 offset:35840
	ds_read_b128 v[208:211], v150 offset:36864
	ds_read_b128 v[212:215], v150 offset:37888
	ds_read_b128 v[216:219], v150 offset:38912
	ds_read_b128 v[220:223], v150 offset:39936
	global_load_lds_dwordx4 v[230:231], off
	v_lshl_add_u64 v[230:231], s[46:47], 0, v[130:131]
	s_mov_b32 m0, s55
	s_nop 0
	global_load_lds_dwordx4 v[230:231], off
	s_waitcnt vmcnt(8)
	s_waitcnt lgkmcnt(0)
	s_barrier
	s_setprio 1
	s_waitcnt lgkmcnt(0)
	v_mfma_f32_16x16x32_bf16 v[124:127], v[160:163], v[192:195], v[124:127]
	v_mfma_f32_16x16x32_bf16 v[116:119], v[168:171], v[192:195], v[116:119]
	v_mfma_f32_16x16x32_bf16 v[100:103], v[168:171], v[200:203], v[100:103]
	v_mfma_f32_16x16x32_bf16 v[108:111], v[160:163], v[200:203], v[108:111]
	v_mfma_f32_16x16x32_bf16 v[92:95], v[160:163], v[208:211], v[92:95]
	v_mfma_f32_16x16x32_bf16 v[84:87], v[168:171], v[208:211], v[84:87]
	v_mfma_f32_16x16x32_bf16 v[68:71], v[168:171], v[216:219], v[68:71]
	v_mfma_f32_16x16x32_bf16 v[76:79], v[160:163], v[216:219], v[76:79]
	v_mfma_f32_16x16x32_bf16 v[124:127], v[164:167], v[196:199], v[124:127]
	v_mfma_f32_16x16x32_bf16 v[116:119], v[172:175], v[196:199], v[116:119]
	v_mfma_f32_16x16x32_bf16 v[100:103], v[172:175], v[204:207], v[100:103]
	v_mfma_f32_16x16x32_bf16 v[108:111], v[164:167], v[204:207], v[108:111]
	v_mfma_f32_16x16x32_bf16 v[92:95], v[164:167], v[212:215], v[92:95]
	v_mfma_f32_16x16x32_bf16 v[84:87], v[172:175], v[212:215], v[84:87]
	v_mfma_f32_16x16x32_bf16 v[68:71], v[172:175], v[220:223], v[68:71]
	v_mfma_f32_16x16x32_bf16 v[76:79], v[164:167], v[220:223], v[76:79]
	s_setprio 0
	s_setprio 1
	v_mfma_f32_16x16x32_bf16 v[120:123], v[176:179], v[192:195], v[120:123]
	v_mfma_f32_16x16x32_bf16 v[112:115], v[184:187], v[192:195], v[112:115]
	v_mfma_f32_16x16x32_bf16 v[96:99], v[184:187], v[200:203], v[96:99]
	v_mfma_f32_16x16x32_bf16 v[104:107], v[176:179], v[200:203], v[104:107]
	v_mfma_f32_16x16x32_bf16 v[88:91], v[176:179], v[208:211], v[88:91]
	v_mfma_f32_16x16x32_bf16 v[80:83], v[184:187], v[208:211], v[80:83]
	v_mfma_f32_16x16x32_bf16 v[64:67], v[184:187], v[216:219], v[64:67]
	v_mfma_f32_16x16x32_bf16 v[72:75], v[176:179], v[216:219], v[72:75]
	v_mfma_f32_16x16x32_bf16 v[120:123], v[180:183], v[196:199], v[120:123]
	v_mfma_f32_16x16x32_bf16 v[112:115], v[188:191], v[196:199], v[112:115]
	v_mfma_f32_16x16x32_bf16 v[96:99], v[188:191], v[204:207], v[96:99]
	v_mfma_f32_16x16x32_bf16 v[104:107], v[180:183], v[204:207], v[104:107]
	v_mfma_f32_16x16x32_bf16 v[88:91], v[180:183], v[212:215], v[88:91]
	v_mfma_f32_16x16x32_bf16 v[80:83], v[188:191], v[212:215], v[80:83]
	v_mfma_f32_16x16x32_bf16 v[64:67], v[188:191], v[220:223], v[64:67]
	v_mfma_f32_16x16x32_bf16 v[72:75], v[180:183], v[220:223], v[72:75]
	s_setprio 0
	s_barrier
	s_add_i32 s46, s71, s49
	v_lshl_add_u64 v[154:155], v[154:155], 0, s[14:15]
	s_mov_b32 m0, s46
	ds_read_b128 v[192:195], v150 offset:49152
	ds_read_b128 v[196:199], v150 offset:50176
	ds_read_b128 v[200:203], v150 offset:51200
	ds_read_b128 v[204:207], v150 offset:52224
	ds_read_b128 v[208:211], v150 offset:53248
	ds_read_b128 v[212:215], v150 offset:54272
	ds_read_b128 v[216:219], v150 offset:55296
	ds_read_b128 v[220:223], v150 offset:56320
	global_load_lds_dwordx4 v[154:155], off
	s_add_i32 m0, s46, 0x2000
	s_add_u32 s44, s44, 0x40080
	v_lshl_add_u64 v[154:155], v[224:225], 0, s[14:15]
	s_addc_u32 s45, s45, 0
	s_add_i32 s46, s72, s49
	global_load_lds_dwordx4 v[154:155], off
	v_lshl_add_u64 v[154:155], s[44:45], 0, v[132:133]
	s_mov_b32 m0, s46
	s_nop 0
	global_load_lds_dwordx4 v[154:155], off
	v_lshl_add_u64 v[154:155], s[44:45], 0, v[128:129]
	s_add_i32 m0, s46, 0x2000
	s_nop 0
	global_load_lds_dwordx4 v[154:155], off
	v_lshl_add_u64 v[154:155], v[226:227], 0, s[14:15]
	s_mov_b32 m0, s57
	s_nop 0
	global_load_lds_dwordx4 v[154:155], off
	v_lshl_add_u64 v[154:155], v[228:229], 0, s[14:15]
	s_mov_b32 m0, s58
	s_nop 0
	global_load_lds_dwordx4 v[154:155], off
	s_waitcnt vmcnt(8)
	s_waitcnt lgkmcnt(0)
	s_barrier
	s_setprio 1
	s_waitcnt lgkmcnt(0)
	v_mfma_f32_16x16x32_bf16 v[60:63], v[160:163], v[192:195], v[60:63]
	v_mfma_f32_16x16x32_bf16 v[52:55], v[168:171], v[192:195], v[52:55]
	v_mfma_f32_16x16x32_bf16 v[36:39], v[168:171], v[200:203], v[36:39]
	v_mfma_f32_16x16x32_bf16 v[44:47], v[160:163], v[200:203], v[44:47]
	v_mfma_f32_16x16x32_bf16 v[28:31], v[160:163], v[208:211], v[28:31]
	v_mfma_f32_16x16x32_bf16 v[20:23], v[168:171], v[208:211], v[20:23]
	v_mfma_f32_16x16x32_bf16 v[4:7], v[168:171], v[216:219], v[4:7]
	v_mfma_f32_16x16x32_bf16 v[12:15], v[160:163], v[216:219], v[12:15]
	v_mfma_f32_16x16x32_bf16 v[60:63], v[164:167], v[196:199], v[60:63]
	v_mfma_f32_16x16x32_bf16 v[52:55], v[172:175], v[196:199], v[52:55]
	v_mfma_f32_16x16x32_bf16 v[36:39], v[172:175], v[204:207], v[36:39]
	v_mfma_f32_16x16x32_bf16 v[44:47], v[164:167], v[204:207], v[44:47]
	v_mfma_f32_16x16x32_bf16 v[28:31], v[164:167], v[212:215], v[28:31]
	v_mfma_f32_16x16x32_bf16 v[20:23], v[172:175], v[212:215], v[20:23]
	v_mfma_f32_16x16x32_bf16 v[4:7], v[172:175], v[220:223], v[4:7]
	v_mfma_f32_16x16x32_bf16 v[12:15], v[164:167], v[220:223], v[12:15]
	s_setprio 0
	s_setprio 1
	v_mfma_f32_16x16x32_bf16 v[56:59], v[176:179], v[192:195], v[56:59]
	v_mfma_f32_16x16x32_bf16 v[48:51], v[184:187], v[192:195], v[48:51]
	v_mfma_f32_16x16x32_bf16 v[32:35], v[184:187], v[200:203], v[32:35]
	v_mfma_f32_16x16x32_bf16 v[40:43], v[176:179], v[200:203], v[40:43]
	v_mfma_f32_16x16x32_bf16 v[24:27], v[176:179], v[208:211], v[24:27]
	v_mfma_f32_16x16x32_bf16 v[16:19], v[184:187], v[208:211], v[16:19]
	v_mfma_f32_16x16x32_bf16 v[0:3], v[184:187], v[216:219], v[0:3]
	v_mfma_f32_16x16x32_bf16 v[8:11], v[176:179], v[216:219], v[8:11]
	v_mfma_f32_16x16x32_bf16 v[56:59], v[180:183], v[196:199], v[56:59]
	v_mfma_f32_16x16x32_bf16 v[48:51], v[188:191], v[196:199], v[48:51]
	v_mfma_f32_16x16x32_bf16 v[32:35], v[188:191], v[204:207], v[32:35]
	v_mfma_f32_16x16x32_bf16 v[40:43], v[180:183], v[204:207], v[40:43]
	v_mfma_f32_16x16x32_bf16 v[24:27], v[180:183], v[212:215], v[24:27]
	v_mfma_f32_16x16x32_bf16 v[16:19], v[188:191], v[212:215], v[16:19]
	v_mfma_f32_16x16x32_bf16 v[0:3], v[188:191], v[220:223], v[0:3]
	v_mfma_f32_16x16x32_bf16 v[8:11], v[180:183], v[220:223], v[8:11]
	s_setprio 0
	s_barrier
	s_add_i32 s70, s70, 2
	s_add_u32 s68, s68, 0x100
	s_addc_u32 s69, s69, 0
	s_add_u32 s30, s30, 0x100
	s_addc_u32 s31, s31, 0
	s_cmp_gt_u32 s70, 13
	s_cbranch_scc1 .LBB0_1100

.LBB0_1180:
	s_add_u32 s72, s50, 0x100
	s_addc_u32 s73, s51, 0
	s_mov_b32 s74, -2
	s_waitcnt lgkmcnt(0)
	ds_read_b128 v[128:131], v188
	ds_read_b128 v[132:135], v188 offset:1024
	ds_read_b128 v[136:139], v188 offset:2048
	ds_read_b128 v[140:143], v188 offset:3072
	ds_read_b128 v[144:147], v189
	ds_read_b128 v[148:151], v189 offset:1024
	ds_read_b128 v[172:175], v189 offset:2048
	ds_read_b128 v[176:179], v189 offset:3072
	s_add_u32 s50, s48, 0x100
	s_addc_u32 s51, s49, 0
	s_cmp_eq_u32 s74, 40
	s_cselect_b32 s55, s11, s51
	s_cselect_b32 s54, s10, s50
	s_cselect_b32 s53, s47, s73
	s_cselect_b32 s52, s46, s72
	v_lshl_add_u64 v[220:221], s[48:49], 0, v[166:167]
	s_add_i32 m0, s59, 0xc000
	ds_read_b128 v[180:183], v190
	ds_read_b128 v[192:195], v190 offset:1024
	ds_read_b128 v[196:199], v190 offset:2048
	ds_read_b128 v[200:203], v190 offset:3072
	ds_read_b128 v[204:207], v190 offset:4096
	ds_read_b128 v[208:211], v190 offset:5120
	ds_read_b128 v[212:215], v190 offset:6144
	ds_read_b128 v[216:219], v190 offset:7168
	global_load_lds_dwordx4 v[220:221], off
	v_lshl_add_u64 v[220:221], s[48:49], 0, v[164:165]
	s_add_i32 m0, s59, 0xe000
	s_nop 0
	global_load_lds_dwordx4 v[220:221], off
	s_waitcnt vmcnt(8)
	s_waitcnt lgkmcnt(0)
	s_barrier
	s_setprio 1
	s_waitcnt lgkmcnt(0)
	v_mfma_f32_16x16x32_bf16 v[124:127], v[128:131], v[180:183], 0
	v_mfma_f32_16x16x32_bf16 v[120:123], v[136:139], v[180:183], 0
	v_mfma_f32_16x16x32_bf16 v[108:111], v[128:131], v[196:199], 0
	v_mfma_f32_16x16x32_bf16 v[104:107], v[136:139], v[196:199], 0
	v_mfma_f32_16x16x32_bf16 v[92:95], v[128:131], v[204:207], 0
	v_mfma_f32_16x16x32_bf16 v[88:91], v[136:139], v[204:207], 0
	v_mfma_f32_16x16x32_bf16 v[76:79], v[128:131], v[212:215], 0
	v_mfma_f32_16x16x32_bf16 v[72:75], v[136:139], v[212:215], 0
	v_mfma_f32_16x16x32_bf16 v[124:127], v[132:135], v[192:195], v[124:127]
	v_mfma_f32_16x16x32_bf16 v[120:123], v[140:143], v[192:195], v[120:123]
	v_mfma_f32_16x16x32_bf16 v[108:111], v[132:135], v[200:203], v[108:111]
	v_mfma_f32_16x16x32_bf16 v[104:107], v[140:143], v[200:203], v[104:107]
	v_mfma_f32_16x16x32_bf16 v[92:95], v[132:135], v[208:211], v[92:95]
	v_mfma_f32_16x16x32_bf16 v[88:91], v[140:143], v[208:211], v[88:91]
	v_mfma_f32_16x16x32_bf16 v[76:79], v[132:135], v[216:219], v[76:79]
	v_mfma_f32_16x16x32_bf16 v[72:75], v[140:143], v[216:219], v[72:75]
	s_setprio 0
	s_setprio 1
	v_mfma_f32_16x16x32_bf16 v[116:119], v[144:147], v[180:183], 0
	v_mfma_f32_16x16x32_bf16 v[112:115], v[172:175], v[180:183], 0
	v_mfma_f32_16x16x32_bf16 v[100:103], v[144:147], v[196:199], 0
	v_mfma_f32_16x16x32_bf16 v[96:99], v[172:175], v[196:199], 0
	v_mfma_f32_16x16x32_bf16 v[84:87], v[144:147], v[204:207], 0
	v_mfma_f32_16x16x32_bf16 v[80:83], v[172:175], v[204:207], 0
	v_mfma_f32_16x16x32_bf16 v[68:71], v[144:147], v[212:215], 0
	v_mfma_f32_16x16x32_bf16 v[64:67], v[172:175], v[212:215], 0
	v_mfma_f32_16x16x32_bf16 v[116:119], v[148:151], v[192:195], v[116:119]
	v_mfma_f32_16x16x32_bf16 v[112:115], v[176:179], v[192:195], v[112:115]
	v_mfma_f32_16x16x32_bf16 v[100:103], v[148:151], v[200:203], v[100:103]
	v_mfma_f32_16x16x32_bf16 v[96:99], v[176:179], v[200:203], v[96:99]
	v_mfma_f32_16x16x32_bf16 v[84:87], v[148:151], v[208:211], v[84:87]
	v_mfma_f32_16x16x32_bf16 v[80:83], v[176:179], v[208:211], v[80:83]
	v_mfma_f32_16x16x32_bf16 v[68:71], v[148:151], v[216:219], v[68:71]
	v_mfma_f32_16x16x32_bf16 v[64:67], v[176:179], v[216:219], v[64:67]
	s_setprio 0
	s_barrier
	s_add_i32 s48, s68, s58
	v_lshl_add_u64 v[220:221], s[52:53], 0, v[154:155]
	s_mov_b32 m0, s48
	ds_read_b128 v[180:183], v190 offset:16384
	ds_read_b128 v[192:195], v190 offset:17408
	ds_read_b128 v[196:199], v190 offset:18432
	ds_read_b128 v[200:203], v190 offset:19456
	ds_read_b128 v[204:207], v190 offset:20480
	ds_read_b128 v[208:211], v190 offset:21504
	ds_read_b128 v[212:215], v190 offset:22528
	ds_read_b128 v[216:219], v190 offset:23552
	global_load_lds_dwordx4 v[220:221], off
	s_add_i32 m0, s48, 0x2000
	s_add_u32 s48, s52, 0xb0000
	v_lshl_add_u64 v[222:223], s[52:53], 0, v[162:163]
	s_addc_u32 s49, s53, 0
	s_add_i32 s75, s69, s58
	global_load_lds_dwordx4 v[222:223], off
	v_lshl_add_u64 v[224:225], s[48:49], 0, v[154:155]
	s_mov_b32 m0, s75
	v_lshl_add_u64 v[226:227], s[54:55], 0, v[160:161]
	global_load_lds_dwordx4 v[224:225], off
	v_lshl_add_u64 v[224:225], s[48:49], 0, v[162:163]
	s_add_i32 m0, s75, 0x2000
	s_nop 0
	global_load_lds_dwordx4 v[224:225], off
	v_lshl_add_u64 v[224:225], s[54:55], 0, v[152:153]
	s_mov_b32 m0, s59
	s_nop 0
	global_load_lds_dwordx4 v[224:225], off
	s_mov_b32 m0, s60
	s_nop 0
	global_load_lds_dwordx4 v[226:227], off
	s_waitcnt vmcnt(8)
	s_waitcnt lgkmcnt(0)
	s_barrier
	s_setprio 1
	s_waitcnt lgkmcnt(0)
	v_mfma_f32_16x16x32_bf16 v[60:63], v[128:131], v[180:183], 0
	v_mfma_f32_16x16x32_bf16 v[56:59], v[136:139], v[180:183], 0
	v_mfma_f32_16x16x32_bf16 v[44:47], v[128:131], v[196:199], 0
	v_mfma_f32_16x16x32_bf16 v[40:43], v[136:139], v[196:199], 0
	v_mfma_f32_16x16x32_bf16 v[28:31], v[128:131], v[204:207], 0
	v_mfma_f32_16x16x32_bf16 v[24:27], v[136:139], v[204:207], 0
	v_mfma_f32_16x16x32_bf16 v[12:15], v[128:131], v[212:215], 0
	v_mfma_f32_16x16x32_bf16 v[8:11], v[136:139], v[212:215], 0
	v_mfma_f32_16x16x32_bf16 v[60:63], v[132:135], v[192:195], v[60:63]
	v_mfma_f32_16x16x32_bf16 v[56:59], v[140:143], v[192:195], v[56:59]
	v_mfma_f32_16x16x32_bf16 v[44:47], v[132:135], v[200:203], v[44:47]
	v_mfma_f32_16x16x32_bf16 v[40:43], v[140:143], v[200:203], v[40:43]
	v_mfma_f32_16x16x32_bf16 v[28:31], v[132:135], v[208:211], v[28:31]
	v_mfma_f32_16x16x32_bf16 v[24:27], v[140:143], v[208:211], v[24:27]
	v_mfma_f32_16x16x32_bf16 v[12:15], v[132:135], v[216:219], v[12:15]
	v_mfma_f32_16x16x32_bf16 v[8:11], v[140:143], v[216:219], v[8:11]
	s_setprio 0
	s_setprio 1
	v_mfma_f32_16x16x32_bf16 v[52:55], v[144:147], v[180:183], 0
	v_mfma_f32_16x16x32_bf16 v[48:51], v[172:175], v[180:183], 0
	v_mfma_f32_16x16x32_bf16 v[36:39], v[144:147], v[196:199], 0
	v_mfma_f32_16x16x32_bf16 v[32:35], v[172:175], v[196:199], 0
	v_mfma_f32_16x16x32_bf16 v[20:23], v[144:147], v[204:207], 0
	v_mfma_f32_16x16x32_bf16 v[16:19], v[172:175], v[204:207], 0
	v_mfma_f32_16x16x32_bf16 v[4:7], v[144:147], v[212:215], 0
	v_mfma_f32_16x16x32_bf16 v[0:3], v[172:175], v[212:215], 0
	v_mfma_f32_16x16x32_bf16 v[52:55], v[148:151], v[192:195], v[52:55]
	v_mfma_f32_16x16x32_bf16 v[48:51], v[176:179], v[192:195], v[48:51]
	v_mfma_f32_16x16x32_bf16 v[36:39], v[148:151], v[200:203], v[36:39]
	v_mfma_f32_16x16x32_bf16 v[32:35], v[176:179], v[200:203], v[32:35]
	v_mfma_f32_16x16x32_bf16 v[20:23], v[148:151], v[208:211], v[20:23]
	v_mfma_f32_16x16x32_bf16 v[16:19], v[176:179], v[208:211], v[16:19]
	v_mfma_f32_16x16x32_bf16 v[4:7], v[148:151], v[216:219], v[4:7]
	v_mfma_f32_16x16x32_bf16 v[0:3], v[176:179], v[216:219], v[0:3]
	s_setprio 0
	s_barrier
	s_add_i32 s75, 0, 0x18000
	s_add_i32 s76, 0, 0x1c000
	v_add_u32_e32 v140, s75, v185
	v_add_u32_e32 v176, s76, v185
	ds_read_b128 v[128:131], v140
	ds_read_b128 v[132:135], v140 offset:1024
	ds_read_b128 v[136:139], v140 offset:2048
	ds_read_b128 v[140:143], v140 offset:3072
	ds_read_b128 v[144:147], v176
	ds_read_b128 v[148:151], v176 offset:1024
	ds_read_b128 v[172:175], v176 offset:2048
	ds_read_b128 v[176:179], v176 offset:3072
	s_add_u32 s48, s54, 0xb0000
	s_addc_u32 s49, s55, 0
	s_mov_b32 m0, s61
	v_lshl_add_u64 v[228:229], s[48:49], 0, v[152:153]
	ds_read_b128 v[180:183], v190 offset:32768
	ds_read_b128 v[192:195], v190 offset:33792
	ds_read_b128 v[196:199], v190 offset:34816
	ds_read_b128 v[200:203], v190 offset:35840
	ds_read_b128 v[204:207], v190 offset:36864
	ds_read_b128 v[208:211], v190 offset:37888
	ds_read_b128 v[212:215], v190 offset:38912
	ds_read_b128 v[216:219], v190 offset:39936
	global_load_lds_dwordx4 v[228:229], off
	v_lshl_add_u64 v[228:229], s[48:49], 0, v[160:161]
	s_mov_b32 m0, s62
	s_nop 0
	global_load_lds_dwordx4 v[228:229], off
	s_waitcnt vmcnt(8)
	s_waitcnt lgkmcnt(0)
	s_barrier
	s_setprio 1
	s_waitcnt lgkmcnt(0)
	v_mfma_f32_16x16x32_bf16 v[124:127], v[128:131], v[180:183], v[124:127]
	v_mfma_f32_16x16x32_bf16 v[120:123], v[136:139], v[180:183], v[120:123]
	v_mfma_f32_16x16x32_bf16 v[104:107], v[136:139], v[196:199], v[104:107]
	v_mfma_f32_16x16x32_bf16 v[108:111], v[128:131], v[196:199], v[108:111]
	v_mfma_f32_16x16x32_bf16 v[92:95], v[128:131], v[204:207], v[92:95]
	v_mfma_f32_16x16x32_bf16 v[88:91], v[136:139], v[204:207], v[88:91]
	v_mfma_f32_16x16x32_bf16 v[72:75], v[136:139], v[212:215], v[72:75]
	v_mfma_f32_16x16x32_bf16 v[76:79], v[128:131], v[212:215], v[76:79]
	v_mfma_f32_16x16x32_bf16 v[124:127], v[132:135], v[192:195], v[124:127]
	v_mfma_f32_16x16x32_bf16 v[120:123], v[140:143], v[192:195], v[120:123]
	v_mfma_f32_16x16x32_bf16 v[104:107], v[140:143], v[200:203], v[104:107]
	v_mfma_f32_16x16x32_bf16 v[108:111], v[132:135], v[200:203], v[108:111]
	v_mfma_f32_16x16x32_bf16 v[92:95], v[132:135], v[208:211], v[92:95]
	v_mfma_f32_16x16x32_bf16 v[88:91], v[140:143], v[208:211], v[88:91]
	v_mfma_f32_16x16x32_bf16 v[72:75], v[140:143], v[216:219], v[72:75]
	v_mfma_f32_16x16x32_bf16 v[76:79], v[132:135], v[216:219], v[76:79]
	s_setprio 0
	s_setprio 1
	v_mfma_f32_16x16x32_bf16 v[116:119], v[144:147], v[180:183], v[116:119]
	v_mfma_f32_16x16x32_bf16 v[112:115], v[172:175], v[180:183], v[112:115]
	v_mfma_f32_16x16x32_bf16 v[96:99], v[172:175], v[196:199], v[96:99]
	v_mfma_f32_16x16x32_bf16 v[100:103], v[144:147], v[196:199], v[100:103]
	v_mfma_f32_16x16x32_bf16 v[84:87], v[144:147], v[204:207], v[84:87]
	v_mfma_f32_16x16x32_bf16 v[80:83], v[172:175], v[204:207], v[80:83]
	v_mfma_f32_16x16x32_bf16 v[64:67], v[172:175], v[212:215], v[64:67]
	v_mfma_f32_16x16x32_bf16 v[68:71], v[144:147], v[212:215], v[68:71]
	v_mfma_f32_16x16x32_bf16 v[116:119], v[148:151], v[192:195], v[116:119]
	v_mfma_f32_16x16x32_bf16 v[112:115], v[176:179], v[192:195], v[112:115]
	v_mfma_f32_16x16x32_bf16 v[96:99], v[176:179], v[200:203], v[96:99]
	v_mfma_f32_16x16x32_bf16 v[100:103], v[148:151], v[200:203], v[100:103]
	v_mfma_f32_16x16x32_bf16 v[84:87], v[148:151], v[208:211], v[84:87]
	v_mfma_f32_16x16x32_bf16 v[80:83], v[176:179], v[208:211], v[80:83]
	v_mfma_f32_16x16x32_bf16 v[64:67], v[176:179], v[216:219], v[64:67]
	v_mfma_f32_16x16x32_bf16 v[68:71], v[148:151], v[216:219], v[68:71]
	s_setprio 0
	s_barrier
	s_add_i32 s48, s75, s58
	v_lshl_add_u64 v[220:221], v[220:221], 0, s[22:23]
	s_mov_b32 m0, s48
	ds_read_b128 v[180:183], v190 offset:49152
	ds_read_b128 v[192:195], v190 offset:50176
	ds_read_b128 v[196:199], v190 offset:51200
	ds_read_b128 v[200:203], v190 offset:52224
	ds_read_b128 v[204:207], v190 offset:53248
	ds_read_b128 v[208:211], v190 offset:54272
	ds_read_b128 v[212:215], v190 offset:55296
	ds_read_b128 v[216:219], v190 offset:56320
	global_load_lds_dwordx4 v[220:221], off
	s_add_i32 m0, s48, 0x2000
	s_add_u32 s48, s52, 0xb0080
	v_lshl_add_u64 v[220:221], v[222:223], 0, s[22:23]
	s_addc_u32 s49, s53, 0
	s_add_i32 s52, s76, s58
	global_load_lds_dwordx4 v[220:221], off
	v_lshl_add_u64 v[220:221], s[48:49], 0, v[154:155]
	s_mov_b32 m0, s52
	s_nop 0
	global_load_lds_dwordx4 v[220:221], off
	v_lshl_add_u64 v[220:221], s[48:49], 0, v[162:163]
	s_add_i32 m0, s52, 0x2000
	s_nop 0
	global_load_lds_dwordx4 v[220:221], off
	v_lshl_add_u64 v[220:221], v[224:225], 0, s[22:23]
	s_mov_b32 m0, s3
	s_nop 0
	global_load_lds_dwordx4 v[220:221], off
	v_lshl_add_u64 v[220:221], v[226:227], 0, s[22:23]
	s_mov_b32 m0, s64
	s_nop 0
	global_load_lds_dwordx4 v[220:221], off
	s_waitcnt vmcnt(8)
	s_waitcnt lgkmcnt(0)
	s_barrier
	s_setprio 1
	s_waitcnt lgkmcnt(0)
	v_mfma_f32_16x16x32_bf16 v[60:63], v[128:131], v[180:183], v[60:63]
	v_mfma_f32_16x16x32_bf16 v[56:59], v[136:139], v[180:183], v[56:59]
	v_mfma_f32_16x16x32_bf16 v[40:43], v[136:139], v[196:199], v[40:43]
	v_mfma_f32_16x16x32_bf16 v[44:47], v[128:131], v[196:199], v[44:47]
	v_mfma_f32_16x16x32_bf16 v[28:31], v[128:131], v[204:207], v[28:31]
	v_mfma_f32_16x16x32_bf16 v[24:27], v[136:139], v[204:207], v[24:27]
	v_mfma_f32_16x16x32_bf16 v[8:11], v[136:139], v[212:215], v[8:11]
	v_mfma_f32_16x16x32_bf16 v[12:15], v[128:131], v[212:215], v[12:15]
	v_mfma_f32_16x16x32_bf16 v[60:63], v[132:135], v[192:195], v[60:63]
	v_mfma_f32_16x16x32_bf16 v[56:59], v[140:143], v[192:195], v[56:59]
	v_mfma_f32_16x16x32_bf16 v[40:43], v[140:143], v[200:203], v[40:43]
	v_mfma_f32_16x16x32_bf16 v[44:47], v[132:135], v[200:203], v[44:47]
	v_mfma_f32_16x16x32_bf16 v[28:31], v[132:135], v[208:211], v[28:31]
	v_mfma_f32_16x16x32_bf16 v[24:27], v[140:143], v[208:211], v[24:27]
	v_mfma_f32_16x16x32_bf16 v[8:11], v[140:143], v[216:219], v[8:11]
	v_mfma_f32_16x16x32_bf16 v[12:15], v[132:135], v[216:219], v[12:15]
	s_setprio 0
	s_setprio 1
	v_mfma_f32_16x16x32_bf16 v[52:55], v[144:147], v[180:183], v[52:55]
	v_mfma_f32_16x16x32_bf16 v[48:51], v[172:175], v[180:183], v[48:51]
	v_mfma_f32_16x16x32_bf16 v[32:35], v[172:175], v[196:199], v[32:35]
	v_mfma_f32_16x16x32_bf16 v[36:39], v[144:147], v[196:199], v[36:39]
	v_mfma_f32_16x16x32_bf16 v[20:23], v[144:147], v[204:207], v[20:23]
	v_mfma_f32_16x16x32_bf16 v[16:19], v[172:175], v[204:207], v[16:19]
	v_mfma_f32_16x16x32_bf16 v[0:3], v[172:175], v[212:215], v[0:3]
	v_mfma_f32_16x16x32_bf16 v[4:7], v[144:147], v[212:215], v[4:7]
	v_mfma_f32_16x16x32_bf16 v[52:55], v[148:151], v[192:195], v[52:55]
	v_mfma_f32_16x16x32_bf16 v[48:51], v[176:179], v[192:195], v[48:51]
	v_mfma_f32_16x16x32_bf16 v[32:35], v[176:179], v[200:203], v[32:35]
	v_mfma_f32_16x16x32_bf16 v[36:39], v[148:151], v[200:203], v[36:39]
	v_mfma_f32_16x16x32_bf16 v[20:23], v[148:151], v[208:211], v[20:23]
	v_mfma_f32_16x16x32_bf16 v[16:19], v[176:179], v[208:211], v[16:19]
	v_mfma_f32_16x16x32_bf16 v[0:3], v[176:179], v[216:219], v[0:3]
	v_mfma_f32_16x16x32_bf16 v[4:7], v[148:151], v[216:219], v[4:7]
	s_setprio 0
	s_barrier
	s_add_i32 s74, s74, 2
	s_add_u32 s72, s72, 0x100
	s_addc_u32 s73, s73, 0
	s_cmp_gt_u32 s74, 41
	s_mov_b64 s[48:49], s[50:51]
.LBB0_1181:
	ds_read_b128 v[128:131], v188
	ds_read_b128 v[132:135], v188 offset:1024
	ds_read_b128 v[136:139], v188 offset:2048
	ds_read_b128 v[140:143], v188 offset:3072
	ds_read_b128 v[144:147], v189
	ds_read_b128 v[148:151], v189 offset:1024
	ds_read_b128 v[172:175], v189 offset:2048
	ds_read_b128 v[176:179], v189 offset:3072
	s_add_u32 s50, s48, 0x100
	s_addc_u32 s51, s49, 0
	s_cmp_eq_u32 s74, 40
	s_cselect_b32 s55, s11, s51
	s_cselect_b32 s54, s10, s50
	s_cselect_b32 s53, s47, s73
	s_cselect_b32 s52, s46, s72
	v_lshl_add_u64 v[220:221], s[48:49], 0, v[166:167]
	s_add_i32 m0, s59, 0xc000
	ds_read_b128 v[180:183], v190
	ds_read_b128 v[192:195], v190 offset:1024
	ds_read_b128 v[196:199], v190 offset:2048
	ds_read_b128 v[200:203], v190 offset:3072
	ds_read_b128 v[204:207], v190 offset:4096
	ds_read_b128 v[208:211], v190 offset:5120
	ds_read_b128 v[212:215], v190 offset:6144
	ds_read_b128 v[216:219], v190 offset:7168
	global_load_lds_dwordx4 v[220:221], off
	v_lshl_add_u64 v[220:221], s[48:49], 0, v[164:165]
	s_add_i32 m0, s59, 0xe000
	s_nop 0
	global_load_lds_dwordx4 v[220:221], off
	s_waitcnt vmcnt(8)
	s_waitcnt lgkmcnt(0)
	s_barrier
	s_setprio 1
	s_waitcnt lgkmcnt(0)
	v_mfma_f32_16x16x32_bf16 v[124:127], v[128:131], v[180:183], v[124:127]
	v_mfma_f32_16x16x32_bf16 v[120:123], v[136:139], v[180:183], v[120:123]
	v_mfma_f32_16x16x32_bf16 v[104:107], v[136:139], v[196:199], v[104:107]
	v_mfma_f32_16x16x32_bf16 v[108:111], v[128:131], v[196:199], v[108:111]
	v_mfma_f32_16x16x32_bf16 v[92:95], v[128:131], v[204:207], v[92:95]
	v_mfma_f32_16x16x32_bf16 v[88:91], v[136:139], v[204:207], v[88:91]
	v_mfma_f32_16x16x32_bf16 v[72:75], v[136:139], v[212:215], v[72:75]
	v_mfma_f32_16x16x32_bf16 v[76:79], v[128:131], v[212:215], v[76:79]
	v_mfma_f32_16x16x32_bf16 v[124:127], v[132:135], v[192:195], v[124:127]
	v_mfma_f32_16x16x32_bf16 v[120:123], v[140:143], v[192:195], v[120:123]
	v_mfma_f32_16x16x32_bf16 v[104:107], v[140:143], v[200:203], v[104:107]
	v_mfma_f32_16x16x32_bf16 v[108:111], v[132:135], v[200:203], v[108:111]
	v_mfma_f32_16x16x32_bf16 v[92:95], v[132:135], v[208:211], v[92:95]
	v_mfma_f32_16x16x32_bf16 v[88:91], v[140:143], v[208:211], v[88:91]
	v_mfma_f32_16x16x32_bf16 v[72:75], v[140:143], v[216:219], v[72:75]
	v_mfma_f32_16x16x32_bf16 v[76:79], v[132:135], v[216:219], v[76:79]
	s_setprio 0
	s_setprio 1
	v_mfma_f32_16x16x32_bf16 v[116:119], v[144:147], v[180:183], v[116:119]
	v_mfma_f32_16x16x32_bf16 v[112:115], v[172:175], v[180:183], v[112:115]
	v_mfma_f32_16x16x32_bf16 v[96:99], v[172:175], v[196:199], v[96:99]
	v_mfma_f32_16x16x32_bf16 v[100:103], v[144:147], v[196:199], v[100:103]
	v_mfma_f32_16x16x32_bf16 v[84:87], v[144:147], v[204:207], v[84:87]
	v_mfma_f32_16x16x32_bf16 v[80:83], v[172:175], v[204:207], v[80:83]
	v_mfma_f32_16x16x32_bf16 v[64:67], v[172:175], v[212:215], v[64:67]
	v_mfma_f32_16x16x32_bf16 v[68:71], v[144:147], v[212:215], v[68:71]
	v_mfma_f32_16x16x32_bf16 v[116:119], v[148:151], v[192:195], v[116:119]
	v_mfma_f32_16x16x32_bf16 v[112:115], v[176:179], v[192:195], v[112:115]
	v_mfma_f32_16x16x32_bf16 v[96:99], v[176:179], v[200:203], v[96:99]
	v_mfma_f32_16x16x32_bf16 v[100:103], v[148:151], v[200:203], v[100:103]
	v_mfma_f32_16x16x32_bf16 v[84:87], v[148:151], v[208:211], v[84:87]
	v_mfma_f32_16x16x32_bf16 v[80:83], v[176:179], v[208:211], v[80:83]
	v_mfma_f32_16x16x32_bf16 v[64:67], v[176:179], v[216:219], v[64:67]
	v_mfma_f32_16x16x32_bf16 v[68:71], v[148:151], v[216:219], v[68:71]
	s_setprio 0
	s_barrier
	s_add_i32 s48, s68, s58
	v_lshl_add_u64 v[220:221], s[52:53], 0, v[154:155]
	s_mov_b32 m0, s48
	ds_read_b128 v[180:183], v190 offset:16384
	ds_read_b128 v[192:195], v190 offset:17408
	ds_read_b128 v[196:199], v190 offset:18432
	ds_read_b128 v[200:203], v190 offset:19456
	ds_read_b128 v[204:207], v190 offset:20480
	ds_read_b128 v[208:211], v190 offset:21504
	ds_read_b128 v[212:215], v190 offset:22528
	ds_read_b128 v[216:219], v190 offset:23552
	global_load_lds_dwordx4 v[220:221], off
	s_add_i32 m0, s48, 0x2000
	s_add_u32 s48, s52, 0xb0000
	v_lshl_add_u64 v[222:223], s[52:53], 0, v[162:163]
	s_addc_u32 s49, s53, 0
	s_add_i32 s75, s69, s58
	global_load_lds_dwordx4 v[222:223], off
	v_lshl_add_u64 v[224:225], s[48:49], 0, v[154:155]
	s_mov_b32 m0, s75
	v_lshl_add_u64 v[226:227], s[54:55], 0, v[160:161]
	global_load_lds_dwordx4 v[224:225], off
	v_lshl_add_u64 v[224:225], s[48:49], 0, v[162:163]
	s_add_i32 m0, s75, 0x2000
	s_nop 0
	global_load_lds_dwordx4 v[224:225], off
	v_lshl_add_u64 v[224:225], s[54:55], 0, v[152:153]
	s_mov_b32 m0, s59
	s_nop 0
	global_load_lds_dwordx4 v[224:225], off
	s_mov_b32 m0, s60
	s_nop 0
	global_load_lds_dwordx4 v[226:227], off
	s_waitcnt vmcnt(8)
	s_waitcnt lgkmcnt(0)
	s_barrier
	s_setprio 1
	s_waitcnt lgkmcnt(0)
	v_mfma_f32_16x16x32_bf16 v[60:63], v[128:131], v[180:183], v[60:63]
	v_mfma_f32_16x16x32_bf16 v[56:59], v[136:139], v[180:183], v[56:59]
	v_mfma_f32_16x16x32_bf16 v[40:43], v[136:139], v[196:199], v[40:43]
	v_mfma_f32_16x16x32_bf16 v[44:47], v[128:131], v[196:199], v[44:47]
	v_mfma_f32_16x16x32_bf16 v[28:31], v[128:131], v[204:207], v[28:31]
	v_mfma_f32_16x16x32_bf16 v[24:27], v[136:139], v[204:207], v[24:27]
	v_mfma_f32_16x16x32_bf16 v[8:11], v[136:139], v[212:215], v[8:11]
	v_mfma_f32_16x16x32_bf16 v[12:15], v[128:131], v[212:215], v[12:15]
	v_mfma_f32_16x16x32_bf16 v[60:63], v[132:135], v[192:195], v[60:63]
	v_mfma_f32_16x16x32_bf16 v[56:59], v[140:143], v[192:195], v[56:59]
	v_mfma_f32_16x16x32_bf16 v[40:43], v[140:143], v[200:203], v[40:43]
	v_mfma_f32_16x16x32_bf16 v[44:47], v[132:135], v[200:203], v[44:47]
	v_mfma_f32_16x16x32_bf16 v[28:31], v[132:135], v[208:211], v[28:31]
	v_mfma_f32_16x16x32_bf16 v[24:27], v[140:143], v[208:211], v[24:27]
	v_mfma_f32_16x16x32_bf16 v[8:11], v[140:143], v[216:219], v[8:11]
	v_mfma_f32_16x16x32_bf16 v[12:15], v[132:135], v[216:219], v[12:15]
	s_setprio 0
	s_setprio 1
	v_mfma_f32_16x16x32_bf16 v[52:55], v[144:147], v[180:183], v[52:55]
	v_mfma_f32_16x16x32_bf16 v[48:51], v[172:175], v[180:183], v[48:51]
	v_mfma_f32_16x16x32_bf16 v[32:35], v[172:175], v[196:199], v[32:35]
	v_mfma_f32_16x16x32_bf16 v[36:39], v[144:147], v[196:199], v[36:39]
	v_mfma_f32_16x16x32_bf16 v[20:23], v[144:147], v[204:207], v[20:23]
	v_mfma_f32_16x16x32_bf16 v[16:19], v[172:175], v[204:207], v[16:19]
	v_mfma_f32_16x16x32_bf16 v[0:3], v[172:175], v[212:215], v[0:3]
	v_mfma_f32_16x16x32_bf16 v[4:7], v[144:147], v[212:215], v[4:7]
	v_mfma_f32_16x16x32_bf16 v[52:55], v[148:151], v[192:195], v[52:55]
	v_mfma_f32_16x16x32_bf16 v[48:51], v[176:179], v[192:195], v[48:51]
	v_mfma_f32_16x16x32_bf16 v[32:35], v[176:179], v[200:203], v[32:35]
	v_mfma_f32_16x16x32_bf16 v[36:39], v[148:151], v[200:203], v[36:39]
	v_mfma_f32_16x16x32_bf16 v[20:23], v[148:151], v[208:211], v[20:23]
	v_mfma_f32_16x16x32_bf16 v[16:19], v[176:179], v[208:211], v[16:19]
	v_mfma_f32_16x16x32_bf16 v[0:3], v[176:179], v[216:219], v[0:3]
	v_mfma_f32_16x16x32_bf16 v[4:7], v[148:151], v[216:219], v[4:7]
	s_setprio 0
	s_barrier
	s_add_i32 s75, 0, 0x18000
	s_add_i32 s76, 0, 0x1c000
	v_add_u32_e32 v140, s75, v185
	v_add_u32_e32 v176, s76, v185
	ds_read_b128 v[128:131], v140
	ds_read_b128 v[132:135], v140 offset:1024
	ds_read_b128 v[136:139], v140 offset:2048
	ds_read_b128 v[140:143], v140 offset:3072
	ds_read_b128 v[144:147], v176
	ds_read_b128 v[148:151], v176 offset:1024
	ds_read_b128 v[172:175], v176 offset:2048
	ds_read_b128 v[176:179], v176 offset:3072
	s_add_u32 s48, s54, 0xb0000
	s_addc_u32 s49, s55, 0
	s_mov_b32 m0, s61
	v_lshl_add_u64 v[228:229], s[48:49], 0, v[152:153]
	ds_read_b128 v[180:183], v190 offset:32768
	ds_read_b128 v[192:195], v190 offset:33792
	ds_read_b128 v[196:199], v190 offset:34816
	ds_read_b128 v[200:203], v190 offset:35840
	ds_read_b128 v[204:207], v190 offset:36864
	ds_read_b128 v[208:211], v190 offset:37888
	ds_read_b128 v[212:215], v190 offset:38912
	ds_read_b128 v[216:219], v190 offset:39936
	global_load_lds_dwordx4 v[228:229], off
	v_lshl_add_u64 v[228:229], s[48:49], 0, v[160:161]
	s_mov_b32 m0, s62
	s_nop 0
	global_load_lds_dwordx4 v[228:229], off
	s_waitcnt vmcnt(8)
	s_waitcnt lgkmcnt(0)
	s_barrier
	s_setprio 1
	s_waitcnt lgkmcnt(0)
	v_mfma_f32_16x16x32_bf16 v[124:127], v[128:131], v[180:183], v[124:127]
	v_mfma_f32_16x16x32_bf16 v[120:123], v[136:139], v[180:183], v[120:123]
	v_mfma_f32_16x16x32_bf16 v[104:107], v[136:139], v[196:199], v[104:107]
	v_mfma_f32_16x16x32_bf16 v[108:111], v[128:131], v[196:199], v[108:111]
	v_mfma_f32_16x16x32_bf16 v[92:95], v[128:131], v[204:207], v[92:95]
	v_mfma_f32_16x16x32_bf16 v[88:91], v[136:139], v[204:207], v[88:91]
	v_mfma_f32_16x16x32_bf16 v[72:75], v[136:139], v[212:215], v[72:75]
	v_mfma_f32_16x16x32_bf16 v[76:79], v[128:131], v[212:215], v[76:79]
	v_mfma_f32_16x16x32_bf16 v[124:127], v[132:135], v[192:195], v[124:127]
	v_mfma_f32_16x16x32_bf16 v[120:123], v[140:143], v[192:195], v[120:123]
	v_mfma_f32_16x16x32_bf16 v[104:107], v[140:143], v[200:203], v[104:107]
	v_mfma_f32_16x16x32_bf16 v[108:111], v[132:135], v[200:203], v[108:111]
	v_mfma_f32_16x16x32_bf16 v[92:95], v[132:135], v[208:211], v[92:95]
	v_mfma_f32_16x16x32_bf16 v[88:91], v[140:143], v[208:211], v[88:91]
	v_mfma_f32_16x16x32_bf16 v[72:75], v[140:143], v[216:219], v[72:75]
	v_mfma_f32_16x16x32_bf16 v[76:79], v[132:135], v[216:219], v[76:79]
	s_setprio 0
	s_setprio 1
	v_mfma_f32_16x16x32_bf16 v[116:119], v[144:147], v[180:183], v[116:119]
	v_mfma_f32_16x16x32_bf16 v[112:115], v[172:175], v[180:183], v[112:115]
	v_mfma_f32_16x16x32_bf16 v[96:99], v[172:175], v[196:199], v[96:99]
	v_mfma_f32_16x16x32_bf16 v[100:103], v[144:147], v[196:199], v[100:103]
	v_mfma_f32_16x16x32_bf16 v[84:87], v[144:147], v[204:207], v[84:87]
	v_mfma_f32_16x16x32_bf16 v[80:83], v[172:175], v[204:207], v[80:83]
	v_mfma_f32_16x16x32_bf16 v[64:67], v[172:175], v[212:215], v[64:67]
	v_mfma_f32_16x16x32_bf16 v[68:71], v[144:147], v[212:215], v[68:71]
	v_mfma_f32_16x16x32_bf16 v[116:119], v[148:151], v[192:195], v[116:119]
	v_mfma_f32_16x16x32_bf16 v[112:115], v[176:179], v[192:195], v[112:115]
	v_mfma_f32_16x16x32_bf16 v[96:99], v[176:179], v[200:203], v[96:99]
	v_mfma_f32_16x16x32_bf16 v[100:103], v[148:151], v[200:203], v[100:103]
	v_mfma_f32_16x16x32_bf16 v[84:87], v[148:151], v[208:211], v[84:87]
	v_mfma_f32_16x16x32_bf16 v[80:83], v[176:179], v[208:211], v[80:83]
	v_mfma_f32_16x16x32_bf16 v[64:67], v[176:179], v[216:219], v[64:67]
	v_mfma_f32_16x16x32_bf16 v[68:71], v[148:151], v[216:219], v[68:71]
	s_setprio 0
	s_barrier
	s_add_i32 s48, s75, s58
	v_lshl_add_u64 v[220:221], v[220:221], 0, s[22:23]
	s_mov_b32 m0, s48
	ds_read_b128 v[180:183], v190 offset:49152
	ds_read_b128 v[192:195], v190 offset:50176
	ds_read_b128 v[196:199], v190 offset:51200
	ds_read_b128 v[200:203], v190 offset:52224
	ds_read_b128 v[204:207], v190 offset:53248
	ds_read_b128 v[208:211], v190 offset:54272
	ds_read_b128 v[212:215], v190 offset:55296
	ds_read_b128 v[216:219], v190 offset:56320
	global_load_lds_dwordx4 v[220:221], off
	s_add_i32 m0, s48, 0x2000
	s_add_u32 s48, s52, 0xb0080
	v_lshl_add_u64 v[220:221], v[222:223], 0, s[22:23]
	s_addc_u32 s49, s53, 0
	s_add_i32 s52, s76, s58
	global_load_lds_dwordx4 v[220:221], off
	v_lshl_add_u64 v[220:221], s[48:49], 0, v[154:155]
	s_mov_b32 m0, s52
	s_nop 0
	global_load_lds_dwordx4 v[220:221], off
	v_lshl_add_u64 v[220:221], s[48:49], 0, v[162:163]
	s_add_i32 m0, s52, 0x2000
	s_nop 0
	global_load_lds_dwordx4 v[220:221], off
	v_lshl_add_u64 v[220:221], v[224:225], 0, s[22:23]
	s_mov_b32 m0, s3
	s_nop 0
	global_load_lds_dwordx4 v[220:221], off
	v_lshl_add_u64 v[220:221], v[226:227], 0, s[22:23]
	s_mov_b32 m0, s64
	s_nop 0
	global_load_lds_dwordx4 v[220:221], off
	s_waitcnt vmcnt(8)
	s_waitcnt lgkmcnt(0)
	s_barrier
	s_setprio 1
	s_waitcnt lgkmcnt(0)
	v_mfma_f32_16x16x32_bf16 v[60:63], v[128:131], v[180:183], v[60:63]
	v_mfma_f32_16x16x32_bf16 v[56:59], v[136:139], v[180:183], v[56:59]
	v_mfma_f32_16x16x32_bf16 v[40:43], v[136:139], v[196:199], v[40:43]
	v_mfma_f32_16x16x32_bf16 v[44:47], v[128:131], v[196:199], v[44:47]
	v_mfma_f32_16x16x32_bf16 v[28:31], v[128:131], v[204:207], v[28:31]
	v_mfma_f32_16x16x32_bf16 v[24:27], v[136:139], v[204:207], v[24:27]
	v_mfma_f32_16x16x32_bf16 v[8:11], v[136:139], v[212:215], v[8:11]
	v_mfma_f32_16x16x32_bf16 v[12:15], v[128:131], v[212:215], v[12:15]
	v_mfma_f32_16x16x32_bf16 v[60:63], v[132:135], v[192:195], v[60:63]
	v_mfma_f32_16x16x32_bf16 v[56:59], v[140:143], v[192:195], v[56:59]
	v_mfma_f32_16x16x32_bf16 v[40:43], v[140:143], v[200:203], v[40:43]
	v_mfma_f32_16x16x32_bf16 v[44:47], v[132:135], v[200:203], v[44:47]
	v_mfma_f32_16x16x32_bf16 v[28:31], v[132:135], v[208:211], v[28:31]
	v_mfma_f32_16x16x32_bf16 v[24:27], v[140:143], v[208:211], v[24:27]
	v_mfma_f32_16x16x32_bf16 v[8:11], v[140:143], v[216:219], v[8:11]
	v_mfma_f32_16x16x32_bf16 v[12:15], v[132:135], v[216:219], v[12:15]
	s_setprio 0
	s_setprio 1
	v_mfma_f32_16x16x32_bf16 v[52:55], v[144:147], v[180:183], v[52:55]
	v_mfma_f32_16x16x32_bf16 v[48:51], v[172:175], v[180:183], v[48:51]
	v_mfma_f32_16x16x32_bf16 v[32:35], v[172:175], v[196:199], v[32:35]
	v_mfma_f32_16x16x32_bf16 v[36:39], v[144:147], v[196:199], v[36:39]
	v_mfma_f32_16x16x32_bf16 v[20:23], v[144:147], v[204:207], v[20:23]
	v_mfma_f32_16x16x32_bf16 v[16:19], v[172:175], v[204:207], v[16:19]
	v_mfma_f32_16x16x32_bf16 v[0:3], v[172:175], v[212:215], v[0:3]
	v_mfma_f32_16x16x32_bf16 v[4:7], v[144:147], v[212:215], v[4:7]
	v_mfma_f32_16x16x32_bf16 v[52:55], v[148:151], v[192:195], v[52:55]
	v_mfma_f32_16x16x32_bf16 v[48:51], v[176:179], v[192:195], v[48:51]
	v_mfma_f32_16x16x32_bf16 v[32:35], v[176:179], v[200:203], v[32:35]
	v_mfma_f32_16x16x32_bf16 v[36:39], v[148:151], v[200:203], v[36:39]
	v_mfma_f32_16x16x32_bf16 v[20:23], v[148:151], v[208:211], v[20:23]
	v_mfma_f32_16x16x32_bf16 v[16:19], v[176:179], v[208:211], v[16:19]
	v_mfma_f32_16x16x32_bf16 v[0:3], v[176:179], v[216:219], v[0:3]
	v_mfma_f32_16x16x32_bf16 v[4:7], v[148:151], v[216:219], v[4:7]
	s_setprio 0
	s_barrier
	s_add_i32 s74, s74, 2
	s_add_u32 s72, s72, 0x100
	s_addc_u32 s73, s73, 0
	s_cmp_gt_u32 s74, 41
	s_mov_b64 s[48:49], s[50:51]
	s_cbranch_scc0 .LBB0_1181
	s_and_b64 vcc, exec, s[24:25]
	s_cbranch_vccz .LBB0_1184
	s_barrier
